# moved the trailing half's restore barrier from after the epilogue to just before the next unit's K-loop (its tile scheduling + accumulator zeroing now overlap the leading half's)
# baseline (speedup 1.0000x reference)
; #define LAS __attribute__((address_space(3)))
; __global__ void __launch_bounds__(NTHREADS, 2) fwd_kernel(Args a) {
;     extern __shared__ __attribute__((aligned(16))) unsigned char lds_raw[];
;     LAS unsigned char* lds = (LAS unsigned char*)lds_raw;
;     cg::grid_group grid = cg::this_grid();
;     volatile LAS unsigned* bst = (volatile LAS unsigned*)(lds + 131072 + 64);
;     if (threadIdx.x < 2) bst[threadIdx.x] = 0u;
;     __syncthreads();
;     XcdBarrier xbar = xcd_barrier_post((unsigned*)(a.p.ws + WS_BAR), bst);
;     unsigned* barw = (unsigned*)(a.p.ws + WS_BAR);
;     unsigned* tick = barw + 3520;
;     if (threadIdx.x == 0) { const unsigned x = xbar.x; bst[2] = (x < 8u) ? __hip_atomic_fetch_add(tick + 64 * x, 1u, __ATOMIC_RELAXED, __HIP_MEMORY_SCOPE_AGENT) : 0u; }
_Z10fwd_kernel4Args:
	s_mov_b32 s100, 0
	s_load_dwordx2 s[74:75], s[0:1], 0x70
	s_load_dwordx4 s[4:7], s[0:1], 0x60
	s_load_dwordx8 s[76:83], s[0:1], 0x40
	s_load_dword s9, s[0:1], 0x88
	s_load_dwordx2 s[36:37], s[0:1], 0x80
	v_writelane_b32 v252, s2, 0
	s_add_u32 s2, s0, 0x80
	s_addc_u32 s3, s1, 0
	s_waitcnt lgkmcnt(0)
	v_writelane_b32 v252, s4, 1
	v_and_b32_e32 v186, 0x3ff, v0
	v_cmp_gt_u32_e32 vcc, 2, v186
	v_writelane_b32 v252, s5, 2
	v_writelane_b32 v252, s6, 3
	v_writelane_b32 v252, s7, 4
	v_writelane_b32 v252, s2, 5
	s_nop 1
	v_writelane_b32 v252, s3, 6
	s_and_saveexec_b64 s[2:3], vcc
	v_lshl_add_u32 v1, v186, 2, 0
	v_add_u32_e32 v1, 0x20040, v1
	v_mov_b32_e32 v2, 0
	ds_write_b32 v1, v2
	s_or_b64 exec, exec, s[2:3]
	s_waitcnt lgkmcnt(0)
	s_barrier
	s_getreg_b32 s2, hwreg(HW_REG_XCC_ID, 0, 4)
	s_and_b32 s8, s2, 15
	v_cmp_eq_u32_e64 s[4:5], 0, v186
	s_mov_b64 s[2:3], exec
	s_nop 0
	v_writelane_b32 v252, s4, 7
	s_nop 1
	v_writelane_b32 v252, s5, 8
	s_and_b64 s[4:5], s[2:3], s[4:5]
	s_mov_b64 exec, s[4:5]
	s_cbranch_execz .LBB0_5
	s_mov_b64 s[4:5], exec
	v_mbcnt_lo_u32_b32 v1, s4, 0
	v_mbcnt_hi_u32_b32 v1, s5, v1
	v_cmp_eq_u32_e32 vcc, 0, v1
	s_and_b64 s[6:7], exec, vcc
	s_mov_b64 exec, s[6:7]
	s_cbranch_execz .LBB0_5
	s_lshl_b32 s6, s8, 8
	s_bcnt1_i32_b64 s4, s[4:5]
	v_mov_b32_e32 v1, s6
	v_mov_b32_e32 v2, s4
	global_atomic_add v1, v2, s[74:75] offset:1024

; #define PG8_STAGE(bufoff, gbase, voff) do { _Pragma("unroll") for (int _i = 0; _i < 2; ++_i) \
;         __builtin_amdgcn_global_load_lds((const unsigned*)((const char*)(gbase) + (voff)[_i]), (PG8_LAS unsigned*)(lds + (bufoff) + ldsw + _i * 8192), 16, 0, 0); } while (0)
; #define PG8_LDA(dst, b, h) do { _Pragma("unroll") for (int m = 0; m < 4; ++m) _Pragma("unroll") for (int k = 0; k < 2; ++k) dst[m][k] = *(const PG8_LAS bf16x8*)(lds + PG8_SA(b, h) + aoff + m * 2048 + k * 1024); } while (0)
; #define PG8_LDB(dst, b, h) do { _Pragma("unroll") for (int n = 0; n < 2; ++n) _Pragma("unroll") for (int k = 0; k < 2; ++k) dst[n][k] = *(const PG8_LAS bf16x8*)(lds + PG8_SB(b, h) + boff + n * 2048 + k * 1024); } while (0)
; #define PG8_BAR __builtin_amdgcn_s_barrier()
; #define PG8_SCHED __builtin_amdgcn_sched_barrier(0)
; template <class Epi, class Sched, bool ALIGN_EPI = false, bool SP2 = false>
; __device__ __forceinline__ void gemm_phase(PG8_LAS unsigned char* lds, const Gemm g, const Sched& S, const Epi& E) {
;     ...
;         const bool has_next = S.next(ui + 1, nxt);
;         const char* nA = has_next ? (const char*)g.A + (size_t)nxt.pm * tstep : cA; const char* nB = has_next ? (const char*)g.Bt + (size_t)nxt.pn * tstep : cB;
;         for (int t = 0; t < nt; t += 2) {
;             const bool last = (t == nt - 2);
;             const char* a1 = cA + (size_t)(t + 1) * kstep;
;             const char* a2 = last ? nA : cA + (size_t)(t + 2) * kstep; const char* b2 = last ? nB : cB + (size_t)(t + 2) * kstep;
;             const char* a3 = a2 + kstep; const char* b3 = b2 + kstep;
;             if (last && has_next) S.a_ready(nxt);
;             if constexpr (SP2) {
;             PG8_LDB(B0, 0, 0); PG8_LDB(B1, 0, 1); PG8_SCHED; PG8_LDA(At, 0, 0); PG8_STAGE(PG8_SA(1, 1), a1 + hstep, voffA);
;     ...
; #pragma unroll
;         for (int a = 0; a < 2; ++a)
; #pragma unroll
;             for (int b = 0; b < 2; ++b)
; #pragma unroll
;                 for (int m = 0; m < 4; ++m)
; #pragma unroll
;                     for (int n = 0; n < 2; ++n) acc[a][b][m][n] = (f32x4){0.f, 0.f, 0.f, 0.f};
;         cur = nxt; cA = nA; cB = nB; ++ui;
;         if constexpr (Epi::PREFETCH) E.prefetch(cur, wr, fr, epre);
;         if constexpr (ALIGN_EPI) { if (wr == 1) PG8_BAR; }
.LBB0_65:
	s_ashr_i32 s47, s46, 31
	s_lshl_b64 s[48:49], s[46:47], 19
	s_add_u32 s48, s62, s48
	s_addc_u32 s49, s63, s49
	s_and_b64 s[50:51], s[86:87], exec
	s_cselect_b32 s47, s49, s93
	s_cselect_b32 vcc_lo, s48, s92
	s_ashr_i32 s45, s44, 31
	s_lshl_b64 s[50:51], s[44:45], 19
	v_readlane_b32 s4, v254, 43
	s_add_u32 s50, s4, s50
	v_readlane_b32 s4, v254, 51
	s_addc_u32 s51, s4, s51
	s_and_b64 s[76:77], s[86:87], exec
	s_cselect_b32 s45, s51, s91
	s_cselect_b32 vcc_hi, s50, s90
	s_add_u32 s4, s90, 0x100
	s_addc_u32 s7, s91, 0
	s_add_u32 s90, s92, 0x40080
	v_mov_b32_e32 v0, 0
	s_addc_u32 s91, s93, 0
	s_mov_b32 s80, -2
	v_mov_b32_e32 v1, v0
	v_mov_b32_e32 v2, v0
	v_mov_b32_e32 v3, v0
	v_mov_b32_e32 v4, v0
	v_mov_b32_e32 v5, v0
	v_mov_b32_e32 v6, v0
	v_mov_b32_e32 v7, v0
	v_mov_b32_e32 v12, v0
	v_mov_b32_e32 v13, v0
	v_mov_b32_e32 v14, v0
	v_mov_b32_e32 v15, v0
	v_mov_b32_e32 v20, v0
	v_mov_b32_e32 v21, v0
	v_mov_b32_e32 v22, v0
	v_mov_b32_e32 v23, v0
	v_mov_b32_e32 v28, v0
	v_mov_b32_e32 v29, v0
	v_mov_b32_e32 v30, v0
	v_mov_b32_e32 v31, v0
	v_mov_b32_e32 v38, v0
	v_mov_b32_e32 v39, v0
	v_mov_b32_e32 v40, v0
	v_mov_b32_e32 v41, v0
	v_mov_b32_e32 v46, v0
	v_mov_b32_e32 v47, v0
	v_mov_b32_e32 v48, v0
	v_mov_b32_e32 v49, v0
	v_mov_b32_e32 v54, v0
	v_mov_b32_e32 v55, v0
	v_mov_b32_e32 v56, v0
	v_mov_b32_e32 v57, v0
	v_mov_b32_e32 v8, v0
	v_mov_b32_e32 v9, v0
	v_mov_b32_e32 v10, v0
	v_mov_b32_e32 v11, v0
	v_mov_b32_e32 v16, v0
	v_mov_b32_e32 v17, v0
	v_mov_b32_e32 v18, v0
	v_mov_b32_e32 v19, v0
	v_mov_b32_e32 v24, v0
	v_mov_b32_e32 v25, v0
	v_mov_b32_e32 v26, v0
	v_mov_b32_e32 v27, v0
	v_mov_b32_e32 v34, v0
	v_mov_b32_e32 v35, v0
	v_mov_b32_e32 v36, v0
	v_mov_b32_e32 v37, v0
	v_mov_b32_e32 v42, v0
	v_mov_b32_e32 v43, v0
	v_mov_b32_e32 v44, v0
	v_mov_b32_e32 v45, v0
	v_mov_b32_e32 v50, v0
	v_mov_b32_e32 v51, v0
	v_mov_b32_e32 v52, v0
	v_mov_b32_e32 v53, v0
	v_mov_b32_e32 v58, v0
	v_mov_b32_e32 v59, v0
	v_mov_b32_e32 v60, v0
	v_mov_b32_e32 v61, v0
	v_mov_b32_e32 v62, v0
	v_mov_b32_e32 v63, v0
	v_mov_b32_e32 v64, v0
	v_mov_b32_e32 v65, v0
	v_mov_b32_e32 v66, v0
	v_mov_b32_e32 v67, v0
	v_mov_b32_e32 v68, v0
	v_mov_b32_e32 v69, v0
	v_mov_b32_e32 v70, v0
	v_mov_b32_e32 v71, v0
	v_mov_b32_e32 v72, v0
	v_mov_b32_e32 v73, v0
	v_mov_b32_e32 v82, v0
	v_mov_b32_e32 v83, v0
	v_mov_b32_e32 v84, v0
	v_mov_b32_e32 v85, v0
	v_mov_b32_e32 v86, v0
	v_mov_b32_e32 v87, v0
	v_mov_b32_e32 v88, v0
	v_mov_b32_e32 v89, v0
	v_mov_b32_e32 v98, v0
	v_mov_b32_e32 v99, v0
	v_mov_b32_e32 v100, v0
	v_mov_b32_e32 v101, v0
	v_mov_b32_e32 v102, v0
	v_mov_b32_e32 v103, v0
	v_mov_b32_e32 v104, v0
	v_mov_b32_e32 v105, v0
	v_mov_b32_e32 v114, v0
	v_mov_b32_e32 v115, v0
	v_mov_b32_e32 v116, v0
	v_mov_b32_e32 v117, v0
	v_mov_b32_e32 v118, v0
	v_mov_b32_e32 v119, v0
	v_mov_b32_e32 v120, v0
	v_mov_b32_e32 v121, v0
	v_mov_b32_e32 v74, v0
	v_mov_b32_e32 v75, v0
	v_mov_b32_e32 v76, v0
	v_mov_b32_e32 v77, v0
	v_mov_b32_e32 v78, v0
	v_mov_b32_e32 v79, v0
	v_mov_b32_e32 v80, v0
	v_mov_b32_e32 v81, v0
	v_mov_b32_e32 v90, v0
	v_mov_b32_e32 v91, v0
	v_mov_b32_e32 v92, v0
	v_mov_b32_e32 v93, v0
	v_mov_b32_e32 v94, v0
	v_mov_b32_e32 v95, v0
	v_mov_b32_e32 v96, v0
	v_mov_b32_e32 v97, v0
	v_mov_b32_e32 v106, v0
	v_mov_b32_e32 v107, v0
	v_mov_b32_e32 v108, v0
	v_mov_b32_e32 v109, v0
	v_mov_b32_e32 v110, v0
	v_mov_b32_e32 v111, v0
	v_mov_b32_e32 v112, v0
	v_mov_b32_e32 v113, v0
	v_mov_b32_e32 v122, v0
	v_mov_b32_e32 v123, v0
	v_mov_b32_e32 v124, v0
	v_mov_b32_e32 v125, v0
	v_mov_b32_e32 v126, v0
	v_mov_b32_e32 v127, v0
	v_mov_b32_e32 v128, v0
	v_mov_b32_e32 v129, v0
	s_cmp_eq_u32 s100, 0
	s_cbranch_scc1 .Lrb0_skip
	s_mov_b32 s100, 0
	s_barrier
.Lrb0_skip:
.LBB0_66:
	s_add_u32 s61, s90, 0xfffc0080
	s_addc_u32 s72, s91, -1
	s_add_i32 s73, 0, 0x10000
	s_cmp_eq_u32 s80, 12
	s_cselect_b32 s95, s47, s72
	s_cselect_b32 s94, vcc_lo, s61
	v_add_u32_e32 v147, s73, v139
	s_cselect_b32 s93, s45, s7
	s_cselect_b32 s92, vcc_hi, s4
	s_add_i32 s61, 0, 0x14000
	ds_read_b128 v[170:173], v147
	ds_read_b128 v[174:177], v147 offset:1024
	ds_read_b128 v[178:181], v147 offset:2048
	ds_read_b128 v[182:185], v147 offset:3072
	v_add_u32_e32 v147, s61, v139
	ds_read_b128 v[196:199], v147
	ds_read_b128 v[200:203], v147 offset:1024
	ds_read_b128 v[204:207], v147 offset:2048
	ds_read_b128 v[208:211], v147 offset:3072
	v_lshl_add_u64 v[160:161], s[90:91], 0, v[150:151]
	s_add_i32 m0, s8, 0xc000
	ds_read_b128 v[212:215], v143
	ds_read_b128 v[216:219], v143 offset:1024
	ds_read_b128 v[220:223], v143 offset:2048
	ds_read_b128 v[224:227], v143 offset:3072
	ds_read_b128 v[228:231], v143 offset:4096
	ds_read_b128 v[232:235], v143 offset:5120
	ds_read_b128 v[236:239], v143 offset:6144
	ds_read_b128 v[240:243], v143 offset:7168
	global_load_lds_dwordx4 v[160:161], off
	v_lshl_add_u64 v[160:161], s[90:91], 0, v[148:149]
	s_add_i32 m0, s8, 0xe000
	s_nop 0
	global_load_lds_dwordx4 v[160:161], off
	s_waitcnt vmcnt(8)
	s_waitcnt lgkmcnt(0)
	s_barrier
; #define PG8_STAGE(bufoff, gbase, voff) do { _Pragma("unroll") for (int _i = 0; _i < 2; ++_i) \
;         __builtin_amdgcn_global_load_lds((const unsigned*)((const char*)(gbase) + (voff)[_i]), (PG8_LAS unsigned*)(lds + (bufoff) + ldsw + _i * 8192), 16, 0, 0); } while (0)
; #define PG8_LDA(dst, b, h) do { _Pragma("unroll") for (int m = 0; m < 4; ++m) _Pragma("unroll") for (int k = 0; k < 2; ++k) dst[m][k] = *(const PG8_LAS bf16x8*)(lds + PG8_SA(b, h) + aoff + m * 2048 + k * 1024); } while (0)
; #define PG8_MMA(ai, bj, At, Bt) do { __builtin_amdgcn_s_setprio(1); _Pragma("unroll") for (int m = 0; m < 4; ++m) _Pragma("unroll") for (int n = 0; n < 2; ++n) _Pragma("unroll") for (int k = 0; k < 2; ++k) \
;         acc[ai][bj][m][n] = __builtin_amdgcn_mfma_f32_16x16x32_bf16(Bt[n][k], At[m][k], acc[ai][bj][m][n], 0, 0, 0); __builtin_amdgcn_s_setprio(0); } while (0)
; #define PG8_WAIT_V(n) asm volatile("s_waitcnt vmcnt(" #n ")" ::: "memory")
; #define PG8_WAIT_L(n) asm volatile("s_waitcnt lgkmcnt(" #n ")" ::: "memory")
; #define PG8_BAR __builtin_amdgcn_s_barrier()
; #define PG8_SCHED __builtin_amdgcn_sched_barrier(0)
; template <class Epi, class Sched, bool ALIGN_EPI = false, bool SP2 = false>
; __device__ __forceinline__ void gemm_phase(PG8_LAS unsigned char* lds, const Gemm g, const Sched& S, const Epi& E) {
;     ...
;             PG8_WAIT_V(8); PG8_WAIT_L(0); PG8_BAR; PG8_MMA(0, 0, At, B0); PG8_MMA(0, 1, At, B1); PG8_BAR; PG8_SCHED;
;             PG8_LDA(At, 0, 1); PG8_STAGE(PG8_SB(0, 0), b2, voffB); PG8_STAGE(PG8_SB(0, 1), b2 + hstep, voffB); PG8_STAGE(PG8_SA(0, 0), a2, voffA);
;             PG8_WAIT_V(8); PG8_WAIT_L(0); PG8_BAR; PG8_MMA(1, 0, At, B0); PG8_MMA(1, 1, At, B1); PG8_BAR; PG8_SCHED;
	v_mfma_f32_16x16x32_bf16 v[126:129], v[170:173], v[212:215], v[126:129]
	v_mfma_f32_16x16x32_bf16 v[122:125], v[178:181], v[212:215], v[122:125]
	v_mfma_f32_16x16x32_bf16 v[110:113], v[170:173], v[220:223], v[110:113]
	v_mfma_f32_16x16x32_bf16 v[106:109], v[178:181], v[220:223], v[106:109]
	v_mfma_f32_16x16x32_bf16 v[94:97], v[170:173], v[228:231], v[94:97]
	v_mfma_f32_16x16x32_bf16 v[90:93], v[178:181], v[228:231], v[90:93]
	v_mfma_f32_16x16x32_bf16 v[78:81], v[170:173], v[236:239], v[78:81]
	v_mfma_f32_16x16x32_bf16 v[74:77], v[178:181], v[236:239], v[74:77]
	v_mfma_f32_16x16x32_bf16 v[126:129], v[174:177], v[216:219], v[126:129]
	v_mfma_f32_16x16x32_bf16 v[122:125], v[182:185], v[216:219], v[122:125]
	v_mfma_f32_16x16x32_bf16 v[110:113], v[174:177], v[224:227], v[110:113]
	v_mfma_f32_16x16x32_bf16 v[106:109], v[182:185], v[224:227], v[106:109]
	v_mfma_f32_16x16x32_bf16 v[94:97], v[174:177], v[232:235], v[94:97]
	v_mfma_f32_16x16x32_bf16 v[90:93], v[182:185], v[232:235], v[90:93]
	v_mfma_f32_16x16x32_bf16 v[78:81], v[174:177], v[240:243], v[78:81]
	v_mfma_f32_16x16x32_bf16 v[74:77], v[182:185], v[240:243], v[74:77]
	v_mfma_f32_16x16x32_bf16 v[118:121], v[196:199], v[212:215], v[118:121]
	v_mfma_f32_16x16x32_bf16 v[114:117], v[204:207], v[212:215], v[114:117]
	v_mfma_f32_16x16x32_bf16 v[102:105], v[196:199], v[220:223], v[102:105]
	v_mfma_f32_16x16x32_bf16 v[98:101], v[204:207], v[220:223], v[98:101]
	v_mfma_f32_16x16x32_bf16 v[86:89], v[196:199], v[228:231], v[86:89]
	v_mfma_f32_16x16x32_bf16 v[82:85], v[204:207], v[228:231], v[82:85]
	v_mfma_f32_16x16x32_bf16 v[70:73], v[196:199], v[236:239], v[70:73]
	v_mfma_f32_16x16x32_bf16 v[66:69], v[204:207], v[236:239], v[66:69]
	v_mfma_f32_16x16x32_bf16 v[118:121], v[200:203], v[216:219], v[118:121]
	v_mfma_f32_16x16x32_bf16 v[114:117], v[208:211], v[216:219], v[114:117]
	v_mfma_f32_16x16x32_bf16 v[102:105], v[200:203], v[224:227], v[102:105]
	v_mfma_f32_16x16x32_bf16 v[98:101], v[208:211], v[224:227], v[98:101]
	v_mfma_f32_16x16x32_bf16 v[86:89], v[200:203], v[232:235], v[86:89]
	v_mfma_f32_16x16x32_bf16 v[82:85], v[208:211], v[232:235], v[82:85]
	v_mfma_f32_16x16x32_bf16 v[70:73], v[200:203], v[240:243], v[70:73]
	v_mfma_f32_16x16x32_bf16 v[66:69], v[208:211], v[240:243], v[66:69]
	s_barrier
	s_add_i32 s72, s73, s5
	v_lshl_add_u64 v[160:161], s[92:93], 0, v[132:133]
	s_mov_b32 m0, s72
	ds_read_b128 v[212:215], v143 offset:16384
	ds_read_b128 v[216:219], v143 offset:17408
	ds_read_b128 v[220:223], v143 offset:18432
	ds_read_b128 v[224:227], v143 offset:19456
	ds_read_b128 v[228:231], v143 offset:20480
	ds_read_b128 v[232:235], v143 offset:21504
	ds_read_b128 v[236:239], v143 offset:22528
	ds_read_b128 v[240:243], v143 offset:23552
	global_load_lds_dwordx4 v[160:161], off
	s_add_i32 m0, s72, 0x2000
	s_add_u32 s76, s92, 0x40000
	v_lshl_add_u64 v[244:245], s[92:93], 0, v[136:137]
	s_addc_u32 s77, s93, 0
	s_add_i32 s61, s61, s5
	global_load_lds_dwordx4 v[244:245], off
	v_lshl_add_u64 v[246:247], s[76:77], 0, v[132:133]
	s_mov_b32 m0, s61
	v_lshl_add_u64 v[248:249], s[94:95], 0, v[134:135]
	global_load_lds_dwordx4 v[246:247], off
	v_lshl_add_u64 v[246:247], s[76:77], 0, v[136:137]
	s_add_i32 m0, s61, 0x2000
	s_nop 0
	global_load_lds_dwordx4 v[246:247], off
	v_lshl_add_u64 v[246:247], s[94:95], 0, v[130:131]
	s_mov_b32 m0, s8
	s_nop 0
	global_load_lds_dwordx4 v[246:247], off
	s_mov_b32 m0, s9
	s_nop 0
	global_load_lds_dwordx4 v[248:249], off
	s_waitcnt vmcnt(8)
	s_waitcnt lgkmcnt(0)
	s_barrier
	v_mfma_f32_16x16x32_bf16 v[62:65], v[170:173], v[212:215], v[62:65]
	v_mfma_f32_16x16x32_bf16 v[58:61], v[178:181], v[212:215], v[58:61]
	v_mfma_f32_16x16x32_bf16 v[50:53], v[170:173], v[220:223], v[50:53]
	v_mfma_f32_16x16x32_bf16 v[42:45], v[178:181], v[220:223], v[42:45]
	v_mfma_f32_16x16x32_bf16 v[34:37], v[170:173], v[228:231], v[34:37]
	v_mfma_f32_16x16x32_bf16 v[24:27], v[178:181], v[228:231], v[24:27]
	v_mfma_f32_16x16x32_bf16 v[16:19], v[170:173], v[236:239], v[16:19]
	v_mfma_f32_16x16x32_bf16 v[8:11], v[178:181], v[236:239], v[8:11]
	v_mfma_f32_16x16x32_bf16 v[62:65], v[174:177], v[216:219], v[62:65]
	v_mfma_f32_16x16x32_bf16 v[58:61], v[182:185], v[216:219], v[58:61]
	v_mfma_f32_16x16x32_bf16 v[50:53], v[174:177], v[224:227], v[50:53]
	v_mfma_f32_16x16x32_bf16 v[42:45], v[182:185], v[224:227], v[42:45]
	v_mfma_f32_16x16x32_bf16 v[34:37], v[174:177], v[232:235], v[34:37]
	v_mfma_f32_16x16x32_bf16 v[24:27], v[182:185], v[232:235], v[24:27]
	v_mfma_f32_16x16x32_bf16 v[16:19], v[174:177], v[240:243], v[16:19]
	v_mfma_f32_16x16x32_bf16 v[8:11], v[182:185], v[240:243], v[8:11]
	v_mfma_f32_16x16x32_bf16 v[54:57], v[196:199], v[212:215], v[54:57]
	v_mfma_f32_16x16x32_bf16 v[46:49], v[204:207], v[212:215], v[46:49]
	v_mfma_f32_16x16x32_bf16 v[38:41], v[196:199], v[220:223], v[38:41]
	v_mfma_f32_16x16x32_bf16 v[28:31], v[204:207], v[220:223], v[28:31]
	v_mfma_f32_16x16x32_bf16 v[20:23], v[196:199], v[228:231], v[20:23]
	v_mfma_f32_16x16x32_bf16 v[12:15], v[204:207], v[228:231], v[12:15]
	v_mfma_f32_16x16x32_bf16 v[4:7], v[196:199], v[236:239], v[4:7]
	v_mfma_f32_16x16x32_bf16 v[0:3], v[204:207], v[236:239], v[0:3]
	v_mfma_f32_16x16x32_bf16 v[54:57], v[200:203], v[216:219], v[54:57]
	v_mfma_f32_16x16x32_bf16 v[46:49], v[208:211], v[216:219], v[46:49]
	v_mfma_f32_16x16x32_bf16 v[38:41], v[200:203], v[224:227], v[38:41]
	v_mfma_f32_16x16x32_bf16 v[28:31], v[208:211], v[224:227], v[28:31]
	v_mfma_f32_16x16x32_bf16 v[20:23], v[200:203], v[232:235], v[20:23]
	v_mfma_f32_16x16x32_bf16 v[12:15], v[208:211], v[232:235], v[12:15]
	v_mfma_f32_16x16x32_bf16 v[4:7], v[200:203], v[240:243], v[4:7]
	v_mfma_f32_16x16x32_bf16 v[0:3], v[208:211], v[240:243], v[0:3]
	s_barrier
; #define PG8_STAGE(bufoff, gbase, voff) do { _Pragma("unroll") for (int _i = 0; _i < 2; ++_i) \
;         __builtin_amdgcn_global_load_lds((const unsigned*)((const char*)(gbase) + (voff)[_i]), (PG8_LAS unsigned*)(lds + (bufoff) + ldsw + _i * 8192), 16, 0, 0); } while (0)
; #define PG8_LDA(dst, b, h) do { _Pragma("unroll") for (int m = 0; m < 4; ++m) _Pragma("unroll") for (int k = 0; k < 2; ++k) dst[m][k] = *(const PG8_LAS bf16x8*)(lds + PG8_SA(b, h) + aoff + m * 2048 + k * 1024); } while (0)
; #define PG8_LDB(dst, b, h) do { _Pragma("unroll") for (int n = 0; n < 2; ++n) _Pragma("unroll") for (int k = 0; k < 2; ++k) dst[n][k] = *(const PG8_LAS bf16x8*)(lds + PG8_SB(b, h) + boff + n * 2048 + k * 1024); } while (0)
; #define PG8_MMA(ai, bj, At, Bt) do { __builtin_amdgcn_s_setprio(1); _Pragma("unroll") for (int m = 0; m < 4; ++m) _Pragma("unroll") for (int n = 0; n < 2; ++n) _Pragma("unroll") for (int k = 0; k < 2; ++k) \
;         acc[ai][bj][m][n] = __builtin_amdgcn_mfma_f32_16x16x32_bf16(Bt[n][k], At[m][k], acc[ai][bj][m][n], 0, 0, 0); __builtin_amdgcn_s_setprio(0); } while (0)
; #define PG8_WAIT_V(n) asm volatile("s_waitcnt vmcnt(" #n ")" ::: "memory")
; #define PG8_WAIT_L(n) asm volatile("s_waitcnt lgkmcnt(" #n ")" ::: "memory")
; #define PG8_BAR __builtin_amdgcn_s_barrier()
; #define PG8_SCHED __builtin_amdgcn_sched_barrier(0)
; template <class Epi, class Sched, bool ALIGN_EPI = false, bool SP2 = false>
; __device__ __forceinline__ void gemm_phase(PG8_LAS unsigned char* lds, const Gemm g, const Sched& S, const Epi& E) {
;     ...
;             PG8_LDB(B0, 1, 0); PG8_LDB(B1, 1, 1); PG8_SCHED; PG8_LDA(At, 1, 0); PG8_STAGE(PG8_SA(0, 1), a2 + hstep, voffA);
;             PG8_WAIT_V(8); PG8_WAIT_L(0); PG8_BAR; PG8_MMA(0, 0, At, B0); PG8_MMA(0, 1, At, B1); PG8_BAR; PG8_SCHED;
;             PG8_LDA(At, 1, 1); PG8_STAGE(PG8_SB(1, 0), b3, voffB); PG8_STAGE(PG8_SB(1, 1), b3 + hstep, voffB); PG8_STAGE(PG8_SA(1, 0), a3, voffA);
;             PG8_WAIT_V(8); PG8_WAIT_L(0); PG8_BAR; PG8_MMA(1, 0, At, B0); PG8_MMA(1, 1, At, B1); PG8_BAR; PG8_SCHED;
	s_add_i32 s61, 0, 0x18000
	v_add_u32_e32 v147, s61, v139
	s_add_i32 s72, 0, 0x1c000
	ds_read_b128 v[170:173], v147
	ds_read_b128 v[174:177], v147 offset:1024
	ds_read_b128 v[178:181], v147 offset:2048
	ds_read_b128 v[182:185], v147 offset:3072
	v_add_u32_e32 v147, s72, v139
	ds_read_b128 v[196:199], v147
	ds_read_b128 v[200:203], v147 offset:1024
	ds_read_b128 v[204:207], v147 offset:2048
	ds_read_b128 v[208:211], v147 offset:3072
	s_add_u32 s76, s94, 0x40000
	s_addc_u32 s77, s95, 0
	s_mov_b32 m0, s89
	v_lshl_add_u64 v[250:251], s[76:77], 0, v[130:131]
	ds_read_b128 v[212:215], v143 offset:32768
	ds_read_b128 v[216:219], v143 offset:33792
	ds_read_b128 v[220:223], v143 offset:34816
	ds_read_b128 v[224:227], v143 offset:35840
	ds_read_b128 v[228:231], v143 offset:36864
	ds_read_b128 v[232:235], v143 offset:37888
	ds_read_b128 v[236:239], v143 offset:38912
	ds_read_b128 v[240:243], v143 offset:39936
	global_load_lds_dwordx4 v[250:251], off
	v_lshl_add_u64 v[250:251], s[76:77], 0, v[134:135]
	s_mov_b32 m0, s96
	s_nop 0
	global_load_lds_dwordx4 v[250:251], off
	s_waitcnt vmcnt(8)
	s_waitcnt lgkmcnt(0)
	s_barrier
	v_mfma_f32_16x16x32_bf16 v[126:129], v[170:173], v[212:215], v[126:129]
	v_mfma_f32_16x16x32_bf16 v[122:125], v[178:181], v[212:215], v[122:125]
	v_mfma_f32_16x16x32_bf16 v[110:113], v[170:173], v[220:223], v[110:113]
	v_mfma_f32_16x16x32_bf16 v[106:109], v[178:181], v[220:223], v[106:109]
	v_mfma_f32_16x16x32_bf16 v[94:97], v[170:173], v[228:231], v[94:97]
	v_mfma_f32_16x16x32_bf16 v[90:93], v[178:181], v[228:231], v[90:93]
	v_mfma_f32_16x16x32_bf16 v[78:81], v[170:173], v[236:239], v[78:81]
	v_mfma_f32_16x16x32_bf16 v[74:77], v[178:181], v[236:239], v[74:77]
	v_mfma_f32_16x16x32_bf16 v[126:129], v[174:177], v[216:219], v[126:129]
	v_mfma_f32_16x16x32_bf16 v[122:125], v[182:185], v[216:219], v[122:125]
	v_mfma_f32_16x16x32_bf16 v[110:113], v[174:177], v[224:227], v[110:113]
	v_mfma_f32_16x16x32_bf16 v[106:109], v[182:185], v[224:227], v[106:109]
	v_mfma_f32_16x16x32_bf16 v[94:97], v[174:177], v[232:235], v[94:97]
	v_mfma_f32_16x16x32_bf16 v[90:93], v[182:185], v[232:235], v[90:93]
	v_mfma_f32_16x16x32_bf16 v[78:81], v[174:177], v[240:243], v[78:81]
	v_mfma_f32_16x16x32_bf16 v[74:77], v[182:185], v[240:243], v[74:77]
	v_mfma_f32_16x16x32_bf16 v[118:121], v[196:199], v[212:215], v[118:121]
	v_mfma_f32_16x16x32_bf16 v[114:117], v[204:207], v[212:215], v[114:117]
	v_mfma_f32_16x16x32_bf16 v[102:105], v[196:199], v[220:223], v[102:105]
	v_mfma_f32_16x16x32_bf16 v[98:101], v[204:207], v[220:223], v[98:101]
	v_mfma_f32_16x16x32_bf16 v[86:89], v[196:199], v[228:231], v[86:89]
	v_mfma_f32_16x16x32_bf16 v[82:85], v[204:207], v[228:231], v[82:85]
	v_mfma_f32_16x16x32_bf16 v[70:73], v[196:199], v[236:239], v[70:73]
	v_mfma_f32_16x16x32_bf16 v[66:69], v[204:207], v[236:239], v[66:69]
	v_mfma_f32_16x16x32_bf16 v[118:121], v[200:203], v[216:219], v[118:121]
	v_mfma_f32_16x16x32_bf16 v[114:117], v[208:211], v[216:219], v[114:117]
	v_mfma_f32_16x16x32_bf16 v[102:105], v[200:203], v[224:227], v[102:105]
	v_mfma_f32_16x16x32_bf16 v[98:101], v[208:211], v[224:227], v[98:101]
	v_mfma_f32_16x16x32_bf16 v[86:89], v[200:203], v[232:235], v[86:89]
	v_mfma_f32_16x16x32_bf16 v[82:85], v[208:211], v[232:235], v[82:85]
	v_mfma_f32_16x16x32_bf16 v[70:73], v[200:203], v[240:243], v[70:73]
	v_mfma_f32_16x16x32_bf16 v[66:69], v[208:211], v[240:243], v[66:69]
	s_barrier
	s_add_i32 s61, s61, s5
	v_lshl_add_u64 v[160:161], v[160:161], 0, s[34:35]
	s_mov_b32 m0, s61
	ds_read_b128 v[212:215], v143 offset:49152
	ds_read_b128 v[216:219], v143 offset:50176
	ds_read_b128 v[220:223], v143 offset:51200
	ds_read_b128 v[224:227], v143 offset:52224
	ds_read_b128 v[228:231], v143 offset:53248
	ds_read_b128 v[232:235], v143 offset:54272
	ds_read_b128 v[236:239], v143 offset:55296
	ds_read_b128 v[240:243], v143 offset:56320
	global_load_lds_dwordx4 v[160:161], off
	s_add_i32 m0, s61, 0x2000
	s_add_u32 s76, s92, 0x40080
	v_lshl_add_u64 v[160:161], v[244:245], 0, s[34:35]
	s_addc_u32 s77, s93, 0
	s_add_i32 s61, s72, s5
	global_load_lds_dwordx4 v[160:161], off
	v_lshl_add_u64 v[160:161], s[76:77], 0, v[132:133]
	s_mov_b32 m0, s61
	s_nop 0
	global_load_lds_dwordx4 v[160:161], off
	v_lshl_add_u64 v[160:161], s[76:77], 0, v[136:137]
	s_add_i32 m0, s61, 0x2000
	s_nop 0
	global_load_lds_dwordx4 v[160:161], off
	v_lshl_add_u64 v[160:161], v[246:247], 0, s[34:35]
	s_mov_b32 m0, s0
	s_nop 0
	global_load_lds_dwordx4 v[160:161], off
	v_lshl_add_u64 v[160:161], v[248:249], 0, s[34:35]
	s_mov_b32 m0, s97
	s_nop 0
	global_load_lds_dwordx4 v[160:161], off
	s_waitcnt vmcnt(8)
	s_waitcnt lgkmcnt(0)
	s_barrier
; __device__ __forceinline__ unsigned cvt_pk_bf16(float lo, float hi) { unsigned r; asm volatile("v_cvt_pk_bf16_f32 %0, %1, %2" : "=v"(r) : "v"(lo), "v"(hi)); return r; }
; #define GAS __attribute__((address_space(1)))
;     __device__ __forceinline__ void operator()(const f32x4 (&acc)[2][2][4][2], const Unit& u, int wr, int wc, int fr, int fq, const float (&pre)[8]) const {
;     ...
;         for (int ai = 0; ai < 2; ++ai)
; #pragma unroll
;             for (int m = 0; m < 4; ++m) {
;                 const int row = row0 + ai * 128 + m * 16; bf16_t* rowp = O + (size_t)row * ldc + col0; float rs = 0.f;
;                 float rsc = 1.f; if (RS == 1) rsc = pre[ai * 4 + m];
; #pragma unroll
;                 for (int bj = 0; bj < 2; ++bj) {
;                     f32x4 v0 = acc[ai][bj][m][0], v1 = acc[ai][bj][m][1];
;                     if (RS == 1) { v0 = v0 * rsc; v1 = v1 * rsc; }
;                     if (RS == 2) { v0 = v0 * csc[bj][0]; v1 = v1 * csc[bj][1]; }
;                     if (ACT == 1) { const f32x2 a = gelu_pk((f32x2){v0[0], v0[1]}), b = gelu_pk((f32x2){v0[2], v0[3]}), c = gelu_pk((f32x2){v1[0], v1[1]}), d = gelu_pk((f32x2){v1[2], v1[3]});
;                         v0 = (f32x4){a.x, a.y, b.x, b.y}; v1 = (f32x4){c.x, c.y, d.x, d.y}; }
;                     v0 = v0 * sc; v1 = v1 * sc;
;                     if (STAT == 1) rs += (v0[0] * v0[0] + v0[1] * v0[1]) + (v0[2] * v0[2] + v0[3] * v0[3]) + (v1[0] * v1[0] + v1[1] * v1[1]) + (v1[2] * v1[2] + v1[3] * v1[3]);
;                     if (STAT == 2) {
; #pragma unroll
;                         for (int e = 0; e < 4; ++e) { cs[bj][0][e] += v0[e]; cq[bj][0][e] += v0[e] * v0[e]; cs[bj][1][e] += v1[e]; cq[bj][1][e] += v1[e] * v1[e]; } }
;                     u32x4 w; w.x = cvt_pk_bf16(v0[0], v0[1]); w.y = cvt_pk_bf16(v0[2], v0[3]); w.z = cvt_pk_bf16(v1[0], v1[1]); w.w = cvt_pk_bf16(v1[2], v1[3]);
;                     *(GAS u32x4*)(rowp + bj * 128) = w; }
	v_mfma_f32_16x16x32_bf16 v[62:65], v[170:173], v[212:215], v[62:65]
	v_mfma_f32_16x16x32_bf16 v[58:61], v[178:181], v[212:215], v[58:61]
	v_mfma_f32_16x16x32_bf16 v[50:53], v[170:173], v[220:223], v[50:53]
	v_mfma_f32_16x16x32_bf16 v[42:45], v[178:181], v[220:223], v[42:45]
	v_mfma_f32_16x16x32_bf16 v[34:37], v[170:173], v[228:231], v[34:37]
	v_mfma_f32_16x16x32_bf16 v[24:27], v[178:181], v[228:231], v[24:27]
	v_mfma_f32_16x16x32_bf16 v[16:19], v[170:173], v[236:239], v[16:19]
	v_mfma_f32_16x16x32_bf16 v[8:11], v[178:181], v[236:239], v[8:11]
	v_mfma_f32_16x16x32_bf16 v[62:65], v[174:177], v[216:219], v[62:65]
	v_mfma_f32_16x16x32_bf16 v[58:61], v[182:185], v[216:219], v[58:61]
	v_mfma_f32_16x16x32_bf16 v[50:53], v[174:177], v[224:227], v[50:53]
	v_mfma_f32_16x16x32_bf16 v[42:45], v[182:185], v[224:227], v[42:45]
	v_mfma_f32_16x16x32_bf16 v[34:37], v[174:177], v[232:235], v[34:37]
	v_mfma_f32_16x16x32_bf16 v[24:27], v[182:185], v[232:235], v[24:27]
	v_mfma_f32_16x16x32_bf16 v[16:19], v[174:177], v[240:243], v[16:19]
	v_mfma_f32_16x16x32_bf16 v[8:11], v[182:185], v[240:243], v[8:11]
	v_mfma_f32_16x16x32_bf16 v[54:57], v[196:199], v[212:215], v[54:57]
	v_mfma_f32_16x16x32_bf16 v[46:49], v[204:207], v[212:215], v[46:49]
	v_mfma_f32_16x16x32_bf16 v[38:41], v[196:199], v[220:223], v[38:41]
	v_mfma_f32_16x16x32_bf16 v[28:31], v[204:207], v[220:223], v[28:31]
	v_mfma_f32_16x16x32_bf16 v[20:23], v[196:199], v[228:231], v[20:23]
	v_mfma_f32_16x16x32_bf16 v[12:15], v[204:207], v[228:231], v[12:15]
	v_mfma_f32_16x16x32_bf16 v[4:7], v[196:199], v[236:239], v[4:7]
	v_mfma_f32_16x16x32_bf16 v[0:3], v[204:207], v[236:239], v[0:3]
	v_mfma_f32_16x16x32_bf16 v[54:57], v[200:203], v[216:219], v[54:57]
	v_mfma_f32_16x16x32_bf16 v[46:49], v[208:211], v[216:219], v[46:49]
	v_mfma_f32_16x16x32_bf16 v[38:41], v[200:203], v[224:227], v[38:41]
	v_mfma_f32_16x16x32_bf16 v[28:31], v[208:211], v[224:227], v[28:31]
	v_mfma_f32_16x16x32_bf16 v[20:23], v[200:203], v[232:235], v[20:23]
	v_mfma_f32_16x16x32_bf16 v[12:15], v[208:211], v[232:235], v[12:15]
	v_mfma_f32_16x16x32_bf16 v[4:7], v[200:203], v[240:243], v[4:7]
	v_mfma_f32_16x16x32_bf16 v[0:3], v[208:211], v[240:243], v[0:3]
	s_barrier
	s_add_i32 s80, s80, 2
	s_add_u32 s4, s4, 0x100
	s_addc_u32 s7, s7, 0
	s_add_u32 s90, s90, 0x100
	s_addc_u32 s91, s91, 0
	s_cmp_gt_u32 s80, 13
	s_cbranch_scc0 .LBB0_66
	s_and_b64 vcc, exec, s[38:39]
	s_cbranch_vccz .LBB0_69
	s_barrier
.LBB0_69:
	v_lshl_add_u32 v172, s88, 8, v33
	v_lshl_or_b32 v170, s3, 8, v141
	s_cmp_lt_i32 s3, 4
	v_ashrrev_i32_e32 v173, 31, v172
	s_cselect_b64 vcc, -1, 0
	v_ashrrev_i32_e32 v171, 31, v170
	v_lshlrev_b64 v[174:175], 12, v[172:173]
	v_cndmask_b32_e32 v160, 1.0, v190, vcc
	v_lshl_add_u64 v[174:175], s[82:83], 0, v[174:175]
	v_lshlrev_b64 v[176:177], 1, v[170:171]
	v_pk_mul_f32 v[128:129], v[158:159], v[128:129] op_sel_hi:[0,1]
	v_pk_mul_f32 v[126:127], v[158:159], v[126:127] op_sel_hi:[0,1]
	v_pk_mul_f32 v[124:125], v[158:159], v[124:125] op_sel_hi:[0,1]
	v_pk_mul_f32 v[122:123], v[158:159], v[122:123] op_sel_hi:[0,1]
	v_lshl_add_u64 v[170:171], v[174:175], 0, v[176:177]
	v_pk_mul_f32 v[128:129], v[160:161], v[128:129] op_sel_hi:[0,1]
	v_pk_mul_f32 v[126:127], v[160:161], v[126:127] op_sel_hi:[0,1]
	v_pk_mul_f32 v[174:175], v[160:161], v[124:125] op_sel_hi:[0,1]
	v_pk_mul_f32 v[124:125], v[160:161], v[122:123] op_sel_hi:[0,1]
	v_cvt_pk_bf16_f32 v122, v126, v127
	v_cvt_pk_bf16_f32 v123, v128, v129
	v_pk_mul_f32 v[118:119], v[158:159], v[118:119] op_sel_hi:[0,1]
	v_pk_mul_f32 v[116:117], v[158:159], v[116:117] op_sel_hi:[0,1]
	v_pk_mul_f32 v[114:115], v[158:159], v[114:115] op_sel_hi:[0,1]
	v_cvt_pk_bf16_f32 v124, v124, v125
	v_cvt_pk_bf16_f32 v125, v174, v175
	global_store_dwordx4 v[170:171], v[122:125], off
	v_pk_mul_f32 v[120:121], v[158:159], v[120:121] op_sel_hi:[0,1]
	v_pk_mul_f32 v[118:119], v[160:161], v[118:119] op_sel_hi:[0,1]
	v_pk_mul_f32 v[122:123], v[160:161], v[116:117] op_sel_hi:[0,1]
	v_pk_mul_f32 v[116:117], v[160:161], v[114:115] op_sel_hi:[0,1]
	v_cvt_pk_bf16_f32 v114, v118, v119
	v_pk_mul_f32 v[120:121], v[160:161], v[120:121] op_sel_hi:[0,1]
	v_cvt_pk_bf16_f32 v115, v120, v121
	v_cvt_pk_bf16_f32 v116, v116, v117
	v_cvt_pk_bf16_f32 v117, v122, v123
	global_store_dwordx4 v[170:171], v[114:117], off offset:256
	v_pk_mul_f32 v[112:113], v[156:157], v[112:113] op_sel_hi:[0,1]
	v_pk_mul_f32 v[110:111], v[156:157], v[110:111] op_sel_hi:[0,1]
	v_or_b32_e32 v114, 16, v172
	v_ashrrev_i32_e32 v115, 31, v114
	v_lshlrev_b64 v[114:115], 12, v[114:115]
	v_lshl_add_u64 v[114:115], s[82:83], 0, v[114:115]
	v_pk_mul_f32 v[108:109], v[156:157], v[108:109] op_sel_hi:[0,1]
	v_pk_mul_f32 v[106:107], v[156:157], v[106:107] op_sel_hi:[0,1]
	v_lshl_add_u64 v[114:115], v[114:115], 0, v[176:177]
	v_pk_mul_f32 v[112:113], v[160:161], v[112:113] op_sel_hi:[0,1]
	v_pk_mul_f32 v[110:111], v[160:161], v[110:111] op_sel_hi:[0,1]
	v_pk_mul_f32 v[116:117], v[160:161], v[108:109] op_sel_hi:[0,1]
	v_pk_mul_f32 v[108:109], v[160:161], v[106:107] op_sel_hi:[0,1]
	v_cvt_pk_bf16_f32 v106, v110, v111
	v_cvt_pk_bf16_f32 v107, v112, v113
	v_pk_mul_f32 v[102:103], v[156:157], v[102:103] op_sel_hi:[0,1]
	v_pk_mul_f32 v[100:101], v[156:157], v[100:101] op_sel_hi:[0,1]
	v_pk_mul_f32 v[98:99], v[156:157], v[98:99] op_sel_hi:[0,1]
	v_cvt_pk_bf16_f32 v108, v108, v109
	v_cvt_pk_bf16_f32 v109, v116, v117
	global_store_dwordx4 v[114:115], v[106:109], off
	v_pk_mul_f32 v[104:105], v[156:157], v[104:105] op_sel_hi:[0,1]
	v_pk_mul_f32 v[102:103], v[160:161], v[102:103] op_sel_hi:[0,1]
	v_pk_mul_f32 v[106:107], v[160:161], v[100:101] op_sel_hi:[0,1]
	v_pk_mul_f32 v[100:101], v[160:161], v[98:99] op_sel_hi:[0,1]
; __device__ __forceinline__ unsigned cvt_pk_bf16(float lo, float hi) { unsigned r; asm volatile("v_cvt_pk_bf16_f32 %0, %1, %2" : "=v"(r) : "v"(lo), "v"(hi)); return r; }
; #define GAS __attribute__((address_space(1)))
;     __device__ __forceinline__ void operator()(const f32x4 (&acc)[2][2][4][2], const Unit& u, int wr, int wc, int fr, int fq, const float (&pre)[8]) const {
;     ...
;         for (int ai = 0; ai < 2; ++ai)
; #pragma unroll
;             for (int m = 0; m < 4; ++m) {
;                 const int row = row0 + ai * 128 + m * 16; bf16_t* rowp = O + (size_t)row * ldc + col0; float rs = 0.f;
;                 float rsc = 1.f; if (RS == 1) rsc = pre[ai * 4 + m];
; #pragma unroll
;                 for (int bj = 0; bj < 2; ++bj) {
;                     f32x4 v0 = acc[ai][bj][m][0], v1 = acc[ai][bj][m][1];
;                     if (RS == 1) { v0 = v0 * rsc; v1 = v1 * rsc; }
;                     if (RS == 2) { v0 = v0 * csc[bj][0]; v1 = v1 * csc[bj][1]; }
;                     if (ACT == 1) { const f32x2 a = gelu_pk((f32x2){v0[0], v0[1]}), b = gelu_pk((f32x2){v0[2], v0[3]}), c = gelu_pk((f32x2){v1[0], v1[1]}), d = gelu_pk((f32x2){v1[2], v1[3]});
;                         v0 = (f32x4){a.x, a.y, b.x, b.y}; v1 = (f32x4){c.x, c.y, d.x, d.y}; }
;                     v0 = v0 * sc; v1 = v1 * sc;
;                     if (STAT == 1) rs += (v0[0] * v0[0] + v0[1] * v0[1]) + (v0[2] * v0[2] + v0[3] * v0[3]) + (v1[0] * v1[0] + v1[1] * v1[1]) + (v1[2] * v1[2] + v1[3] * v1[3]);
;                     if (STAT == 2) {
; #pragma unroll
;                         for (int e = 0; e < 4; ++e) { cs[bj][0][e] += v0[e]; cq[bj][0][e] += v0[e] * v0[e]; cs[bj][1][e] += v1[e]; cq[bj][1][e] += v1[e] * v1[e]; } }
;                     u32x4 w; w.x = cvt_pk_bf16(v0[0], v0[1]); w.y = cvt_pk_bf16(v0[2], v0[3]); w.z = cvt_pk_bf16(v1[0], v1[1]); w.w = cvt_pk_bf16(v1[2], v1[3]);
;                     *(GAS u32x4*)(rowp + bj * 128) = w; }
	v_cvt_pk_bf16_f32 v98, v102, v103
	v_pk_mul_f32 v[104:105], v[160:161], v[104:105] op_sel_hi:[0,1]
	v_cvt_pk_bf16_f32 v99, v104, v105
	v_cvt_pk_bf16_f32 v100, v100, v101
	v_cvt_pk_bf16_f32 v101, v106, v107
	global_store_dwordx4 v[114:115], v[98:101], off offset:256
	v_pk_mul_f32 v[96:97], v[154:155], v[96:97] op_sel_hi:[0,1]
	v_pk_mul_f32 v[94:95], v[154:155], v[94:95] op_sel_hi:[0,1]
	v_or_b32_e32 v98, 32, v172
	v_ashrrev_i32_e32 v99, 31, v98
	v_lshlrev_b64 v[98:99], 12, v[98:99]
	v_lshl_add_u64 v[98:99], s[82:83], 0, v[98:99]
	v_pk_mul_f32 v[92:93], v[154:155], v[92:93] op_sel_hi:[0,1]
	v_pk_mul_f32 v[90:91], v[154:155], v[90:91] op_sel_hi:[0,1]
	v_lshl_add_u64 v[98:99], v[98:99], 0, v[176:177]
	v_pk_mul_f32 v[96:97], v[160:161], v[96:97] op_sel_hi:[0,1]
	v_pk_mul_f32 v[94:95], v[160:161], v[94:95] op_sel_hi:[0,1]
	v_pk_mul_f32 v[100:101], v[160:161], v[92:93] op_sel_hi:[0,1]
	v_pk_mul_f32 v[92:93], v[160:161], v[90:91] op_sel_hi:[0,1]
	v_cvt_pk_bf16_f32 v90, v94, v95
	v_cvt_pk_bf16_f32 v91, v96, v97
	v_pk_mul_f32 v[86:87], v[154:155], v[86:87] op_sel_hi:[0,1]
	v_pk_mul_f32 v[84:85], v[154:155], v[84:85] op_sel_hi:[0,1]
	v_pk_mul_f32 v[82:83], v[154:155], v[82:83] op_sel_hi:[0,1]
	v_cvt_pk_bf16_f32 v92, v92, v93
	v_cvt_pk_bf16_f32 v93, v100, v101
	global_store_dwordx4 v[98:99], v[90:93], off
	v_pk_mul_f32 v[88:89], v[154:155], v[88:89] op_sel_hi:[0,1]
	v_pk_mul_f32 v[86:87], v[160:161], v[86:87] op_sel_hi:[0,1]
	v_pk_mul_f32 v[90:91], v[160:161], v[84:85] op_sel_hi:[0,1]
	v_pk_mul_f32 v[84:85], v[160:161], v[82:83] op_sel_hi:[0,1]
	v_cvt_pk_bf16_f32 v82, v86, v87
	v_pk_mul_f32 v[88:89], v[160:161], v[88:89] op_sel_hi:[0,1]
	v_cvt_pk_bf16_f32 v83, v88, v89
	v_cvt_pk_bf16_f32 v84, v84, v85
	v_cvt_pk_bf16_f32 v85, v90, v91
	global_store_dwordx4 v[98:99], v[82:85], off offset:256
	v_pk_mul_f32 v[80:81], v[152:153], v[80:81] op_sel_hi:[0,1]
	v_pk_mul_f32 v[78:79], v[152:153], v[78:79] op_sel_hi:[0,1]
	v_or_b32_e32 v82, 48, v172
	v_ashrrev_i32_e32 v83, 31, v82
	v_lshlrev_b64 v[82:83], 12, v[82:83]
	v_lshl_add_u64 v[82:83], s[82:83], 0, v[82:83]
	v_pk_mul_f32 v[76:77], v[152:153], v[76:77] op_sel_hi:[0,1]
	v_pk_mul_f32 v[74:75], v[152:153], v[74:75] op_sel_hi:[0,1]
	v_lshl_add_u64 v[82:83], v[82:83], 0, v[176:177]
	v_pk_mul_f32 v[80:81], v[160:161], v[80:81] op_sel_hi:[0,1]
	v_pk_mul_f32 v[78:79], v[160:161], v[78:79] op_sel_hi:[0,1]
	v_pk_mul_f32 v[84:85], v[160:161], v[76:77] op_sel_hi:[0,1]
	v_pk_mul_f32 v[76:77], v[160:161], v[74:75] op_sel_hi:[0,1]
	v_cvt_pk_bf16_f32 v74, v78, v79
	v_cvt_pk_bf16_f32 v75, v80, v81
	v_pk_mul_f32 v[68:69], v[152:153], v[68:69] op_sel_hi:[0,1]
	v_pk_mul_f32 v[66:67], v[152:153], v[66:67] op_sel_hi:[0,1]
	v_cvt_pk_bf16_f32 v76, v76, v77
	v_cvt_pk_bf16_f32 v77, v84, v85
	global_store_dwordx4 v[82:83], v[74:77], off
	v_pk_mul_f32 v[72:73], v[152:153], v[72:73] op_sel_hi:[0,1]
	v_pk_mul_f32 v[70:71], v[152:153], v[70:71] op_sel_hi:[0,1]
	v_pk_mul_f32 v[74:75], v[160:161], v[68:69] op_sel_hi:[0,1]
	v_pk_mul_f32 v[68:69], v[160:161], v[66:67] op_sel_hi:[0,1]
	v_pk_mul_f32 v[62:63], v[146:147], v[62:63] op_sel_hi:[0,1]
	v_pk_mul_f32 v[72:73], v[160:161], v[72:73] op_sel_hi:[0,1]
	v_pk_mul_f32 v[70:71], v[160:161], v[70:71] op_sel_hi:[0,1]
	v_cvt_pk_bf16_f32 v66, v70, v71
	v_cvt_pk_bf16_f32 v67, v72, v73
	v_cvt_pk_bf16_f32 v68, v68, v69
	v_cvt_pk_bf16_f32 v69, v74, v75
	v_pk_mul_f32 v[60:61], v[146:147], v[60:61] op_sel_hi:[0,1]
	v_pk_mul_f32 v[58:59], v[146:147], v[58:59] op_sel_hi:[0,1]
	v_pk_mul_f32 v[62:63], v[160:161], v[62:63] op_sel_hi:[0,1]
	s_mov_b32 s3, 0x80000
	global_store_dwordx4 v[82:83], v[66:69], off offset:256
	v_pk_mul_f32 v[64:65], v[146:147], v[64:65] op_sel_hi:[0,1]
	v_pk_mul_f32 v[64:65], v[160:161], v[64:65] op_sel_hi:[0,1]
	v_pk_mul_f32 v[68:69], v[160:161], v[60:61] op_sel_hi:[0,1]
	v_pk_mul_f32 v[60:61], v[160:161], v[58:59] op_sel_hi:[0,1]
	v_cvt_pk_bf16_f32 v58, v62, v63
	v_add_co_u32_e32 v62, vcc, s3, v170
	v_cvt_pk_bf16_f32 v59, v64, v65
	v_pk_mul_f32 v[48:49], v[146:147], v[48:49] op_sel_hi:[0,1]
	s_nop 0
	v_addc_co_u32_e32 v63, vcc, 0, v171, vcc
	v_pk_mul_f32 v[46:47], v[146:147], v[46:47] op_sel_hi:[0,1]
	s_mov_b64 s[76:77], 0x80000
	v_cvt_pk_bf16_f32 v60, v60, v61
	v_cvt_pk_bf16_f32 v61, v68, v69
	global_store_dwordx4 v[62:63], v[58:61], off
	v_pk_mul_f32 v[56:57], v[146:147], v[56:57] op_sel_hi:[0,1]
	v_pk_mul_f32 v[54:55], v[146:147], v[54:55] op_sel_hi:[0,1]
	v_pk_mul_f32 v[58:59], v[160:161], v[48:49] op_sel_hi:[0,1]
	v_pk_mul_f32 v[48:49], v[160:161], v[46:47] op_sel_hi:[0,1]
	v_lshl_add_u64 v[66:67], v[170:171], 0, s[76:77]
	v_pk_mul_f32 v[56:57], v[160:161], v[56:57] op_sel_hi:[0,1]
	v_pk_mul_f32 v[54:55], v[160:161], v[54:55] op_sel_hi:[0,1]
	v_cvt_pk_bf16_f32 v46, v54, v55
	v_cvt_pk_bf16_f32 v47, v56, v57
	v_cvt_pk_bf16_f32 v48, v48, v49
	v_cvt_pk_bf16_f32 v49, v58, v59
	global_store_dwordx4 v[66:67], v[46:49], off offset:256
	v_pk_mul_f32 v[50:51], v[142:143], v[50:51] op_sel_hi:[0,1]
	v_pk_mul_f32 v[44:45], v[142:143], v[44:45] op_sel_hi:[0,1]
	v_pk_mul_f32 v[48:49], v[142:143], v[52:53] op_sel_hi:[0,1]
; __device__ __forceinline__ unsigned cvt_pk_bf16(float lo, float hi) { unsigned r; asm volatile("v_cvt_pk_bf16_f32 %0, %1, %2" : "=v"(r) : "v"(lo), "v"(hi)); return r; }
; #define PG8_BAR __builtin_amdgcn_s_barrier()
; #define GAS __attribute__((address_space(1)))
; template <class Epi, class Sched, bool ALIGN_EPI = false, bool SP2 = false>
; __device__ __forceinline__ void gemm_phase(PG8_LAS unsigned char* lds, const Gemm g, const Sched& S, const Epi& E) {
;     ...
;         if constexpr (Epi::PREFETCH) E.prefetch(cur, wr, fr, epre);
;         if constexpr (ALIGN_EPI) { if (wr == 1) PG8_BAR; }
;     __device__ __forceinline__ void operator()(const f32x4 (&acc)[2][2][4][2], const Unit& u, int wr, int wc, int fr, int fq, const float (&pre)[8]) const {
;     ...
;         for (int ai = 0; ai < 2; ++ai)
; #pragma unroll
;             for (int m = 0; m < 4; ++m) {
;                 const int row = row0 + ai * 128 + m * 16; bf16_t* rowp = O + (size_t)row * ldc + col0; float rs = 0.f;
;                 float rsc = 1.f; if (RS == 1) rsc = pre[ai * 4 + m];
; #pragma unroll
;                 for (int bj = 0; bj < 2; ++bj) {
;                     f32x4 v0 = acc[ai][bj][m][0], v1 = acc[ai][bj][m][1];
;                     if (RS == 1) { v0 = v0 * rsc; v1 = v1 * rsc; }
;                     if (RS == 2) { v0 = v0 * csc[bj][0]; v1 = v1 * csc[bj][1]; }
;                     if (ACT == 1) { const f32x2 a = gelu_pk((f32x2){v0[0], v0[1]}), b = gelu_pk((f32x2){v0[2], v0[3]}), c = gelu_pk((f32x2){v1[0], v1[1]}), d = gelu_pk((f32x2){v1[2], v1[3]});
;                         v0 = (f32x4){a.x, a.y, b.x, b.y}; v1 = (f32x4){c.x, c.y, d.x, d.y}; }
;                     v0 = v0 * sc; v1 = v1 * sc;
;                     if (STAT == 1) rs += (v0[0] * v0[0] + v0[1] * v0[1]) + (v0[2] * v0[2] + v0[3] * v0[3]) + (v1[0] * v1[0] + v1[1] * v1[1]) + (v1[2] * v1[2] + v1[3] * v1[3]);
;                     if (STAT == 2) {
; #pragma unroll
;                         for (int e = 0; e < 4; ++e) { cs[bj][0][e] += v0[e]; cq[bj][0][e] += v0[e] * v0[e]; cs[bj][1][e] += v1[e]; cq[bj][1][e] += v1[e] * v1[e]; } }
;                     u32x4 w; w.x = cvt_pk_bf16(v0[0], v0[1]); w.y = cvt_pk_bf16(v0[2], v0[3]); w.z = cvt_pk_bf16(v1[0], v1[1]); w.w = cvt_pk_bf16(v1[2], v1[3]);
;                     *(GAS u32x4*)(rowp + bj * 128) = w; }
	v_pk_mul_f32 v[42:43], v[142:143], v[42:43] op_sel_hi:[0,1]
	v_pk_mul_f32 v[48:49], v[160:161], v[48:49] op_sel_hi:[0,1]
	s_mov_b32 s3, 0x90000
	v_pk_mul_f32 v[50:51], v[160:161], v[50:51] op_sel_hi:[0,1]
	v_pk_mul_f32 v[52:53], v[160:161], v[44:45] op_sel_hi:[0,1]
	v_pk_mul_f32 v[44:45], v[160:161], v[42:43] op_sel_hi:[0,1]
	v_cvt_pk_bf16_f32 v42, v50, v51
	v_cvt_pk_bf16_f32 v43, v48, v49
	v_add_co_u32_e32 v48, vcc, s3, v170
	v_pk_mul_f32 v[30:31], v[142:143], v[30:31] op_sel_hi:[0,1]
	s_nop 0
	v_addc_co_u32_e32 v49, vcc, 0, v171, vcc
	v_pk_mul_f32 v[28:29], v[142:143], v[28:29] op_sel_hi:[0,1]
	s_mov_b64 s[76:77], 0x90000
	v_cvt_pk_bf16_f32 v44, v44, v45
	v_cvt_pk_bf16_f32 v45, v52, v53
	global_store_dwordx4 v[48:49], v[42:45], off
	v_pk_mul_f32 v[40:41], v[142:143], v[40:41] op_sel_hi:[0,1]
	v_pk_mul_f32 v[38:39], v[142:143], v[38:39] op_sel_hi:[0,1]
	v_pk_mul_f32 v[42:43], v[160:161], v[30:31] op_sel_hi:[0,1]
	v_pk_mul_f32 v[30:31], v[160:161], v[28:29] op_sel_hi:[0,1]
	v_lshl_add_u64 v[46:47], v[170:171], 0, s[76:77]
	v_pk_mul_f32 v[40:41], v[160:161], v[40:41] op_sel_hi:[0,1]
	v_pk_mul_f32 v[38:39], v[160:161], v[38:39] op_sel_hi:[0,1]
	v_cvt_pk_bf16_f32 v28, v38, v39
	v_cvt_pk_bf16_f32 v29, v40, v41
	v_cvt_pk_bf16_f32 v30, v30, v31
	v_cvt_pk_bf16_f32 v31, v42, v43
	global_store_dwordx4 v[46:47], v[28:31], off offset:256
	v_pk_mul_f32 v[34:35], v[140:141], v[34:35] op_sel_hi:[0,1]
	v_pk_mul_f32 v[26:27], v[140:141], v[26:27] op_sel_hi:[0,1]
	v_pk_mul_f32 v[30:31], v[140:141], v[36:37] op_sel_hi:[0,1]
	v_pk_mul_f32 v[24:25], v[140:141], v[24:25] op_sel_hi:[0,1]
	v_pk_mul_f32 v[30:31], v[160:161], v[30:31] op_sel_hi:[0,1]
	s_mov_b32 s3, 0xa0000
	v_pk_mul_f32 v[34:35], v[160:161], v[34:35] op_sel_hi:[0,1]
	v_pk_mul_f32 v[36:37], v[160:161], v[26:27] op_sel_hi:[0,1]
	v_pk_mul_f32 v[26:27], v[160:161], v[24:25] op_sel_hi:[0,1]
	v_cvt_pk_bf16_f32 v24, v34, v35
	v_cvt_pk_bf16_f32 v25, v30, v31
	v_add_co_u32_e32 v30, vcc, s3, v170
	v_pk_mul_f32 v[14:15], v[140:141], v[14:15] op_sel_hi:[0,1]
	s_nop 0
	v_addc_co_u32_e32 v31, vcc, 0, v171, vcc
	v_pk_mul_f32 v[12:13], v[140:141], v[12:13] op_sel_hi:[0,1]
	s_mov_b64 s[76:77], 0xa0000
	v_cvt_pk_bf16_f32 v26, v26, v27
	v_cvt_pk_bf16_f32 v27, v36, v37
	global_store_dwordx4 v[30:31], v[24:27], off
	v_pk_mul_f32 v[22:23], v[140:141], v[22:23] op_sel_hi:[0,1]
	v_pk_mul_f32 v[20:21], v[140:141], v[20:21] op_sel_hi:[0,1]
	v_pk_mul_f32 v[24:25], v[160:161], v[14:15] op_sel_hi:[0,1]
	v_pk_mul_f32 v[14:15], v[160:161], v[12:13] op_sel_hi:[0,1]
	v_lshl_add_u64 v[28:29], v[170:171], 0, s[76:77]
	v_pk_mul_f32 v[22:23], v[160:161], v[22:23] op_sel_hi:[0,1]
	v_pk_mul_f32 v[20:21], v[160:161], v[20:21] op_sel_hi:[0,1]
	v_cvt_pk_bf16_f32 v12, v20, v21
	v_cvt_pk_bf16_f32 v13, v22, v23
	v_cvt_pk_bf16_f32 v14, v14, v15
	v_cvt_pk_bf16_f32 v15, v24, v25
	global_store_dwordx4 v[28:29], v[12:15], off offset:256
	v_pk_mul_f32 v[16:17], v[138:139], v[16:17] op_sel_hi:[0,1]
	v_pk_mul_f32 v[10:11], v[138:139], v[10:11] op_sel_hi:[0,1]
	v_pk_mul_f32 v[14:15], v[138:139], v[18:19] op_sel_hi:[0,1]
	v_pk_mul_f32 v[8:9], v[138:139], v[8:9] op_sel_hi:[0,1]
	v_pk_mul_f32 v[14:15], v[160:161], v[14:15] op_sel_hi:[0,1]
	s_mov_b32 s3, 0xb0000
	v_pk_mul_f32 v[16:17], v[160:161], v[16:17] op_sel_hi:[0,1]
	v_pk_mul_f32 v[18:19], v[160:161], v[10:11] op_sel_hi:[0,1]
	v_pk_mul_f32 v[10:11], v[160:161], v[8:9] op_sel_hi:[0,1]
	v_cvt_pk_bf16_f32 v8, v16, v17
	v_cvt_pk_bf16_f32 v9, v14, v15
	v_add_co_u32_e32 v14, vcc, s3, v170
	s_mov_b64 s[76:77], 0xb0000
	s_nop 0
	v_addc_co_u32_e32 v15, vcc, 0, v171, vcc
	v_pk_mul_f32 v[2:3], v[138:139], v[2:3] op_sel_hi:[0,1]
	v_pk_mul_f32 v[0:1], v[138:139], v[0:1] op_sel_hi:[0,1]
	v_lshl_add_u64 v[12:13], v[170:171], 0, s[76:77]
	v_cvt_pk_bf16_f32 v10, v10, v11
	v_cvt_pk_bf16_f32 v11, v18, v19
	global_store_dwordx4 v[14:15], v[8:11], off
	v_pk_mul_f32 v[6:7], v[138:139], v[6:7] op_sel_hi:[0,1]
	v_pk_mul_f32 v[4:5], v[138:139], v[4:5] op_sel_hi:[0,1]
	v_pk_mul_f32 v[8:9], v[160:161], v[2:3] op_sel_hi:[0,1]
	v_pk_mul_f32 v[2:3], v[160:161], v[0:1] op_sel_hi:[0,1]
	s_andn2_b64 vcc, exec, s[86:87]
	s_mov_b64 s[86:87], -1
	v_pk_mul_f32 v[6:7], v[160:161], v[6:7] op_sel_hi:[0,1]
	v_pk_mul_f32 v[4:5], v[160:161], v[4:5] op_sel_hi:[0,1]
	v_cvt_pk_bf16_f32 v0, v4, v5
	v_cvt_pk_bf16_f32 v1, v6, v7
	v_cvt_pk_bf16_f32 v2, v2, v3
	v_cvt_pk_bf16_f32 v3, v8, v9
	global_store_dwordx4 v[12:13], v[0:3], off offset:256
	s_cbranch_vccnz .LBB0_57
	s_lshl_b32 s76, s46, 8
	s_ashr_i32 s77, s76, 31
	v_lshl_add_u64 v[0:1], s[76:77], 2, v[144:145]
	global_load_dword v158, v[0:1], off
	global_load_dword v156, v[0:1], off offset:64
	global_load_dword v154, v[0:1], off offset:128
	global_load_dword v152, v[0:1], off offset:192
	global_load_dword v146, v[0:1], off offset:512
	global_load_dword v142, v[0:1], off offset:576
	global_load_dword v140, v[0:1], off offset:640
	global_load_dword v138, v[0:1], off offset:704
	v_readlane_b32 s72, v254, 49
	v_readlane_b32 s73, v254, 50
	s_andn2_b64 vcc, exec, s[72:73]
	s_cmp_lg_u32 s72, 0
	s_cselect_b32 s100, 1, 0
	s_branch .LBB0_56

; #define PG8_STAGE(bufoff, gbase, voff) do { _Pragma("unroll") for (int _i = 0; _i < 2; ++_i) \
;         __builtin_amdgcn_global_load_lds((const unsigned*)((const char*)(gbase) + (voff)[_i]), (PG8_LAS unsigned*)(lds + (bufoff) + ldsw + _i * 8192), 16, 0, 0); } while (0)
; #define PG8_LDA(dst, b, h) do { _Pragma("unroll") for (int m = 0; m < 4; ++m) _Pragma("unroll") for (int k = 0; k < 2; ++k) dst[m][k] = *(const PG8_LAS bf16x8*)(lds + PG8_SA(b, h) + aoff + m * 2048 + k * 1024); } while (0)
; #define PG8_LDB(dst, b, h) do { _Pragma("unroll") for (int n = 0; n < 2; ++n) _Pragma("unroll") for (int k = 0; k < 2; ++k) dst[n][k] = *(const PG8_LAS bf16x8*)(lds + PG8_SB(b, h) + boff + n * 2048 + k * 1024); } while (0)
; #define PG8_BAR __builtin_amdgcn_s_barrier()
; #define PG8_SCHED __builtin_amdgcn_sched_barrier(0)
; template <class Epi, class Sched, bool ALIGN_EPI = false, bool SP2 = false>
; __device__ __forceinline__ void gemm_phase(PG8_LAS unsigned char* lds, const Gemm g, const Sched& S, const Epi& E) {
;     ...
;         const bool has_next = S.next(ui + 1, nxt);
;         const char* nA = has_next ? (const char*)g.A + (size_t)nxt.pm * tstep : cA; const char* nB = has_next ? (const char*)g.Bt + (size_t)nxt.pn * tstep : cB;
;         for (int t = 0; t < nt; t += 2) {
;             const bool last = (t == nt - 2);
;             const char* a1 = cA + (size_t)(t + 1) * kstep;
;             const char* a2 = last ? nA : cA + (size_t)(t + 2) * kstep; const char* b2 = last ? nB : cB + (size_t)(t + 2) * kstep;
;             const char* a3 = a2 + kstep; const char* b3 = b2 + kstep;
;             if (last && has_next) S.a_ready(nxt);
;             if constexpr (SP2) {
;             PG8_LDB(B0, 0, 0); PG8_LDB(B1, 0, 1); PG8_SCHED; PG8_LDA(At, 0, 0); PG8_STAGE(PG8_SA(1, 1), a1 + hstep, voffA);
;     ...
; #pragma unroll
;         for (int a = 0; a < 2; ++a)
; #pragma unroll
;             for (int b = 0; b < 2; ++b)
; #pragma unroll
;                 for (int m = 0; m < 4; ++m)
; #pragma unroll
;                     for (int n = 0; n < 2; ++n) acc[a][b][m][n] = (f32x4){0.f, 0.f, 0.f, 0.f};
;         cur = nxt; cA = nA; cB = nB; ++ui;
;         if constexpr (Epi::PREFETCH) E.prefetch(cur, wr, fr, epre);
;         if constexpr (ALIGN_EPI) { if (wr == 1) PG8_BAR; }
.LBB0_90:
	s_ashr_i32 s89, s88, 31
	s_lshl_b64 s[50:51], s[88:89], 19
	s_add_u32 s92, s73, s50
	s_addc_u32 s93, s81, s51
	s_and_b64 s[50:51], s[90:91], exec
	s_cselect_b32 s89, s93, s49
	s_cselect_b32 vcc_lo, s92, s48
	s_ashr_i32 s87, s86, 31
	s_lshl_b64 s[50:51], s[86:87], 19
	s_add_u32 s94, s62, s50
	s_addc_u32 s95, s63, s51
	s_and_b64 s[50:51], s[90:91], exec
	s_cselect_b32 s87, s95, s47
	s_cselect_b32 vcc_hi, s94, s46
	s_add_u32 s5, s46, 0x100
	s_addc_u32 s7, s47, 0
	s_add_u32 s46, s48, 0x40080
	v_mov_b32_e32 v0, 0
	s_addc_u32 s47, s49, 0
	s_mov_b32 s80, -2
	v_mov_b32_e32 v1, v0
	v_mov_b32_e32 v2, v0
	v_mov_b32_e32 v3, v0
	v_mov_b32_e32 v4, v0
	v_mov_b32_e32 v5, v0
	v_mov_b32_e32 v6, v0
	v_mov_b32_e32 v7, v0
	v_mov_b32_e32 v16, v0
	v_mov_b32_e32 v17, v0
	v_mov_b32_e32 v18, v0
	v_mov_b32_e32 v19, v0
	v_mov_b32_e32 v20, v0
	v_mov_b32_e32 v21, v0
	v_mov_b32_e32 v22, v0
	v_mov_b32_e32 v23, v0
	v_mov_b32_e32 v28, v0
	v_mov_b32_e32 v29, v0
	v_mov_b32_e32 v30, v0
	v_mov_b32_e32 v31, v0
	v_mov_b32_e32 v38, v0
	v_mov_b32_e32 v39, v0
	v_mov_b32_e32 v40, v0
	v_mov_b32_e32 v41, v0
	v_mov_b32_e32 v46, v0
	v_mov_b32_e32 v47, v0
	v_mov_b32_e32 v48, v0
	v_mov_b32_e32 v49, v0
	v_mov_b32_e32 v54, v0
	v_mov_b32_e32 v55, v0
	v_mov_b32_e32 v56, v0
	v_mov_b32_e32 v57, v0
	v_mov_b32_e32 v8, v0
	v_mov_b32_e32 v9, v0
	v_mov_b32_e32 v10, v0
	v_mov_b32_e32 v11, v0
	v_mov_b32_e32 v12, v0
	v_mov_b32_e32 v13, v0
	v_mov_b32_e32 v14, v0
	v_mov_b32_e32 v15, v0
	v_mov_b32_e32 v24, v0
	v_mov_b32_e32 v25, v0
	v_mov_b32_e32 v26, v0
	v_mov_b32_e32 v27, v0
	v_mov_b32_e32 v34, v0
	v_mov_b32_e32 v35, v0
	v_mov_b32_e32 v36, v0
	v_mov_b32_e32 v37, v0
	v_mov_b32_e32 v42, v0
	v_mov_b32_e32 v43, v0
	v_mov_b32_e32 v44, v0
	v_mov_b32_e32 v45, v0
	v_mov_b32_e32 v50, v0
	v_mov_b32_e32 v51, v0
	v_mov_b32_e32 v52, v0
	v_mov_b32_e32 v53, v0
	v_mov_b32_e32 v58, v0
	v_mov_b32_e32 v59, v0
	v_mov_b32_e32 v60, v0
	v_mov_b32_e32 v61, v0
	v_mov_b32_e32 v62, v0
	v_mov_b32_e32 v63, v0
	v_mov_b32_e32 v64, v0
	v_mov_b32_e32 v65, v0
	v_mov_b32_e32 v66, v0
	v_mov_b32_e32 v67, v0
	v_mov_b32_e32 v68, v0
	v_mov_b32_e32 v69, v0
	v_mov_b32_e32 v70, v0
	v_mov_b32_e32 v71, v0
	v_mov_b32_e32 v72, v0
	v_mov_b32_e32 v73, v0
	v_mov_b32_e32 v82, v0
	v_mov_b32_e32 v83, v0
	v_mov_b32_e32 v84, v0
	v_mov_b32_e32 v85, v0
	v_mov_b32_e32 v86, v0
	v_mov_b32_e32 v87, v0
	v_mov_b32_e32 v88, v0
	v_mov_b32_e32 v89, v0
	v_mov_b32_e32 v114, v0
	v_mov_b32_e32 v115, v0
	v_mov_b32_e32 v116, v0
	v_mov_b32_e32 v117, v0
	v_mov_b32_e32 v118, v0
	v_mov_b32_e32 v119, v0
	v_mov_b32_e32 v120, v0
	v_mov_b32_e32 v121, v0
	v_mov_b32_e32 v130, v0
	v_mov_b32_e32 v131, v0
	v_mov_b32_e32 v132, v0
	v_mov_b32_e32 v133, v0
	v_mov_b32_e32 v134, v0
	v_mov_b32_e32 v135, v0
	v_mov_b32_e32 v136, v0
	v_mov_b32_e32 v137, v0
	v_mov_b32_e32 v74, v0
	v_mov_b32_e32 v75, v0
	v_mov_b32_e32 v76, v0
	v_mov_b32_e32 v77, v0
	v_mov_b32_e32 v78, v0
	v_mov_b32_e32 v79, v0
	v_mov_b32_e32 v80, v0
	v_mov_b32_e32 v81, v0
	v_mov_b32_e32 v90, v0
	v_mov_b32_e32 v91, v0
	v_mov_b32_e32 v92, v0
	v_mov_b32_e32 v93, v0
	v_mov_b32_e32 v94, v0
	v_mov_b32_e32 v95, v0
	v_mov_b32_e32 v96, v0
	v_mov_b32_e32 v97, v0
	v_mov_b32_e32 v122, v0
	v_mov_b32_e32 v123, v0
	v_mov_b32_e32 v124, v0
	v_mov_b32_e32 v125, v0
	v_mov_b32_e32 v126, v0
	v_mov_b32_e32 v127, v0
	v_mov_b32_e32 v128, v0
	v_mov_b32_e32 v129, v0
	s_waitcnt vmcnt(0)
	v_mov_b32_e32 v138, v0
	v_mov_b32_e32 v139, v0
	v_mov_b32_e32 v140, v0
	v_mov_b32_e32 v141, v0
	v_mov_b32_e32 v142, v0
	v_mov_b32_e32 v143, v0
	v_mov_b32_e32 v144, v0
	v_mov_b32_e32 v145, v0
	s_cmp_eq_u32 s100, 0
	s_cbranch_scc1 .Lrb1_skip
	s_mov_b32 s100, 0
	s_barrier
.Lrb1_skip:
.LBB0_91:
	s_add_u32 s48, s46, 0xfffc0080
	s_addc_u32 s49, s47, -1
	s_add_i32 s61, 0, 0x10000
	s_cmp_eq_u32 s80, 12
	s_cselect_b32 s51, s89, s49
	s_cselect_b32 s50, vcc_lo, s48
	s_cselect_b32 s49, s87, s7
	s_cselect_b32 s48, vcc_hi, s5
	s_add_i32 s72, 0, 0x14000
	v_add_u32_e32 v110, s61, v170
	v_add_u32_e32 v173, s72, v170
	ds_read_b128 v[98:101], v110
	ds_read_b128 v[102:105], v110 offset:1024
	ds_read_b128 v[106:109], v110 offset:2048
	ds_read_b128 v[110:113], v110 offset:3072
	ds_read_b128 v[158:161], v173
	ds_read_b128 v[174:177], v173 offset:1024
	ds_read_b128 v[178:181], v173 offset:2048
	ds_read_b128 v[182:185], v173 offset:3072
	v_lshl_add_u64 v[228:229], s[46:47], 0, v[156:157]
	s_add_i32 m0, s9, 0xc000
	ds_read_b128 v[196:199], v172
	ds_read_b128 v[200:203], v172 offset:1024
	ds_read_b128 v[204:207], v172 offset:2048
	ds_read_b128 v[208:211], v172 offset:3072
	ds_read_b128 v[212:215], v172 offset:4096
	ds_read_b128 v[216:219], v172 offset:5120
	ds_read_b128 v[220:223], v172 offset:6144
	ds_read_b128 v[224:227], v172 offset:7168
	global_load_lds_dwordx4 v[228:229], off
	v_lshl_add_u64 v[228:229], s[46:47], 0, v[154:155]
	s_add_i32 m0, s9, 0xe000
	s_nop 0
	global_load_lds_dwordx4 v[228:229], off
	s_waitcnt vmcnt(8)
	s_waitcnt lgkmcnt(0)
	s_barrier
; #define PG8_STAGE(bufoff, gbase, voff) do { _Pragma("unroll") for (int _i = 0; _i < 2; ++_i) \
;         __builtin_amdgcn_global_load_lds((const unsigned*)((const char*)(gbase) + (voff)[_i]), (PG8_LAS unsigned*)(lds + (bufoff) + ldsw + _i * 8192), 16, 0, 0); } while (0)
; #define PG8_LDA(dst, b, h) do { _Pragma("unroll") for (int m = 0; m < 4; ++m) _Pragma("unroll") for (int k = 0; k < 2; ++k) dst[m][k] = *(const PG8_LAS bf16x8*)(lds + PG8_SA(b, h) + aoff + m * 2048 + k * 1024); } while (0)
; #define PG8_MMA(ai, bj, At, Bt) do { __builtin_amdgcn_s_setprio(1); _Pragma("unroll") for (int m = 0; m < 4; ++m) _Pragma("unroll") for (int n = 0; n < 2; ++n) _Pragma("unroll") for (int k = 0; k < 2; ++k) \
;         acc[ai][bj][m][n] = __builtin_amdgcn_mfma_f32_16x16x32_bf16(Bt[n][k], At[m][k], acc[ai][bj][m][n], 0, 0, 0); __builtin_amdgcn_s_setprio(0); } while (0)
; #define PG8_WAIT_V(n) asm volatile("s_waitcnt vmcnt(" #n ")" ::: "memory")
; #define PG8_WAIT_L(n) asm volatile("s_waitcnt lgkmcnt(" #n ")" ::: "memory")
; #define PG8_BAR __builtin_amdgcn_s_barrier()
; #define PG8_SCHED __builtin_amdgcn_sched_barrier(0)
; template <class Epi, class Sched, bool ALIGN_EPI = false, bool SP2 = false>
; __device__ __forceinline__ void gemm_phase(PG8_LAS unsigned char* lds, const Gemm g, const Sched& S, const Epi& E) {
;     ...
;             PG8_WAIT_V(8); PG8_WAIT_L(0); PG8_BAR; PG8_MMA(0, 0, At, B0); PG8_MMA(0, 1, At, B1); PG8_BAR; PG8_SCHED;
;             PG8_LDA(At, 0, 1); PG8_STAGE(PG8_SB(0, 0), b2, voffB); PG8_STAGE(PG8_SB(0, 1), b2 + hstep, voffB); PG8_STAGE(PG8_SA(0, 0), a2, voffA);
;             PG8_WAIT_V(8); PG8_WAIT_L(0); PG8_BAR; PG8_MMA(1, 0, At, B0); PG8_MMA(1, 1, At, B1); PG8_BAR; PG8_SCHED;
	v_mfma_f32_16x16x32_bf16 v[142:145], v[98:101], v[196:199], v[142:145]
	v_mfma_f32_16x16x32_bf16 v[138:141], v[106:109], v[196:199], v[138:141]
	v_mfma_f32_16x16x32_bf16 v[126:129], v[98:101], v[204:207], v[126:129]
	v_mfma_f32_16x16x32_bf16 v[122:125], v[106:109], v[204:207], v[122:125]
	v_mfma_f32_16x16x32_bf16 v[94:97], v[98:101], v[212:215], v[94:97]
	v_mfma_f32_16x16x32_bf16 v[90:93], v[106:109], v[212:215], v[90:93]
	v_mfma_f32_16x16x32_bf16 v[78:81], v[98:101], v[220:223], v[78:81]
	v_mfma_f32_16x16x32_bf16 v[74:77], v[106:109], v[220:223], v[74:77]
	v_mfma_f32_16x16x32_bf16 v[142:145], v[102:105], v[200:203], v[142:145]
	v_mfma_f32_16x16x32_bf16 v[138:141], v[110:113], v[200:203], v[138:141]
	v_mfma_f32_16x16x32_bf16 v[126:129], v[102:105], v[208:211], v[126:129]
	v_mfma_f32_16x16x32_bf16 v[122:125], v[110:113], v[208:211], v[122:125]
	v_mfma_f32_16x16x32_bf16 v[94:97], v[102:105], v[216:219], v[94:97]
	v_mfma_f32_16x16x32_bf16 v[90:93], v[110:113], v[216:219], v[90:93]
	v_mfma_f32_16x16x32_bf16 v[78:81], v[102:105], v[224:227], v[78:81]
	v_mfma_f32_16x16x32_bf16 v[74:77], v[110:113], v[224:227], v[74:77]
	v_mfma_f32_16x16x32_bf16 v[134:137], v[158:161], v[196:199], v[134:137]
	v_mfma_f32_16x16x32_bf16 v[130:133], v[178:181], v[196:199], v[130:133]
	v_mfma_f32_16x16x32_bf16 v[118:121], v[158:161], v[204:207], v[118:121]
	v_mfma_f32_16x16x32_bf16 v[114:117], v[178:181], v[204:207], v[114:117]
	v_mfma_f32_16x16x32_bf16 v[86:89], v[158:161], v[212:215], v[86:89]
	v_mfma_f32_16x16x32_bf16 v[82:85], v[178:181], v[212:215], v[82:85]
	v_mfma_f32_16x16x32_bf16 v[70:73], v[158:161], v[220:223], v[70:73]
	v_mfma_f32_16x16x32_bf16 v[66:69], v[178:181], v[220:223], v[66:69]
	v_mfma_f32_16x16x32_bf16 v[134:137], v[174:177], v[200:203], v[134:137]
	v_mfma_f32_16x16x32_bf16 v[130:133], v[182:185], v[200:203], v[130:133]
	v_mfma_f32_16x16x32_bf16 v[118:121], v[174:177], v[208:211], v[118:121]
	v_mfma_f32_16x16x32_bf16 v[114:117], v[182:185], v[208:211], v[114:117]
	v_mfma_f32_16x16x32_bf16 v[86:89], v[174:177], v[216:219], v[86:89]
	v_mfma_f32_16x16x32_bf16 v[82:85], v[182:185], v[216:219], v[82:85]
	v_mfma_f32_16x16x32_bf16 v[70:73], v[174:177], v[224:227], v[70:73]
	v_mfma_f32_16x16x32_bf16 v[66:69], v[182:185], v[224:227], v[66:69]
	s_barrier
	s_add_i32 s61, s61, s8
	v_lshl_add_u64 v[228:229], s[48:49], 0, v[148:149]
	s_mov_b32 m0, s61
	ds_read_b128 v[196:199], v172 offset:16384
	ds_read_b128 v[200:203], v172 offset:17408
	ds_read_b128 v[204:207], v172 offset:18432
	ds_read_b128 v[208:211], v172 offset:19456
	ds_read_b128 v[212:215], v172 offset:20480
	ds_read_b128 v[216:219], v172 offset:21504
	ds_read_b128 v[220:223], v172 offset:22528
	ds_read_b128 v[224:227], v172 offset:23552
	global_load_lds_dwordx4 v[228:229], off
	s_add_i32 m0, s61, 0x2000
	s_add_u32 s76, s48, 0x40000
	v_lshl_add_u64 v[230:231], s[48:49], 0, v[152:153]
	s_addc_u32 s77, s49, 0
	s_add_i32 s61, s72, s8
	global_load_lds_dwordx4 v[230:231], off
	v_lshl_add_u64 v[232:233], s[76:77], 0, v[148:149]
	s_mov_b32 m0, s61
	v_lshl_add_u64 v[234:235], s[50:51], 0, v[150:151]
	global_load_lds_dwordx4 v[232:233], off
	v_lshl_add_u64 v[232:233], s[76:77], 0, v[152:153]
	s_add_i32 m0, s61, 0x2000
	s_nop 0
	global_load_lds_dwordx4 v[232:233], off
	v_lshl_add_u64 v[232:233], s[50:51], 0, v[146:147]
	s_mov_b32 m0, s9
	s_nop 0
	global_load_lds_dwordx4 v[232:233], off
	s_mov_b32 m0, s96
	s_nop 0
	global_load_lds_dwordx4 v[234:235], off
	s_waitcnt vmcnt(8)
	s_waitcnt lgkmcnt(0)
	s_barrier
	v_mfma_f32_16x16x32_bf16 v[62:65], v[98:101], v[196:199], v[62:65]
	v_mfma_f32_16x16x32_bf16 v[58:61], v[106:109], v[196:199], v[58:61]
	v_mfma_f32_16x16x32_bf16 v[50:53], v[98:101], v[204:207], v[50:53]
	v_mfma_f32_16x16x32_bf16 v[42:45], v[106:109], v[204:207], v[42:45]
	v_mfma_f32_16x16x32_bf16 v[34:37], v[98:101], v[212:215], v[34:37]
	v_mfma_f32_16x16x32_bf16 v[24:27], v[106:109], v[212:215], v[24:27]
	v_mfma_f32_16x16x32_bf16 v[12:15], v[98:101], v[220:223], v[12:15]
	v_mfma_f32_16x16x32_bf16 v[8:11], v[106:109], v[220:223], v[8:11]
	v_mfma_f32_16x16x32_bf16 v[62:65], v[102:105], v[200:203], v[62:65]
	v_mfma_f32_16x16x32_bf16 v[58:61], v[110:113], v[200:203], v[58:61]
	v_mfma_f32_16x16x32_bf16 v[50:53], v[102:105], v[208:211], v[50:53]
	v_mfma_f32_16x16x32_bf16 v[42:45], v[110:113], v[208:211], v[42:45]
	v_mfma_f32_16x16x32_bf16 v[34:37], v[102:105], v[216:219], v[34:37]
	v_mfma_f32_16x16x32_bf16 v[24:27], v[110:113], v[216:219], v[24:27]
	v_mfma_f32_16x16x32_bf16 v[12:15], v[102:105], v[224:227], v[12:15]
	v_mfma_f32_16x16x32_bf16 v[8:11], v[110:113], v[224:227], v[8:11]
	v_mfma_f32_16x16x32_bf16 v[54:57], v[158:161], v[196:199], v[54:57]
	v_mfma_f32_16x16x32_bf16 v[46:49], v[178:181], v[196:199], v[46:49]
	v_mfma_f32_16x16x32_bf16 v[38:41], v[158:161], v[204:207], v[38:41]
	v_mfma_f32_16x16x32_bf16 v[28:31], v[178:181], v[204:207], v[28:31]
	v_mfma_f32_16x16x32_bf16 v[20:23], v[158:161], v[212:215], v[20:23]
	v_mfma_f32_16x16x32_bf16 v[16:19], v[178:181], v[212:215], v[16:19]
	v_mfma_f32_16x16x32_bf16 v[4:7], v[158:161], v[220:223], v[4:7]
	v_mfma_f32_16x16x32_bf16 v[0:3], v[178:181], v[220:223], v[0:3]
	v_mfma_f32_16x16x32_bf16 v[54:57], v[174:177], v[200:203], v[54:57]
	v_mfma_f32_16x16x32_bf16 v[46:49], v[182:185], v[200:203], v[46:49]
	v_mfma_f32_16x16x32_bf16 v[38:41], v[174:177], v[208:211], v[38:41]
	v_mfma_f32_16x16x32_bf16 v[28:31], v[182:185], v[208:211], v[28:31]
	v_mfma_f32_16x16x32_bf16 v[20:23], v[174:177], v[216:219], v[20:23]
	v_mfma_f32_16x16x32_bf16 v[16:19], v[182:185], v[216:219], v[16:19]
	v_mfma_f32_16x16x32_bf16 v[4:7], v[174:177], v[224:227], v[4:7]
	v_mfma_f32_16x16x32_bf16 v[0:3], v[182:185], v[224:227], v[0:3]
	s_barrier
; #define PG8_STAGE(bufoff, gbase, voff) do { _Pragma("unroll") for (int _i = 0; _i < 2; ++_i) \
;         __builtin_amdgcn_global_load_lds((const unsigned*)((const char*)(gbase) + (voff)[_i]), (PG8_LAS unsigned*)(lds + (bufoff) + ldsw + _i * 8192), 16, 0, 0); } while (0)
; #define PG8_LDA(dst, b, h) do { _Pragma("unroll") for (int m = 0; m < 4; ++m) _Pragma("unroll") for (int k = 0; k < 2; ++k) dst[m][k] = *(const PG8_LAS bf16x8*)(lds + PG8_SA(b, h) + aoff + m * 2048 + k * 1024); } while (0)
; #define PG8_LDB(dst, b, h) do { _Pragma("unroll") for (int n = 0; n < 2; ++n) _Pragma("unroll") for (int k = 0; k < 2; ++k) dst[n][k] = *(const PG8_LAS bf16x8*)(lds + PG8_SB(b, h) + boff + n * 2048 + k * 1024); } while (0)
; #define PG8_MMA(ai, bj, At, Bt) do { __builtin_amdgcn_s_setprio(1); _Pragma("unroll") for (int m = 0; m < 4; ++m) _Pragma("unroll") for (int n = 0; n < 2; ++n) _Pragma("unroll") for (int k = 0; k < 2; ++k) \
;         acc[ai][bj][m][n] = __builtin_amdgcn_mfma_f32_16x16x32_bf16(Bt[n][k], At[m][k], acc[ai][bj][m][n], 0, 0, 0); __builtin_amdgcn_s_setprio(0); } while (0)
; #define PG8_WAIT_V(n) asm volatile("s_waitcnt vmcnt(" #n ")" ::: "memory")
; #define PG8_WAIT_L(n) asm volatile("s_waitcnt lgkmcnt(" #n ")" ::: "memory")
; #define PG8_BAR __builtin_amdgcn_s_barrier()
; #define PG8_SCHED __builtin_amdgcn_sched_barrier(0)
; template <class Epi, class Sched, bool ALIGN_EPI = false, bool SP2 = false>
; __device__ __forceinline__ void gemm_phase(PG8_LAS unsigned char* lds, const Gemm g, const Sched& S, const Epi& E) {
;     ...
;             PG8_LDB(B0, 1, 0); PG8_LDB(B1, 1, 1); PG8_SCHED; PG8_LDA(At, 1, 0); PG8_STAGE(PG8_SA(0, 1), a2 + hstep, voffA);
;             PG8_WAIT_V(8); PG8_WAIT_L(0); PG8_BAR; PG8_MMA(0, 0, At, B0); PG8_MMA(0, 1, At, B1); PG8_BAR; PG8_SCHED;
;             PG8_LDA(At, 1, 1); PG8_STAGE(PG8_SB(1, 0), b3, voffB); PG8_STAGE(PG8_SB(1, 1), b3 + hstep, voffB); PG8_STAGE(PG8_SA(1, 0), a3, voffA);
;             PG8_WAIT_V(8); PG8_WAIT_L(0); PG8_BAR; PG8_MMA(1, 0, At, B0); PG8_MMA(1, 1, At, B1); PG8_BAR; PG8_SCHED;
	s_add_i32 s61, 0, 0x18000
	s_add_i32 s72, 0, 0x1c000
	v_add_u32_e32 v110, s61, v170
	v_add_u32_e32 v173, s72, v170
	ds_read_b128 v[98:101], v110
	ds_read_b128 v[102:105], v110 offset:1024
	ds_read_b128 v[106:109], v110 offset:2048
	ds_read_b128 v[110:113], v110 offset:3072
	ds_read_b128 v[158:161], v173
	ds_read_b128 v[174:177], v173 offset:1024
	ds_read_b128 v[178:181], v173 offset:2048
	ds_read_b128 v[182:185], v173 offset:3072
	s_add_u32 s50, s50, 0x40000
	s_addc_u32 s51, s51, 0
	s_mov_b32 m0, s97
	v_lshl_add_u64 v[236:237], s[50:51], 0, v[146:147]
	ds_read_b128 v[196:199], v172 offset:32768
	ds_read_b128 v[200:203], v172 offset:33792
	ds_read_b128 v[204:207], v172 offset:34816
	ds_read_b128 v[208:211], v172 offset:35840
	ds_read_b128 v[212:215], v172 offset:36864
	ds_read_b128 v[216:219], v172 offset:37888
	ds_read_b128 v[220:223], v172 offset:38912
	ds_read_b128 v[224:227], v172 offset:39936
	global_load_lds_dwordx4 v[236:237], off
	v_lshl_add_u64 v[236:237], s[50:51], 0, v[150:151]
	s_mov_b32 m0, s2
	s_nop 0
	global_load_lds_dwordx4 v[236:237], off
	s_waitcnt vmcnt(8)
	s_waitcnt lgkmcnt(0)
	s_barrier
	v_mfma_f32_16x16x32_bf16 v[142:145], v[98:101], v[196:199], v[142:145]
	v_mfma_f32_16x16x32_bf16 v[138:141], v[106:109], v[196:199], v[138:141]
	v_mfma_f32_16x16x32_bf16 v[126:129], v[98:101], v[204:207], v[126:129]
	v_mfma_f32_16x16x32_bf16 v[122:125], v[106:109], v[204:207], v[122:125]
	v_mfma_f32_16x16x32_bf16 v[94:97], v[98:101], v[212:215], v[94:97]
	v_mfma_f32_16x16x32_bf16 v[90:93], v[106:109], v[212:215], v[90:93]
	v_mfma_f32_16x16x32_bf16 v[78:81], v[98:101], v[220:223], v[78:81]
	v_mfma_f32_16x16x32_bf16 v[74:77], v[106:109], v[220:223], v[74:77]
	v_mfma_f32_16x16x32_bf16 v[142:145], v[102:105], v[200:203], v[142:145]
	v_mfma_f32_16x16x32_bf16 v[138:141], v[110:113], v[200:203], v[138:141]
	v_mfma_f32_16x16x32_bf16 v[126:129], v[102:105], v[208:211], v[126:129]
	v_mfma_f32_16x16x32_bf16 v[122:125], v[110:113], v[208:211], v[122:125]
	v_mfma_f32_16x16x32_bf16 v[94:97], v[102:105], v[216:219], v[94:97]
	v_mfma_f32_16x16x32_bf16 v[90:93], v[110:113], v[216:219], v[90:93]
	v_mfma_f32_16x16x32_bf16 v[78:81], v[102:105], v[224:227], v[78:81]
	v_mfma_f32_16x16x32_bf16 v[74:77], v[110:113], v[224:227], v[74:77]
	v_mfma_f32_16x16x32_bf16 v[134:137], v[158:161], v[196:199], v[134:137]
	v_mfma_f32_16x16x32_bf16 v[130:133], v[178:181], v[196:199], v[130:133]
	v_mfma_f32_16x16x32_bf16 v[118:121], v[158:161], v[204:207], v[118:121]
	v_mfma_f32_16x16x32_bf16 v[114:117], v[178:181], v[204:207], v[114:117]
	v_mfma_f32_16x16x32_bf16 v[86:89], v[158:161], v[212:215], v[86:89]
	v_mfma_f32_16x16x32_bf16 v[82:85], v[178:181], v[212:215], v[82:85]
	v_mfma_f32_16x16x32_bf16 v[70:73], v[158:161], v[220:223], v[70:73]
	v_mfma_f32_16x16x32_bf16 v[66:69], v[178:181], v[220:223], v[66:69]
	v_mfma_f32_16x16x32_bf16 v[134:137], v[174:177], v[200:203], v[134:137]
	v_mfma_f32_16x16x32_bf16 v[130:133], v[182:185], v[200:203], v[130:133]
	v_mfma_f32_16x16x32_bf16 v[118:121], v[174:177], v[208:211], v[118:121]
	v_mfma_f32_16x16x32_bf16 v[114:117], v[182:185], v[208:211], v[114:117]
	v_mfma_f32_16x16x32_bf16 v[86:89], v[174:177], v[216:219], v[86:89]
	v_mfma_f32_16x16x32_bf16 v[82:85], v[182:185], v[216:219], v[82:85]
	v_mfma_f32_16x16x32_bf16 v[70:73], v[174:177], v[224:227], v[70:73]
	v_mfma_f32_16x16x32_bf16 v[66:69], v[182:185], v[224:227], v[66:69]
	s_barrier
	s_add_i32 s50, s61, s8
	v_lshl_add_u64 v[228:229], v[228:229], 0, s[34:35]
	s_mov_b32 m0, s50
	ds_read_b128 v[196:199], v172 offset:49152
	ds_read_b128 v[200:203], v172 offset:50176
	ds_read_b128 v[204:207], v172 offset:51200
	ds_read_b128 v[208:211], v172 offset:52224
	ds_read_b128 v[212:215], v172 offset:53248
	ds_read_b128 v[216:219], v172 offset:54272
	ds_read_b128 v[220:223], v172 offset:55296
	ds_read_b128 v[224:227], v172 offset:56320
	global_load_lds_dwordx4 v[228:229], off
	s_add_i32 m0, s50, 0x2000
	s_add_u32 s48, s48, 0x40080
	v_lshl_add_u64 v[228:229], v[230:231], 0, s[34:35]
	s_addc_u32 s49, s49, 0
	s_add_i32 s50, s72, s8
	global_load_lds_dwordx4 v[228:229], off
	v_lshl_add_u64 v[228:229], s[48:49], 0, v[148:149]
	s_mov_b32 m0, s50
	s_nop 0
	global_load_lds_dwordx4 v[228:229], off
	v_lshl_add_u64 v[228:229], s[48:49], 0, v[152:153]
	s_add_i32 m0, s50, 0x2000
	s_nop 0
	global_load_lds_dwordx4 v[228:229], off
	v_lshl_add_u64 v[228:229], v[232:233], 0, s[34:35]
	s_mov_b32 m0, s0
	s_nop 0
	global_load_lds_dwordx4 v[228:229], off
	v_lshl_add_u64 v[228:229], v[234:235], 0, s[34:35]
	s_mov_b32 m0, s3
	s_nop 0
	global_load_lds_dwordx4 v[228:229], off
	s_waitcnt vmcnt(8)
	s_waitcnt lgkmcnt(0)
	s_barrier
; __device__ __forceinline__ unsigned cvt_pk_bf16(float lo, float hi) { unsigned r; asm volatile("v_cvt_pk_bf16_f32 %0, %1, %2" : "=v"(r) : "v"(lo), "v"(hi)); return r; }
; #define GAS __attribute__((address_space(1)))
;     __device__ __forceinline__ void operator()(const f32x4 (&acc)[2][2][4][2], const Unit& u, int wr, int wc, int fr, int fq, const float (&pre)[8]) const {
;     ...
;         if (RS == 2) {
; #pragma unroll
;             for (int bj = 0; bj < 2; ++bj) { csc[bj][0] = *(const GAS f32x4*)(rs + col0 + bj * 128); csc[bj][1] = *(const GAS f32x4*)(rs + col0 + bj * 128 + 4); }
;         }
; #pragma unroll
;         for (int ai = 0; ai < 2; ++ai)
; #pragma unroll
;             for (int m = 0; m < 4; ++m) {
;                 const int row = row0 + ai * 128 + m * 16; bf16_t* rowp = O + (size_t)row * ldc + col0; float rs = 0.f;
;                 float rsc = 1.f; if (RS == 1) rsc = pre[ai * 4 + m];
; #pragma unroll
;                 for (int bj = 0; bj < 2; ++bj) {
;                     f32x4 v0 = acc[ai][bj][m][0], v1 = acc[ai][bj][m][1];
;                     if (RS == 1) { v0 = v0 * rsc; v1 = v1 * rsc; }
;                     if (RS == 2) { v0 = v0 * csc[bj][0]; v1 = v1 * csc[bj][1]; }
;                     if (ACT == 1) { const f32x2 a = gelu_pk((f32x2){v0[0], v0[1]}), b = gelu_pk((f32x2){v0[2], v0[3]}), c = gelu_pk((f32x2){v1[0], v1[1]}), d = gelu_pk((f32x2){v1[2], v1[3]});
;                         v0 = (f32x4){a.x, a.y, b.x, b.y}; v1 = (f32x4){c.x, c.y, d.x, d.y}; }
;                     v0 = v0 * sc; v1 = v1 * sc;
;                     if (STAT == 1) rs += (v0[0] * v0[0] + v0[1] * v0[1]) + (v0[2] * v0[2] + v0[3] * v0[3]) + (v1[0] * v1[0] + v1[1] * v1[1]) + (v1[2] * v1[2] + v1[3] * v1[3]);
;                     if (STAT == 2) {
; #pragma unroll
;                         for (int e = 0; e < 4; ++e) { cs[bj][0][e] += v0[e]; cq[bj][0][e] += v0[e] * v0[e]; cs[bj][1][e] += v1[e]; cq[bj][1][e] += v1[e] * v1[e]; } }
;                     u32x4 w; w.x = cvt_pk_bf16(v0[0], v0[1]); w.y = cvt_pk_bf16(v0[2], v0[3]); w.z = cvt_pk_bf16(v1[0], v1[1]); w.w = cvt_pk_bf16(v1[2], v1[3]);
;                     *(GAS u32x4*)(rowp + bj * 128) = w; }
	v_mfma_f32_16x16x32_bf16 v[62:65], v[98:101], v[196:199], v[62:65]
	v_mfma_f32_16x16x32_bf16 v[58:61], v[106:109], v[196:199], v[58:61]
	v_mfma_f32_16x16x32_bf16 v[50:53], v[98:101], v[204:207], v[50:53]
	v_mfma_f32_16x16x32_bf16 v[42:45], v[106:109], v[204:207], v[42:45]
	v_mfma_f32_16x16x32_bf16 v[34:37], v[98:101], v[212:215], v[34:37]
	v_mfma_f32_16x16x32_bf16 v[24:27], v[106:109], v[212:215], v[24:27]
	v_mfma_f32_16x16x32_bf16 v[12:15], v[98:101], v[220:223], v[12:15]
	v_mfma_f32_16x16x32_bf16 v[8:11], v[106:109], v[220:223], v[8:11]
	v_mfma_f32_16x16x32_bf16 v[62:65], v[102:105], v[200:203], v[62:65]
	v_mfma_f32_16x16x32_bf16 v[58:61], v[110:113], v[200:203], v[58:61]
	v_mfma_f32_16x16x32_bf16 v[50:53], v[102:105], v[208:211], v[50:53]
	v_mfma_f32_16x16x32_bf16 v[42:45], v[110:113], v[208:211], v[42:45]
	v_mfma_f32_16x16x32_bf16 v[34:37], v[102:105], v[216:219], v[34:37]
	v_mfma_f32_16x16x32_bf16 v[24:27], v[110:113], v[216:219], v[24:27]
	v_mfma_f32_16x16x32_bf16 v[12:15], v[102:105], v[224:227], v[12:15]
	v_mfma_f32_16x16x32_bf16 v[8:11], v[110:113], v[224:227], v[8:11]
	v_mfma_f32_16x16x32_bf16 v[54:57], v[158:161], v[196:199], v[54:57]
	v_mfma_f32_16x16x32_bf16 v[46:49], v[178:181], v[196:199], v[46:49]
	v_mfma_f32_16x16x32_bf16 v[38:41], v[158:161], v[204:207], v[38:41]
	v_mfma_f32_16x16x32_bf16 v[28:31], v[178:181], v[204:207], v[28:31]
	v_mfma_f32_16x16x32_bf16 v[20:23], v[158:161], v[212:215], v[20:23]
	v_mfma_f32_16x16x32_bf16 v[16:19], v[178:181], v[212:215], v[16:19]
	v_mfma_f32_16x16x32_bf16 v[4:7], v[158:161], v[220:223], v[4:7]
	v_mfma_f32_16x16x32_bf16 v[0:3], v[178:181], v[220:223], v[0:3]
	v_mfma_f32_16x16x32_bf16 v[54:57], v[174:177], v[200:203], v[54:57]
	v_mfma_f32_16x16x32_bf16 v[46:49], v[182:185], v[200:203], v[46:49]
	v_mfma_f32_16x16x32_bf16 v[38:41], v[174:177], v[208:211], v[38:41]
	v_mfma_f32_16x16x32_bf16 v[28:31], v[182:185], v[208:211], v[28:31]
	v_mfma_f32_16x16x32_bf16 v[20:23], v[174:177], v[216:219], v[20:23]
	v_mfma_f32_16x16x32_bf16 v[16:19], v[182:185], v[216:219], v[16:19]
	v_mfma_f32_16x16x32_bf16 v[4:7], v[174:177], v[224:227], v[4:7]
	v_mfma_f32_16x16x32_bf16 v[0:3], v[182:185], v[224:227], v[0:3]
	s_barrier
	s_add_i32 s80, s80, 2
	s_add_u32 s5, s5, 0x100
	s_addc_u32 s7, s7, 0
	s_add_u32 s46, s46, 0x100
	s_addc_u32 s47, s47, 0
	s_cmp_gt_u32 s80, 13
	s_cbranch_scc0 .LBB0_91
	s_and_b64 vcc, exec, s[38:39]
	s_cbranch_vccz .LBB0_94
	s_barrier
.LBB0_94:
	v_lshl_or_b32 v160, s45, 8, v171
	v_ashrrev_i32_e32 v161, 31, v160
	v_lshl_add_u64 v[102:103], v[160:161], 2, s[66:67]
	global_load_dwordx4 v[106:109], v[102:103], off offset:16
	global_load_dwordx4 v[110:113], v[102:103], off
	global_load_dwordx4 v[98:101], v[102:103], off offset:528
	s_nop 0
	global_load_dwordx4 v[102:105], v[102:103], off offset:512
	v_lshl_add_u32 v158, s44, 8, v33
	v_ashrrev_i32_e32 v159, 31, v158
	v_readlane_b32 s5, v253, 2
	v_lshlrev_b64 v[160:161], 1, v[160:161]
	s_mov_b64 s[44:45], -1
	v_lshlrev_b64 v[174:175], s5, v[158:159]
	v_lshl_add_u64 v[174:175], v[174:175], 1, s[84:85]
	v_lshl_add_u64 v[174:175], v[174:175], 0, v[160:161]
	s_andn2_b64 vcc, exec, s[90:91]
	s_waitcnt vmcnt(0)
	v_pk_mul_f32 v[176:177], v[140:141], v[108:109]
	v_pk_mul_f32 v[144:145], v[144:145], v[112:113]
	v_pk_mul_f32 v[142:143], v[142:143], v[110:111]
	v_pk_mul_f32 v[140:141], v[138:139], v[106:107]
	v_cvt_pk_bf16_f32 v138, v142, v143
	v_cvt_pk_bf16_f32 v139, v144, v145
	v_pk_mul_f32 v[134:135], v[134:135], v[102:103]
	v_cvt_pk_bf16_f32 v140, v140, v141
	v_cvt_pk_bf16_f32 v141, v176, v177
	global_store_dwordx4 v[174:175], v[138:141], off
	v_pk_mul_f32 v[136:137], v[136:137], v[104:105]
	v_pk_mul_f32 v[128:129], v[128:129], v[112:113]
	v_pk_mul_f32 v[138:139], v[132:133], v[100:101]
	v_pk_mul_f32 v[132:133], v[130:131], v[98:99]
	v_cvt_pk_bf16_f32 v130, v134, v135
	v_cvt_pk_bf16_f32 v131, v136, v137
	v_pk_mul_f32 v[126:127], v[126:127], v[110:111]
	v_cvt_pk_bf16_f32 v132, v132, v133
	v_cvt_pk_bf16_f32 v133, v138, v139
	global_store_dwordx4 v[174:175], v[130:133], off offset:256
	v_pk_mul_f32 v[118:119], v[118:119], v[102:103]
	v_pk_mul_f32 v[120:121], v[120:121], v[104:105]
	v_or_b32_e32 v130, 16, v158
	v_ashrrev_i32_e32 v131, 31, v130
	v_lshlrev_b64 v[130:131], s5, v[130:131]
	v_lshl_add_u64 v[130:131], v[130:131], 1, s[84:85]
	v_lshl_add_u64 v[130:131], v[130:131], 0, v[160:161]
	v_pk_mul_f32 v[132:133], v[124:125], v[108:109]
	v_pk_mul_f32 v[124:125], v[122:123], v[106:107]
	v_cvt_pk_bf16_f32 v122, v126, v127
	v_cvt_pk_bf16_f32 v123, v128, v129
	v_pk_mul_f32 v[96:97], v[96:97], v[112:113]
	v_cvt_pk_bf16_f32 v124, v124, v125
	v_cvt_pk_bf16_f32 v125, v132, v133
	global_store_dwordx4 v[130:131], v[122:125], off
	v_pk_mul_f32 v[94:95], v[94:95], v[110:111]
	v_pk_mul_f32 v[86:87], v[86:87], v[102:103]
	v_pk_mul_f32 v[122:123], v[116:117], v[100:101]
	v_pk_mul_f32 v[116:117], v[114:115], v[98:99]
	v_cvt_pk_bf16_f32 v114, v118, v119
	v_cvt_pk_bf16_f32 v115, v120, v121
	v_pk_mul_f32 v[88:89], v[88:89], v[104:105]
	v_cvt_pk_bf16_f32 v116, v116, v117
	v_cvt_pk_bf16_f32 v117, v122, v123
	global_store_dwordx4 v[130:131], v[114:117], off offset:256
	v_pk_mul_f32 v[80:81], v[80:81], v[112:113]
	v_pk_mul_f32 v[78:79], v[78:79], v[110:111]
	v_or_b32_e32 v114, 32, v158
	v_ashrrev_i32_e32 v115, 31, v114
	v_lshlrev_b64 v[114:115], s5, v[114:115]
	v_lshl_add_u64 v[114:115], v[114:115], 1, s[84:85]
; #define PG8_BAR __builtin_amdgcn_s_barrier()
; #define GAS __attribute__((address_space(1)))
; template <class Epi, class Sched, bool ALIGN_EPI = false, bool SP2 = false>
; __device__ __forceinline__ void gemm_phase(PG8_LAS unsigned char* lds, const Gemm g, const Sched& S, const Epi& E) {
;     ...
;         if constexpr (ALIGN_EPI) { if (wr == 0) PG8_BAR; }
;         if constexpr (!Epi::AFTER_DRAIN) { if constexpr (Epi::PREFETCH) E(acc, cur, wr, wc, fr, fq, epre); else E(acc, cur, wr, wc, fr, fq); S.done(cur); }
;         if (!has_next) break;
; #pragma unroll
;         for (int a = 0; a < 2; ++a)
; #pragma unroll
;             for (int b = 0; b < 2; ++b)
; #pragma unroll
;                 for (int m = 0; m < 4; ++m)
; #pragma unroll
;                     for (int n = 0; n < 2; ++n) acc[a][b][m][n] = (f32x4){0.f, 0.f, 0.f, 0.f};
;         cur = nxt; cA = nA; cB = nB; ++ui;
;         if constexpr (Epi::PREFETCH) E.prefetch(cur, wr, fr, epre);
;         if constexpr (ALIGN_EPI) { if (wr == 1) PG8_BAR; }
;     __device__ __forceinline__ void operator()(const f32x4 (&acc)[2][2][4][2], const Unit& u, int wr, int wc, int fr, int fq, const float (&pre)[8]) const {
;     ...
;                     f32x4 v0 = acc[ai][bj][m][0], v1 = acc[ai][bj][m][1];
;                     if (RS == 1) { v0 = v0 * rsc; v1 = v1 * rsc; }
;                     if (RS == 2) { v0 = v0 * csc[bj][0]; v1 = v1 * csc[bj][1]; }
;                     if (ACT == 1) { const f32x2 a = gelu_pk((f32x2){v0[0], v0[1]}), b = gelu_pk((f32x2){v0[2], v0[3]}), c = gelu_pk((f32x2){v1[0], v1[1]}), d = gelu_pk((f32x2){v1[2], v1[3]});
;                         v0 = (f32x4){a.x, a.y, b.x, b.y}; v1 = (f32x4){c.x, c.y, d.x, d.y}; }
;                     v0 = v0 * sc; v1 = v1 * sc;
;                     if (STAT == 1) rs += (v0[0] * v0[0] + v0[1] * v0[1]) + (v0[2] * v0[2] + v0[3] * v0[3]) + (v1[0] * v1[0] + v1[1] * v1[1]) + (v1[2] * v1[2] + v1[3] * v1[3]);
;                     if (STAT == 2) {
; #pragma unroll
;                         for (int e = 0; e < 4; ++e) { cs[bj][0][e] += v0[e]; cq[bj][0][e] += v0[e] * v0[e]; cs[bj][1][e] += v1[e]; cq[bj][1][e] += v1[e] * v1[e]; } }
;                     u32x4 w; w.x = cvt_pk_bf16(v0[0], v0[1]); w.y = cvt_pk_bf16(v0[2], v0[3]); w.z = cvt_pk_bf16(v1[0], v1[1]); w.w = cvt_pk_bf16(v1[2], v1[3]);
;                     *(GAS u32x4*)(rowp + bj * 128) = w; }
	v_lshl_add_u64 v[114:115], v[114:115], 0, v[160:161]
	v_pk_mul_f32 v[116:117], v[92:93], v[108:109]
	v_pk_mul_f32 v[92:93], v[90:91], v[106:107]
	v_cvt_pk_bf16_f32 v90, v94, v95
	v_cvt_pk_bf16_f32 v91, v96, v97
	v_pk_mul_f32 v[70:71], v[70:71], v[102:103]
	v_cvt_pk_bf16_f32 v92, v92, v93
	v_cvt_pk_bf16_f32 v93, v116, v117
	global_store_dwordx4 v[114:115], v[90:93], off
	v_pk_mul_f32 v[72:73], v[72:73], v[104:105]
	v_pk_mul_f32 v[64:65], v[64:65], v[112:113]
	v_pk_mul_f32 v[90:91], v[84:85], v[100:101]
	v_pk_mul_f32 v[84:85], v[82:83], v[98:99]
	v_cvt_pk_bf16_f32 v82, v86, v87
	v_cvt_pk_bf16_f32 v83, v88, v89
	v_pk_mul_f32 v[62:63], v[62:63], v[110:111]
	v_cvt_pk_bf16_f32 v84, v84, v85
	v_cvt_pk_bf16_f32 v85, v90, v91
	global_store_dwordx4 v[114:115], v[82:85], off offset:256
	v_pk_mul_f32 v[54:55], v[54:55], v[102:103]
	v_pk_mul_f32 v[56:57], v[56:57], v[104:105]
	v_or_b32_e32 v82, 48, v158
	v_ashrrev_i32_e32 v83, 31, v82
	v_lshlrev_b64 v[82:83], s5, v[82:83]
	v_lshl_add_u64 v[82:83], v[82:83], 1, s[84:85]
	v_lshl_add_u64 v[82:83], v[82:83], 0, v[160:161]
	v_pk_mul_f32 v[84:85], v[76:77], v[108:109]
	v_pk_mul_f32 v[76:77], v[74:75], v[106:107]
	v_cvt_pk_bf16_f32 v74, v78, v79
	v_cvt_pk_bf16_f32 v75, v80, v81
	v_pk_mul_f32 v[50:51], v[50:51], v[110:111]
	v_cvt_pk_bf16_f32 v76, v76, v77
	v_cvt_pk_bf16_f32 v77, v84, v85
	global_store_dwordx4 v[82:83], v[74:77], off
	v_pk_mul_f32 v[38:39], v[38:39], v[102:103]
	v_pk_mul_f32 v[40:41], v[40:41], v[104:105]
	v_pk_mul_f32 v[74:75], v[68:69], v[100:101]
	v_pk_mul_f32 v[68:69], v[66:67], v[98:99]
	v_cvt_pk_bf16_f32 v66, v70, v71
	v_cvt_pk_bf16_f32 v67, v72, v73
	v_pk_mul_f32 v[34:35], v[34:35], v[110:111]
	v_cvt_pk_bf16_f32 v68, v68, v69
	v_cvt_pk_bf16_f32 v69, v74, v75
	global_store_dwordx4 v[82:83], v[66:69], off offset:256
	v_pk_mul_f32 v[20:21], v[20:21], v[102:103]
	v_pk_mul_f32 v[22:23], v[22:23], v[104:105]
	v_add_u32_e32 v66, 0x80, v158
	v_ashrrev_i32_e32 v67, 31, v66
	v_lshlrev_b64 v[66:67], s5, v[66:67]
	v_lshl_add_u64 v[66:67], v[66:67], 1, s[84:85]
	v_lshl_add_u64 v[66:67], v[66:67], 0, v[160:161]
	v_pk_mul_f32 v[68:69], v[60:61], v[108:109]
	v_pk_mul_f32 v[60:61], v[58:59], v[106:107]
	v_cvt_pk_bf16_f32 v58, v62, v63
	v_cvt_pk_bf16_f32 v59, v64, v65
	v_pk_mul_f32 v[14:15], v[14:15], v[112:113]
	v_cvt_pk_bf16_f32 v60, v60, v61
	v_cvt_pk_bf16_f32 v61, v68, v69
	global_store_dwordx4 v[66:67], v[58:61], off
	v_pk_mul_f32 v[12:13], v[12:13], v[110:111]
	v_pk_mul_f32 v[6:7], v[6:7], v[104:105]
	v_pk_mul_f32 v[58:59], v[48:49], v[100:101]
	v_pk_mul_f32 v[48:49], v[46:47], v[98:99]
	v_cvt_pk_bf16_f32 v46, v54, v55
	v_cvt_pk_bf16_f32 v47, v56, v57
	v_pk_mul_f32 v[4:5], v[4:5], v[102:103]
	v_cvt_pk_bf16_f32 v48, v48, v49
	v_cvt_pk_bf16_f32 v49, v58, v59
	global_store_dwordx4 v[66:67], v[46:49], off offset:256
	s_nop 1
	v_add_u32_e32 v46, 0x90, v158
	v_ashrrev_i32_e32 v47, 31, v46
	v_lshlrev_b64 v[46:47], s5, v[46:47]
	v_lshl_add_u64 v[46:47], v[46:47], 1, s[84:85]
	v_lshl_add_u64 v[46:47], v[46:47], 0, v[160:161]
	v_pk_mul_f32 v[48:49], v[52:53], v[112:113]
	v_pk_mul_f32 v[52:53], v[44:45], v[108:109]
	v_pk_mul_f32 v[44:45], v[42:43], v[106:107]
	v_cvt_pk_bf16_f32 v42, v50, v51
	v_cvt_pk_bf16_f32 v43, v48, v49
	s_nop 0
	v_cvt_pk_bf16_f32 v44, v44, v45
	v_cvt_pk_bf16_f32 v45, v52, v53
	global_store_dwordx4 v[46:47], v[42:45], off
	s_nop 1
	v_pk_mul_f32 v[42:43], v[30:31], v[100:101]
	v_pk_mul_f32 v[30:31], v[28:29], v[98:99]
	v_cvt_pk_bf16_f32 v28, v38, v39
	v_cvt_pk_bf16_f32 v29, v40, v41
	s_nop 0
	v_cvt_pk_bf16_f32 v30, v30, v31
	v_cvt_pk_bf16_f32 v31, v42, v43
	global_store_dwordx4 v[46:47], v[28:31], off offset:256
	s_nop 1
	v_add_u32_e32 v28, 0xa0, v158
	v_ashrrev_i32_e32 v29, 31, v28
	v_lshlrev_b64 v[28:29], s5, v[28:29]
	v_lshl_add_u64 v[28:29], v[28:29], 1, s[84:85]
	v_lshl_add_u64 v[28:29], v[28:29], 0, v[160:161]
	v_pk_mul_f32 v[30:31], v[36:37], v[112:113]
	v_pk_mul_f32 v[36:37], v[26:27], v[108:109]
	v_pk_mul_f32 v[26:27], v[24:25], v[106:107]
	v_cvt_pk_bf16_f32 v24, v34, v35
	v_cvt_pk_bf16_f32 v25, v30, v31
	s_nop 0
	v_cvt_pk_bf16_f32 v26, v26, v27
	v_cvt_pk_bf16_f32 v27, v36, v37
	global_store_dwordx4 v[28:29], v[24:27], off
	s_nop 1
	v_pk_mul_f32 v[24:25], v[18:19], v[100:101]
	v_pk_mul_f32 v[18:19], v[16:17], v[98:99]
	v_cvt_pk_bf16_f32 v16, v20, v21
	v_cvt_pk_bf16_f32 v17, v22, v23
	s_nop 0
	v_cvt_pk_bf16_f32 v18, v18, v19
	v_cvt_pk_bf16_f32 v19, v24, v25
	global_store_dwordx4 v[28:29], v[16:19], off offset:256
	s_nop 1
	v_add_u32_e32 v16, 0xb0, v158
	v_ashrrev_i32_e32 v17, 31, v16
	v_lshlrev_b64 v[16:17], s5, v[16:17]
	v_lshl_add_u64 v[16:17], v[16:17], 1, s[84:85]
	v_lshl_add_u64 v[16:17], v[16:17], 0, v[160:161]
	v_pk_mul_f32 v[18:19], v[10:11], v[108:109]
	v_pk_mul_f32 v[10:11], v[8:9], v[106:107]
	v_cvt_pk_bf16_f32 v8, v12, v13
	v_cvt_pk_bf16_f32 v9, v14, v15
	s_nop 0
	v_cvt_pk_bf16_f32 v10, v10, v11
	v_cvt_pk_bf16_f32 v11, v18, v19
	global_store_dwordx4 v[16:17], v[8:11], off
	s_nop 1
	v_pk_mul_f32 v[8:9], v[2:3], v[100:101]
	v_pk_mul_f32 v[2:3], v[0:1], v[98:99]
	v_cvt_pk_bf16_f32 v0, v4, v5
	v_cvt_pk_bf16_f32 v1, v6, v7
	s_nop 0
	v_cvt_pk_bf16_f32 v2, v2, v3
	v_cvt_pk_bf16_f32 v3, v8, v9
	global_store_dwordx4 v[16:17], v[0:3], off offset:256
	s_cbranch_vccnz .LBB0_82
	v_readlane_b32 s44, v254, 43
	v_readlane_b32 s45, v254, 44
	s_andn2_b64 vcc, exec, s[44:45]
	s_cmp_lg_u32 s44, 0
	s_cselect_b32 s100, 1, 0
	s_branch .LBB0_81

; #define PG8_STAGE(bufoff, gbase, voff) do { _Pragma("unroll") for (int _i = 0; _i < 2; ++_i) \
;         __builtin_amdgcn_global_load_lds((const unsigned*)((const char*)(gbase) + (voff)[_i]), (PG8_LAS unsigned*)(lds + (bufoff) + ldsw + _i * 8192), 16, 0, 0); } while (0)
; #define PG8_LDA(dst, b, h) do { _Pragma("unroll") for (int m = 0; m < 4; ++m) _Pragma("unroll") for (int k = 0; k < 2; ++k) dst[m][k] = *(const PG8_LAS bf16x8*)(lds + PG8_SA(b, h) + aoff + m * 2048 + k * 1024); } while (0)
; #define PG8_LDB(dst, b, h) do { _Pragma("unroll") for (int n = 0; n < 2; ++n) _Pragma("unroll") for (int k = 0; k < 2; ++k) dst[n][k] = *(const PG8_LAS bf16x8*)(lds + PG8_SB(b, h) + boff + n * 2048 + k * 1024); } while (0)
; #define PG8_WAIT_V(n) asm volatile("s_waitcnt vmcnt(" #n ")" ::: "memory")
; #define PG8_WAIT_L(n) asm volatile("s_waitcnt lgkmcnt(" #n ")" ::: "memory")
; #define PG8_BAR __builtin_amdgcn_s_barrier()
; template <class Epi, class Sched, bool ALIGN_EPI = false, bool SP2 = false>
; __device__ __forceinline__ void gemm_phase(PG8_LAS unsigned char* lds, const Gemm g, const Sched& S, const Epi& E) {
;     ...
;         const bool has_next = S.next(ui + 1, nxt);
;         const char* nA = has_next ? (const char*)g.A + (size_t)nxt.pm * tstep : cA; const char* nB = has_next ? (const char*)g.Bt + (size_t)nxt.pn * tstep : cB;
;         for (int t = 0; t < nt; t += 2) {
;             const bool last = (t == nt - 2);
;             const char* a1 = cA + (size_t)(t + 1) * kstep;
;             const char* a2 = last ? nA : cA + (size_t)(t + 2) * kstep; const char* b2 = last ? nB : cB + (size_t)(t + 2) * kstep;
;             const char* a3 = a2 + kstep; const char* b3 = b2 + kstep;
;             if (last && has_next) S.a_ready(nxt);
;             if constexpr (SP2) {
;             PG8_LDB(B0, 0, 0); PG8_LDB(B1, 0, 1); PG8_SCHED; PG8_LDA(At, 0, 0); PG8_STAGE(PG8_SA(1, 1), a1 + hstep, voffA);
;             PG8_WAIT_V(8); PG8_WAIT_L(0); PG8_BAR; PG8_MMA(0, 0, At, B0); PG8_MMA(0, 1, At, B1); PG8_BAR; PG8_SCHED;
;     ...
; #pragma unroll
;         for (int a = 0; a < 2; ++a)
; #pragma unroll
;             for (int b = 0; b < 2; ++b)
; #pragma unroll
;                 for (int m = 0; m < 4; ++m)
; #pragma unroll
;                     for (int n = 0; n < 2; ++n) acc[a][b][m][n] = (f32x4){0.f, 0.f, 0.f, 0.f};
;         cur = nxt; cA = nA; cB = nB; ++ui;
.LBB0_117:
	s_ashr_i32 s91, s90, 31
	s_lshl_b64 s[50:51], s[90:91], 19
	s_add_u32 s92, s62, s50
	s_addc_u32 s93, s63, s51
	s_and_b64 s[50:51], s[96:97], exec
	s_cselect_b32 s5, s93, s49
	s_cselect_b32 s7, s92, s48
	s_ashr_i32 s89, s88, 31
	s_lshl_b64 s[50:51], s[88:89], 19
	v_readlane_b32 s8, v254, 41
	s_add_u32 s94, s8, s50
	v_readlane_b32 s8, v254, 43
	s_addc_u32 s95, s8, s51
	s_and_b64 s[50:51], s[96:97], exec
	s_cselect_b32 s8, s95, s47
	s_cselect_b32 s45, s94, s46
	s_add_u32 s89, s46, 0x100
	s_addc_u32 s91, s47, 0
	s_add_u32 s46, s48, 0x40080
	v_mov_b32_e32 v0, 0
	s_addc_u32 s47, s49, 0
	s_mov_b32 vcc_lo, -2
	v_mov_b32_e32 v1, v0
	v_mov_b32_e32 v2, v0
	v_mov_b32_e32 v3, v0
	v_mov_b32_e32 v4, v0
	v_mov_b32_e32 v5, v0
	v_mov_b32_e32 v6, v0
	v_mov_b32_e32 v7, v0
	v_mov_b32_e32 v16, v0
	v_mov_b32_e32 v17, v0
	v_mov_b32_e32 v18, v0
	v_mov_b32_e32 v19, v0
	v_mov_b32_e32 v20, v0
	v_mov_b32_e32 v21, v0
	v_mov_b32_e32 v22, v0
	v_mov_b32_e32 v23, v0
	v_mov_b32_e32 v34, v0
	v_mov_b32_e32 v35, v0
	v_mov_b32_e32 v36, v0
	v_mov_b32_e32 v37, v0
	v_mov_b32_e32 v38, v0
	v_mov_b32_e32 v39, v0
	v_mov_b32_e32 v40, v0
	v_mov_b32_e32 v41, v0
	v_mov_b32_e32 v50, v0
	v_mov_b32_e32 v51, v0
	v_mov_b32_e32 v52, v0
	v_mov_b32_e32 v53, v0
	v_mov_b32_e32 v54, v0
	v_mov_b32_e32 v55, v0
	v_mov_b32_e32 v56, v0
	v_mov_b32_e32 v57, v0
	v_mov_b32_e32 v8, v0
	v_mov_b32_e32 v9, v0
	v_mov_b32_e32 v10, v0
	v_mov_b32_e32 v11, v0
	v_mov_b32_e32 v12, v0
	v_mov_b32_e32 v13, v0
	v_mov_b32_e32 v14, v0
	v_mov_b32_e32 v15, v0
	v_mov_b32_e32 v24, v0
	v_mov_b32_e32 v25, v0
	v_mov_b32_e32 v26, v0
	v_mov_b32_e32 v27, v0
	v_mov_b32_e32 v28, v0
	v_mov_b32_e32 v29, v0
	v_mov_b32_e32 v30, v0
	v_mov_b32_e32 v31, v0
	v_mov_b32_e32 v42, v0
	v_mov_b32_e32 v43, v0
	v_mov_b32_e32 v44, v0
	v_mov_b32_e32 v45, v0
	v_mov_b32_e32 v46, v0
	v_mov_b32_e32 v47, v0
	v_mov_b32_e32 v48, v0
	v_mov_b32_e32 v49, v0
	v_mov_b32_e32 v58, v0
	v_mov_b32_e32 v59, v0
	v_mov_b32_e32 v60, v0
	v_mov_b32_e32 v61, v0
	v_mov_b32_e32 v62, v0
	v_mov_b32_e32 v63, v0
	v_mov_b32_e32 v64, v0
	v_mov_b32_e32 v65, v0
	v_mov_b32_e32 v66, v0
	v_mov_b32_e32 v67, v0
	v_mov_b32_e32 v68, v0
	v_mov_b32_e32 v69, v0
	v_mov_b32_e32 v70, v0
	v_mov_b32_e32 v71, v0
	v_mov_b32_e32 v72, v0
	v_mov_b32_e32 v73, v0
	v_mov_b32_e32 v82, v0
	v_mov_b32_e32 v83, v0
	v_mov_b32_e32 v84, v0
	v_mov_b32_e32 v85, v0
	v_mov_b32_e32 v86, v0
	v_mov_b32_e32 v87, v0
	v_mov_b32_e32 v88, v0
	v_mov_b32_e32 v89, v0
	v_mov_b32_e32 v98, v0
	v_mov_b32_e32 v99, v0
	v_mov_b32_e32 v100, v0
	v_mov_b32_e32 v101, v0
	v_mov_b32_e32 v102, v0
	v_mov_b32_e32 v103, v0
	v_mov_b32_e32 v104, v0
	v_mov_b32_e32 v105, v0
	v_mov_b32_e32 v114, v0
	v_mov_b32_e32 v115, v0
	v_mov_b32_e32 v116, v0
	v_mov_b32_e32 v117, v0
	v_mov_b32_e32 v118, v0
	v_mov_b32_e32 v119, v0
	v_mov_b32_e32 v120, v0
	v_mov_b32_e32 v121, v0
	v_mov_b32_e32 v74, v0
	v_mov_b32_e32 v75, v0
	v_mov_b32_e32 v76, v0
	v_mov_b32_e32 v77, v0
	v_mov_b32_e32 v78, v0
	v_mov_b32_e32 v79, v0
	v_mov_b32_e32 v80, v0
	v_mov_b32_e32 v81, v0
	v_mov_b32_e32 v90, v0
	v_mov_b32_e32 v91, v0
	v_mov_b32_e32 v92, v0
	v_mov_b32_e32 v93, v0
	v_mov_b32_e32 v94, v0
	v_mov_b32_e32 v95, v0
	v_mov_b32_e32 v96, v0
	v_mov_b32_e32 v97, v0
	v_mov_b32_e32 v106, v0
	v_mov_b32_e32 v107, v0
	v_mov_b32_e32 v108, v0
	v_mov_b32_e32 v109, v0
	v_mov_b32_e32 v110, v0
	v_mov_b32_e32 v111, v0
	v_mov_b32_e32 v112, v0
	v_mov_b32_e32 v113, v0
	v_mov_b32_e32 v122, v0
	v_mov_b32_e32 v123, v0
	v_mov_b32_e32 v124, v0
	v_mov_b32_e32 v125, v0
	v_mov_b32_e32 v126, v0
	v_mov_b32_e32 v127, v0
	v_mov_b32_e32 v128, v0
	v_mov_b32_e32 v129, v0
	s_cmp_eq_u32 s100, 0
	s_cbranch_scc1 .Lrb2_skip
	s_mov_b32 s100, 0
	s_barrier
.Lrb2_skip:
.LBB0_118:
	s_add_u32 s48, s46, 0xfffc0080
	s_addc_u32 s49, s47, -1
	s_add_i32 s61, 0, 0x10000
	s_cmp_eq_u32 vcc_lo, 12
	s_cselect_b32 s51, s5, s49
	s_cselect_b32 s50, s7, s48
	v_add_u32_e32 v150, s61, v145
	s_cselect_b32 s49, s8, s91
	s_cselect_b32 s48, s45, s89
	s_add_i32 s72, 0, 0x14000
	ds_read_b128 v[174:177], v150
	ds_read_b128 v[178:181], v150 offset:1024
	ds_read_b128 v[182:185], v150 offset:2048
	ds_read_b128 v[196:199], v150 offset:3072
	v_add_u32_e32 v150, s72, v145
	ds_read_b128 v[200:203], v150
	ds_read_b128 v[204:207], v150 offset:1024
	ds_read_b128 v[208:211], v150 offset:2048
	ds_read_b128 v[212:215], v150 offset:3072
	v_lshl_add_u64 v[150:151], s[46:47], 0, v[142:143]
	s_add_i32 m0, s39, 0xc000
	ds_read_b128 v[216:219], v149
	ds_read_b128 v[220:223], v149 offset:1024
	ds_read_b128 v[224:227], v149 offset:2048
	ds_read_b128 v[228:231], v149 offset:3072
	ds_read_b128 v[232:235], v149 offset:4096
	ds_read_b128 v[236:239], v149 offset:5120
	ds_read_b128 v[240:243], v149 offset:6144
	ds_read_b128 v[244:247], v149 offset:7168
	global_load_lds_dwordx4 v[150:151], off
	v_lshl_add_u64 v[150:151], s[46:47], 0, v[140:141]
	s_add_i32 m0, s39, 0xe000
	s_nop 0
	global_load_lds_dwordx4 v[150:151], off
	s_waitcnt vmcnt(8)
	s_waitcnt lgkmcnt(0)
	s_barrier
; #define PG8_STAGE(bufoff, gbase, voff) do { _Pragma("unroll") for (int _i = 0; _i < 2; ++_i) \
;         __builtin_amdgcn_global_load_lds((const unsigned*)((const char*)(gbase) + (voff)[_i]), (PG8_LAS unsigned*)(lds + (bufoff) + ldsw + _i * 8192), 16, 0, 0); } while (0)
; #define PG8_LDA(dst, b, h) do { _Pragma("unroll") for (int m = 0; m < 4; ++m) _Pragma("unroll") for (int k = 0; k < 2; ++k) dst[m][k] = *(const PG8_LAS bf16x8*)(lds + PG8_SA(b, h) + aoff + m * 2048 + k * 1024); } while (0)
; #define PG8_LDB(dst, b, h) do { _Pragma("unroll") for (int n = 0; n < 2; ++n) _Pragma("unroll") for (int k = 0; k < 2; ++k) dst[n][k] = *(const PG8_LAS bf16x8*)(lds + PG8_SB(b, h) + boff + n * 2048 + k * 1024); } while (0)
; #define PG8_MMA(ai, bj, At, Bt) do { __builtin_amdgcn_s_setprio(1); _Pragma("unroll") for (int m = 0; m < 4; ++m) _Pragma("unroll") for (int n = 0; n < 2; ++n) _Pragma("unroll") for (int k = 0; k < 2; ++k) \
;         acc[ai][bj][m][n] = __builtin_amdgcn_mfma_f32_16x16x32_bf16(Bt[n][k], At[m][k], acc[ai][bj][m][n], 0, 0, 0); __builtin_amdgcn_s_setprio(0); } while (0)
; #define PG8_WAIT_V(n) asm volatile("s_waitcnt vmcnt(" #n ")" ::: "memory")
; #define PG8_WAIT_L(n) asm volatile("s_waitcnt lgkmcnt(" #n ")" ::: "memory")
; #define PG8_BAR __builtin_amdgcn_s_barrier()
; #define PG8_SCHED __builtin_amdgcn_sched_barrier(0)
; template <class Epi, class Sched, bool ALIGN_EPI = false, bool SP2 = false>
; __device__ __forceinline__ void gemm_phase(PG8_LAS unsigned char* lds, const Gemm g, const Sched& S, const Epi& E) {
;     ...
;             PG8_LDB(B0, 0, 0); PG8_LDB(B1, 0, 1); PG8_SCHED; PG8_LDA(At, 0, 0); PG8_STAGE(PG8_SA(1, 1), a1 + hstep, voffA);
;             PG8_WAIT_V(8); PG8_WAIT_L(0); PG8_BAR; PG8_MMA(0, 0, At, B0); PG8_MMA(0, 1, At, B1); PG8_BAR; PG8_SCHED;
;             PG8_LDA(At, 0, 1); PG8_STAGE(PG8_SB(0, 0), b2, voffB); PG8_STAGE(PG8_SB(0, 1), b2 + hstep, voffB); PG8_STAGE(PG8_SA(0, 0), a2, voffA);
;             PG8_WAIT_V(8); PG8_WAIT_L(0); PG8_BAR; PG8_MMA(1, 0, At, B0); PG8_MMA(1, 1, At, B1); PG8_BAR; PG8_SCHED;
	v_mfma_f32_16x16x32_bf16 v[126:129], v[174:177], v[216:219], v[126:129]
	v_mfma_f32_16x16x32_bf16 v[122:125], v[182:185], v[216:219], v[122:125]
	v_mfma_f32_16x16x32_bf16 v[110:113], v[174:177], v[224:227], v[110:113]
	v_mfma_f32_16x16x32_bf16 v[106:109], v[182:185], v[224:227], v[106:109]
	v_mfma_f32_16x16x32_bf16 v[94:97], v[174:177], v[232:235], v[94:97]
	v_mfma_f32_16x16x32_bf16 v[90:93], v[182:185], v[232:235], v[90:93]
	v_mfma_f32_16x16x32_bf16 v[78:81], v[174:177], v[240:243], v[78:81]
	v_mfma_f32_16x16x32_bf16 v[74:77], v[182:185], v[240:243], v[74:77]
	v_mfma_f32_16x16x32_bf16 v[126:129], v[178:181], v[220:223], v[126:129]
	v_mfma_f32_16x16x32_bf16 v[122:125], v[196:199], v[220:223], v[122:125]
	v_mfma_f32_16x16x32_bf16 v[110:113], v[178:181], v[228:231], v[110:113]
	v_mfma_f32_16x16x32_bf16 v[106:109], v[196:199], v[228:231], v[106:109]
	v_mfma_f32_16x16x32_bf16 v[94:97], v[178:181], v[236:239], v[94:97]
	v_mfma_f32_16x16x32_bf16 v[90:93], v[196:199], v[236:239], v[90:93]
	v_mfma_f32_16x16x32_bf16 v[78:81], v[178:181], v[244:247], v[78:81]
	v_mfma_f32_16x16x32_bf16 v[74:77], v[196:199], v[244:247], v[74:77]
	v_mfma_f32_16x16x32_bf16 v[118:121], v[200:203], v[216:219], v[118:121]
	v_mfma_f32_16x16x32_bf16 v[114:117], v[208:211], v[216:219], v[114:117]
	v_mfma_f32_16x16x32_bf16 v[102:105], v[200:203], v[224:227], v[102:105]
	v_mfma_f32_16x16x32_bf16 v[98:101], v[208:211], v[224:227], v[98:101]
	v_mfma_f32_16x16x32_bf16 v[86:89], v[200:203], v[232:235], v[86:89]
	v_mfma_f32_16x16x32_bf16 v[82:85], v[208:211], v[232:235], v[82:85]
	v_mfma_f32_16x16x32_bf16 v[70:73], v[200:203], v[240:243], v[70:73]
	v_mfma_f32_16x16x32_bf16 v[66:69], v[208:211], v[240:243], v[66:69]
	v_mfma_f32_16x16x32_bf16 v[118:121], v[204:207], v[220:223], v[118:121]
	v_mfma_f32_16x16x32_bf16 v[114:117], v[212:215], v[220:223], v[114:117]
	v_mfma_f32_16x16x32_bf16 v[102:105], v[204:207], v[228:231], v[102:105]
	v_mfma_f32_16x16x32_bf16 v[98:101], v[212:215], v[228:231], v[98:101]
	v_mfma_f32_16x16x32_bf16 v[86:89], v[204:207], v[236:239], v[86:89]
	v_mfma_f32_16x16x32_bf16 v[82:85], v[212:215], v[236:239], v[82:85]
	v_mfma_f32_16x16x32_bf16 v[70:73], v[204:207], v[244:247], v[70:73]
	v_mfma_f32_16x16x32_bf16 v[66:69], v[212:215], v[244:247], v[66:69]
	s_barrier
	s_add_i32 s61, s61, s38
	v_lshl_add_u64 v[150:151], s[48:49], 0, v[132:133]
	s_mov_b32 m0, s61
	ds_read_b128 v[216:219], v149 offset:16384
	ds_read_b128 v[220:223], v149 offset:17408
	ds_read_b128 v[224:227], v149 offset:18432
	ds_read_b128 v[228:231], v149 offset:19456
	ds_read_b128 v[232:235], v149 offset:20480
	ds_read_b128 v[236:239], v149 offset:21504
	ds_read_b128 v[240:243], v149 offset:22528
	ds_read_b128 v[244:247], v149 offset:23552
	global_load_lds_dwordx4 v[150:151], off
	s_add_i32 m0, s61, 0x2000
	s_add_u32 s80, s48, 0x40000
	v_lshl_add_u64 v[160:161], s[48:49], 0, v[136:137]
	s_addc_u32 s81, s49, 0
	s_add_i32 s61, s72, s38
	global_load_lds_dwordx4 v[160:161], off
	v_lshl_add_u64 v[170:171], s[80:81], 0, v[132:133]
	s_mov_b32 m0, s61
	v_lshl_add_u64 v[248:249], s[50:51], 0, v[134:135]
	global_load_lds_dwordx4 v[170:171], off
	v_lshl_add_u64 v[170:171], s[80:81], 0, v[136:137]
	s_add_i32 m0, s61, 0x2000
	s_nop 0
	global_load_lds_dwordx4 v[170:171], off
	v_lshl_add_u64 v[170:171], s[50:51], 0, v[130:131]
	s_mov_b32 m0, s39
	s_nop 0
	global_load_lds_dwordx4 v[170:171], off
	s_mov_b32 m0, s2
	s_nop 0
	global_load_lds_dwordx4 v[248:249], off
	s_waitcnt vmcnt(8)
	s_waitcnt lgkmcnt(0)
	s_barrier
	v_mfma_f32_16x16x32_bf16 v[62:65], v[174:177], v[216:219], v[62:65]
	v_mfma_f32_16x16x32_bf16 v[58:61], v[182:185], v[216:219], v[58:61]
	v_mfma_f32_16x16x32_bf16 v[46:49], v[174:177], v[224:227], v[46:49]
	v_mfma_f32_16x16x32_bf16 v[42:45], v[182:185], v[224:227], v[42:45]
	v_mfma_f32_16x16x32_bf16 v[28:31], v[174:177], v[232:235], v[28:31]
	v_mfma_f32_16x16x32_bf16 v[24:27], v[182:185], v[232:235], v[24:27]
	v_mfma_f32_16x16x32_bf16 v[12:15], v[174:177], v[240:243], v[12:15]
	v_mfma_f32_16x16x32_bf16 v[8:11], v[182:185], v[240:243], v[8:11]
	v_mfma_f32_16x16x32_bf16 v[62:65], v[178:181], v[220:223], v[62:65]
	v_mfma_f32_16x16x32_bf16 v[58:61], v[196:199], v[220:223], v[58:61]
	v_mfma_f32_16x16x32_bf16 v[46:49], v[178:181], v[228:231], v[46:49]
	v_mfma_f32_16x16x32_bf16 v[42:45], v[196:199], v[228:231], v[42:45]
	v_mfma_f32_16x16x32_bf16 v[28:31], v[178:181], v[236:239], v[28:31]
	v_mfma_f32_16x16x32_bf16 v[24:27], v[196:199], v[236:239], v[24:27]
	v_mfma_f32_16x16x32_bf16 v[12:15], v[178:181], v[244:247], v[12:15]
	v_mfma_f32_16x16x32_bf16 v[8:11], v[196:199], v[244:247], v[8:11]
	v_mfma_f32_16x16x32_bf16 v[54:57], v[200:203], v[216:219], v[54:57]
	v_mfma_f32_16x16x32_bf16 v[50:53], v[208:211], v[216:219], v[50:53]
	v_mfma_f32_16x16x32_bf16 v[38:41], v[200:203], v[224:227], v[38:41]
	v_mfma_f32_16x16x32_bf16 v[34:37], v[208:211], v[224:227], v[34:37]
	v_mfma_f32_16x16x32_bf16 v[20:23], v[200:203], v[232:235], v[20:23]
	v_mfma_f32_16x16x32_bf16 v[16:19], v[208:211], v[232:235], v[16:19]
	v_mfma_f32_16x16x32_bf16 v[4:7], v[200:203], v[240:243], v[4:7]
	v_mfma_f32_16x16x32_bf16 v[0:3], v[208:211], v[240:243], v[0:3]
	v_mfma_f32_16x16x32_bf16 v[54:57], v[204:207], v[220:223], v[54:57]
	v_mfma_f32_16x16x32_bf16 v[50:53], v[212:215], v[220:223], v[50:53]
	v_mfma_f32_16x16x32_bf16 v[38:41], v[204:207], v[228:231], v[38:41]
	v_mfma_f32_16x16x32_bf16 v[34:37], v[212:215], v[228:231], v[34:37]
	v_mfma_f32_16x16x32_bf16 v[20:23], v[204:207], v[236:239], v[20:23]
	v_mfma_f32_16x16x32_bf16 v[16:19], v[212:215], v[236:239], v[16:19]
	v_mfma_f32_16x16x32_bf16 v[4:7], v[204:207], v[244:247], v[4:7]
	v_mfma_f32_16x16x32_bf16 v[0:3], v[212:215], v[244:247], v[0:3]
	s_barrier
; #define PG8_STAGE(bufoff, gbase, voff) do { _Pragma("unroll") for (int _i = 0; _i < 2; ++_i) \
;         __builtin_amdgcn_global_load_lds((const unsigned*)((const char*)(gbase) + (voff)[_i]), (PG8_LAS unsigned*)(lds + (bufoff) + ldsw + _i * 8192), 16, 0, 0); } while (0)
; #define PG8_LDA(dst, b, h) do { _Pragma("unroll") for (int m = 0; m < 4; ++m) _Pragma("unroll") for (int k = 0; k < 2; ++k) dst[m][k] = *(const PG8_LAS bf16x8*)(lds + PG8_SA(b, h) + aoff + m * 2048 + k * 1024); } while (0)
; #define PG8_LDB(dst, b, h) do { _Pragma("unroll") for (int n = 0; n < 2; ++n) _Pragma("unroll") for (int k = 0; k < 2; ++k) dst[n][k] = *(const PG8_LAS bf16x8*)(lds + PG8_SB(b, h) + boff + n * 2048 + k * 1024); } while (0)
; #define PG8_MMA(ai, bj, At, Bt) do { __builtin_amdgcn_s_setprio(1); _Pragma("unroll") for (int m = 0; m < 4; ++m) _Pragma("unroll") for (int n = 0; n < 2; ++n) _Pragma("unroll") for (int k = 0; k < 2; ++k) \
;         acc[ai][bj][m][n] = __builtin_amdgcn_mfma_f32_16x16x32_bf16(Bt[n][k], At[m][k], acc[ai][bj][m][n], 0, 0, 0); __builtin_amdgcn_s_setprio(0); } while (0)
; #define PG8_WAIT_V(n) asm volatile("s_waitcnt vmcnt(" #n ")" ::: "memory")
; #define PG8_WAIT_L(n) asm volatile("s_waitcnt lgkmcnt(" #n ")" ::: "memory")
; #define PG8_BAR __builtin_amdgcn_s_barrier()
; #define PG8_SCHED __builtin_amdgcn_sched_barrier(0)
; template <class Epi, class Sched, bool ALIGN_EPI = false, bool SP2 = false>
; __device__ __forceinline__ void gemm_phase(PG8_LAS unsigned char* lds, const Gemm g, const Sched& S, const Epi& E) {
;     ...
;             PG8_LDB(B0, 1, 0); PG8_LDB(B1, 1, 1); PG8_SCHED; PG8_LDA(At, 1, 0); PG8_STAGE(PG8_SA(0, 1), a2 + hstep, voffA);
;             PG8_WAIT_V(8); PG8_WAIT_L(0); PG8_BAR; PG8_MMA(0, 0, At, B0); PG8_MMA(0, 1, At, B1); PG8_BAR; PG8_SCHED;
;             PG8_LDA(At, 1, 1); PG8_STAGE(PG8_SB(1, 0), b3, voffB); PG8_STAGE(PG8_SB(1, 1), b3 + hstep, voffB); PG8_STAGE(PG8_SA(1, 0), a3, voffA);
;             PG8_WAIT_V(8); PG8_WAIT_L(0); PG8_BAR; PG8_MMA(1, 0, At, B0); PG8_MMA(1, 1, At, B1); PG8_BAR; PG8_SCHED;
	s_add_i32 s61, 0, 0x18000
	v_add_u32_e32 v153, s61, v145
	s_add_i32 s72, 0, 0x1c000
	ds_read_b128 v[174:177], v153
	ds_read_b128 v[178:181], v153 offset:1024
	ds_read_b128 v[182:185], v153 offset:2048
	ds_read_b128 v[196:199], v153 offset:3072
	v_add_u32_e32 v153, s72, v145
	ds_read_b128 v[200:203], v153
	ds_read_b128 v[204:207], v153 offset:1024
	ds_read_b128 v[208:211], v153 offset:2048
	ds_read_b128 v[212:215], v153 offset:3072
	s_add_u32 s50, s50, 0x40000
	s_addc_u32 s51, s51, 0
	s_mov_b32 m0, s3
	v_lshl_add_u64 v[250:251], s[50:51], 0, v[130:131]
	ds_read_b128 v[216:219], v149 offset:32768
	ds_read_b128 v[220:223], v149 offset:33792
	ds_read_b128 v[224:227], v149 offset:34816
	ds_read_b128 v[228:231], v149 offset:35840
	ds_read_b128 v[232:235], v149 offset:36864
	ds_read_b128 v[236:239], v149 offset:37888
	ds_read_b128 v[240:243], v149 offset:38912
	ds_read_b128 v[244:247], v149 offset:39936
	global_load_lds_dwordx4 v[250:251], off
	v_lshl_add_u64 v[250:251], s[50:51], 0, v[134:135]
	s_mov_b32 m0, s87
	s_nop 0
	global_load_lds_dwordx4 v[250:251], off
	s_waitcnt vmcnt(8)
	s_waitcnt lgkmcnt(0)
	s_barrier
	v_mfma_f32_16x16x32_bf16 v[126:129], v[174:177], v[216:219], v[126:129]
	v_mfma_f32_16x16x32_bf16 v[122:125], v[182:185], v[216:219], v[122:125]
	v_mfma_f32_16x16x32_bf16 v[110:113], v[174:177], v[224:227], v[110:113]
	v_mfma_f32_16x16x32_bf16 v[106:109], v[182:185], v[224:227], v[106:109]
	v_mfma_f32_16x16x32_bf16 v[94:97], v[174:177], v[232:235], v[94:97]
	v_mfma_f32_16x16x32_bf16 v[90:93], v[182:185], v[232:235], v[90:93]
	v_mfma_f32_16x16x32_bf16 v[78:81], v[174:177], v[240:243], v[78:81]
	v_mfma_f32_16x16x32_bf16 v[74:77], v[182:185], v[240:243], v[74:77]
	v_mfma_f32_16x16x32_bf16 v[126:129], v[178:181], v[220:223], v[126:129]
	v_mfma_f32_16x16x32_bf16 v[122:125], v[196:199], v[220:223], v[122:125]
	v_mfma_f32_16x16x32_bf16 v[110:113], v[178:181], v[228:231], v[110:113]
	v_mfma_f32_16x16x32_bf16 v[106:109], v[196:199], v[228:231], v[106:109]
	v_mfma_f32_16x16x32_bf16 v[94:97], v[178:181], v[236:239], v[94:97]
	v_mfma_f32_16x16x32_bf16 v[90:93], v[196:199], v[236:239], v[90:93]
	v_mfma_f32_16x16x32_bf16 v[78:81], v[178:181], v[244:247], v[78:81]
	v_mfma_f32_16x16x32_bf16 v[74:77], v[196:199], v[244:247], v[74:77]
	v_mfma_f32_16x16x32_bf16 v[118:121], v[200:203], v[216:219], v[118:121]
	v_mfma_f32_16x16x32_bf16 v[114:117], v[208:211], v[216:219], v[114:117]
	v_mfma_f32_16x16x32_bf16 v[102:105], v[200:203], v[224:227], v[102:105]
	v_mfma_f32_16x16x32_bf16 v[98:101], v[208:211], v[224:227], v[98:101]
	v_mfma_f32_16x16x32_bf16 v[86:89], v[200:203], v[232:235], v[86:89]
	v_mfma_f32_16x16x32_bf16 v[82:85], v[208:211], v[232:235], v[82:85]
	v_mfma_f32_16x16x32_bf16 v[70:73], v[200:203], v[240:243], v[70:73]
	v_mfma_f32_16x16x32_bf16 v[66:69], v[208:211], v[240:243], v[66:69]
	v_mfma_f32_16x16x32_bf16 v[118:121], v[204:207], v[220:223], v[118:121]
	v_mfma_f32_16x16x32_bf16 v[114:117], v[212:215], v[220:223], v[114:117]
	v_mfma_f32_16x16x32_bf16 v[102:105], v[204:207], v[228:231], v[102:105]
	v_mfma_f32_16x16x32_bf16 v[98:101], v[212:215], v[228:231], v[98:101]
	v_mfma_f32_16x16x32_bf16 v[86:89], v[204:207], v[236:239], v[86:89]
	v_mfma_f32_16x16x32_bf16 v[82:85], v[212:215], v[236:239], v[82:85]
	v_mfma_f32_16x16x32_bf16 v[70:73], v[204:207], v[244:247], v[70:73]
	v_mfma_f32_16x16x32_bf16 v[66:69], v[212:215], v[244:247], v[66:69]
	s_barrier
	s_add_i32 s50, s61, s38
	v_lshl_add_u64 v[150:151], v[150:151], 0, s[34:35]
	s_mov_b32 m0, s50
	ds_read_b128 v[216:219], v149 offset:49152
	ds_read_b128 v[220:223], v149 offset:50176
	ds_read_b128 v[224:227], v149 offset:51200
	ds_read_b128 v[228:231], v149 offset:52224
	ds_read_b128 v[232:235], v149 offset:53248
	ds_read_b128 v[236:239], v149 offset:54272
	ds_read_b128 v[240:243], v149 offset:55296
	ds_read_b128 v[244:247], v149 offset:56320
	global_load_lds_dwordx4 v[150:151], off
	s_add_i32 m0, s50, 0x2000
	s_add_u32 s48, s48, 0x40080
	v_lshl_add_u64 v[150:151], v[160:161], 0, s[34:35]
	s_addc_u32 s49, s49, 0
	s_add_i32 s50, s72, s38
	global_load_lds_dwordx4 v[150:151], off
	v_lshl_add_u64 v[150:151], s[48:49], 0, v[132:133]
	s_mov_b32 m0, s50
	s_nop 0
	global_load_lds_dwordx4 v[150:151], off
	v_lshl_add_u64 v[150:151], s[48:49], 0, v[136:137]
	s_add_i32 m0, s50, 0x2000
	s_nop 0
	global_load_lds_dwordx4 v[150:151], off
	v_lshl_add_u64 v[150:151], v[170:171], 0, s[34:35]
	s_mov_b32 m0, s0
	s_nop 0
	global_load_lds_dwordx4 v[150:151], off
	v_lshl_add_u64 v[150:151], v[248:249], 0, s[34:35]
	s_mov_b32 m0, s86
	s_nop 0
	global_load_lds_dwordx4 v[150:151], off
	s_waitcnt vmcnt(8)
	s_waitcnt lgkmcnt(0)
	s_barrier
; #define PG8_BAR __builtin_amdgcn_s_barrier()
; template <class Epi, class Sched, bool ALIGN_EPI = false, bool SP2 = false>
; __device__ __forceinline__ void gemm_phase(PG8_LAS unsigned char* lds, const Gemm g, const Sched& S, const Epi& E) {
;     ...
;             PG8_WAIT_V(8); PG8_WAIT_L(0); PG8_BAR; PG8_MMA(1, 0, At, B0); PG8_MMA(1, 1, At, B1); PG8_BAR; PG8_SCHED;
;             } else {
;             PG8_LDB(B0, 0, 0); PG8_SCHED; PG8_LDA(At, 0, 0); PG8_STAGE(PG8_SA(1, 1), a1 + hstep, voffA);
;             PG8_WAIT_L(8); PG8_BAR; PG8_WAIT_L(0); PG8_MMA(0, 0, At, B0); PG8_BAR; PG8_SCHED;
;             PG8_LDB(B1, 0, 1); PG8_STAGE(PG8_SB(0, 0), b2, voffB);
;             PG8_BAR; PG8_WAIT_L(0); PG8_MMA(0, 1, At, B1); PG8_BAR;
;             PG8_LDA(At, 0, 1); PG8_STAGE(PG8_SA(0, 0), a2, voffA);
;             PG8_BAR; PG8_WAIT_L(0); PG8_MMA(1, 0, At, B0); PG8_BAR; PG8_SCHED;
;             PG8_STAGE(PG8_SB(0, 1), b2 + hstep, voffB);
;             PG8_WAIT_V(6); PG8_BAR; PG8_MMA(1, 1, At, B1); PG8_BAR;
;             PG8_LDB(B0, 1, 0); PG8_SCHED; PG8_LDA(At, 1, 0); PG8_STAGE(PG8_SA(0, 1), a2 + hstep, voffA);
;             PG8_WAIT_L(8); PG8_BAR; PG8_WAIT_L(0); PG8_MMA(0, 0, At, B0); PG8_BAR; PG8_SCHED;
;             PG8_LDB(B1, 1, 1); PG8_STAGE(PG8_SB(1, 0), b3, voffB);
;             PG8_BAR; PG8_WAIT_L(0); PG8_MMA(0, 1, At, B1); PG8_BAR;
;             PG8_LDA(At, 1, 1); PG8_STAGE(PG8_SA(1, 0), a3, voffA);
;             PG8_BAR; PG8_WAIT_L(0); PG8_MMA(1, 0, At, B0); PG8_BAR; PG8_SCHED;
;             PG8_STAGE(PG8_SB(1, 1), b3 + hstep, voffB);
;             PG8_WAIT_V(6); PG8_BAR; PG8_MMA(1, 1, At, B1); PG8_BAR;
;             }
;         }
;         if constexpr (ALIGN_EPI) { if (wr == 0) PG8_BAR; }
;         if constexpr (!Epi::AFTER_DRAIN) { if constexpr (Epi::PREFETCH) E(acc, cur, wr, wc, fr, fq, epre); else E(acc, cur, wr, wc, fr, fq); S.done(cur); }
;     __device__ __forceinline__ void operator()(const f32x4 (&acc)[2][2][4][2], const Unit& u, int wr, int wc, int fr, int fq, const float (&pre)[8]) const {
;     ...
;         for (int ai = 0; ai < 2; ++ai)
; #pragma unroll
;             for (int m = 0; m < 4; ++m) {
;                 const int row = row0 + ai * 128 + m * 16; bf16_t* rowp = O + (size_t)row * ldc + col0; float rs = 0.f;
;                 float rsc = 1.f; if (RS == 1) rsc = pre[ai * 4 + m];
; #pragma unroll
;                 for (int bj = 0; bj < 2; ++bj) {
	v_mfma_f32_16x16x32_bf16 v[62:65], v[174:177], v[216:219], v[62:65]
	v_mfma_f32_16x16x32_bf16 v[58:61], v[182:185], v[216:219], v[58:61]
	v_mfma_f32_16x16x32_bf16 v[46:49], v[174:177], v[224:227], v[46:49]
	v_mfma_f32_16x16x32_bf16 v[42:45], v[182:185], v[224:227], v[42:45]
	v_mfma_f32_16x16x32_bf16 v[28:31], v[174:177], v[232:235], v[28:31]
	v_mfma_f32_16x16x32_bf16 v[24:27], v[182:185], v[232:235], v[24:27]
	v_mfma_f32_16x16x32_bf16 v[12:15], v[174:177], v[240:243], v[12:15]
	v_mfma_f32_16x16x32_bf16 v[8:11], v[182:185], v[240:243], v[8:11]
	v_mfma_f32_16x16x32_bf16 v[62:65], v[178:181], v[220:223], v[62:65]
	v_mfma_f32_16x16x32_bf16 v[58:61], v[196:199], v[220:223], v[58:61]
	v_mfma_f32_16x16x32_bf16 v[46:49], v[178:181], v[228:231], v[46:49]
	v_mfma_f32_16x16x32_bf16 v[42:45], v[196:199], v[228:231], v[42:45]
	v_mfma_f32_16x16x32_bf16 v[28:31], v[178:181], v[236:239], v[28:31]
	v_mfma_f32_16x16x32_bf16 v[24:27], v[196:199], v[236:239], v[24:27]
	v_mfma_f32_16x16x32_bf16 v[12:15], v[178:181], v[244:247], v[12:15]
	v_mfma_f32_16x16x32_bf16 v[8:11], v[196:199], v[244:247], v[8:11]
	v_mfma_f32_16x16x32_bf16 v[54:57], v[200:203], v[216:219], v[54:57]
	v_mfma_f32_16x16x32_bf16 v[50:53], v[208:211], v[216:219], v[50:53]
	v_mfma_f32_16x16x32_bf16 v[38:41], v[200:203], v[224:227], v[38:41]
	v_mfma_f32_16x16x32_bf16 v[34:37], v[208:211], v[224:227], v[34:37]
	v_mfma_f32_16x16x32_bf16 v[20:23], v[200:203], v[232:235], v[20:23]
	v_mfma_f32_16x16x32_bf16 v[16:19], v[208:211], v[232:235], v[16:19]
	v_mfma_f32_16x16x32_bf16 v[4:7], v[200:203], v[240:243], v[4:7]
	v_mfma_f32_16x16x32_bf16 v[0:3], v[208:211], v[240:243], v[0:3]
	v_mfma_f32_16x16x32_bf16 v[54:57], v[204:207], v[220:223], v[54:57]
	v_mfma_f32_16x16x32_bf16 v[50:53], v[212:215], v[220:223], v[50:53]
	v_mfma_f32_16x16x32_bf16 v[38:41], v[204:207], v[228:231], v[38:41]
	v_mfma_f32_16x16x32_bf16 v[34:37], v[212:215], v[228:231], v[34:37]
	v_mfma_f32_16x16x32_bf16 v[20:23], v[204:207], v[236:239], v[20:23]
	v_mfma_f32_16x16x32_bf16 v[16:19], v[212:215], v[236:239], v[16:19]
	v_mfma_f32_16x16x32_bf16 v[4:7], v[204:207], v[244:247], v[4:7]
	v_mfma_f32_16x16x32_bf16 v[0:3], v[212:215], v[244:247], v[0:3]
	s_barrier
	s_add_i32 vcc_lo, vcc_lo, 2
	s_add_u32 s89, s89, 0x100
	s_addc_u32 s91, s91, 0
	s_add_u32 s46, s46, 0x100
	s_addc_u32 s47, s47, 0
	s_cmp_gt_u32 vcc_lo, 13
	s_cbranch_scc0 .LBB0_118
	v_readlane_b32 s46, v254, 51
	v_readlane_b32 s47, v254, 52
	s_and_b64 vcc, exec, s[46:47]
	s_cbranch_vccz .LBB0_121
	s_barrier
.LBB0_121:
	v_lshl_add_u32 v160, s44, 8, v33
	v_lshl_or_b32 v150, s4, 8, v147
	v_ashrrev_i32_e32 v161, 31, v160
	v_ashrrev_i32_e32 v151, 31, v150
	v_lshlrev_b64 v[170:171], 11, v[160:161]
	v_lshl_add_u64 v[174:175], s[40:41], 0, v[170:171]
	v_lshlrev_b64 v[170:171], 1, v[150:151]
	v_pk_mul_f32 v[126:127], v[172:173], v[126:127] op_sel_hi:[0,1]
	v_lshl_add_u64 v[150:151], v[174:175], 0, v[170:171]
	v_pk_mul_f32 v[174:175], v[172:173], v[122:123] op_sel_hi:[0,1]
	v_and_b32_e32 v123, 0x7fffffff, v127
	v_and_b32_e32 v122, 0x7fffffff, v126
	v_pk_fma_f32 v[122:123], v[122:123], s[28:29], 1.0 op_sel_hi:[1,0,0]
	s_mov_b32 s4, 0xbf3a00e3
	v_rcp_f32_e32 v176, v122
	v_rcp_f32_e32 v177, v123
	v_mov_b64_e32 v[122:123], s[4:5]
	v_pk_mul_f32 v[180:181], v[126:127], v[126:127]
	v_pk_mul_f32 v[128:129], v[172:173], v[128:129] op_sel_hi:[0,1]
	v_pk_fma_f32 v[178:179], v[176:177], s[30:31], v[122:123] op_sel_hi:[1,0,0]
	v_pk_mul_f32 v[180:181], v[180:181], s[58:59] op_sel_hi:[1,0]
	v_pk_fma_f32 v[178:179], v[176:177], v[178:179], s[52:53] op_sel_hi:[1,1,0]
	v_exp_f32_e32 v180, v180
	v_exp_f32_e32 v181, v181
	v_pk_fma_f32 v[178:179], v[176:177], v[178:179], s[54:55] op_sel_hi:[1,1,0]
	v_cmp_gt_f32_e32 vcc, 0, v126
	v_pk_fma_f32 v[178:179], v[176:177], v[178:179], s[56:57] op_sel_hi:[1,1,0]
	v_pk_mul_f32 v[124:125], v[172:173], v[124:125] op_sel_hi:[0,1]
	v_pk_mul_f32 v[176:177], v[176:177], v[178:179]
	v_pk_mul_f32 v[178:179], v[128:129], v[128:129]
	v_pk_mul_f32 v[176:177], v[180:181], v[176:177]
	s_mov_b64 s[4:5], 0x40000
	v_pk_mul_f32 v[180:181], v[126:127], v[176:177]
	v_pk_fma_f32 v[176:177], v[126:127], v[176:177], v[126:127] neg_lo:[1,0,0] neg_hi:[1,0,0]
	v_and_b32_e32 v126, 0x7fffffff, v128
	v_cndmask_b32_e32 v153, v176, v180, vcc
	v_cmp_gt_f32_e32 vcc, 0, v127
	v_and_b32_e32 v127, 0x7fffffff, v129
	v_pk_fma_f32 v[126:127], v[126:127], s[28:29], 1.0 op_sel_hi:[1,0,0]
	v_cndmask_b32_e32 v155, v177, v181, vcc
	v_rcp_f32_e32 v126, v126
	v_rcp_f32_e32 v127, v127
	v_cmp_gt_f32_e32 vcc, 0, v128
	v_pk_mul_f32 v[78:79], v[154:155], v[78:79] op_sel_hi:[0,1]
	v_pk_mul_f32 v[80:81], v[154:155], v[80:81] op_sel_hi:[0,1]
	v_pk_fma_f32 v[176:177], v[126:127], s[30:31], v[122:123] op_sel_hi:[1,0,0]
	v_pk_mul_f32 v[74:75], v[154:155], v[74:75] op_sel_hi:[0,1]
	v_pk_fma_f32 v[176:177], v[126:127], v[176:177], s[52:53] op_sel_hi:[1,1,0]
	v_pk_mul_f32 v[76:77], v[154:155], v[76:77] op_sel_hi:[0,1]
	v_pk_fma_f32 v[176:177], v[126:127], v[176:177], s[54:55] op_sel_hi:[1,1,0]
	v_pk_mul_f32 v[70:71], v[154:155], v[70:71] op_sel_hi:[0,1]
	v_pk_fma_f32 v[176:177], v[126:127], v[176:177], s[56:57] op_sel_hi:[1,1,0]
	v_pk_mul_f32 v[72:73], v[154:155], v[72:73] op_sel_hi:[0,1]
	v_pk_mul_f32 v[126:127], v[126:127], v[176:177]
	v_pk_mul_f32 v[176:177], v[178:179], s[58:59] op_sel_hi:[1,0]
	v_pk_mul_f32 v[66:67], v[154:155], v[66:67] op_sel_hi:[0,1]
	v_exp_f32_e32 v176, v176
	v_exp_f32_e32 v177, v177
	v_pk_mul_f32 v[68:69], v[154:155], v[68:69] op_sel_hi:[0,1]
	v_pk_mul_f32 v[62:63], v[152:153], v[62:63] op_sel_hi:[0,1]
	v_pk_mul_f32 v[64:65], v[152:153], v[64:65] op_sel_hi:[0,1]
	v_pk_mul_f32 v[126:127], v[176:177], v[126:127]
; __device__ __forceinline__ unsigned cvt_pk_bf16(float lo, float hi) { unsigned r; asm volatile("v_cvt_pk_bf16_f32 %0, %1, %2" : "=v"(r) : "v"(lo), "v"(hi)); return r; }
; #define GAS __attribute__((address_space(1)))
; __device__ __forceinline__ f32x2 gelu_pk(f32x2 v) {
;     const f32x2 av = __builtin_elementwise_abs(v), d = av * 0.2316418882f + 1.0f;
;     f32x2 t; t.x = __builtin_amdgcn_rcpf(d.x); t.y = __builtin_amdgcn_rcpf(d.y);
;     f32x2 q = t * 0.5307027145f + (-0.7265760135f); q = q * t + 0.7107068705f; q = q * t + (-0.142248368f); q = q * t + 0.127414796f; q = q * t;
;     const f32x2 s = (v * v) * (-0.72134752044f);
;     f32x2 e; e.x = __builtin_amdgcn_exp2f(s.x); e.y = __builtin_amdgcn_exp2f(s.y);
;     const f32x2 m = v * (q * e), r = v - m;
;     f32x2 o; o.x = v.x < 0.f ? m.x : r.x; o.y = v.y < 0.f ? m.y : r.y; return o;
; }
;     __device__ __forceinline__ void operator()(const f32x4 (&acc)[2][2][4][2], const Unit& u, int wr, int wc, int fr, int fq, const float (&pre)[8]) const {
;     ...
;                     f32x4 v0 = acc[ai][bj][m][0], v1 = acc[ai][bj][m][1];
;                     if (RS == 1) { v0 = v0 * rsc; v1 = v1 * rsc; }
;                     if (RS == 2) { v0 = v0 * csc[bj][0]; v1 = v1 * csc[bj][1]; }
;                     if (ACT == 1) { const f32x2 a = gelu_pk((f32x2){v0[0], v0[1]}), b = gelu_pk((f32x2){v0[2], v0[3]}), c = gelu_pk((f32x2){v1[0], v1[1]}), d = gelu_pk((f32x2){v1[2], v1[3]});
;                         v0 = (f32x4){a.x, a.y, b.x, b.y}; v1 = (f32x4){c.x, c.y, d.x, d.y}; }
;                     v0 = v0 * sc; v1 = v1 * sc;
;                     if (STAT == 1) rs += (v0[0] * v0[0] + v0[1] * v0[1]) + (v0[2] * v0[2] + v0[3] * v0[3]) + (v1[0] * v1[0] + v1[1] * v1[1]) + (v1[2] * v1[2] + v1[3] * v1[3]);
;                     if (STAT == 2) {
; #pragma unroll
;                         for (int e = 0; e < 4; ++e) { cs[bj][0][e] += v0[e]; cq[bj][0][e] += v0[e] * v0[e]; cs[bj][1][e] += v1[e]; cq[bj][1][e] += v1[e] * v1[e]; } }
;                     u32x4 w; w.x = cvt_pk_bf16(v0[0], v0[1]); w.y = cvt_pk_bf16(v0[2], v0[3]); w.z = cvt_pk_bf16(v1[0], v1[1]); w.w = cvt_pk_bf16(v1[2], v1[3]);
;                     *(GAS u32x4*)(rowp + bj * 128) = w; }
	v_pk_mul_f32 v[58:59], v[152:153], v[58:59] op_sel_hi:[0,1]
	v_pk_mul_f32 v[176:177], v[128:129], v[126:127]
	v_pk_fma_f32 v[126:127], v[128:129], v[126:127], v[128:129] neg_lo:[1,0,0] neg_hi:[1,0,0]
	v_pk_mul_f32 v[60:61], v[152:153], v[60:61] op_sel_hi:[0,1]
	v_cndmask_b32_e32 v157, v126, v176, vcc
	v_cmp_gt_f32_e32 vcc, 0, v129
	v_and_b32_e32 v126, 0x7fffffff, v174
	v_pk_mul_f32 v[94:95], v[156:157], v[94:95] op_sel_hi:[0,1]
	v_cndmask_b32_e32 v159, v127, v177, vcc
	v_and_b32_e32 v127, 0x7fffffff, v175
	v_pk_fma_f32 v[126:127], v[126:127], s[28:29], 1.0 op_sel_hi:[1,0,0]
	v_pk_mul_f32 v[176:177], v[174:175], v[174:175]
	v_rcp_f32_e32 v126, v126
	v_rcp_f32_e32 v127, v127
	v_pk_mul_f32 v[176:177], v[176:177], s[58:59] op_sel_hi:[1,0]
	v_cmp_gt_f32_e32 vcc, 0, v174
	v_exp_f32_e32 v176, v176
	v_pk_fma_f32 v[128:129], v[126:127], s[30:31], v[122:123] op_sel_hi:[1,0,0]
	v_exp_f32_e32 v177, v177
	v_pk_fma_f32 v[128:129], v[126:127], v[128:129], s[52:53] op_sel_hi:[1,1,0]
	v_pk_mul_f32 v[110:111], v[158:159], v[110:111] op_sel_hi:[0,1]
	v_pk_fma_f32 v[128:129], v[126:127], v[128:129], s[54:55] op_sel_hi:[1,1,0]
	v_pk_mul_f32 v[112:113], v[158:159], v[112:113] op_sel_hi:[0,1]
	v_pk_fma_f32 v[128:129], v[126:127], v[128:129], s[56:57] op_sel_hi:[1,1,0]
	v_pk_mul_f32 v[106:107], v[158:159], v[106:107] op_sel_hi:[0,1]
	v_pk_mul_f32 v[126:127], v[126:127], v[128:129]
	v_pk_mul_f32 v[128:129], v[124:125], v[124:125]
	v_pk_mul_f32 v[126:127], v[176:177], v[126:127]
	v_pk_mul_f32 v[128:129], v[128:129], s[58:59] op_sel_hi:[1,0]
	v_pk_mul_f32 v[176:177], v[174:175], v[126:127]
	v_pk_fma_f32 v[126:127], v[174:175], v[126:127], v[174:175] neg_lo:[1,0,0] neg_hi:[1,0,0]
	v_exp_f32_e32 v128, v128
	v_cndmask_b32_e32 v161, v126, v176, vcc
	v_cmp_gt_f32_e32 vcc, 0, v175
	v_and_b32_e32 v126, 0x7fffffff, v124
	v_exp_f32_e32 v129, v129
	v_cndmask_b32_e32 v173, v127, v177, vcc
	v_and_b32_e32 v127, 0x7fffffff, v125
	v_pk_fma_f32 v[126:127], v[126:127], s[28:29], 1.0 op_sel_hi:[1,0,0]
	v_cmp_gt_f32_e32 vcc, 0, v124
	v_rcp_f32_e32 v126, v126
	v_rcp_f32_e32 v127, v127
	v_pk_mul_f32 v[118:119], v[172:173], v[118:119] op_sel_hi:[0,1]
	v_pk_mul_f32 v[120:121], v[172:173], v[120:121] op_sel_hi:[0,1]
	v_pk_mul_f32 v[114:115], v[172:173], v[114:115] op_sel_hi:[0,1]
	v_pk_fma_f32 v[174:175], v[126:127], s[30:31], v[122:123] op_sel_hi:[1,0,0]
	v_pk_mul_f32 v[116:117], v[172:173], v[116:117] op_sel_hi:[0,1]
	v_pk_fma_f32 v[174:175], v[126:127], v[174:175], s[52:53] op_sel_hi:[1,1,0]
	v_pk_mul_f32 v[108:109], v[158:159], v[108:109] op_sel_hi:[0,1]
	v_pk_fma_f32 v[174:175], v[126:127], v[174:175], s[54:55] op_sel_hi:[1,1,0]
	v_pk_mul_f32 v[102:103], v[158:159], v[102:103] op_sel_hi:[0,1]
	v_pk_fma_f32 v[174:175], v[126:127], v[174:175], s[56:57] op_sel_hi:[1,1,0]
	v_pk_mul_f32 v[104:105], v[158:159], v[104:105] op_sel_hi:[0,1]
	v_pk_mul_f32 v[126:127], v[126:127], v[174:175]
	v_pk_mul_f32 v[98:99], v[158:159], v[98:99] op_sel_hi:[0,1]
	v_pk_mul_f32 v[126:127], v[128:129], v[126:127]
	v_pk_mul_f32 v[100:101], v[158:159], v[100:101] op_sel_hi:[0,1]
	v_pk_mul_f32 v[128:129], v[124:125], v[126:127]
	v_pk_fma_f32 v[126:127], v[124:125], v[126:127], v[124:125] neg_lo:[1,0,0] neg_hi:[1,0,0]
	v_cvt_pk_bf16_f32 v124, v153, v155
	v_pk_mul_f32 v[96:97], v[156:157], v[96:97] op_sel_hi:[0,1]
	v_cndmask_b32_e32 v128, v126, v128, vcc
	v_cmp_gt_f32_e32 vcc, 0, v125
	v_cvt_pk_bf16_f32 v125, v157, v159
	v_cvt_pk_bf16_f32 v126, v161, v173
	v_pk_mul_f32 v[90:91], v[156:157], v[90:91] op_sel_hi:[0,1]
	v_pk_mul_f32 v[92:93], v[156:157], v[92:93] op_sel_hi:[0,1]
	v_cndmask_b32_e32 v127, v127, v129, vcc
	v_cvt_pk_bf16_f32 v127, v128, v127
	global_store_dwordx4 v[150:151], v[124:127], off
	v_pk_mul_f32 v[128:129], v[118:119], v[118:119]
	v_cmp_gt_f32_e32 vcc, 0, v118
	v_and_b32_e32 v125, 0x7fffffff, v119
	v_and_b32_e32 v124, 0x7fffffff, v118
	v_pk_fma_f32 v[124:125], v[124:125], s[28:29], 1.0 op_sel_hi:[1,0,0]
	v_pk_mul_f32 v[128:129], v[128:129], s[58:59] op_sel_hi:[1,0]
	v_rcp_f32_e32 v124, v124
	v_rcp_f32_e32 v125, v125
	v_exp_f32_e32 v128, v128
	v_exp_f32_e32 v129, v129
	v_pk_mul_f32 v[86:87], v[156:157], v[86:87] op_sel_hi:[0,1]
	v_pk_fma_f32 v[126:127], v[124:125], s[30:31], v[122:123] op_sel_hi:[1,0,0]
	v_pk_mul_f32 v[88:89], v[156:157], v[88:89] op_sel_hi:[0,1]
	v_pk_fma_f32 v[126:127], v[124:125], v[126:127], s[52:53] op_sel_hi:[1,1,0]
	v_pk_mul_f32 v[82:83], v[156:157], v[82:83] op_sel_hi:[0,1]
	v_pk_fma_f32 v[126:127], v[124:125], v[126:127], s[54:55] op_sel_hi:[1,1,0]
	v_pk_mul_f32 v[84:85], v[156:157], v[84:85] op_sel_hi:[0,1]
	v_pk_fma_f32 v[126:127], v[124:125], v[126:127], s[56:57] op_sel_hi:[1,1,0]
	v_pk_mul_f32 v[54:55], v[152:153], v[54:55] op_sel_hi:[0,1]
	v_pk_mul_f32 v[124:125], v[124:125], v[126:127]
	v_pk_mul_f32 v[126:127], v[120:121], v[120:121]
	v_pk_mul_f32 v[124:125], v[128:129], v[124:125]
	v_pk_mul_f32 v[56:57], v[152:153], v[56:57] op_sel_hi:[0,1]
	v_pk_mul_f32 v[128:129], v[118:119], v[124:125]
	v_pk_fma_f32 v[124:125], v[118:119], v[124:125], v[118:119] neg_lo:[1,0,0] neg_hi:[1,0,0]
	v_and_b32_e32 v118, 0x7fffffff, v120
	v_cndmask_b32_e32 v128, v124, v128, vcc
	v_cmp_gt_f32_e32 vcc, 0, v119
	v_and_b32_e32 v119, 0x7fffffff, v121
	v_pk_fma_f32 v[118:119], v[118:119], s[28:29], 1.0 op_sel_hi:[1,0,0]
	v_cndmask_b32_e32 v129, v125, v129, vcc
	v_rcp_f32_e32 v118, v118
	v_rcp_f32_e32 v119, v119
	v_cmp_gt_f32_e32 vcc, 0, v120
	v_pk_mul_f32 v[50:51], v[152:153], v[50:51] op_sel_hi:[0,1]
	v_pk_mul_f32 v[52:53], v[152:153], v[52:53] op_sel_hi:[0,1]
	v_pk_fma_f32 v[124:125], v[118:119], s[30:31], v[122:123] op_sel_hi:[1,0,0]
	v_pk_mul_f32 v[46:47], v[148:149], v[46:47] op_sel_hi:[0,1]
; __device__ __forceinline__ unsigned cvt_pk_bf16(float lo, float hi) { unsigned r; asm volatile("v_cvt_pk_bf16_f32 %0, %1, %2" : "=v"(r) : "v"(lo), "v"(hi)); return r; }
; #define GAS __attribute__((address_space(1)))
; __device__ __forceinline__ f32x2 gelu_pk(f32x2 v) {
;     const f32x2 av = __builtin_elementwise_abs(v), d = av * 0.2316418882f + 1.0f;
;     f32x2 t; t.x = __builtin_amdgcn_rcpf(d.x); t.y = __builtin_amdgcn_rcpf(d.y);
;     f32x2 q = t * 0.5307027145f + (-0.7265760135f); q = q * t + 0.7107068705f; q = q * t + (-0.142248368f); q = q * t + 0.127414796f; q = q * t;
;     const f32x2 s = (v * v) * (-0.72134752044f);
;     f32x2 e; e.x = __builtin_amdgcn_exp2f(s.x); e.y = __builtin_amdgcn_exp2f(s.y);
;     const f32x2 m = v * (q * e), r = v - m;
;     f32x2 o; o.x = v.x < 0.f ? m.x : r.x; o.y = v.y < 0.f ? m.y : r.y; return o;
; }
;     __device__ __forceinline__ void operator()(const f32x4 (&acc)[2][2][4][2], const Unit& u, int wr, int wc, int fr, int fq, const float (&pre)[8]) const {
;     ...
;                     f32x4 v0 = acc[ai][bj][m][0], v1 = acc[ai][bj][m][1];
;                     if (RS == 1) { v0 = v0 * rsc; v1 = v1 * rsc; }
;                     if (RS == 2) { v0 = v0 * csc[bj][0]; v1 = v1 * csc[bj][1]; }
;                     if (ACT == 1) { const f32x2 a = gelu_pk((f32x2){v0[0], v0[1]}), b = gelu_pk((f32x2){v0[2], v0[3]}), c = gelu_pk((f32x2){v1[0], v1[1]}), d = gelu_pk((f32x2){v1[2], v1[3]});
;                         v0 = (f32x4){a.x, a.y, b.x, b.y}; v1 = (f32x4){c.x, c.y, d.x, d.y}; }
;                     v0 = v0 * sc; v1 = v1 * sc;
;                     if (STAT == 1) rs += (v0[0] * v0[0] + v0[1] * v0[1]) + (v0[2] * v0[2] + v0[3] * v0[3]) + (v1[0] * v1[0] + v1[1] * v1[1]) + (v1[2] * v1[2] + v1[3] * v1[3]);
;                     if (STAT == 2) {
; #pragma unroll
;                         for (int e = 0; e < 4; ++e) { cs[bj][0][e] += v0[e]; cq[bj][0][e] += v0[e] * v0[e]; cs[bj][1][e] += v1[e]; cq[bj][1][e] += v1[e] * v1[e]; } }
;                     u32x4 w; w.x = cvt_pk_bf16(v0[0], v0[1]); w.y = cvt_pk_bf16(v0[2], v0[3]); w.z = cvt_pk_bf16(v1[0], v1[1]); w.w = cvt_pk_bf16(v1[2], v1[3]);
;                     *(GAS u32x4*)(rowp + bj * 128) = w; }
	v_pk_fma_f32 v[124:125], v[118:119], v[124:125], s[52:53] op_sel_hi:[1,1,0]
	v_pk_mul_f32 v[48:49], v[148:149], v[48:49] op_sel_hi:[0,1]
	v_pk_fma_f32 v[124:125], v[118:119], v[124:125], s[54:55] op_sel_hi:[1,1,0]
	v_pk_mul_f32 v[42:43], v[148:149], v[42:43] op_sel_hi:[0,1]
	v_pk_fma_f32 v[124:125], v[118:119], v[124:125], s[56:57] op_sel_hi:[1,1,0]
	v_pk_mul_f32 v[44:45], v[148:149], v[44:45] op_sel_hi:[0,1]
	v_pk_mul_f32 v[118:119], v[118:119], v[124:125]
	v_pk_mul_f32 v[124:125], v[126:127], s[58:59] op_sel_hi:[1,0]
	v_pk_mul_f32 v[38:39], v[148:149], v[38:39] op_sel_hi:[0,1]
	v_exp_f32_e32 v124, v124
	v_exp_f32_e32 v125, v125
	v_pk_mul_f32 v[40:41], v[148:149], v[40:41] op_sel_hi:[0,1]
	v_pk_mul_f32 v[34:35], v[148:149], v[34:35] op_sel_hi:[0,1]
	v_pk_mul_f32 v[36:37], v[148:149], v[36:37] op_sel_hi:[0,1]
	v_pk_mul_f32 v[118:119], v[124:125], v[118:119]
	v_pk_mul_f32 v[28:29], v[146:147], v[28:29] op_sel_hi:[0,1]
	v_pk_mul_f32 v[124:125], v[120:121], v[118:119]
	v_pk_fma_f32 v[118:119], v[120:121], v[118:119], v[120:121] neg_lo:[1,0,0] neg_hi:[1,0,0]
	v_pk_mul_f32 v[30:31], v[146:147], v[30:31] op_sel_hi:[0,1]
	v_cndmask_b32_e32 v126, v118, v124, vcc
	v_cmp_gt_f32_e32 vcc, 0, v121
	v_and_b32_e32 v118, 0x7fffffff, v114
	v_pk_mul_f32 v[24:25], v[146:147], v[24:25] op_sel_hi:[0,1]
	v_cndmask_b32_e32 v127, v119, v125, vcc
	v_and_b32_e32 v119, 0x7fffffff, v115
	v_pk_fma_f32 v[118:119], v[118:119], s[28:29], 1.0 op_sel_hi:[1,0,0]
	v_pk_mul_f32 v[124:125], v[114:115], v[114:115]
	v_rcp_f32_e32 v118, v118
	v_rcp_f32_e32 v119, v119
	v_pk_mul_f32 v[124:125], v[124:125], s[58:59] op_sel_hi:[1,0]
	v_cmp_gt_f32_e32 vcc, 0, v114
	v_exp_f32_e32 v124, v124
	v_pk_fma_f32 v[120:121], v[118:119], s[30:31], v[122:123] op_sel_hi:[1,0,0]
	v_exp_f32_e32 v125, v125
	v_pk_fma_f32 v[120:121], v[118:119], v[120:121], s[52:53] op_sel_hi:[1,1,0]
	v_pk_mul_f32 v[26:27], v[146:147], v[26:27] op_sel_hi:[0,1]
	v_pk_fma_f32 v[120:121], v[118:119], v[120:121], s[54:55] op_sel_hi:[1,1,0]
	v_pk_mul_f32 v[20:21], v[146:147], v[20:21] op_sel_hi:[0,1]
	v_pk_fma_f32 v[120:121], v[118:119], v[120:121], s[56:57] op_sel_hi:[1,1,0]
	v_pk_mul_f32 v[22:23], v[146:147], v[22:23] op_sel_hi:[0,1]
	v_pk_mul_f32 v[118:119], v[118:119], v[120:121]
	v_pk_mul_f32 v[120:121], v[116:117], v[116:117]
	v_pk_mul_f32 v[118:119], v[124:125], v[118:119]
	v_pk_mul_f32 v[16:17], v[146:147], v[16:17] op_sel_hi:[0,1]
	v_pk_mul_f32 v[124:125], v[114:115], v[118:119]
	v_pk_fma_f32 v[118:119], v[114:115], v[118:119], v[114:115] neg_lo:[1,0,0] neg_hi:[1,0,0]
	v_and_b32_e32 v114, 0x7fffffff, v116
	v_cndmask_b32_e32 v124, v118, v124, vcc
	v_cmp_gt_f32_e32 vcc, 0, v115
	v_and_b32_e32 v115, 0x7fffffff, v117
	v_pk_fma_f32 v[114:115], v[114:115], s[28:29], 1.0 op_sel_hi:[1,0,0]
	v_cndmask_b32_e32 v125, v119, v125, vcc
	v_rcp_f32_e32 v114, v114
	v_rcp_f32_e32 v115, v115
	v_cmp_gt_f32_e32 vcc, 0, v116
	v_pk_mul_f32 v[18:19], v[146:147], v[18:19] op_sel_hi:[0,1]
	v_pk_mul_f32 v[12:13], v[144:145], v[12:13] op_sel_hi:[0,1]
	v_pk_fma_f32 v[118:119], v[114:115], s[30:31], v[122:123] op_sel_hi:[1,0,0]
	v_pk_mul_f32 v[14:15], v[144:145], v[14:15] op_sel_hi:[0,1]
	v_pk_fma_f32 v[118:119], v[114:115], v[118:119], s[52:53] op_sel_hi:[1,1,0]
	v_pk_mul_f32 v[8:9], v[144:145], v[8:9] op_sel_hi:[0,1]
	v_pk_fma_f32 v[118:119], v[114:115], v[118:119], s[54:55] op_sel_hi:[1,1,0]
	v_pk_mul_f32 v[10:11], v[144:145], v[10:11] op_sel_hi:[0,1]
	v_pk_fma_f32 v[118:119], v[114:115], v[118:119], s[56:57] op_sel_hi:[1,1,0]
	v_pk_mul_f32 v[4:5], v[144:145], v[4:5] op_sel_hi:[0,1]
	v_pk_mul_f32 v[114:115], v[114:115], v[118:119]
	v_pk_mul_f32 v[118:119], v[120:121], s[58:59] op_sel_hi:[1,0]
	v_pk_mul_f32 v[120:121], v[110:111], v[110:111]
	v_exp_f32_e32 v118, v118
	v_exp_f32_e32 v119, v119
	v_pk_mul_f32 v[120:121], v[120:121], s[58:59] op_sel_hi:[1,0]
	v_pk_mul_f32 v[6:7], v[144:145], v[6:7] op_sel_hi:[0,1]
	v_exp_f32_e32 v120, v120
	v_pk_mul_f32 v[114:115], v[118:119], v[114:115]
	v_exp_f32_e32 v121, v121
	v_pk_mul_f32 v[118:119], v[116:117], v[114:115]
	v_pk_fma_f32 v[114:115], v[116:117], v[114:115], v[116:117] neg_lo:[1,0,0] neg_hi:[1,0,0]
	v_pk_mul_f32 v[0:1], v[144:145], v[0:1] op_sel_hi:[0,1]
	v_cndmask_b32_e32 v118, v114, v118, vcc
	v_cmp_gt_f32_e32 vcc, 0, v117
	v_cvt_pk_bf16_f32 v114, v128, v129
	v_pk_mul_f32 v[2:3], v[144:145], v[2:3] op_sel_hi:[0,1]
	s_mov_b64 s[44:45], -1
	v_cndmask_b32_e32 v117, v115, v119, vcc
	v_cvt_pk_bf16_f32 v115, v126, v127
	v_cvt_pk_bf16_f32 v116, v124, v125
	v_cvt_pk_bf16_f32 v117, v118, v117
	global_store_dwordx4 v[150:151], v[114:117], off offset:256
	v_cmp_gt_f32_e32 vcc, 0, v110
	s_nop 0
	v_and_b32_e32 v117, 0x7fffffff, v111
	v_and_b32_e32 v116, 0x7fffffff, v110
	v_pk_fma_f32 v[116:117], v[116:117], s[28:29], 1.0 op_sel_hi:[1,0,0]
	v_or_b32_e32 v114, 16, v160
	v_rcp_f32_e32 v116, v116
	v_rcp_f32_e32 v117, v117
	v_ashrrev_i32_e32 v115, 31, v114
	v_lshlrev_b64 v[114:115], 11, v[114:115]
	v_lshl_add_u64 v[114:115], s[40:41], 0, v[114:115]
	v_pk_fma_f32 v[118:119], v[116:117], s[30:31], v[122:123] op_sel_hi:[1,0,0]
	v_lshl_add_u64 v[114:115], v[114:115], 0, v[170:171]
	v_pk_fma_f32 v[118:119], v[116:117], v[118:119], s[52:53] op_sel_hi:[1,1,0]
	s_nop 0
	v_pk_fma_f32 v[118:119], v[116:117], v[118:119], s[54:55] op_sel_hi:[1,1,0]
	s_nop 0
	v_pk_fma_f32 v[118:119], v[116:117], v[118:119], s[56:57] op_sel_hi:[1,1,0]
	s_nop 0
	v_pk_mul_f32 v[116:117], v[116:117], v[118:119]
	v_pk_mul_f32 v[118:119], v[112:113], v[112:113]
	v_pk_mul_f32 v[116:117], v[120:121], v[116:117]
	s_nop 0
	v_pk_mul_f32 v[120:121], v[110:111], v[116:117]
	v_pk_fma_f32 v[116:117], v[110:111], v[116:117], v[110:111] neg_lo:[1,0,0] neg_hi:[1,0,0]
; __device__ __forceinline__ unsigned cvt_pk_bf16(float lo, float hi) { unsigned r; asm volatile("v_cvt_pk_bf16_f32 %0, %1, %2" : "=v"(r) : "v"(lo), "v"(hi)); return r; }
; #define GAS __attribute__((address_space(1)))
; __device__ __forceinline__ f32x2 gelu_pk(f32x2 v) {
;     const f32x2 av = __builtin_elementwise_abs(v), d = av * 0.2316418882f + 1.0f;
;     f32x2 t; t.x = __builtin_amdgcn_rcpf(d.x); t.y = __builtin_amdgcn_rcpf(d.y);
;     f32x2 q = t * 0.5307027145f + (-0.7265760135f); q = q * t + 0.7107068705f; q = q * t + (-0.142248368f); q = q * t + 0.127414796f; q = q * t;
;     const f32x2 s = (v * v) * (-0.72134752044f);
;     f32x2 e; e.x = __builtin_amdgcn_exp2f(s.x); e.y = __builtin_amdgcn_exp2f(s.y);
;     const f32x2 m = v * (q * e), r = v - m;
;     f32x2 o; o.x = v.x < 0.f ? m.x : r.x; o.y = v.y < 0.f ? m.y : r.y; return o;
; }
;     __device__ __forceinline__ void operator()(const f32x4 (&acc)[2][2][4][2], const Unit& u, int wr, int wc, int fr, int fq, const float (&pre)[8]) const {
;     ...
;                     f32x4 v0 = acc[ai][bj][m][0], v1 = acc[ai][bj][m][1];
;                     if (RS == 1) { v0 = v0 * rsc; v1 = v1 * rsc; }
;                     if (RS == 2) { v0 = v0 * csc[bj][0]; v1 = v1 * csc[bj][1]; }
;                     if (ACT == 1) { const f32x2 a = gelu_pk((f32x2){v0[0], v0[1]}), b = gelu_pk((f32x2){v0[2], v0[3]}), c = gelu_pk((f32x2){v1[0], v1[1]}), d = gelu_pk((f32x2){v1[2], v1[3]});
;                         v0 = (f32x4){a.x, a.y, b.x, b.y}; v1 = (f32x4){c.x, c.y, d.x, d.y}; }
;                     v0 = v0 * sc; v1 = v1 * sc;
;                     if (STAT == 1) rs += (v0[0] * v0[0] + v0[1] * v0[1]) + (v0[2] * v0[2] + v0[3] * v0[3]) + (v1[0] * v1[0] + v1[1] * v1[1]) + (v1[2] * v1[2] + v1[3] * v1[3]);
;                     if (STAT == 2) {
; #pragma unroll
;                         for (int e = 0; e < 4; ++e) { cs[bj][0][e] += v0[e]; cq[bj][0][e] += v0[e] * v0[e]; cs[bj][1][e] += v1[e]; cq[bj][1][e] += v1[e] * v1[e]; } }
;                     u32x4 w; w.x = cvt_pk_bf16(v0[0], v0[1]); w.y = cvt_pk_bf16(v0[2], v0[3]); w.z = cvt_pk_bf16(v1[0], v1[1]); w.w = cvt_pk_bf16(v1[2], v1[3]);
;                     *(GAS u32x4*)(rowp + bj * 128) = w; }
	v_and_b32_e32 v110, 0x7fffffff, v112
	v_cndmask_b32_e32 v120, v116, v120, vcc
	v_cmp_gt_f32_e32 vcc, 0, v111
	v_and_b32_e32 v111, 0x7fffffff, v113
	v_pk_fma_f32 v[110:111], v[110:111], s[28:29], 1.0 op_sel_hi:[1,0,0]
	v_cndmask_b32_e32 v121, v117, v121, vcc
	v_rcp_f32_e32 v110, v110
	v_rcp_f32_e32 v111, v111
	v_cmp_gt_f32_e32 vcc, 0, v112
	v_pk_fma_f32 v[116:117], v[110:111], s[30:31], v[122:123] op_sel_hi:[1,0,0]
	s_nop 0
	v_pk_fma_f32 v[116:117], v[110:111], v[116:117], s[52:53] op_sel_hi:[1,1,0]
	s_nop 0
	v_pk_fma_f32 v[116:117], v[110:111], v[116:117], s[54:55] op_sel_hi:[1,1,0]
	s_nop 0
	v_pk_fma_f32 v[116:117], v[110:111], v[116:117], s[56:57] op_sel_hi:[1,1,0]
	s_nop 0
	v_pk_mul_f32 v[110:111], v[110:111], v[116:117]
	v_pk_mul_f32 v[116:117], v[118:119], s[58:59] op_sel_hi:[1,0]
	s_nop 0
	v_exp_f32_e32 v116, v116
	v_exp_f32_e32 v117, v117
	s_nop 0
	v_pk_mul_f32 v[110:111], v[116:117], v[110:111]
	s_nop 0
	v_pk_mul_f32 v[116:117], v[112:113], v[110:111]
	v_pk_fma_f32 v[110:111], v[112:113], v[110:111], v[112:113] neg_lo:[1,0,0] neg_hi:[1,0,0]
	s_nop 0
	v_cndmask_b32_e32 v118, v110, v116, vcc
	v_cmp_gt_f32_e32 vcc, 0, v113
	v_and_b32_e32 v110, 0x7fffffff, v106
	s_nop 0
	v_cndmask_b32_e32 v119, v111, v117, vcc
	v_and_b32_e32 v111, 0x7fffffff, v107
	v_pk_fma_f32 v[110:111], v[110:111], s[28:29], 1.0 op_sel_hi:[1,0,0]
	v_pk_mul_f32 v[116:117], v[106:107], v[106:107]
	v_rcp_f32_e32 v110, v110
	v_rcp_f32_e32 v111, v111
	v_pk_mul_f32 v[116:117], v[116:117], s[58:59] op_sel_hi:[1,0]
	v_cmp_gt_f32_e32 vcc, 0, v106
	v_exp_f32_e32 v116, v116
	v_pk_fma_f32 v[112:113], v[110:111], s[30:31], v[122:123] op_sel_hi:[1,0,0]
	v_exp_f32_e32 v117, v117
	v_pk_fma_f32 v[112:113], v[110:111], v[112:113], s[52:53] op_sel_hi:[1,1,0]
	s_nop 0
	v_pk_fma_f32 v[112:113], v[110:111], v[112:113], s[54:55] op_sel_hi:[1,1,0]
	s_nop 0
	v_pk_fma_f32 v[112:113], v[110:111], v[112:113], s[56:57] op_sel_hi:[1,1,0]
	s_nop 0
	v_pk_mul_f32 v[110:111], v[110:111], v[112:113]
	v_pk_mul_f32 v[112:113], v[108:109], v[108:109]
	v_pk_mul_f32 v[110:111], v[116:117], v[110:111]
	s_nop 0
	v_pk_mul_f32 v[116:117], v[106:107], v[110:111]
	v_pk_fma_f32 v[110:111], v[106:107], v[110:111], v[106:107] neg_lo:[1,0,0] neg_hi:[1,0,0]
	v_and_b32_e32 v106, 0x7fffffff, v108
	v_cndmask_b32_e32 v116, v110, v116, vcc
	v_cmp_gt_f32_e32 vcc, 0, v107
	v_and_b32_e32 v107, 0x7fffffff, v109
	v_pk_fma_f32 v[106:107], v[106:107], s[28:29], 1.0 op_sel_hi:[1,0,0]
	v_cndmask_b32_e32 v117, v111, v117, vcc
	v_rcp_f32_e32 v106, v106
	v_rcp_f32_e32 v107, v107
	v_cmp_gt_f32_e32 vcc, 0, v108
	v_pk_fma_f32 v[110:111], v[106:107], s[30:31], v[122:123] op_sel_hi:[1,0,0]
	s_nop 0
	v_pk_fma_f32 v[110:111], v[106:107], v[110:111], s[52:53] op_sel_hi:[1,1,0]
	s_nop 0
	v_pk_fma_f32 v[110:111], v[106:107], v[110:111], s[54:55] op_sel_hi:[1,1,0]
	s_nop 0
	v_pk_fma_f32 v[110:111], v[106:107], v[110:111], s[56:57] op_sel_hi:[1,1,0]
	s_nop 0
	v_pk_mul_f32 v[106:107], v[106:107], v[110:111]
	v_pk_mul_f32 v[110:111], v[112:113], s[58:59] op_sel_hi:[1,0]
	s_nop 0
	v_exp_f32_e32 v110, v110
	v_exp_f32_e32 v111, v111
	s_nop 0
	v_pk_mul_f32 v[106:107], v[110:111], v[106:107]
	s_nop 0
	v_pk_mul_f32 v[110:111], v[108:109], v[106:107]
	v_pk_fma_f32 v[106:107], v[108:109], v[106:107], v[108:109] neg_lo:[1,0,0] neg_hi:[1,0,0]
	s_nop 0
	v_cndmask_b32_e32 v110, v106, v110, vcc
	v_cmp_gt_f32_e32 vcc, 0, v109
	v_cvt_pk_bf16_f32 v106, v120, v121
	s_nop 1
	v_cndmask_b32_e32 v109, v107, v111, vcc
	v_cvt_pk_bf16_f32 v107, v118, v119
	v_cvt_pk_bf16_f32 v108, v116, v117
	v_cvt_pk_bf16_f32 v109, v110, v109
	global_store_dwordx4 v[114:115], v[106:109], off
	v_pk_mul_f32 v[110:111], v[102:103], v[102:103]
	v_cmp_gt_f32_e32 vcc, 0, v102
	v_and_b32_e32 v107, 0x7fffffff, v103
	v_and_b32_e32 v106, 0x7fffffff, v102
	v_pk_fma_f32 v[106:107], v[106:107], s[28:29], 1.0 op_sel_hi:[1,0,0]
	v_pk_mul_f32 v[110:111], v[110:111], s[58:59] op_sel_hi:[1,0]
	v_rcp_f32_e32 v106, v106
	v_rcp_f32_e32 v107, v107
	v_exp_f32_e32 v110, v110
	v_exp_f32_e32 v111, v111
	v_pk_fma_f32 v[108:109], v[106:107], s[30:31], v[122:123] op_sel_hi:[1,0,0]
	s_nop 0
	v_pk_fma_f32 v[108:109], v[106:107], v[108:109], s[52:53] op_sel_hi:[1,1,0]
	s_nop 0
	v_pk_fma_f32 v[108:109], v[106:107], v[108:109], s[54:55] op_sel_hi:[1,1,0]
	s_nop 0
	v_pk_fma_f32 v[108:109], v[106:107], v[108:109], s[56:57] op_sel_hi:[1,1,0]
	s_nop 0
	v_pk_mul_f32 v[106:107], v[106:107], v[108:109]
	v_pk_mul_f32 v[108:109], v[104:105], v[104:105]
	v_pk_mul_f32 v[106:107], v[110:111], v[106:107]
	s_nop 0
	v_pk_mul_f32 v[110:111], v[102:103], v[106:107]
	v_pk_fma_f32 v[106:107], v[102:103], v[106:107], v[102:103] neg_lo:[1,0,0] neg_hi:[1,0,0]
	v_and_b32_e32 v102, 0x7fffffff, v104
	v_cndmask_b32_e32 v110, v106, v110, vcc
	v_cmp_gt_f32_e32 vcc, 0, v103
	v_and_b32_e32 v103, 0x7fffffff, v105
	v_pk_fma_f32 v[102:103], v[102:103], s[28:29], 1.0 op_sel_hi:[1,0,0]
	v_cndmask_b32_e32 v111, v107, v111, vcc
	v_rcp_f32_e32 v102, v102
	v_rcp_f32_e32 v103, v103
	v_cmp_gt_f32_e32 vcc, 0, v104
	v_pk_fma_f32 v[106:107], v[102:103], s[30:31], v[122:123] op_sel_hi:[1,0,0]
	s_nop 0
	v_pk_fma_f32 v[106:107], v[102:103], v[106:107], s[52:53] op_sel_hi:[1,1,0]
	s_nop 0
	v_pk_fma_f32 v[106:107], v[102:103], v[106:107], s[54:55] op_sel_hi:[1,1,0]
	s_nop 0
	v_pk_fma_f32 v[106:107], v[102:103], v[106:107], s[56:57] op_sel_hi:[1,1,0]
	s_nop 0
	v_pk_mul_f32 v[102:103], v[102:103], v[106:107]
	v_pk_mul_f32 v[106:107], v[108:109], s[58:59] op_sel_hi:[1,0]
	s_nop 0
	v_exp_f32_e32 v106, v106
	v_exp_f32_e32 v107, v107
	s_nop 0
	v_pk_mul_f32 v[102:103], v[106:107], v[102:103]
	s_nop 0
	v_pk_mul_f32 v[106:107], v[104:105], v[102:103]
; __device__ __forceinline__ unsigned cvt_pk_bf16(float lo, float hi) { unsigned r; asm volatile("v_cvt_pk_bf16_f32 %0, %1, %2" : "=v"(r) : "v"(lo), "v"(hi)); return r; }
; #define GAS __attribute__((address_space(1)))
; __device__ __forceinline__ f32x2 gelu_pk(f32x2 v) {
;     const f32x2 av = __builtin_elementwise_abs(v), d = av * 0.2316418882f + 1.0f;
;     f32x2 t; t.x = __builtin_amdgcn_rcpf(d.x); t.y = __builtin_amdgcn_rcpf(d.y);
;     f32x2 q = t * 0.5307027145f + (-0.7265760135f); q = q * t + 0.7107068705f; q = q * t + (-0.142248368f); q = q * t + 0.127414796f; q = q * t;
;     const f32x2 s = (v * v) * (-0.72134752044f);
;     f32x2 e; e.x = __builtin_amdgcn_exp2f(s.x); e.y = __builtin_amdgcn_exp2f(s.y);
;     const f32x2 m = v * (q * e), r = v - m;
;     f32x2 o; o.x = v.x < 0.f ? m.x : r.x; o.y = v.y < 0.f ? m.y : r.y; return o;
; }
;     __device__ __forceinline__ void operator()(const f32x4 (&acc)[2][2][4][2], const Unit& u, int wr, int wc, int fr, int fq, const float (&pre)[8]) const {
;     ...
;                     f32x4 v0 = acc[ai][bj][m][0], v1 = acc[ai][bj][m][1];
;                     if (RS == 1) { v0 = v0 * rsc; v1 = v1 * rsc; }
;                     if (RS == 2) { v0 = v0 * csc[bj][0]; v1 = v1 * csc[bj][1]; }
;                     if (ACT == 1) { const f32x2 a = gelu_pk((f32x2){v0[0], v0[1]}), b = gelu_pk((f32x2){v0[2], v0[3]}), c = gelu_pk((f32x2){v1[0], v1[1]}), d = gelu_pk((f32x2){v1[2], v1[3]});
;                         v0 = (f32x4){a.x, a.y, b.x, b.y}; v1 = (f32x4){c.x, c.y, d.x, d.y}; }
;                     v0 = v0 * sc; v1 = v1 * sc;
;                     if (STAT == 1) rs += (v0[0] * v0[0] + v0[1] * v0[1]) + (v0[2] * v0[2] + v0[3] * v0[3]) + (v1[0] * v1[0] + v1[1] * v1[1]) + (v1[2] * v1[2] + v1[3] * v1[3]);
;                     if (STAT == 2) {
; #pragma unroll
;                         for (int e = 0; e < 4; ++e) { cs[bj][0][e] += v0[e]; cq[bj][0][e] += v0[e] * v0[e]; cs[bj][1][e] += v1[e]; cq[bj][1][e] += v1[e] * v1[e]; } }
;                     u32x4 w; w.x = cvt_pk_bf16(v0[0], v0[1]); w.y = cvt_pk_bf16(v0[2], v0[3]); w.z = cvt_pk_bf16(v1[0], v1[1]); w.w = cvt_pk_bf16(v1[2], v1[3]);
;                     *(GAS u32x4*)(rowp + bj * 128) = w; }
	v_pk_fma_f32 v[102:103], v[104:105], v[102:103], v[104:105] neg_lo:[1,0,0] neg_hi:[1,0,0]
	s_nop 0
	v_cndmask_b32_e32 v108, v102, v106, vcc
	v_cmp_gt_f32_e32 vcc, 0, v105
	v_and_b32_e32 v102, 0x7fffffff, v98
	s_nop 0
	v_cndmask_b32_e32 v109, v103, v107, vcc
	v_and_b32_e32 v103, 0x7fffffff, v99
	v_pk_fma_f32 v[102:103], v[102:103], s[28:29], 1.0 op_sel_hi:[1,0,0]
	v_pk_mul_f32 v[106:107], v[98:99], v[98:99]
	v_rcp_f32_e32 v102, v102
	v_rcp_f32_e32 v103, v103
	v_pk_mul_f32 v[106:107], v[106:107], s[58:59] op_sel_hi:[1,0]
	v_cmp_gt_f32_e32 vcc, 0, v98
	v_exp_f32_e32 v106, v106
	v_pk_fma_f32 v[104:105], v[102:103], s[30:31], v[122:123] op_sel_hi:[1,0,0]
	v_exp_f32_e32 v107, v107
	v_pk_fma_f32 v[104:105], v[102:103], v[104:105], s[52:53] op_sel_hi:[1,1,0]
	s_nop 0
	v_pk_fma_f32 v[104:105], v[102:103], v[104:105], s[54:55] op_sel_hi:[1,1,0]
	s_nop 0
	v_pk_fma_f32 v[104:105], v[102:103], v[104:105], s[56:57] op_sel_hi:[1,1,0]
	s_nop 0
	v_pk_mul_f32 v[102:103], v[102:103], v[104:105]
	v_pk_mul_f32 v[104:105], v[100:101], v[100:101]
	v_pk_mul_f32 v[102:103], v[106:107], v[102:103]
	s_nop 0
	v_pk_mul_f32 v[106:107], v[98:99], v[102:103]
	v_pk_fma_f32 v[102:103], v[98:99], v[102:103], v[98:99] neg_lo:[1,0,0] neg_hi:[1,0,0]
	v_and_b32_e32 v98, 0x7fffffff, v100
	v_cndmask_b32_e32 v106, v102, v106, vcc
	v_cmp_gt_f32_e32 vcc, 0, v99
	v_and_b32_e32 v99, 0x7fffffff, v101
	v_pk_fma_f32 v[98:99], v[98:99], s[28:29], 1.0 op_sel_hi:[1,0,0]
	v_cndmask_b32_e32 v107, v103, v107, vcc
	v_rcp_f32_e32 v98, v98
	v_rcp_f32_e32 v99, v99
	v_cmp_gt_f32_e32 vcc, 0, v100
	v_pk_fma_f32 v[102:103], v[98:99], s[30:31], v[122:123] op_sel_hi:[1,0,0]
	s_nop 0
	v_pk_fma_f32 v[102:103], v[98:99], v[102:103], s[52:53] op_sel_hi:[1,1,0]
	s_nop 0
	v_pk_fma_f32 v[102:103], v[98:99], v[102:103], s[54:55] op_sel_hi:[1,1,0]
	s_nop 0
	v_pk_fma_f32 v[102:103], v[98:99], v[102:103], s[56:57] op_sel_hi:[1,1,0]
	s_nop 0
	v_pk_mul_f32 v[98:99], v[98:99], v[102:103]
	v_pk_mul_f32 v[102:103], v[104:105], s[58:59] op_sel_hi:[1,0]
	v_pk_mul_f32 v[104:105], v[94:95], v[94:95]
	v_exp_f32_e32 v102, v102
	v_exp_f32_e32 v103, v103
	v_pk_mul_f32 v[104:105], v[104:105], s[58:59] op_sel_hi:[1,0]
	v_pk_mul_f32 v[98:99], v[102:103], v[98:99]
	s_nop 0
	v_pk_mul_f32 v[102:103], v[100:101], v[98:99]
	v_pk_fma_f32 v[98:99], v[100:101], v[98:99], v[100:101] neg_lo:[1,0,0] neg_hi:[1,0,0]
	v_exp_f32_e32 v104, v104
	v_cndmask_b32_e32 v102, v98, v102, vcc
	v_cmp_gt_f32_e32 vcc, 0, v101
	v_cvt_pk_bf16_f32 v98, v110, v111
	v_exp_f32_e32 v105, v105
	s_nop 0
	v_cndmask_b32_e32 v101, v99, v103, vcc
	v_cvt_pk_bf16_f32 v99, v108, v109
	v_cvt_pk_bf16_f32 v100, v106, v107
	v_cvt_pk_bf16_f32 v101, v102, v101
	global_store_dwordx4 v[114:115], v[98:101], off offset:256
	v_cmp_gt_f32_e32 vcc, 0, v94
	s_nop 0
	v_and_b32_e32 v101, 0x7fffffff, v95
	v_and_b32_e32 v100, 0x7fffffff, v94
	v_pk_fma_f32 v[100:101], v[100:101], s[28:29], 1.0 op_sel_hi:[1,0,0]
	v_or_b32_e32 v98, 32, v160
	v_rcp_f32_e32 v100, v100
	v_rcp_f32_e32 v101, v101
	v_ashrrev_i32_e32 v99, 31, v98
	v_lshlrev_b64 v[98:99], 11, v[98:99]
	v_lshl_add_u64 v[98:99], s[40:41], 0, v[98:99]
	v_pk_fma_f32 v[102:103], v[100:101], s[30:31], v[122:123] op_sel_hi:[1,0,0]
	v_lshl_add_u64 v[98:99], v[98:99], 0, v[170:171]
	v_pk_fma_f32 v[102:103], v[100:101], v[102:103], s[52:53] op_sel_hi:[1,1,0]
	s_nop 0
	v_pk_fma_f32 v[102:103], v[100:101], v[102:103], s[54:55] op_sel_hi:[1,1,0]
	s_nop 0
	v_pk_fma_f32 v[102:103], v[100:101], v[102:103], s[56:57] op_sel_hi:[1,1,0]
	s_nop 0
	v_pk_mul_f32 v[100:101], v[100:101], v[102:103]
	v_pk_mul_f32 v[102:103], v[96:97], v[96:97]
	v_pk_mul_f32 v[100:101], v[104:105], v[100:101]
	s_nop 0
	v_pk_mul_f32 v[104:105], v[94:95], v[100:101]
	v_pk_fma_f32 v[100:101], v[94:95], v[100:101], v[94:95] neg_lo:[1,0,0] neg_hi:[1,0,0]
	v_and_b32_e32 v94, 0x7fffffff, v96
	v_cndmask_b32_e32 v104, v100, v104, vcc
	v_cmp_gt_f32_e32 vcc, 0, v95
	v_and_b32_e32 v95, 0x7fffffff, v97
	v_pk_fma_f32 v[94:95], v[94:95], s[28:29], 1.0 op_sel_hi:[1,0,0]
	v_cndmask_b32_e32 v105, v101, v105, vcc
	v_rcp_f32_e32 v94, v94
	v_rcp_f32_e32 v95, v95
	v_cmp_gt_f32_e32 vcc, 0, v96
	v_pk_fma_f32 v[100:101], v[94:95], s[30:31], v[122:123] op_sel_hi:[1,0,0]
	s_nop 0
	v_pk_fma_f32 v[100:101], v[94:95], v[100:101], s[52:53] op_sel_hi:[1,1,0]
	s_nop 0
	v_pk_fma_f32 v[100:101], v[94:95], v[100:101], s[54:55] op_sel_hi:[1,1,0]
	s_nop 0
	v_pk_fma_f32 v[100:101], v[94:95], v[100:101], s[56:57] op_sel_hi:[1,1,0]
	s_nop 0
	v_pk_mul_f32 v[94:95], v[94:95], v[100:101]
	v_pk_mul_f32 v[100:101], v[102:103], s[58:59] op_sel_hi:[1,0]
	s_nop 0
	v_exp_f32_e32 v100, v100
	v_exp_f32_e32 v101, v101
	s_nop 0
	v_pk_mul_f32 v[94:95], v[100:101], v[94:95]
	s_nop 0
	v_pk_mul_f32 v[100:101], v[96:97], v[94:95]
	v_pk_fma_f32 v[94:95], v[96:97], v[94:95], v[96:97] neg_lo:[1,0,0] neg_hi:[1,0,0]
	s_nop 0
	v_cndmask_b32_e32 v102, v94, v100, vcc
	v_cmp_gt_f32_e32 vcc, 0, v97
	v_and_b32_e32 v94, 0x7fffffff, v90
	s_nop 0
	v_cndmask_b32_e32 v103, v95, v101, vcc
	v_and_b32_e32 v95, 0x7fffffff, v91
	v_pk_fma_f32 v[94:95], v[94:95], s[28:29], 1.0 op_sel_hi:[1,0,0]
	v_pk_mul_f32 v[100:101], v[90:91], v[90:91]
	v_rcp_f32_e32 v94, v94
	v_rcp_f32_e32 v95, v95
	v_pk_mul_f32 v[100:101], v[100:101], s[58:59] op_sel_hi:[1,0]
	v_cmp_gt_f32_e32 vcc, 0, v90
	v_exp_f32_e32 v100, v100
	v_pk_fma_f32 v[96:97], v[94:95], s[30:31], v[122:123] op_sel_hi:[1,0,0]
	v_exp_f32_e32 v101, v101
	v_pk_fma_f32 v[96:97], v[94:95], v[96:97], s[52:53] op_sel_hi:[1,1,0]
	s_nop 0
	v_pk_fma_f32 v[96:97], v[94:95], v[96:97], s[54:55] op_sel_hi:[1,1,0]
	s_nop 0
	v_pk_fma_f32 v[96:97], v[94:95], v[96:97], s[56:57] op_sel_hi:[1,1,0]
	s_nop 0
; __device__ __forceinline__ unsigned cvt_pk_bf16(float lo, float hi) { unsigned r; asm volatile("v_cvt_pk_bf16_f32 %0, %1, %2" : "=v"(r) : "v"(lo), "v"(hi)); return r; }
; #define GAS __attribute__((address_space(1)))
; __device__ __forceinline__ f32x2 gelu_pk(f32x2 v) {
;     const f32x2 av = __builtin_elementwise_abs(v), d = av * 0.2316418882f + 1.0f;
;     f32x2 t; t.x = __builtin_amdgcn_rcpf(d.x); t.y = __builtin_amdgcn_rcpf(d.y);
;     f32x2 q = t * 0.5307027145f + (-0.7265760135f); q = q * t + 0.7107068705f; q = q * t + (-0.142248368f); q = q * t + 0.127414796f; q = q * t;
;     const f32x2 s = (v * v) * (-0.72134752044f);
;     f32x2 e; e.x = __builtin_amdgcn_exp2f(s.x); e.y = __builtin_amdgcn_exp2f(s.y);
;     const f32x2 m = v * (q * e), r = v - m;
;     f32x2 o; o.x = v.x < 0.f ? m.x : r.x; o.y = v.y < 0.f ? m.y : r.y; return o;
; }
;     __device__ __forceinline__ void operator()(const f32x4 (&acc)[2][2][4][2], const Unit& u, int wr, int wc, int fr, int fq, const float (&pre)[8]) const {
;     ...
;                     f32x4 v0 = acc[ai][bj][m][0], v1 = acc[ai][bj][m][1];
;                     if (RS == 1) { v0 = v0 * rsc; v1 = v1 * rsc; }
;                     if (RS == 2) { v0 = v0 * csc[bj][0]; v1 = v1 * csc[bj][1]; }
;                     if (ACT == 1) { const f32x2 a = gelu_pk((f32x2){v0[0], v0[1]}), b = gelu_pk((f32x2){v0[2], v0[3]}), c = gelu_pk((f32x2){v1[0], v1[1]}), d = gelu_pk((f32x2){v1[2], v1[3]});
;                         v0 = (f32x4){a.x, a.y, b.x, b.y}; v1 = (f32x4){c.x, c.y, d.x, d.y}; }
;                     v0 = v0 * sc; v1 = v1 * sc;
;                     if (STAT == 1) rs += (v0[0] * v0[0] + v0[1] * v0[1]) + (v0[2] * v0[2] + v0[3] * v0[3]) + (v1[0] * v1[0] + v1[1] * v1[1]) + (v1[2] * v1[2] + v1[3] * v1[3]);
;                     if (STAT == 2) {
; #pragma unroll
;                         for (int e = 0; e < 4; ++e) { cs[bj][0][e] += v0[e]; cq[bj][0][e] += v0[e] * v0[e]; cs[bj][1][e] += v1[e]; cq[bj][1][e] += v1[e] * v1[e]; } }
;                     u32x4 w; w.x = cvt_pk_bf16(v0[0], v0[1]); w.y = cvt_pk_bf16(v0[2], v0[3]); w.z = cvt_pk_bf16(v1[0], v1[1]); w.w = cvt_pk_bf16(v1[2], v1[3]);
;                     *(GAS u32x4*)(rowp + bj * 128) = w; }
	v_pk_mul_f32 v[94:95], v[94:95], v[96:97]
	v_pk_mul_f32 v[96:97], v[92:93], v[92:93]
	v_pk_mul_f32 v[94:95], v[100:101], v[94:95]
	s_nop 0
	v_pk_mul_f32 v[100:101], v[90:91], v[94:95]
	v_pk_fma_f32 v[94:95], v[90:91], v[94:95], v[90:91] neg_lo:[1,0,0] neg_hi:[1,0,0]
	v_and_b32_e32 v90, 0x7fffffff, v92
	v_cndmask_b32_e32 v100, v94, v100, vcc
	v_cmp_gt_f32_e32 vcc, 0, v91
	v_and_b32_e32 v91, 0x7fffffff, v93
	v_pk_fma_f32 v[90:91], v[90:91], s[28:29], 1.0 op_sel_hi:[1,0,0]
	v_cndmask_b32_e32 v101, v95, v101, vcc
	v_rcp_f32_e32 v90, v90
	v_rcp_f32_e32 v91, v91
	v_cmp_gt_f32_e32 vcc, 0, v92
	v_pk_fma_f32 v[94:95], v[90:91], s[30:31], v[122:123] op_sel_hi:[1,0,0]
	s_nop 0
	v_pk_fma_f32 v[94:95], v[90:91], v[94:95], s[52:53] op_sel_hi:[1,1,0]
	s_nop 0
	v_pk_fma_f32 v[94:95], v[90:91], v[94:95], s[54:55] op_sel_hi:[1,1,0]
	s_nop 0
	v_pk_fma_f32 v[94:95], v[90:91], v[94:95], s[56:57] op_sel_hi:[1,1,0]
	s_nop 0
	v_pk_mul_f32 v[90:91], v[90:91], v[94:95]
	v_pk_mul_f32 v[94:95], v[96:97], s[58:59] op_sel_hi:[1,0]
	s_nop 0
	v_exp_f32_e32 v94, v94
	v_exp_f32_e32 v95, v95
	s_nop 0
	v_pk_mul_f32 v[90:91], v[94:95], v[90:91]
	s_nop 0
	v_pk_mul_f32 v[94:95], v[92:93], v[90:91]
	v_pk_fma_f32 v[90:91], v[92:93], v[90:91], v[92:93] neg_lo:[1,0,0] neg_hi:[1,0,0]
	s_nop 0
	v_cndmask_b32_e32 v94, v90, v94, vcc
	v_cmp_gt_f32_e32 vcc, 0, v93
	v_cvt_pk_bf16_f32 v90, v104, v105
	s_nop 1
	v_cndmask_b32_e32 v93, v91, v95, vcc
	v_cvt_pk_bf16_f32 v91, v102, v103
	v_cvt_pk_bf16_f32 v92, v100, v101
	v_cvt_pk_bf16_f32 v93, v94, v93
	global_store_dwordx4 v[98:99], v[90:93], off
	v_pk_mul_f32 v[94:95], v[86:87], v[86:87]
	v_cmp_gt_f32_e32 vcc, 0, v86
	v_and_b32_e32 v91, 0x7fffffff, v87
	v_and_b32_e32 v90, 0x7fffffff, v86
	v_pk_fma_f32 v[90:91], v[90:91], s[28:29], 1.0 op_sel_hi:[1,0,0]
	v_pk_mul_f32 v[94:95], v[94:95], s[58:59] op_sel_hi:[1,0]
	v_rcp_f32_e32 v90, v90
	v_rcp_f32_e32 v91, v91
	v_exp_f32_e32 v94, v94
	v_exp_f32_e32 v95, v95
	v_pk_fma_f32 v[92:93], v[90:91], s[30:31], v[122:123] op_sel_hi:[1,0,0]
	s_nop 0
	v_pk_fma_f32 v[92:93], v[90:91], v[92:93], s[52:53] op_sel_hi:[1,1,0]
	s_nop 0
	v_pk_fma_f32 v[92:93], v[90:91], v[92:93], s[54:55] op_sel_hi:[1,1,0]
	s_nop 0
	v_pk_fma_f32 v[92:93], v[90:91], v[92:93], s[56:57] op_sel_hi:[1,1,0]
	s_nop 0
	v_pk_mul_f32 v[90:91], v[90:91], v[92:93]
	v_pk_mul_f32 v[92:93], v[88:89], v[88:89]
	v_pk_mul_f32 v[90:91], v[94:95], v[90:91]
	s_nop 0
	v_pk_mul_f32 v[94:95], v[86:87], v[90:91]
	v_pk_fma_f32 v[90:91], v[86:87], v[90:91], v[86:87] neg_lo:[1,0,0] neg_hi:[1,0,0]
	v_and_b32_e32 v86, 0x7fffffff, v88
	v_cndmask_b32_e32 v94, v90, v94, vcc
	v_cmp_gt_f32_e32 vcc, 0, v87
	v_and_b32_e32 v87, 0x7fffffff, v89
	v_pk_fma_f32 v[86:87], v[86:87], s[28:29], 1.0 op_sel_hi:[1,0,0]
	v_cndmask_b32_e32 v95, v91, v95, vcc
	v_rcp_f32_e32 v86, v86
	v_rcp_f32_e32 v87, v87
	v_cmp_gt_f32_e32 vcc, 0, v88
	v_pk_fma_f32 v[90:91], v[86:87], s[30:31], v[122:123] op_sel_hi:[1,0,0]
	s_nop 0
	v_pk_fma_f32 v[90:91], v[86:87], v[90:91], s[52:53] op_sel_hi:[1,1,0]
	s_nop 0
	v_pk_fma_f32 v[90:91], v[86:87], v[90:91], s[54:55] op_sel_hi:[1,1,0]
	s_nop 0
	v_pk_fma_f32 v[90:91], v[86:87], v[90:91], s[56:57] op_sel_hi:[1,1,0]
	s_nop 0
	v_pk_mul_f32 v[86:87], v[86:87], v[90:91]
	v_pk_mul_f32 v[90:91], v[92:93], s[58:59] op_sel_hi:[1,0]
	s_nop 0
	v_exp_f32_e32 v90, v90
	v_exp_f32_e32 v91, v91
	s_nop 0
	v_pk_mul_f32 v[86:87], v[90:91], v[86:87]
	s_nop 0
	v_pk_mul_f32 v[90:91], v[88:89], v[86:87]
	v_pk_fma_f32 v[86:87], v[88:89], v[86:87], v[88:89] neg_lo:[1,0,0] neg_hi:[1,0,0]
	s_nop 0
	v_cndmask_b32_e32 v92, v86, v90, vcc
	v_cmp_gt_f32_e32 vcc, 0, v89
	v_and_b32_e32 v86, 0x7fffffff, v82
	s_nop 0
	v_cndmask_b32_e32 v93, v87, v91, vcc
	v_and_b32_e32 v87, 0x7fffffff, v83
	v_pk_fma_f32 v[86:87], v[86:87], s[28:29], 1.0 op_sel_hi:[1,0,0]
	v_pk_mul_f32 v[90:91], v[82:83], v[82:83]
	v_rcp_f32_e32 v86, v86
	v_rcp_f32_e32 v87, v87
	v_pk_mul_f32 v[90:91], v[90:91], s[58:59] op_sel_hi:[1,0]
	v_cmp_gt_f32_e32 vcc, 0, v82
	v_exp_f32_e32 v90, v90
	v_pk_fma_f32 v[88:89], v[86:87], s[30:31], v[122:123] op_sel_hi:[1,0,0]
	v_exp_f32_e32 v91, v91
	v_pk_fma_f32 v[88:89], v[86:87], v[88:89], s[52:53] op_sel_hi:[1,1,0]
	s_nop 0
	v_pk_fma_f32 v[88:89], v[86:87], v[88:89], s[54:55] op_sel_hi:[1,1,0]
	s_nop 0
	v_pk_fma_f32 v[88:89], v[86:87], v[88:89], s[56:57] op_sel_hi:[1,1,0]
	s_nop 0
	v_pk_mul_f32 v[86:87], v[86:87], v[88:89]
	v_pk_mul_f32 v[88:89], v[84:85], v[84:85]
	v_pk_mul_f32 v[86:87], v[90:91], v[86:87]
	s_nop 0
	v_pk_mul_f32 v[90:91], v[82:83], v[86:87]
	v_pk_fma_f32 v[86:87], v[82:83], v[86:87], v[82:83] neg_lo:[1,0,0] neg_hi:[1,0,0]
	v_and_b32_e32 v82, 0x7fffffff, v84
	v_cndmask_b32_e32 v90, v86, v90, vcc
	v_cmp_gt_f32_e32 vcc, 0, v83
	v_and_b32_e32 v83, 0x7fffffff, v85
	v_pk_fma_f32 v[82:83], v[82:83], s[28:29], 1.0 op_sel_hi:[1,0,0]
	v_cndmask_b32_e32 v91, v87, v91, vcc
	v_rcp_f32_e32 v82, v82
	v_rcp_f32_e32 v83, v83
	v_cmp_gt_f32_e32 vcc, 0, v84
	v_pk_fma_f32 v[86:87], v[82:83], s[30:31], v[122:123] op_sel_hi:[1,0,0]
	s_nop 0
	v_pk_fma_f32 v[86:87], v[82:83], v[86:87], s[52:53] op_sel_hi:[1,1,0]
	s_nop 0
	v_pk_fma_f32 v[86:87], v[82:83], v[86:87], s[54:55] op_sel_hi:[1,1,0]
	s_nop 0
	v_pk_fma_f32 v[86:87], v[82:83], v[86:87], s[56:57] op_sel_hi:[1,1,0]
	s_nop 0
	v_pk_mul_f32 v[82:83], v[82:83], v[86:87]
	v_pk_mul_f32 v[86:87], v[88:89], s[58:59] op_sel_hi:[1,0]
	v_pk_mul_f32 v[88:89], v[78:79], v[78:79]
	v_exp_f32_e32 v86, v86
	v_exp_f32_e32 v87, v87
	v_pk_mul_f32 v[88:89], v[88:89], s[58:59] op_sel_hi:[1,0]
	v_pk_mul_f32 v[82:83], v[86:87], v[82:83]
	s_nop 0
	v_pk_mul_f32 v[86:87], v[84:85], v[82:83]
	v_pk_fma_f32 v[82:83], v[84:85], v[82:83], v[84:85] neg_lo:[1,0,0] neg_hi:[1,0,0]
; __device__ __forceinline__ unsigned cvt_pk_bf16(float lo, float hi) { unsigned r; asm volatile("v_cvt_pk_bf16_f32 %0, %1, %2" : "=v"(r) : "v"(lo), "v"(hi)); return r; }
; #define GAS __attribute__((address_space(1)))
; __device__ __forceinline__ f32x2 gelu_pk(f32x2 v) {
;     const f32x2 av = __builtin_elementwise_abs(v), d = av * 0.2316418882f + 1.0f;
;     f32x2 t; t.x = __builtin_amdgcn_rcpf(d.x); t.y = __builtin_amdgcn_rcpf(d.y);
;     f32x2 q = t * 0.5307027145f + (-0.7265760135f); q = q * t + 0.7107068705f; q = q * t + (-0.142248368f); q = q * t + 0.127414796f; q = q * t;
;     const f32x2 s = (v * v) * (-0.72134752044f);
;     f32x2 e; e.x = __builtin_amdgcn_exp2f(s.x); e.y = __builtin_amdgcn_exp2f(s.y);
;     const f32x2 m = v * (q * e), r = v - m;
;     f32x2 o; o.x = v.x < 0.f ? m.x : r.x; o.y = v.y < 0.f ? m.y : r.y; return o;
; }
;     __device__ __forceinline__ void operator()(const f32x4 (&acc)[2][2][4][2], const Unit& u, int wr, int wc, int fr, int fq, const float (&pre)[8]) const {
;     ...
;                     f32x4 v0 = acc[ai][bj][m][0], v1 = acc[ai][bj][m][1];
;                     if (RS == 1) { v0 = v0 * rsc; v1 = v1 * rsc; }
;                     if (RS == 2) { v0 = v0 * csc[bj][0]; v1 = v1 * csc[bj][1]; }
;                     if (ACT == 1) { const f32x2 a = gelu_pk((f32x2){v0[0], v0[1]}), b = gelu_pk((f32x2){v0[2], v0[3]}), c = gelu_pk((f32x2){v1[0], v1[1]}), d = gelu_pk((f32x2){v1[2], v1[3]});
;                         v0 = (f32x4){a.x, a.y, b.x, b.y}; v1 = (f32x4){c.x, c.y, d.x, d.y}; }
;                     v0 = v0 * sc; v1 = v1 * sc;
;                     if (STAT == 1) rs += (v0[0] * v0[0] + v0[1] * v0[1]) + (v0[2] * v0[2] + v0[3] * v0[3]) + (v1[0] * v1[0] + v1[1] * v1[1]) + (v1[2] * v1[2] + v1[3] * v1[3]);
;                     if (STAT == 2) {
; #pragma unroll
;                         for (int e = 0; e < 4; ++e) { cs[bj][0][e] += v0[e]; cq[bj][0][e] += v0[e] * v0[e]; cs[bj][1][e] += v1[e]; cq[bj][1][e] += v1[e] * v1[e]; } }
;                     u32x4 w; w.x = cvt_pk_bf16(v0[0], v0[1]); w.y = cvt_pk_bf16(v0[2], v0[3]); w.z = cvt_pk_bf16(v1[0], v1[1]); w.w = cvt_pk_bf16(v1[2], v1[3]);
;                     *(GAS u32x4*)(rowp + bj * 128) = w; }
	v_exp_f32_e32 v88, v88
	v_cndmask_b32_e32 v86, v82, v86, vcc
	v_cmp_gt_f32_e32 vcc, 0, v85
	v_cvt_pk_bf16_f32 v82, v94, v95
	v_exp_f32_e32 v89, v89
	s_nop 0
	v_cndmask_b32_e32 v85, v83, v87, vcc
	v_cvt_pk_bf16_f32 v83, v92, v93
	v_cvt_pk_bf16_f32 v84, v90, v91
	v_cvt_pk_bf16_f32 v85, v86, v85
	global_store_dwordx4 v[98:99], v[82:85], off offset:256
	v_cmp_gt_f32_e32 vcc, 0, v78
	s_nop 0
	v_and_b32_e32 v85, 0x7fffffff, v79
	v_and_b32_e32 v84, 0x7fffffff, v78
	v_pk_fma_f32 v[84:85], v[84:85], s[28:29], 1.0 op_sel_hi:[1,0,0]
	v_or_b32_e32 v82, 48, v160
	v_rcp_f32_e32 v84, v84
	v_rcp_f32_e32 v85, v85
	v_ashrrev_i32_e32 v83, 31, v82
	v_lshlrev_b64 v[82:83], 11, v[82:83]
	v_lshl_add_u64 v[82:83], s[40:41], 0, v[82:83]
	v_pk_fma_f32 v[86:87], v[84:85], s[30:31], v[122:123] op_sel_hi:[1,0,0]
	v_lshl_add_u64 v[82:83], v[82:83], 0, v[170:171]
	v_pk_fma_f32 v[86:87], v[84:85], v[86:87], s[52:53] op_sel_hi:[1,1,0]
	s_nop 0
	v_pk_fma_f32 v[86:87], v[84:85], v[86:87], s[54:55] op_sel_hi:[1,1,0]
	s_nop 0
	v_pk_fma_f32 v[86:87], v[84:85], v[86:87], s[56:57] op_sel_hi:[1,1,0]
	s_nop 0
	v_pk_mul_f32 v[84:85], v[84:85], v[86:87]
	v_pk_mul_f32 v[86:87], v[80:81], v[80:81]
	v_pk_mul_f32 v[84:85], v[88:89], v[84:85]
	s_nop 0
	v_pk_mul_f32 v[88:89], v[78:79], v[84:85]
	v_pk_fma_f32 v[84:85], v[78:79], v[84:85], v[78:79] neg_lo:[1,0,0] neg_hi:[1,0,0]
	v_and_b32_e32 v78, 0x7fffffff, v80
	v_cndmask_b32_e32 v88, v84, v88, vcc
	v_cmp_gt_f32_e32 vcc, 0, v79
	v_and_b32_e32 v79, 0x7fffffff, v81
	v_pk_fma_f32 v[78:79], v[78:79], s[28:29], 1.0 op_sel_hi:[1,0,0]
	v_cndmask_b32_e32 v89, v85, v89, vcc
	v_rcp_f32_e32 v78, v78
	v_rcp_f32_e32 v79, v79
	v_cmp_gt_f32_e32 vcc, 0, v80
	v_pk_fma_f32 v[84:85], v[78:79], s[30:31], v[122:123] op_sel_hi:[1,0,0]
	s_nop 0
	v_pk_fma_f32 v[84:85], v[78:79], v[84:85], s[52:53] op_sel_hi:[1,1,0]
	s_nop 0
	v_pk_fma_f32 v[84:85], v[78:79], v[84:85], s[54:55] op_sel_hi:[1,1,0]
	s_nop 0
	v_pk_fma_f32 v[84:85], v[78:79], v[84:85], s[56:57] op_sel_hi:[1,1,0]
	s_nop 0
	v_pk_mul_f32 v[78:79], v[78:79], v[84:85]
	v_pk_mul_f32 v[84:85], v[86:87], s[58:59] op_sel_hi:[1,0]
	s_nop 0
	v_exp_f32_e32 v84, v84
	v_exp_f32_e32 v85, v85
	s_nop 0
	v_pk_mul_f32 v[78:79], v[84:85], v[78:79]
	s_nop 0
	v_pk_mul_f32 v[84:85], v[80:81], v[78:79]
	v_pk_fma_f32 v[78:79], v[80:81], v[78:79], v[80:81] neg_lo:[1,0,0] neg_hi:[1,0,0]
	s_nop 0
	v_cndmask_b32_e32 v86, v78, v84, vcc
	v_cmp_gt_f32_e32 vcc, 0, v81
	v_and_b32_e32 v78, 0x7fffffff, v74
	s_nop 0
	v_cndmask_b32_e32 v87, v79, v85, vcc
	v_and_b32_e32 v79, 0x7fffffff, v75
	v_pk_fma_f32 v[78:79], v[78:79], s[28:29], 1.0 op_sel_hi:[1,0,0]
	v_pk_mul_f32 v[84:85], v[74:75], v[74:75]
	v_rcp_f32_e32 v78, v78
	v_rcp_f32_e32 v79, v79
	v_pk_mul_f32 v[84:85], v[84:85], s[58:59] op_sel_hi:[1,0]
	v_cmp_gt_f32_e32 vcc, 0, v74
	v_exp_f32_e32 v84, v84
	v_pk_fma_f32 v[80:81], v[78:79], s[30:31], v[122:123] op_sel_hi:[1,0,0]
	v_exp_f32_e32 v85, v85
	v_pk_fma_f32 v[80:81], v[78:79], v[80:81], s[52:53] op_sel_hi:[1,1,0]
	s_nop 0
	v_pk_fma_f32 v[80:81], v[78:79], v[80:81], s[54:55] op_sel_hi:[1,1,0]
	s_nop 0
	v_pk_fma_f32 v[80:81], v[78:79], v[80:81], s[56:57] op_sel_hi:[1,1,0]
	s_nop 0
	v_pk_mul_f32 v[78:79], v[78:79], v[80:81]
	v_pk_mul_f32 v[80:81], v[76:77], v[76:77]
	v_pk_mul_f32 v[78:79], v[84:85], v[78:79]
	s_nop 0
	v_pk_mul_f32 v[84:85], v[74:75], v[78:79]
	v_pk_fma_f32 v[78:79], v[74:75], v[78:79], v[74:75] neg_lo:[1,0,0] neg_hi:[1,0,0]
	v_and_b32_e32 v74, 0x7fffffff, v76
	v_cndmask_b32_e32 v84, v78, v84, vcc
	v_cmp_gt_f32_e32 vcc, 0, v75
	v_and_b32_e32 v75, 0x7fffffff, v77
	v_pk_fma_f32 v[74:75], v[74:75], s[28:29], 1.0 op_sel_hi:[1,0,0]
	v_cndmask_b32_e32 v85, v79, v85, vcc
	v_rcp_f32_e32 v74, v74
	v_rcp_f32_e32 v75, v75
	v_cmp_gt_f32_e32 vcc, 0, v76
	v_pk_fma_f32 v[78:79], v[74:75], s[30:31], v[122:123] op_sel_hi:[1,0,0]
	s_nop 0
	v_pk_fma_f32 v[78:79], v[74:75], v[78:79], s[52:53] op_sel_hi:[1,1,0]
	s_nop 0
	v_pk_fma_f32 v[78:79], v[74:75], v[78:79], s[54:55] op_sel_hi:[1,1,0]
	s_nop 0
	v_pk_fma_f32 v[78:79], v[74:75], v[78:79], s[56:57] op_sel_hi:[1,1,0]
	s_nop 0
	v_pk_mul_f32 v[74:75], v[74:75], v[78:79]
	v_pk_mul_f32 v[78:79], v[80:81], s[58:59] op_sel_hi:[1,0]
	s_nop 0
	v_exp_f32_e32 v78, v78
	v_exp_f32_e32 v79, v79
	s_nop 0
	v_pk_mul_f32 v[74:75], v[78:79], v[74:75]
	s_nop 0
	v_pk_mul_f32 v[78:79], v[76:77], v[74:75]
	v_pk_fma_f32 v[74:75], v[76:77], v[74:75], v[76:77] neg_lo:[1,0,0] neg_hi:[1,0,0]
	s_nop 0
	v_cndmask_b32_e32 v78, v74, v78, vcc
	v_cmp_gt_f32_e32 vcc, 0, v77
	v_cvt_pk_bf16_f32 v74, v88, v89
	s_nop 1
	v_cndmask_b32_e32 v77, v75, v79, vcc
	v_cvt_pk_bf16_f32 v75, v86, v87
	v_cvt_pk_bf16_f32 v76, v84, v85
	v_cvt_pk_bf16_f32 v77, v78, v77
	global_store_dwordx4 v[82:83], v[74:77], off
	v_pk_mul_f32 v[78:79], v[70:71], v[70:71]
	v_cmp_gt_f32_e32 vcc, 0, v70
	v_and_b32_e32 v75, 0x7fffffff, v71
	v_and_b32_e32 v74, 0x7fffffff, v70
	v_pk_fma_f32 v[74:75], v[74:75], s[28:29], 1.0 op_sel_hi:[1,0,0]
	v_pk_mul_f32 v[78:79], v[78:79], s[58:59] op_sel_hi:[1,0]
	v_rcp_f32_e32 v74, v74
	v_rcp_f32_e32 v75, v75
	v_exp_f32_e32 v78, v78
	v_exp_f32_e32 v79, v79
	v_pk_fma_f32 v[76:77], v[74:75], s[30:31], v[122:123] op_sel_hi:[1,0,0]
	s_nop 0
	v_pk_fma_f32 v[76:77], v[74:75], v[76:77], s[52:53] op_sel_hi:[1,1,0]
	s_nop 0
	v_pk_fma_f32 v[76:77], v[74:75], v[76:77], s[54:55] op_sel_hi:[1,1,0]
	s_nop 0
	v_pk_fma_f32 v[76:77], v[74:75], v[76:77], s[56:57] op_sel_hi:[1,1,0]
	s_nop 0
	v_pk_mul_f32 v[74:75], v[74:75], v[76:77]
	v_pk_mul_f32 v[76:77], v[72:73], v[72:73]
	v_pk_mul_f32 v[74:75], v[78:79], v[74:75]
	s_nop 0
	v_pk_mul_f32 v[78:79], v[70:71], v[74:75]
	v_pk_fma_f32 v[74:75], v[70:71], v[74:75], v[70:71] neg_lo:[1,0,0] neg_hi:[1,0,0]
; __device__ __forceinline__ unsigned cvt_pk_bf16(float lo, float hi) { unsigned r; asm volatile("v_cvt_pk_bf16_f32 %0, %1, %2" : "=v"(r) : "v"(lo), "v"(hi)); return r; }
; #define GAS __attribute__((address_space(1)))
; __device__ __forceinline__ f32x2 gelu_pk(f32x2 v) {
;     const f32x2 av = __builtin_elementwise_abs(v), d = av * 0.2316418882f + 1.0f;
;     f32x2 t; t.x = __builtin_amdgcn_rcpf(d.x); t.y = __builtin_amdgcn_rcpf(d.y);
;     f32x2 q = t * 0.5307027145f + (-0.7265760135f); q = q * t + 0.7107068705f; q = q * t + (-0.142248368f); q = q * t + 0.127414796f; q = q * t;
;     const f32x2 s = (v * v) * (-0.72134752044f);
;     f32x2 e; e.x = __builtin_amdgcn_exp2f(s.x); e.y = __builtin_amdgcn_exp2f(s.y);
;     const f32x2 m = v * (q * e), r = v - m;
;     f32x2 o; o.x = v.x < 0.f ? m.x : r.x; o.y = v.y < 0.f ? m.y : r.y; return o;
; }
;     __device__ __forceinline__ void operator()(const f32x4 (&acc)[2][2][4][2], const Unit& u, int wr, int wc, int fr, int fq, const float (&pre)[8]) const {
;     ...
;                     f32x4 v0 = acc[ai][bj][m][0], v1 = acc[ai][bj][m][1];
;                     if (RS == 1) { v0 = v0 * rsc; v1 = v1 * rsc; }
;                     if (RS == 2) { v0 = v0 * csc[bj][0]; v1 = v1 * csc[bj][1]; }
;                     if (ACT == 1) { const f32x2 a = gelu_pk((f32x2){v0[0], v0[1]}), b = gelu_pk((f32x2){v0[2], v0[3]}), c = gelu_pk((f32x2){v1[0], v1[1]}), d = gelu_pk((f32x2){v1[2], v1[3]});
;                         v0 = (f32x4){a.x, a.y, b.x, b.y}; v1 = (f32x4){c.x, c.y, d.x, d.y}; }
;                     v0 = v0 * sc; v1 = v1 * sc;
;                     if (STAT == 1) rs += (v0[0] * v0[0] + v0[1] * v0[1]) + (v0[2] * v0[2] + v0[3] * v0[3]) + (v1[0] * v1[0] + v1[1] * v1[1]) + (v1[2] * v1[2] + v1[3] * v1[3]);
;                     if (STAT == 2) {
; #pragma unroll
;                         for (int e = 0; e < 4; ++e) { cs[bj][0][e] += v0[e]; cq[bj][0][e] += v0[e] * v0[e]; cs[bj][1][e] += v1[e]; cq[bj][1][e] += v1[e] * v1[e]; } }
;                     u32x4 w; w.x = cvt_pk_bf16(v0[0], v0[1]); w.y = cvt_pk_bf16(v0[2], v0[3]); w.z = cvt_pk_bf16(v1[0], v1[1]); w.w = cvt_pk_bf16(v1[2], v1[3]);
;                     *(GAS u32x4*)(rowp + bj * 128) = w; }
	v_and_b32_e32 v70, 0x7fffffff, v72
	v_cndmask_b32_e32 v78, v74, v78, vcc
	v_cmp_gt_f32_e32 vcc, 0, v71
	v_and_b32_e32 v71, 0x7fffffff, v73
	v_pk_fma_f32 v[70:71], v[70:71], s[28:29], 1.0 op_sel_hi:[1,0,0]
	v_cndmask_b32_e32 v79, v75, v79, vcc
	v_rcp_f32_e32 v70, v70
	v_rcp_f32_e32 v71, v71
	v_cmp_gt_f32_e32 vcc, 0, v72
	v_pk_fma_f32 v[74:75], v[70:71], s[30:31], v[122:123] op_sel_hi:[1,0,0]
	s_nop 0
	v_pk_fma_f32 v[74:75], v[70:71], v[74:75], s[52:53] op_sel_hi:[1,1,0]
	s_nop 0
	v_pk_fma_f32 v[74:75], v[70:71], v[74:75], s[54:55] op_sel_hi:[1,1,0]
	s_nop 0
	v_pk_fma_f32 v[74:75], v[70:71], v[74:75], s[56:57] op_sel_hi:[1,1,0]
	s_nop 0
	v_pk_mul_f32 v[70:71], v[70:71], v[74:75]
	v_pk_mul_f32 v[74:75], v[76:77], s[58:59] op_sel_hi:[1,0]
	s_nop 0
	v_exp_f32_e32 v74, v74
	v_exp_f32_e32 v75, v75
	s_nop 0
	v_pk_mul_f32 v[70:71], v[74:75], v[70:71]
	s_nop 0
	v_pk_mul_f32 v[74:75], v[72:73], v[70:71]
	v_pk_fma_f32 v[70:71], v[72:73], v[70:71], v[72:73] neg_lo:[1,0,0] neg_hi:[1,0,0]
	s_nop 0
	v_cndmask_b32_e32 v76, v70, v74, vcc
	v_cmp_gt_f32_e32 vcc, 0, v73
	v_and_b32_e32 v70, 0x7fffffff, v66
	s_nop 0
	v_cndmask_b32_e32 v77, v71, v75, vcc
	v_and_b32_e32 v71, 0x7fffffff, v67
	v_pk_fma_f32 v[70:71], v[70:71], s[28:29], 1.0 op_sel_hi:[1,0,0]
	v_pk_mul_f32 v[74:75], v[66:67], v[66:67]
	v_rcp_f32_e32 v70, v70
	v_rcp_f32_e32 v71, v71
	v_pk_mul_f32 v[74:75], v[74:75], s[58:59] op_sel_hi:[1,0]
	v_cmp_gt_f32_e32 vcc, 0, v66
	v_exp_f32_e32 v74, v74
	v_pk_fma_f32 v[72:73], v[70:71], s[30:31], v[122:123] op_sel_hi:[1,0,0]
	v_exp_f32_e32 v75, v75
	v_pk_fma_f32 v[72:73], v[70:71], v[72:73], s[52:53] op_sel_hi:[1,1,0]
	s_nop 0
	v_pk_fma_f32 v[72:73], v[70:71], v[72:73], s[54:55] op_sel_hi:[1,1,0]
	s_nop 0
	v_pk_fma_f32 v[72:73], v[70:71], v[72:73], s[56:57] op_sel_hi:[1,1,0]
	s_nop 0
	v_pk_mul_f32 v[70:71], v[70:71], v[72:73]
	v_pk_mul_f32 v[72:73], v[68:69], v[68:69]
	v_pk_mul_f32 v[70:71], v[74:75], v[70:71]
	s_nop 0
	v_pk_mul_f32 v[74:75], v[66:67], v[70:71]
	v_pk_fma_f32 v[70:71], v[66:67], v[70:71], v[66:67] neg_lo:[1,0,0] neg_hi:[1,0,0]
	v_and_b32_e32 v66, 0x7fffffff, v68
	v_cndmask_b32_e32 v74, v70, v74, vcc
	v_cmp_gt_f32_e32 vcc, 0, v67
	v_and_b32_e32 v67, 0x7fffffff, v69
	v_pk_fma_f32 v[66:67], v[66:67], s[28:29], 1.0 op_sel_hi:[1,0,0]
	v_cndmask_b32_e32 v75, v71, v75, vcc
	v_rcp_f32_e32 v66, v66
	v_rcp_f32_e32 v67, v67
	v_cmp_gt_f32_e32 vcc, 0, v68
	v_pk_fma_f32 v[70:71], v[66:67], s[30:31], v[122:123] op_sel_hi:[1,0,0]
	s_nop 0
	v_pk_fma_f32 v[70:71], v[66:67], v[70:71], s[52:53] op_sel_hi:[1,1,0]
	s_nop 0
	v_pk_fma_f32 v[70:71], v[66:67], v[70:71], s[54:55] op_sel_hi:[1,1,0]
	s_nop 0
	v_pk_fma_f32 v[70:71], v[66:67], v[70:71], s[56:57] op_sel_hi:[1,1,0]
	s_nop 0
	v_pk_mul_f32 v[66:67], v[66:67], v[70:71]
	v_pk_mul_f32 v[70:71], v[72:73], s[58:59] op_sel_hi:[1,0]
	v_pk_mul_f32 v[72:73], v[62:63], v[62:63]
	v_exp_f32_e32 v70, v70
	v_exp_f32_e32 v71, v71
	v_pk_mul_f32 v[72:73], v[72:73], s[58:59] op_sel_hi:[1,0]
	v_pk_mul_f32 v[66:67], v[70:71], v[66:67]
	s_nop 0
	v_pk_mul_f32 v[70:71], v[68:69], v[66:67]
	v_pk_fma_f32 v[66:67], v[68:69], v[66:67], v[68:69] neg_lo:[1,0,0] neg_hi:[1,0,0]
	v_exp_f32_e32 v72, v72
	v_cndmask_b32_e32 v70, v66, v70, vcc
	v_cmp_gt_f32_e32 vcc, 0, v69
	v_cvt_pk_bf16_f32 v66, v78, v79
	v_exp_f32_e32 v73, v73
	s_nop 0
	v_cndmask_b32_e32 v69, v67, v71, vcc
	v_cvt_pk_bf16_f32 v67, v76, v77
	v_cvt_pk_bf16_f32 v68, v74, v75
	v_cvt_pk_bf16_f32 v69, v70, v69
	global_store_dwordx4 v[82:83], v[66:69], off offset:256
	v_cmp_gt_f32_e32 vcc, 0, v62
	s_nop 0
	v_and_b32_e32 v69, 0x7fffffff, v63
	v_and_b32_e32 v68, 0x7fffffff, v62
	v_pk_fma_f32 v[68:69], v[68:69], s[28:29], 1.0 op_sel_hi:[1,0,0]
	v_lshl_add_u64 v[66:67], v[150:151], 0, s[4:5]
	v_rcp_f32_e32 v68, v68
	v_rcp_f32_e32 v69, v69
	s_mov_b32 s4, 0x40000
	v_pk_fma_f32 v[70:71], v[68:69], s[30:31], v[122:123] op_sel_hi:[1,0,0]
	s_nop 0
	v_pk_fma_f32 v[70:71], v[68:69], v[70:71], s[52:53] op_sel_hi:[1,1,0]
	s_nop 0
	v_pk_fma_f32 v[70:71], v[68:69], v[70:71], s[54:55] op_sel_hi:[1,1,0]
	s_nop 0
	v_pk_fma_f32 v[70:71], v[68:69], v[70:71], s[56:57] op_sel_hi:[1,1,0]
	s_nop 0
	v_pk_mul_f32 v[68:69], v[68:69], v[70:71]
	v_pk_mul_f32 v[70:71], v[64:65], v[64:65]
	v_pk_mul_f32 v[68:69], v[72:73], v[68:69]
	s_nop 0
	v_pk_mul_f32 v[72:73], v[62:63], v[68:69]
	v_pk_fma_f32 v[68:69], v[62:63], v[68:69], v[62:63] neg_lo:[1,0,0] neg_hi:[1,0,0]
	v_and_b32_e32 v62, 0x7fffffff, v64
	v_cndmask_b32_e32 v72, v68, v72, vcc
	v_cmp_gt_f32_e32 vcc, 0, v63
	v_and_b32_e32 v63, 0x7fffffff, v65
	v_pk_fma_f32 v[62:63], v[62:63], s[28:29], 1.0 op_sel_hi:[1,0,0]
	v_cndmask_b32_e32 v73, v69, v73, vcc
	v_rcp_f32_e32 v62, v62
	v_rcp_f32_e32 v63, v63
	v_cmp_gt_f32_e32 vcc, 0, v64
	v_pk_fma_f32 v[68:69], v[62:63], s[30:31], v[122:123] op_sel_hi:[1,0,0]
	s_nop 0
	v_pk_fma_f32 v[68:69], v[62:63], v[68:69], s[52:53] op_sel_hi:[1,1,0]
	s_nop 0
	v_pk_fma_f32 v[68:69], v[62:63], v[68:69], s[54:55] op_sel_hi:[1,1,0]
	s_nop 0
	v_pk_fma_f32 v[68:69], v[62:63], v[68:69], s[56:57] op_sel_hi:[1,1,0]
	s_nop 0
	v_pk_mul_f32 v[62:63], v[62:63], v[68:69]
	v_pk_mul_f32 v[68:69], v[70:71], s[58:59] op_sel_hi:[1,0]
	s_nop 0
	v_exp_f32_e32 v68, v68
	v_exp_f32_e32 v69, v69
	s_nop 0
	v_pk_mul_f32 v[62:63], v[68:69], v[62:63]
	s_nop 0
	v_pk_mul_f32 v[68:69], v[64:65], v[62:63]
	v_pk_fma_f32 v[62:63], v[64:65], v[62:63], v[64:65] neg_lo:[1,0,0] neg_hi:[1,0,0]
	s_nop 0
	v_cndmask_b32_e32 v70, v62, v68, vcc
	v_cmp_gt_f32_e32 vcc, 0, v65
	v_and_b32_e32 v62, 0x7fffffff, v58
	s_nop 0
	v_cndmask_b32_e32 v71, v63, v69, vcc
	v_and_b32_e32 v63, 0x7fffffff, v59
	v_pk_fma_f32 v[62:63], v[62:63], s[28:29], 1.0 op_sel_hi:[1,0,0]
	v_pk_mul_f32 v[68:69], v[58:59], v[58:59]
; __device__ __forceinline__ unsigned cvt_pk_bf16(float lo, float hi) { unsigned r; asm volatile("v_cvt_pk_bf16_f32 %0, %1, %2" : "=v"(r) : "v"(lo), "v"(hi)); return r; }
; #define GAS __attribute__((address_space(1)))
; __device__ __forceinline__ f32x2 gelu_pk(f32x2 v) {
;     const f32x2 av = __builtin_elementwise_abs(v), d = av * 0.2316418882f + 1.0f;
;     f32x2 t; t.x = __builtin_amdgcn_rcpf(d.x); t.y = __builtin_amdgcn_rcpf(d.y);
;     f32x2 q = t * 0.5307027145f + (-0.7265760135f); q = q * t + 0.7107068705f; q = q * t + (-0.142248368f); q = q * t + 0.127414796f; q = q * t;
;     const f32x2 s = (v * v) * (-0.72134752044f);
;     f32x2 e; e.x = __builtin_amdgcn_exp2f(s.x); e.y = __builtin_amdgcn_exp2f(s.y);
;     const f32x2 m = v * (q * e), r = v - m;
;     f32x2 o; o.x = v.x < 0.f ? m.x : r.x; o.y = v.y < 0.f ? m.y : r.y; return o;
; }
;     __device__ __forceinline__ void operator()(const f32x4 (&acc)[2][2][4][2], const Unit& u, int wr, int wc, int fr, int fq, const float (&pre)[8]) const {
;     ...
;                     f32x4 v0 = acc[ai][bj][m][0], v1 = acc[ai][bj][m][1];
;                     if (RS == 1) { v0 = v0 * rsc; v1 = v1 * rsc; }
;                     if (RS == 2) { v0 = v0 * csc[bj][0]; v1 = v1 * csc[bj][1]; }
;                     if (ACT == 1) { const f32x2 a = gelu_pk((f32x2){v0[0], v0[1]}), b = gelu_pk((f32x2){v0[2], v0[3]}), c = gelu_pk((f32x2){v1[0], v1[1]}), d = gelu_pk((f32x2){v1[2], v1[3]});
;                         v0 = (f32x4){a.x, a.y, b.x, b.y}; v1 = (f32x4){c.x, c.y, d.x, d.y}; }
;                     v0 = v0 * sc; v1 = v1 * sc;
;                     if (STAT == 1) rs += (v0[0] * v0[0] + v0[1] * v0[1]) + (v0[2] * v0[2] + v0[3] * v0[3]) + (v1[0] * v1[0] + v1[1] * v1[1]) + (v1[2] * v1[2] + v1[3] * v1[3]);
;                     if (STAT == 2) {
; #pragma unroll
;                         for (int e = 0; e < 4; ++e) { cs[bj][0][e] += v0[e]; cq[bj][0][e] += v0[e] * v0[e]; cs[bj][1][e] += v1[e]; cq[bj][1][e] += v1[e] * v1[e]; } }
;                     u32x4 w; w.x = cvt_pk_bf16(v0[0], v0[1]); w.y = cvt_pk_bf16(v0[2], v0[3]); w.z = cvt_pk_bf16(v1[0], v1[1]); w.w = cvt_pk_bf16(v1[2], v1[3]);
;                     *(GAS u32x4*)(rowp + bj * 128) = w; }
	v_rcp_f32_e32 v62, v62
	v_rcp_f32_e32 v63, v63
	v_pk_mul_f32 v[68:69], v[68:69], s[58:59] op_sel_hi:[1,0]
	v_cmp_gt_f32_e32 vcc, 0, v58
	v_exp_f32_e32 v68, v68
	v_pk_fma_f32 v[64:65], v[62:63], s[30:31], v[122:123] op_sel_hi:[1,0,0]
	v_exp_f32_e32 v69, v69
	v_pk_fma_f32 v[64:65], v[62:63], v[64:65], s[52:53] op_sel_hi:[1,1,0]
	s_nop 0
	v_pk_fma_f32 v[64:65], v[62:63], v[64:65], s[54:55] op_sel_hi:[1,1,0]
	s_nop 0
	v_pk_fma_f32 v[64:65], v[62:63], v[64:65], s[56:57] op_sel_hi:[1,1,0]
	s_nop 0
	v_pk_mul_f32 v[62:63], v[62:63], v[64:65]
	v_pk_mul_f32 v[64:65], v[60:61], v[60:61]
	v_pk_mul_f32 v[62:63], v[68:69], v[62:63]
	s_nop 0
	v_pk_mul_f32 v[68:69], v[58:59], v[62:63]
	v_pk_fma_f32 v[62:63], v[58:59], v[62:63], v[58:59] neg_lo:[1,0,0] neg_hi:[1,0,0]
	v_and_b32_e32 v58, 0x7fffffff, v60
	v_cndmask_b32_e32 v68, v62, v68, vcc
	v_cmp_gt_f32_e32 vcc, 0, v59
	v_and_b32_e32 v59, 0x7fffffff, v61
	v_pk_fma_f32 v[58:59], v[58:59], s[28:29], 1.0 op_sel_hi:[1,0,0]
	v_cndmask_b32_e32 v69, v63, v69, vcc
	v_rcp_f32_e32 v58, v58
	v_rcp_f32_e32 v59, v59
	v_cmp_gt_f32_e32 vcc, 0, v60
	v_pk_fma_f32 v[62:63], v[58:59], s[30:31], v[122:123] op_sel_hi:[1,0,0]
	s_nop 0
	v_pk_fma_f32 v[62:63], v[58:59], v[62:63], s[52:53] op_sel_hi:[1,1,0]
	s_nop 0
	v_pk_fma_f32 v[62:63], v[58:59], v[62:63], s[54:55] op_sel_hi:[1,1,0]
	s_nop 0
	v_pk_fma_f32 v[62:63], v[58:59], v[62:63], s[56:57] op_sel_hi:[1,1,0]
	s_nop 0
	v_pk_mul_f32 v[58:59], v[58:59], v[62:63]
	v_pk_mul_f32 v[62:63], v[64:65], s[58:59] op_sel_hi:[1,0]
	s_nop 0
	v_exp_f32_e32 v62, v62
	v_exp_f32_e32 v63, v63
	s_nop 0
	v_pk_mul_f32 v[58:59], v[62:63], v[58:59]
	s_nop 0
	v_pk_mul_f32 v[62:63], v[60:61], v[58:59]
	v_pk_fma_f32 v[58:59], v[60:61], v[58:59], v[60:61] neg_lo:[1,0,0] neg_hi:[1,0,0]
	s_nop 0
	v_cndmask_b32_e32 v62, v58, v62, vcc
	v_cmp_gt_f32_e32 vcc, 0, v61
	v_cvt_pk_bf16_f32 v58, v72, v73
	s_nop 1
	v_cndmask_b32_e32 v61, v59, v63, vcc
	v_cvt_pk_bf16_f32 v59, v70, v71
	v_cvt_pk_bf16_f32 v60, v68, v69
	v_cvt_pk_bf16_f32 v61, v62, v61
	v_add_co_u32_e32 v62, vcc, s4, v150
	s_mov_b64 s[4:5], 0x48000
	s_nop 0
	v_addc_co_u32_e32 v63, vcc, 0, v151, vcc
	global_store_dwordx4 v[62:63], v[58:61], off
	v_pk_mul_f32 v[62:63], v[54:55], v[54:55]
	v_cmp_gt_f32_e32 vcc, 0, v54
	v_and_b32_e32 v59, 0x7fffffff, v55
	v_and_b32_e32 v58, 0x7fffffff, v54
	v_pk_fma_f32 v[58:59], v[58:59], s[28:29], 1.0 op_sel_hi:[1,0,0]
	v_pk_mul_f32 v[62:63], v[62:63], s[58:59] op_sel_hi:[1,0]
	v_rcp_f32_e32 v58, v58
	v_rcp_f32_e32 v59, v59
	v_exp_f32_e32 v62, v62
	v_exp_f32_e32 v63, v63
	v_pk_fma_f32 v[60:61], v[58:59], s[30:31], v[122:123] op_sel_hi:[1,0,0]
	s_nop 0
	v_pk_fma_f32 v[60:61], v[58:59], v[60:61], s[52:53] op_sel_hi:[1,1,0]
	s_nop 0
	v_pk_fma_f32 v[60:61], v[58:59], v[60:61], s[54:55] op_sel_hi:[1,1,0]
	s_nop 0
	v_pk_fma_f32 v[60:61], v[58:59], v[60:61], s[56:57] op_sel_hi:[1,1,0]
	s_nop 0
	v_pk_mul_f32 v[58:59], v[58:59], v[60:61]
	v_pk_mul_f32 v[60:61], v[56:57], v[56:57]
	v_pk_mul_f32 v[58:59], v[62:63], v[58:59]
	s_nop 0
	v_pk_mul_f32 v[62:63], v[54:55], v[58:59]
	v_pk_fma_f32 v[58:59], v[54:55], v[58:59], v[54:55] neg_lo:[1,0,0] neg_hi:[1,0,0]
	v_and_b32_e32 v54, 0x7fffffff, v56
	v_cndmask_b32_e32 v62, v58, v62, vcc
	v_cmp_gt_f32_e32 vcc, 0, v55
	v_and_b32_e32 v55, 0x7fffffff, v57
	v_pk_fma_f32 v[54:55], v[54:55], s[28:29], 1.0 op_sel_hi:[1,0,0]
	v_cndmask_b32_e32 v63, v59, v63, vcc
	v_rcp_f32_e32 v54, v54
	v_rcp_f32_e32 v55, v55
	v_cmp_gt_f32_e32 vcc, 0, v56
	v_pk_fma_f32 v[58:59], v[54:55], s[30:31], v[122:123] op_sel_hi:[1,0,0]
	s_nop 0
	v_pk_fma_f32 v[58:59], v[54:55], v[58:59], s[52:53] op_sel_hi:[1,1,0]
	s_nop 0
	v_pk_fma_f32 v[58:59], v[54:55], v[58:59], s[54:55] op_sel_hi:[1,1,0]
	s_nop 0
	v_pk_fma_f32 v[58:59], v[54:55], v[58:59], s[56:57] op_sel_hi:[1,1,0]
	s_nop 0
	v_pk_mul_f32 v[54:55], v[54:55], v[58:59]
	v_pk_mul_f32 v[58:59], v[60:61], s[58:59] op_sel_hi:[1,0]
	s_nop 0
	v_exp_f32_e32 v58, v58
	v_exp_f32_e32 v59, v59
	s_nop 0
	v_pk_mul_f32 v[54:55], v[58:59], v[54:55]
	s_nop 0
	v_pk_mul_f32 v[58:59], v[56:57], v[54:55]
	v_pk_fma_f32 v[54:55], v[56:57], v[54:55], v[56:57] neg_lo:[1,0,0] neg_hi:[1,0,0]
	s_nop 0
	v_cndmask_b32_e32 v60, v54, v58, vcc
	v_cmp_gt_f32_e32 vcc, 0, v57
	v_and_b32_e32 v54, 0x7fffffff, v50
	s_nop 0
	v_cndmask_b32_e32 v61, v55, v59, vcc
	v_and_b32_e32 v55, 0x7fffffff, v51
	v_pk_fma_f32 v[54:55], v[54:55], s[28:29], 1.0 op_sel_hi:[1,0,0]
	v_pk_mul_f32 v[58:59], v[50:51], v[50:51]
	v_rcp_f32_e32 v54, v54
	v_rcp_f32_e32 v55, v55
	v_pk_mul_f32 v[58:59], v[58:59], s[58:59] op_sel_hi:[1,0]
	v_cmp_gt_f32_e32 vcc, 0, v50
	v_exp_f32_e32 v58, v58
	v_pk_fma_f32 v[56:57], v[54:55], s[30:31], v[122:123] op_sel_hi:[1,0,0]
	v_exp_f32_e32 v59, v59
	v_pk_fma_f32 v[56:57], v[54:55], v[56:57], s[52:53] op_sel_hi:[1,1,0]
	s_nop 0
	v_pk_fma_f32 v[56:57], v[54:55], v[56:57], s[54:55] op_sel_hi:[1,1,0]
	s_nop 0
	v_pk_fma_f32 v[56:57], v[54:55], v[56:57], s[56:57] op_sel_hi:[1,1,0]
	s_nop 0
	v_pk_mul_f32 v[54:55], v[54:55], v[56:57]
	v_pk_mul_f32 v[56:57], v[52:53], v[52:53]
	v_pk_mul_f32 v[54:55], v[58:59], v[54:55]
	s_nop 0
	v_pk_mul_f32 v[58:59], v[50:51], v[54:55]
	v_pk_fma_f32 v[54:55], v[50:51], v[54:55], v[50:51] neg_lo:[1,0,0] neg_hi:[1,0,0]
	v_and_b32_e32 v50, 0x7fffffff, v52
	v_cndmask_b32_e32 v58, v54, v58, vcc
	v_cmp_gt_f32_e32 vcc, 0, v51
	v_and_b32_e32 v51, 0x7fffffff, v53
	v_pk_fma_f32 v[50:51], v[50:51], s[28:29], 1.0 op_sel_hi:[1,0,0]
	v_cndmask_b32_e32 v59, v55, v59, vcc
	v_rcp_f32_e32 v50, v50
	v_rcp_f32_e32 v51, v51
	v_cmp_gt_f32_e32 vcc, 0, v52
	v_pk_fma_f32 v[54:55], v[50:51], s[30:31], v[122:123] op_sel_hi:[1,0,0]
	s_nop 0
	v_pk_fma_f32 v[54:55], v[50:51], v[54:55], s[52:53] op_sel_hi:[1,1,0]
; __device__ __forceinline__ unsigned cvt_pk_bf16(float lo, float hi) { unsigned r; asm volatile("v_cvt_pk_bf16_f32 %0, %1, %2" : "=v"(r) : "v"(lo), "v"(hi)); return r; }
; #define GAS __attribute__((address_space(1)))
; __device__ __forceinline__ f32x2 gelu_pk(f32x2 v) {
;     const f32x2 av = __builtin_elementwise_abs(v), d = av * 0.2316418882f + 1.0f;
;     f32x2 t; t.x = __builtin_amdgcn_rcpf(d.x); t.y = __builtin_amdgcn_rcpf(d.y);
;     f32x2 q = t * 0.5307027145f + (-0.7265760135f); q = q * t + 0.7107068705f; q = q * t + (-0.142248368f); q = q * t + 0.127414796f; q = q * t;
;     const f32x2 s = (v * v) * (-0.72134752044f);
;     f32x2 e; e.x = __builtin_amdgcn_exp2f(s.x); e.y = __builtin_amdgcn_exp2f(s.y);
;     const f32x2 m = v * (q * e), r = v - m;
;     f32x2 o; o.x = v.x < 0.f ? m.x : r.x; o.y = v.y < 0.f ? m.y : r.y; return o;
; }
;     __device__ __forceinline__ void operator()(const f32x4 (&acc)[2][2][4][2], const Unit& u, int wr, int wc, int fr, int fq, const float (&pre)[8]) const {
;     ...
;                     f32x4 v0 = acc[ai][bj][m][0], v1 = acc[ai][bj][m][1];
;                     if (RS == 1) { v0 = v0 * rsc; v1 = v1 * rsc; }
;                     if (RS == 2) { v0 = v0 * csc[bj][0]; v1 = v1 * csc[bj][1]; }
;                     if (ACT == 1) { const f32x2 a = gelu_pk((f32x2){v0[0], v0[1]}), b = gelu_pk((f32x2){v0[2], v0[3]}), c = gelu_pk((f32x2){v1[0], v1[1]}), d = gelu_pk((f32x2){v1[2], v1[3]});
;                         v0 = (f32x4){a.x, a.y, b.x, b.y}; v1 = (f32x4){c.x, c.y, d.x, d.y}; }
;                     v0 = v0 * sc; v1 = v1 * sc;
;                     if (STAT == 1) rs += (v0[0] * v0[0] + v0[1] * v0[1]) + (v0[2] * v0[2] + v0[3] * v0[3]) + (v1[0] * v1[0] + v1[1] * v1[1]) + (v1[2] * v1[2] + v1[3] * v1[3]);
;                     if (STAT == 2) {
; #pragma unroll
;                         for (int e = 0; e < 4; ++e) { cs[bj][0][e] += v0[e]; cq[bj][0][e] += v0[e] * v0[e]; cs[bj][1][e] += v1[e]; cq[bj][1][e] += v1[e] * v1[e]; } }
;                     u32x4 w; w.x = cvt_pk_bf16(v0[0], v0[1]); w.y = cvt_pk_bf16(v0[2], v0[3]); w.z = cvt_pk_bf16(v1[0], v1[1]); w.w = cvt_pk_bf16(v1[2], v1[3]);
;                     *(GAS u32x4*)(rowp + bj * 128) = w; }
	s_nop 0
	v_pk_fma_f32 v[54:55], v[50:51], v[54:55], s[54:55] op_sel_hi:[1,1,0]
	s_nop 0
	v_pk_fma_f32 v[54:55], v[50:51], v[54:55], s[56:57] op_sel_hi:[1,1,0]
	s_nop 0
	v_pk_mul_f32 v[50:51], v[50:51], v[54:55]
	v_pk_mul_f32 v[54:55], v[56:57], s[58:59] op_sel_hi:[1,0]
	v_pk_mul_f32 v[56:57], v[46:47], v[46:47]
	v_exp_f32_e32 v54, v54
	v_exp_f32_e32 v55, v55
	v_pk_mul_f32 v[56:57], v[56:57], s[58:59] op_sel_hi:[1,0]
	v_pk_mul_f32 v[50:51], v[54:55], v[50:51]
	s_nop 0
	v_pk_mul_f32 v[54:55], v[52:53], v[50:51]
	v_pk_fma_f32 v[50:51], v[52:53], v[50:51], v[52:53] neg_lo:[1,0,0] neg_hi:[1,0,0]
	v_exp_f32_e32 v56, v56
	v_cndmask_b32_e32 v54, v50, v54, vcc
	v_cmp_gt_f32_e32 vcc, 0, v53
	v_cvt_pk_bf16_f32 v50, v62, v63
	v_exp_f32_e32 v57, v57
	s_nop 0
	v_cndmask_b32_e32 v53, v51, v55, vcc
	v_cvt_pk_bf16_f32 v51, v60, v61
	v_cvt_pk_bf16_f32 v52, v58, v59
	v_cvt_pk_bf16_f32 v53, v54, v53
	global_store_dwordx4 v[66:67], v[50:53], off offset:256
	v_cmp_gt_f32_e32 vcc, 0, v46
	s_nop 0
	v_and_b32_e32 v53, 0x7fffffff, v47
	v_and_b32_e32 v52, 0x7fffffff, v46
	v_pk_fma_f32 v[52:53], v[52:53], s[28:29], 1.0 op_sel_hi:[1,0,0]
	v_lshl_add_u64 v[50:51], v[150:151], 0, s[4:5]
	v_rcp_f32_e32 v52, v52
	v_rcp_f32_e32 v53, v53
	s_mov_b32 s4, 0x48000
	v_pk_fma_f32 v[54:55], v[52:53], s[30:31], v[122:123] op_sel_hi:[1,0,0]
	s_nop 0
	v_pk_fma_f32 v[54:55], v[52:53], v[54:55], s[52:53] op_sel_hi:[1,1,0]
	s_nop 0
	v_pk_fma_f32 v[54:55], v[52:53], v[54:55], s[54:55] op_sel_hi:[1,1,0]
	s_nop 0
	v_pk_fma_f32 v[54:55], v[52:53], v[54:55], s[56:57] op_sel_hi:[1,1,0]
	s_nop 0
	v_pk_mul_f32 v[52:53], v[52:53], v[54:55]
	v_pk_mul_f32 v[54:55], v[48:49], v[48:49]
	v_pk_mul_f32 v[52:53], v[56:57], v[52:53]
	s_nop 0
	v_pk_mul_f32 v[56:57], v[46:47], v[52:53]
	v_pk_fma_f32 v[52:53], v[46:47], v[52:53], v[46:47] neg_lo:[1,0,0] neg_hi:[1,0,0]
	v_and_b32_e32 v46, 0x7fffffff, v48
	v_cndmask_b32_e32 v56, v52, v56, vcc
	v_cmp_gt_f32_e32 vcc, 0, v47
	v_and_b32_e32 v47, 0x7fffffff, v49
	v_pk_fma_f32 v[46:47], v[46:47], s[28:29], 1.0 op_sel_hi:[1,0,0]
	v_cndmask_b32_e32 v57, v53, v57, vcc
	v_rcp_f32_e32 v46, v46
	v_rcp_f32_e32 v47, v47
	v_cmp_gt_f32_e32 vcc, 0, v48
	v_pk_fma_f32 v[52:53], v[46:47], s[30:31], v[122:123] op_sel_hi:[1,0,0]
	s_nop 0
	v_pk_fma_f32 v[52:53], v[46:47], v[52:53], s[52:53] op_sel_hi:[1,1,0]
	s_nop 0
	v_pk_fma_f32 v[52:53], v[46:47], v[52:53], s[54:55] op_sel_hi:[1,1,0]
	s_nop 0
	v_pk_fma_f32 v[52:53], v[46:47], v[52:53], s[56:57] op_sel_hi:[1,1,0]
	s_nop 0
	v_pk_mul_f32 v[46:47], v[46:47], v[52:53]
	v_pk_mul_f32 v[52:53], v[54:55], s[58:59] op_sel_hi:[1,0]
	s_nop 0
	v_exp_f32_e32 v52, v52
	v_exp_f32_e32 v53, v53
	s_nop 0
	v_pk_mul_f32 v[46:47], v[52:53], v[46:47]
	s_nop 0
	v_pk_mul_f32 v[52:53], v[48:49], v[46:47]
	v_pk_fma_f32 v[46:47], v[48:49], v[46:47], v[48:49] neg_lo:[1,0,0] neg_hi:[1,0,0]
	s_nop 0
	v_cndmask_b32_e32 v54, v46, v52, vcc
	v_cmp_gt_f32_e32 vcc, 0, v49
	v_and_b32_e32 v46, 0x7fffffff, v42
	s_nop 0
	v_cndmask_b32_e32 v55, v47, v53, vcc
	v_and_b32_e32 v47, 0x7fffffff, v43
	v_pk_fma_f32 v[46:47], v[46:47], s[28:29], 1.0 op_sel_hi:[1,0,0]
	v_pk_mul_f32 v[52:53], v[42:43], v[42:43]
	v_rcp_f32_e32 v46, v46
	v_rcp_f32_e32 v47, v47
	v_pk_mul_f32 v[52:53], v[52:53], s[58:59] op_sel_hi:[1,0]
	v_cmp_gt_f32_e32 vcc, 0, v42
	v_exp_f32_e32 v52, v52
	v_pk_fma_f32 v[48:49], v[46:47], s[30:31], v[122:123] op_sel_hi:[1,0,0]
	v_exp_f32_e32 v53, v53
	v_pk_fma_f32 v[48:49], v[46:47], v[48:49], s[52:53] op_sel_hi:[1,1,0]
	s_nop 0
	v_pk_fma_f32 v[48:49], v[46:47], v[48:49], s[54:55] op_sel_hi:[1,1,0]
	s_nop 0
	v_pk_fma_f32 v[48:49], v[46:47], v[48:49], s[56:57] op_sel_hi:[1,1,0]
	s_nop 0
	v_pk_mul_f32 v[46:47], v[46:47], v[48:49]
	v_pk_mul_f32 v[48:49], v[44:45], v[44:45]
	v_pk_mul_f32 v[46:47], v[52:53], v[46:47]
	s_nop 0
	v_pk_mul_f32 v[52:53], v[42:43], v[46:47]
	v_pk_fma_f32 v[46:47], v[42:43], v[46:47], v[42:43] neg_lo:[1,0,0] neg_hi:[1,0,0]
	v_and_b32_e32 v42, 0x7fffffff, v44
	v_cndmask_b32_e32 v52, v46, v52, vcc
	v_cmp_gt_f32_e32 vcc, 0, v43
	v_and_b32_e32 v43, 0x7fffffff, v45
	v_pk_fma_f32 v[42:43], v[42:43], s[28:29], 1.0 op_sel_hi:[1,0,0]
	v_cndmask_b32_e32 v53, v47, v53, vcc
	v_rcp_f32_e32 v42, v42
	v_rcp_f32_e32 v43, v43
	v_cmp_gt_f32_e32 vcc, 0, v44
	v_pk_fma_f32 v[46:47], v[42:43], s[30:31], v[122:123] op_sel_hi:[1,0,0]
	s_nop 0
	v_pk_fma_f32 v[46:47], v[42:43], v[46:47], s[52:53] op_sel_hi:[1,1,0]
	s_nop 0
	v_pk_fma_f32 v[46:47], v[42:43], v[46:47], s[54:55] op_sel_hi:[1,1,0]
	s_nop 0
	v_pk_fma_f32 v[46:47], v[42:43], v[46:47], s[56:57] op_sel_hi:[1,1,0]
	s_nop 0
	v_pk_mul_f32 v[42:43], v[42:43], v[46:47]
	v_pk_mul_f32 v[46:47], v[48:49], s[58:59] op_sel_hi:[1,0]
	s_nop 0
	v_exp_f32_e32 v46, v46
	v_exp_f32_e32 v47, v47
	s_nop 0
	v_pk_mul_f32 v[42:43], v[46:47], v[42:43]
	s_nop 0
	v_pk_mul_f32 v[46:47], v[44:45], v[42:43]
	v_pk_fma_f32 v[42:43], v[44:45], v[42:43], v[44:45] neg_lo:[1,0,0] neg_hi:[1,0,0]
	s_nop 0
	v_cndmask_b32_e32 v46, v42, v46, vcc
	v_cmp_gt_f32_e32 vcc, 0, v45
	v_cvt_pk_bf16_f32 v42, v56, v57
	s_nop 1
	v_cndmask_b32_e32 v45, v43, v47, vcc
	v_cvt_pk_bf16_f32 v43, v54, v55
	v_cvt_pk_bf16_f32 v44, v52, v53
	v_cvt_pk_bf16_f32 v45, v46, v45
	v_add_co_u32_e32 v46, vcc, s4, v150
	s_mov_b64 s[4:5], 0x50000
	s_nop 0
	v_addc_co_u32_e32 v47, vcc, 0, v151, vcc
	global_store_dwordx4 v[46:47], v[42:45], off
	v_pk_mul_f32 v[46:47], v[38:39], v[38:39]
	v_cmp_gt_f32_e32 vcc, 0, v38
	v_and_b32_e32 v43, 0x7fffffff, v39
	v_and_b32_e32 v42, 0x7fffffff, v38
	v_pk_fma_f32 v[42:43], v[42:43], s[28:29], 1.0 op_sel_hi:[1,0,0]
	v_pk_mul_f32 v[46:47], v[46:47], s[58:59] op_sel_hi:[1,0]
	v_rcp_f32_e32 v42, v42
	v_rcp_f32_e32 v43, v43
	v_exp_f32_e32 v46, v46
; __device__ __forceinline__ unsigned cvt_pk_bf16(float lo, float hi) { unsigned r; asm volatile("v_cvt_pk_bf16_f32 %0, %1, %2" : "=v"(r) : "v"(lo), "v"(hi)); return r; }
; #define GAS __attribute__((address_space(1)))
; __device__ __forceinline__ f32x2 gelu_pk(f32x2 v) {
;     const f32x2 av = __builtin_elementwise_abs(v), d = av * 0.2316418882f + 1.0f;
;     f32x2 t; t.x = __builtin_amdgcn_rcpf(d.x); t.y = __builtin_amdgcn_rcpf(d.y);
;     f32x2 q = t * 0.5307027145f + (-0.7265760135f); q = q * t + 0.7107068705f; q = q * t + (-0.142248368f); q = q * t + 0.127414796f; q = q * t;
;     const f32x2 s = (v * v) * (-0.72134752044f);
;     f32x2 e; e.x = __builtin_amdgcn_exp2f(s.x); e.y = __builtin_amdgcn_exp2f(s.y);
;     const f32x2 m = v * (q * e), r = v - m;
;     f32x2 o; o.x = v.x < 0.f ? m.x : r.x; o.y = v.y < 0.f ? m.y : r.y; return o;
; }
;     __device__ __forceinline__ void operator()(const f32x4 (&acc)[2][2][4][2], const Unit& u, int wr, int wc, int fr, int fq, const float (&pre)[8]) const {
;     ...
;                     f32x4 v0 = acc[ai][bj][m][0], v1 = acc[ai][bj][m][1];
;                     if (RS == 1) { v0 = v0 * rsc; v1 = v1 * rsc; }
;                     if (RS == 2) { v0 = v0 * csc[bj][0]; v1 = v1 * csc[bj][1]; }
;                     if (ACT == 1) { const f32x2 a = gelu_pk((f32x2){v0[0], v0[1]}), b = gelu_pk((f32x2){v0[2], v0[3]}), c = gelu_pk((f32x2){v1[0], v1[1]}), d = gelu_pk((f32x2){v1[2], v1[3]});
;                         v0 = (f32x4){a.x, a.y, b.x, b.y}; v1 = (f32x4){c.x, c.y, d.x, d.y}; }
;                     v0 = v0 * sc; v1 = v1 * sc;
;                     if (STAT == 1) rs += (v0[0] * v0[0] + v0[1] * v0[1]) + (v0[2] * v0[2] + v0[3] * v0[3]) + (v1[0] * v1[0] + v1[1] * v1[1]) + (v1[2] * v1[2] + v1[3] * v1[3]);
;                     if (STAT == 2) {
; #pragma unroll
;                         for (int e = 0; e < 4; ++e) { cs[bj][0][e] += v0[e]; cq[bj][0][e] += v0[e] * v0[e]; cs[bj][1][e] += v1[e]; cq[bj][1][e] += v1[e] * v1[e]; } }
;                     u32x4 w; w.x = cvt_pk_bf16(v0[0], v0[1]); w.y = cvt_pk_bf16(v0[2], v0[3]); w.z = cvt_pk_bf16(v1[0], v1[1]); w.w = cvt_pk_bf16(v1[2], v1[3]);
;                     *(GAS u32x4*)(rowp + bj * 128) = w; }
	v_exp_f32_e32 v47, v47
	v_pk_fma_f32 v[44:45], v[42:43], s[30:31], v[122:123] op_sel_hi:[1,0,0]
	s_nop 0
	v_pk_fma_f32 v[44:45], v[42:43], v[44:45], s[52:53] op_sel_hi:[1,1,0]
	s_nop 0
	v_pk_fma_f32 v[44:45], v[42:43], v[44:45], s[54:55] op_sel_hi:[1,1,0]
	s_nop 0
	v_pk_fma_f32 v[44:45], v[42:43], v[44:45], s[56:57] op_sel_hi:[1,1,0]
	s_nop 0
	v_pk_mul_f32 v[42:43], v[42:43], v[44:45]
	v_pk_mul_f32 v[44:45], v[40:41], v[40:41]
	v_pk_mul_f32 v[42:43], v[46:47], v[42:43]
	s_nop 0
	v_pk_mul_f32 v[46:47], v[38:39], v[42:43]
	v_pk_fma_f32 v[42:43], v[38:39], v[42:43], v[38:39] neg_lo:[1,0,0] neg_hi:[1,0,0]
	v_and_b32_e32 v38, 0x7fffffff, v40
	v_cndmask_b32_e32 v46, v42, v46, vcc
	v_cmp_gt_f32_e32 vcc, 0, v39
	v_and_b32_e32 v39, 0x7fffffff, v41
	v_pk_fma_f32 v[38:39], v[38:39], s[28:29], 1.0 op_sel_hi:[1,0,0]
	v_cndmask_b32_e32 v47, v43, v47, vcc
	v_rcp_f32_e32 v38, v38
	v_rcp_f32_e32 v39, v39
	v_cmp_gt_f32_e32 vcc, 0, v40
	v_pk_fma_f32 v[42:43], v[38:39], s[30:31], v[122:123] op_sel_hi:[1,0,0]
	s_nop 0
	v_pk_fma_f32 v[42:43], v[38:39], v[42:43], s[52:53] op_sel_hi:[1,1,0]
	s_nop 0
	v_pk_fma_f32 v[42:43], v[38:39], v[42:43], s[54:55] op_sel_hi:[1,1,0]
	s_nop 0
	v_pk_fma_f32 v[42:43], v[38:39], v[42:43], s[56:57] op_sel_hi:[1,1,0]
	s_nop 0
	v_pk_mul_f32 v[38:39], v[38:39], v[42:43]
	v_pk_mul_f32 v[42:43], v[44:45], s[58:59] op_sel_hi:[1,0]
	s_nop 0
	v_exp_f32_e32 v42, v42
	v_exp_f32_e32 v43, v43
	s_nop 0
	v_pk_mul_f32 v[38:39], v[42:43], v[38:39]
	s_nop 0
	v_pk_mul_f32 v[42:43], v[40:41], v[38:39]
	v_pk_fma_f32 v[38:39], v[40:41], v[38:39], v[40:41] neg_lo:[1,0,0] neg_hi:[1,0,0]
	s_nop 0
	v_cndmask_b32_e32 v44, v38, v42, vcc
	v_cmp_gt_f32_e32 vcc, 0, v41
	v_and_b32_e32 v38, 0x7fffffff, v34
	s_nop 0
	v_cndmask_b32_e32 v45, v39, v43, vcc
	v_and_b32_e32 v39, 0x7fffffff, v35
	v_pk_fma_f32 v[38:39], v[38:39], s[28:29], 1.0 op_sel_hi:[1,0,0]
	v_pk_mul_f32 v[42:43], v[34:35], v[34:35]
	v_rcp_f32_e32 v38, v38
	v_rcp_f32_e32 v39, v39
	v_pk_mul_f32 v[42:43], v[42:43], s[58:59] op_sel_hi:[1,0]
	v_cmp_gt_f32_e32 vcc, 0, v34
	v_exp_f32_e32 v42, v42
	v_pk_fma_f32 v[40:41], v[38:39], s[30:31], v[122:123] op_sel_hi:[1,0,0]
	v_exp_f32_e32 v43, v43
	v_pk_fma_f32 v[40:41], v[38:39], v[40:41], s[52:53] op_sel_hi:[1,1,0]
	s_nop 0
	v_pk_fma_f32 v[40:41], v[38:39], v[40:41], s[54:55] op_sel_hi:[1,1,0]
	s_nop 0
	v_pk_fma_f32 v[40:41], v[38:39], v[40:41], s[56:57] op_sel_hi:[1,1,0]
	s_nop 0
	v_pk_mul_f32 v[38:39], v[38:39], v[40:41]
	v_pk_mul_f32 v[40:41], v[36:37], v[36:37]
	v_pk_mul_f32 v[38:39], v[42:43], v[38:39]
	s_nop 0
	v_pk_mul_f32 v[42:43], v[34:35], v[38:39]
	v_pk_fma_f32 v[38:39], v[34:35], v[38:39], v[34:35] neg_lo:[1,0,0] neg_hi:[1,0,0]
	v_and_b32_e32 v34, 0x7fffffff, v36
	v_cndmask_b32_e32 v42, v38, v42, vcc
	v_cmp_gt_f32_e32 vcc, 0, v35
	v_and_b32_e32 v35, 0x7fffffff, v37
	v_pk_fma_f32 v[34:35], v[34:35], s[28:29], 1.0 op_sel_hi:[1,0,0]
	v_cndmask_b32_e32 v43, v39, v43, vcc
	v_rcp_f32_e32 v34, v34
	v_rcp_f32_e32 v35, v35
	v_cmp_gt_f32_e32 vcc, 0, v36
	v_pk_fma_f32 v[38:39], v[34:35], s[30:31], v[122:123] op_sel_hi:[1,0,0]
	s_nop 0
	v_pk_fma_f32 v[38:39], v[34:35], v[38:39], s[52:53] op_sel_hi:[1,1,0]
	s_nop 0
	v_pk_fma_f32 v[38:39], v[34:35], v[38:39], s[54:55] op_sel_hi:[1,1,0]
	s_nop 0
	v_pk_fma_f32 v[38:39], v[34:35], v[38:39], s[56:57] op_sel_hi:[1,1,0]
	s_nop 0
	v_pk_mul_f32 v[34:35], v[34:35], v[38:39]
	v_pk_mul_f32 v[38:39], v[40:41], s[58:59] op_sel_hi:[1,0]
	v_pk_mul_f32 v[40:41], v[28:29], v[28:29]
	v_exp_f32_e32 v38, v38
	v_exp_f32_e32 v39, v39
	v_pk_mul_f32 v[40:41], v[40:41], s[58:59] op_sel_hi:[1,0]
	v_pk_mul_f32 v[34:35], v[38:39], v[34:35]
	s_nop 0
	v_pk_mul_f32 v[38:39], v[36:37], v[34:35]
	v_pk_fma_f32 v[34:35], v[36:37], v[34:35], v[36:37] neg_lo:[1,0,0] neg_hi:[1,0,0]
	v_exp_f32_e32 v40, v40
	v_cndmask_b32_e32 v38, v34, v38, vcc
	v_cmp_gt_f32_e32 vcc, 0, v37
	v_cvt_pk_bf16_f32 v34, v46, v47
	v_exp_f32_e32 v41, v41
	s_nop 0
	v_cndmask_b32_e32 v37, v35, v39, vcc
	v_cvt_pk_bf16_f32 v35, v44, v45
	v_cvt_pk_bf16_f32 v36, v42, v43
	v_cvt_pk_bf16_f32 v37, v38, v37
	global_store_dwordx4 v[50:51], v[34:37], off offset:256
	v_cmp_gt_f32_e32 vcc, 0, v28
	s_nop 0
	v_and_b32_e32 v37, 0x7fffffff, v29
	v_and_b32_e32 v36, 0x7fffffff, v28
	v_pk_fma_f32 v[36:37], v[36:37], s[28:29], 1.0 op_sel_hi:[1,0,0]
	v_lshl_add_u64 v[34:35], v[150:151], 0, s[4:5]
	v_rcp_f32_e32 v36, v36
	v_rcp_f32_e32 v37, v37
	s_mov_b32 s4, 0x50000
	v_pk_fma_f32 v[38:39], v[36:37], s[30:31], v[122:123] op_sel_hi:[1,0,0]
	s_nop 0
	v_pk_fma_f32 v[38:39], v[36:37], v[38:39], s[52:53] op_sel_hi:[1,1,0]
	s_nop 0
	v_pk_fma_f32 v[38:39], v[36:37], v[38:39], s[54:55] op_sel_hi:[1,1,0]
	s_nop 0
	v_pk_fma_f32 v[38:39], v[36:37], v[38:39], s[56:57] op_sel_hi:[1,1,0]
	s_nop 0
	v_pk_mul_f32 v[36:37], v[36:37], v[38:39]
	v_pk_mul_f32 v[38:39], v[30:31], v[30:31]
	v_pk_mul_f32 v[36:37], v[40:41], v[36:37]
	s_nop 0
	v_pk_mul_f32 v[40:41], v[28:29], v[36:37]
	v_pk_fma_f32 v[36:37], v[28:29], v[36:37], v[28:29] neg_lo:[1,0,0] neg_hi:[1,0,0]
	v_and_b32_e32 v28, 0x7fffffff, v30
	v_cndmask_b32_e32 v40, v36, v40, vcc
	v_cmp_gt_f32_e32 vcc, 0, v29
	v_and_b32_e32 v29, 0x7fffffff, v31
	v_pk_fma_f32 v[28:29], v[28:29], s[28:29], 1.0 op_sel_hi:[1,0,0]
	v_cndmask_b32_e32 v41, v37, v41, vcc
	v_rcp_f32_e32 v28, v28
	v_rcp_f32_e32 v29, v29
	v_cmp_gt_f32_e32 vcc, 0, v30
	v_pk_fma_f32 v[36:37], v[28:29], s[30:31], v[122:123] op_sel_hi:[1,0,0]
	s_nop 0
	v_pk_fma_f32 v[36:37], v[28:29], v[36:37], s[52:53] op_sel_hi:[1,1,0]
	s_nop 0
	v_pk_fma_f32 v[36:37], v[28:29], v[36:37], s[54:55] op_sel_hi:[1,1,0]
	s_nop 0
	v_pk_fma_f32 v[36:37], v[28:29], v[36:37], s[56:57] op_sel_hi:[1,1,0]
	s_nop 0
; __device__ __forceinline__ unsigned cvt_pk_bf16(float lo, float hi) { unsigned r; asm volatile("v_cvt_pk_bf16_f32 %0, %1, %2" : "=v"(r) : "v"(lo), "v"(hi)); return r; }
; #define GAS __attribute__((address_space(1)))
; __device__ __forceinline__ f32x2 gelu_pk(f32x2 v) {
;     const f32x2 av = __builtin_elementwise_abs(v), d = av * 0.2316418882f + 1.0f;
;     f32x2 t; t.x = __builtin_amdgcn_rcpf(d.x); t.y = __builtin_amdgcn_rcpf(d.y);
;     f32x2 q = t * 0.5307027145f + (-0.7265760135f); q = q * t + 0.7107068705f; q = q * t + (-0.142248368f); q = q * t + 0.127414796f; q = q * t;
;     const f32x2 s = (v * v) * (-0.72134752044f);
;     f32x2 e; e.x = __builtin_amdgcn_exp2f(s.x); e.y = __builtin_amdgcn_exp2f(s.y);
;     const f32x2 m = v * (q * e), r = v - m;
;     f32x2 o; o.x = v.x < 0.f ? m.x : r.x; o.y = v.y < 0.f ? m.y : r.y; return o;
; }
;     __device__ __forceinline__ void operator()(const f32x4 (&acc)[2][2][4][2], const Unit& u, int wr, int wc, int fr, int fq, const float (&pre)[8]) const {
;     ...
;                     f32x4 v0 = acc[ai][bj][m][0], v1 = acc[ai][bj][m][1];
;                     if (RS == 1) { v0 = v0 * rsc; v1 = v1 * rsc; }
;                     if (RS == 2) { v0 = v0 * csc[bj][0]; v1 = v1 * csc[bj][1]; }
;                     if (ACT == 1) { const f32x2 a = gelu_pk((f32x2){v0[0], v0[1]}), b = gelu_pk((f32x2){v0[2], v0[3]}), c = gelu_pk((f32x2){v1[0], v1[1]}), d = gelu_pk((f32x2){v1[2], v1[3]});
;                         v0 = (f32x4){a.x, a.y, b.x, b.y}; v1 = (f32x4){c.x, c.y, d.x, d.y}; }
;                     v0 = v0 * sc; v1 = v1 * sc;
;                     if (STAT == 1) rs += (v0[0] * v0[0] + v0[1] * v0[1]) + (v0[2] * v0[2] + v0[3] * v0[3]) + (v1[0] * v1[0] + v1[1] * v1[1]) + (v1[2] * v1[2] + v1[3] * v1[3]);
;                     if (STAT == 2) {
; #pragma unroll
;                         for (int e = 0; e < 4; ++e) { cs[bj][0][e] += v0[e]; cq[bj][0][e] += v0[e] * v0[e]; cs[bj][1][e] += v1[e]; cq[bj][1][e] += v1[e] * v1[e]; } }
;                     u32x4 w; w.x = cvt_pk_bf16(v0[0], v0[1]); w.y = cvt_pk_bf16(v0[2], v0[3]); w.z = cvt_pk_bf16(v1[0], v1[1]); w.w = cvt_pk_bf16(v1[2], v1[3]);
;                     *(GAS u32x4*)(rowp + bj * 128) = w; }
	v_pk_mul_f32 v[28:29], v[28:29], v[36:37]
	v_pk_mul_f32 v[36:37], v[38:39], s[58:59] op_sel_hi:[1,0]
	s_nop 0
	v_exp_f32_e32 v36, v36
	v_exp_f32_e32 v37, v37
	s_nop 0
	v_pk_mul_f32 v[28:29], v[36:37], v[28:29]
	s_nop 0
	v_pk_mul_f32 v[36:37], v[30:31], v[28:29]
	v_pk_fma_f32 v[28:29], v[30:31], v[28:29], v[30:31] neg_lo:[1,0,0] neg_hi:[1,0,0]
	s_nop 0
	v_cndmask_b32_e32 v38, v28, v36, vcc
	v_cmp_gt_f32_e32 vcc, 0, v31
	v_and_b32_e32 v28, 0x7fffffff, v24
	s_nop 0
	v_cndmask_b32_e32 v39, v29, v37, vcc
	v_and_b32_e32 v29, 0x7fffffff, v25
	v_pk_fma_f32 v[28:29], v[28:29], s[28:29], 1.0 op_sel_hi:[1,0,0]
	v_pk_mul_f32 v[36:37], v[24:25], v[24:25]
	v_rcp_f32_e32 v28, v28
	v_rcp_f32_e32 v29, v29
	v_pk_mul_f32 v[36:37], v[36:37], s[58:59] op_sel_hi:[1,0]
	v_cmp_gt_f32_e32 vcc, 0, v24
	v_exp_f32_e32 v36, v36
	v_pk_fma_f32 v[30:31], v[28:29], s[30:31], v[122:123] op_sel_hi:[1,0,0]
	v_exp_f32_e32 v37, v37
	v_pk_fma_f32 v[30:31], v[28:29], v[30:31], s[52:53] op_sel_hi:[1,1,0]
	s_nop 0
	v_pk_fma_f32 v[30:31], v[28:29], v[30:31], s[54:55] op_sel_hi:[1,1,0]
	s_nop 0
	v_pk_fma_f32 v[30:31], v[28:29], v[30:31], s[56:57] op_sel_hi:[1,1,0]
	s_nop 0
	v_pk_mul_f32 v[28:29], v[28:29], v[30:31]
	v_pk_mul_f32 v[30:31], v[26:27], v[26:27]
	v_pk_mul_f32 v[28:29], v[36:37], v[28:29]
	s_nop 0
	v_pk_mul_f32 v[36:37], v[24:25], v[28:29]
	v_pk_fma_f32 v[28:29], v[24:25], v[28:29], v[24:25] neg_lo:[1,0,0] neg_hi:[1,0,0]
	v_and_b32_e32 v24, 0x7fffffff, v26
	v_cndmask_b32_e32 v36, v28, v36, vcc
	v_cmp_gt_f32_e32 vcc, 0, v25
	v_and_b32_e32 v25, 0x7fffffff, v27
	v_pk_fma_f32 v[24:25], v[24:25], s[28:29], 1.0 op_sel_hi:[1,0,0]
	v_cndmask_b32_e32 v37, v29, v37, vcc
	v_rcp_f32_e32 v24, v24
	v_rcp_f32_e32 v25, v25
	v_cmp_gt_f32_e32 vcc, 0, v26
	v_pk_fma_f32 v[28:29], v[24:25], s[30:31], v[122:123] op_sel_hi:[1,0,0]
	s_nop 0
	v_pk_fma_f32 v[28:29], v[24:25], v[28:29], s[52:53] op_sel_hi:[1,1,0]
	s_nop 0
	v_pk_fma_f32 v[28:29], v[24:25], v[28:29], s[54:55] op_sel_hi:[1,1,0]
	s_nop 0
	v_pk_fma_f32 v[28:29], v[24:25], v[28:29], s[56:57] op_sel_hi:[1,1,0]
	s_nop 0
	v_pk_mul_f32 v[24:25], v[24:25], v[28:29]
	v_pk_mul_f32 v[28:29], v[30:31], s[58:59] op_sel_hi:[1,0]
	s_nop 0
	v_exp_f32_e32 v28, v28
	v_exp_f32_e32 v29, v29
	s_nop 0
	v_pk_mul_f32 v[24:25], v[28:29], v[24:25]
	s_nop 0
	v_pk_mul_f32 v[28:29], v[26:27], v[24:25]
	v_pk_fma_f32 v[24:25], v[26:27], v[24:25], v[26:27] neg_lo:[1,0,0] neg_hi:[1,0,0]
	s_nop 0
	v_cndmask_b32_e32 v28, v24, v28, vcc
	v_cmp_gt_f32_e32 vcc, 0, v27
	v_cvt_pk_bf16_f32 v24, v40, v41
	s_nop 1
	v_cndmask_b32_e32 v27, v25, v29, vcc
	v_cvt_pk_bf16_f32 v25, v38, v39
	v_cvt_pk_bf16_f32 v26, v36, v37
	v_cvt_pk_bf16_f32 v27, v28, v27
	v_add_co_u32_e32 v28, vcc, s4, v150
	s_mov_b64 s[4:5], 0x58000
	s_nop 0
	v_addc_co_u32_e32 v29, vcc, 0, v151, vcc
	global_store_dwordx4 v[28:29], v[24:27], off
	v_pk_mul_f32 v[28:29], v[20:21], v[20:21]
	v_cmp_gt_f32_e32 vcc, 0, v20
	v_and_b32_e32 v25, 0x7fffffff, v21
	v_and_b32_e32 v24, 0x7fffffff, v20
	v_pk_fma_f32 v[24:25], v[24:25], s[28:29], 1.0 op_sel_hi:[1,0,0]
	v_pk_mul_f32 v[28:29], v[28:29], s[58:59] op_sel_hi:[1,0]
	v_rcp_f32_e32 v24, v24
	v_rcp_f32_e32 v25, v25
	v_exp_f32_e32 v28, v28
	v_exp_f32_e32 v29, v29
	v_pk_fma_f32 v[26:27], v[24:25], s[30:31], v[122:123] op_sel_hi:[1,0,0]
	s_nop 0
	v_pk_fma_f32 v[26:27], v[24:25], v[26:27], s[52:53] op_sel_hi:[1,1,0]
	s_nop 0
	v_pk_fma_f32 v[26:27], v[24:25], v[26:27], s[54:55] op_sel_hi:[1,1,0]
	s_nop 0
	v_pk_fma_f32 v[26:27], v[24:25], v[26:27], s[56:57] op_sel_hi:[1,1,0]
	s_nop 0
	v_pk_mul_f32 v[24:25], v[24:25], v[26:27]
	v_pk_mul_f32 v[26:27], v[22:23], v[22:23]
	v_pk_mul_f32 v[24:25], v[28:29], v[24:25]
	s_nop 0
	v_pk_mul_f32 v[28:29], v[20:21], v[24:25]
	v_pk_fma_f32 v[24:25], v[20:21], v[24:25], v[20:21] neg_lo:[1,0,0] neg_hi:[1,0,0]
	v_and_b32_e32 v20, 0x7fffffff, v22
	v_cndmask_b32_e32 v28, v24, v28, vcc
	v_cmp_gt_f32_e32 vcc, 0, v21
	v_and_b32_e32 v21, 0x7fffffff, v23
	v_pk_fma_f32 v[20:21], v[20:21], s[28:29], 1.0 op_sel_hi:[1,0,0]
	v_cndmask_b32_e32 v29, v25, v29, vcc
	v_rcp_f32_e32 v20, v20
	v_rcp_f32_e32 v21, v21
	v_cmp_gt_f32_e32 vcc, 0, v22
	v_pk_fma_f32 v[24:25], v[20:21], s[30:31], v[122:123] op_sel_hi:[1,0,0]
	s_nop 0
	v_pk_fma_f32 v[24:25], v[20:21], v[24:25], s[52:53] op_sel_hi:[1,1,0]
	s_nop 0
	v_pk_fma_f32 v[24:25], v[20:21], v[24:25], s[54:55] op_sel_hi:[1,1,0]
	s_nop 0
	v_pk_fma_f32 v[24:25], v[20:21], v[24:25], s[56:57] op_sel_hi:[1,1,0]
	s_nop 0
	v_pk_mul_f32 v[20:21], v[20:21], v[24:25]
	v_pk_mul_f32 v[24:25], v[26:27], s[58:59] op_sel_hi:[1,0]
	s_nop 0
	v_exp_f32_e32 v24, v24
	v_exp_f32_e32 v25, v25
	s_nop 0
	v_pk_mul_f32 v[20:21], v[24:25], v[20:21]
	s_nop 0
	v_pk_mul_f32 v[24:25], v[22:23], v[20:21]
	v_pk_fma_f32 v[20:21], v[22:23], v[20:21], v[22:23] neg_lo:[1,0,0] neg_hi:[1,0,0]
	s_nop 0
	v_cndmask_b32_e32 v26, v20, v24, vcc
	v_cmp_gt_f32_e32 vcc, 0, v23
	v_and_b32_e32 v20, 0x7fffffff, v16
	s_nop 0
	v_cndmask_b32_e32 v27, v21, v25, vcc
	v_and_b32_e32 v21, 0x7fffffff, v17
	v_pk_fma_f32 v[20:21], v[20:21], s[28:29], 1.0 op_sel_hi:[1,0,0]
	v_pk_mul_f32 v[24:25], v[16:17], v[16:17]
	v_rcp_f32_e32 v20, v20
	v_rcp_f32_e32 v21, v21
	v_pk_mul_f32 v[24:25], v[24:25], s[58:59] op_sel_hi:[1,0]
	v_cmp_gt_f32_e32 vcc, 0, v16
	v_exp_f32_e32 v24, v24
	v_pk_fma_f32 v[22:23], v[20:21], s[30:31], v[122:123] op_sel_hi:[1,0,0]
	v_exp_f32_e32 v25, v25
	v_pk_fma_f32 v[22:23], v[20:21], v[22:23], s[52:53] op_sel_hi:[1,1,0]
	s_nop 0
	v_pk_fma_f32 v[22:23], v[20:21], v[22:23], s[54:55] op_sel_hi:[1,1,0]
	s_nop 0
	v_pk_fma_f32 v[22:23], v[20:21], v[22:23], s[56:57] op_sel_hi:[1,1,0]
	s_nop 0
	v_pk_mul_f32 v[20:21], v[20:21], v[22:23]
	v_pk_mul_f32 v[22:23], v[18:19], v[18:19]
; __device__ __forceinline__ unsigned cvt_pk_bf16(float lo, float hi) { unsigned r; asm volatile("v_cvt_pk_bf16_f32 %0, %1, %2" : "=v"(r) : "v"(lo), "v"(hi)); return r; }
; #define GAS __attribute__((address_space(1)))
; __device__ __forceinline__ f32x2 gelu_pk(f32x2 v) {
;     const f32x2 av = __builtin_elementwise_abs(v), d = av * 0.2316418882f + 1.0f;
;     f32x2 t; t.x = __builtin_amdgcn_rcpf(d.x); t.y = __builtin_amdgcn_rcpf(d.y);
;     f32x2 q = t * 0.5307027145f + (-0.7265760135f); q = q * t + 0.7107068705f; q = q * t + (-0.142248368f); q = q * t + 0.127414796f; q = q * t;
;     const f32x2 s = (v * v) * (-0.72134752044f);
;     f32x2 e; e.x = __builtin_amdgcn_exp2f(s.x); e.y = __builtin_amdgcn_exp2f(s.y);
;     const f32x2 m = v * (q * e), r = v - m;
;     f32x2 o; o.x = v.x < 0.f ? m.x : r.x; o.y = v.y < 0.f ? m.y : r.y; return o;
; }
;     __device__ __forceinline__ void operator()(const f32x4 (&acc)[2][2][4][2], const Unit& u, int wr, int wc, int fr, int fq, const float (&pre)[8]) const {
;     ...
;                     f32x4 v0 = acc[ai][bj][m][0], v1 = acc[ai][bj][m][1];
;                     if (RS == 1) { v0 = v0 * rsc; v1 = v1 * rsc; }
;                     if (RS == 2) { v0 = v0 * csc[bj][0]; v1 = v1 * csc[bj][1]; }
;                     if (ACT == 1) { const f32x2 a = gelu_pk((f32x2){v0[0], v0[1]}), b = gelu_pk((f32x2){v0[2], v0[3]}), c = gelu_pk((f32x2){v1[0], v1[1]}), d = gelu_pk((f32x2){v1[2], v1[3]});
;                         v0 = (f32x4){a.x, a.y, b.x, b.y}; v1 = (f32x4){c.x, c.y, d.x, d.y}; }
;                     v0 = v0 * sc; v1 = v1 * sc;
;                     if (STAT == 1) rs += (v0[0] * v0[0] + v0[1] * v0[1]) + (v0[2] * v0[2] + v0[3] * v0[3]) + (v1[0] * v1[0] + v1[1] * v1[1]) + (v1[2] * v1[2] + v1[3] * v1[3]);
;                     if (STAT == 2) {
; #pragma unroll
;                         for (int e = 0; e < 4; ++e) { cs[bj][0][e] += v0[e]; cq[bj][0][e] += v0[e] * v0[e]; cs[bj][1][e] += v1[e]; cq[bj][1][e] += v1[e] * v1[e]; } }
;                     u32x4 w; w.x = cvt_pk_bf16(v0[0], v0[1]); w.y = cvt_pk_bf16(v0[2], v0[3]); w.z = cvt_pk_bf16(v1[0], v1[1]); w.w = cvt_pk_bf16(v1[2], v1[3]);
;                     *(GAS u32x4*)(rowp + bj * 128) = w; }
	v_pk_mul_f32 v[20:21], v[24:25], v[20:21]
	s_nop 0
	v_pk_mul_f32 v[24:25], v[16:17], v[20:21]
	v_pk_fma_f32 v[20:21], v[16:17], v[20:21], v[16:17] neg_lo:[1,0,0] neg_hi:[1,0,0]
	v_and_b32_e32 v16, 0x7fffffff, v18
	v_cndmask_b32_e32 v24, v20, v24, vcc
	v_cmp_gt_f32_e32 vcc, 0, v17
	v_and_b32_e32 v17, 0x7fffffff, v19
	v_pk_fma_f32 v[16:17], v[16:17], s[28:29], 1.0 op_sel_hi:[1,0,0]
	v_cndmask_b32_e32 v25, v21, v25, vcc
	v_rcp_f32_e32 v16, v16
	v_rcp_f32_e32 v17, v17
	v_cmp_gt_f32_e32 vcc, 0, v18
	v_pk_fma_f32 v[20:21], v[16:17], s[30:31], v[122:123] op_sel_hi:[1,0,0]
	s_nop 0
	v_pk_fma_f32 v[20:21], v[16:17], v[20:21], s[52:53] op_sel_hi:[1,1,0]
	s_nop 0
	v_pk_fma_f32 v[20:21], v[16:17], v[20:21], s[54:55] op_sel_hi:[1,1,0]
	s_nop 0
	v_pk_fma_f32 v[20:21], v[16:17], v[20:21], s[56:57] op_sel_hi:[1,1,0]
	s_nop 0
	v_pk_mul_f32 v[16:17], v[16:17], v[20:21]
	v_pk_mul_f32 v[20:21], v[22:23], s[58:59] op_sel_hi:[1,0]
	v_pk_mul_f32 v[22:23], v[12:13], v[12:13]
	v_exp_f32_e32 v20, v20
	v_exp_f32_e32 v21, v21
	v_pk_mul_f32 v[22:23], v[22:23], s[58:59] op_sel_hi:[1,0]
	v_pk_mul_f32 v[16:17], v[20:21], v[16:17]
	s_nop 0
	v_pk_mul_f32 v[20:21], v[18:19], v[16:17]
	v_pk_fma_f32 v[16:17], v[18:19], v[16:17], v[18:19] neg_lo:[1,0,0] neg_hi:[1,0,0]
	v_exp_f32_e32 v22, v22
	v_cndmask_b32_e32 v20, v16, v20, vcc
	v_cmp_gt_f32_e32 vcc, 0, v19
	v_cvt_pk_bf16_f32 v16, v28, v29
	v_exp_f32_e32 v23, v23
	s_nop 0
	v_cndmask_b32_e32 v19, v17, v21, vcc
	v_cvt_pk_bf16_f32 v17, v26, v27
	v_cvt_pk_bf16_f32 v18, v24, v25
	v_cvt_pk_bf16_f32 v19, v20, v19
	global_store_dwordx4 v[34:35], v[16:19], off offset:256
	v_cmp_gt_f32_e32 vcc, 0, v12
	s_nop 0
	v_and_b32_e32 v19, 0x7fffffff, v13
	v_and_b32_e32 v18, 0x7fffffff, v12
	v_pk_fma_f32 v[18:19], v[18:19], s[28:29], 1.0 op_sel_hi:[1,0,0]
	v_lshl_add_u64 v[16:17], v[150:151], 0, s[4:5]
	v_rcp_f32_e32 v18, v18
	v_rcp_f32_e32 v19, v19
	s_mov_b32 s4, 0x58000
	v_pk_fma_f32 v[20:21], v[18:19], s[30:31], v[122:123] op_sel_hi:[1,0,0]
	s_nop 0
	v_pk_fma_f32 v[20:21], v[18:19], v[20:21], s[52:53] op_sel_hi:[1,1,0]
	s_nop 0
	v_pk_fma_f32 v[20:21], v[18:19], v[20:21], s[54:55] op_sel_hi:[1,1,0]
	s_nop 0
	v_pk_fma_f32 v[20:21], v[18:19], v[20:21], s[56:57] op_sel_hi:[1,1,0]
	s_nop 0
	v_pk_mul_f32 v[18:19], v[18:19], v[20:21]
	v_pk_mul_f32 v[20:21], v[14:15], v[14:15]
	v_pk_mul_f32 v[18:19], v[22:23], v[18:19]
	s_nop 0
	v_pk_mul_f32 v[22:23], v[12:13], v[18:19]
	v_pk_fma_f32 v[18:19], v[12:13], v[18:19], v[12:13] neg_lo:[1,0,0] neg_hi:[1,0,0]
	v_and_b32_e32 v12, 0x7fffffff, v14
	v_cndmask_b32_e32 v22, v18, v22, vcc
	v_cmp_gt_f32_e32 vcc, 0, v13
	v_and_b32_e32 v13, 0x7fffffff, v15
	v_pk_fma_f32 v[12:13], v[12:13], s[28:29], 1.0 op_sel_hi:[1,0,0]
	v_cndmask_b32_e32 v23, v19, v23, vcc
	v_rcp_f32_e32 v12, v12
	v_rcp_f32_e32 v13, v13
	v_cmp_gt_f32_e32 vcc, 0, v14
	v_pk_fma_f32 v[18:19], v[12:13], s[30:31], v[122:123] op_sel_hi:[1,0,0]
	s_nop 0
	v_pk_fma_f32 v[18:19], v[12:13], v[18:19], s[52:53] op_sel_hi:[1,1,0]
	s_nop 0
	v_pk_fma_f32 v[18:19], v[12:13], v[18:19], s[54:55] op_sel_hi:[1,1,0]
	s_nop 0
	v_pk_fma_f32 v[18:19], v[12:13], v[18:19], s[56:57] op_sel_hi:[1,1,0]
	s_nop 0
	v_pk_mul_f32 v[12:13], v[12:13], v[18:19]
	v_pk_mul_f32 v[18:19], v[20:21], s[58:59] op_sel_hi:[1,0]
	s_nop 0
	v_exp_f32_e32 v18, v18
	v_exp_f32_e32 v19, v19
	s_nop 0
	v_pk_mul_f32 v[12:13], v[18:19], v[12:13]
	s_nop 0
	v_pk_mul_f32 v[18:19], v[14:15], v[12:13]
	v_pk_fma_f32 v[12:13], v[14:15], v[12:13], v[14:15] neg_lo:[1,0,0] neg_hi:[1,0,0]
	s_nop 0
	v_cndmask_b32_e32 v20, v12, v18, vcc
	v_cmp_gt_f32_e32 vcc, 0, v15
	v_and_b32_e32 v12, 0x7fffffff, v8
	s_nop 0
	v_cndmask_b32_e32 v21, v13, v19, vcc
	v_and_b32_e32 v13, 0x7fffffff, v9
	v_pk_fma_f32 v[12:13], v[12:13], s[28:29], 1.0 op_sel_hi:[1,0,0]
	v_pk_mul_f32 v[18:19], v[8:9], v[8:9]
	v_rcp_f32_e32 v12, v12
	v_rcp_f32_e32 v13, v13
	v_pk_mul_f32 v[18:19], v[18:19], s[58:59] op_sel_hi:[1,0]
	v_cmp_gt_f32_e32 vcc, 0, v8
	v_exp_f32_e32 v18, v18
	v_pk_fma_f32 v[14:15], v[12:13], s[30:31], v[122:123] op_sel_hi:[1,0,0]
	v_exp_f32_e32 v19, v19
	v_pk_fma_f32 v[14:15], v[12:13], v[14:15], s[52:53] op_sel_hi:[1,1,0]
	s_nop 0
	v_pk_fma_f32 v[14:15], v[12:13], v[14:15], s[54:55] op_sel_hi:[1,1,0]
	s_nop 0
	v_pk_fma_f32 v[14:15], v[12:13], v[14:15], s[56:57] op_sel_hi:[1,1,0]
	s_nop 0
	v_pk_mul_f32 v[12:13], v[12:13], v[14:15]
	v_pk_mul_f32 v[14:15], v[10:11], v[10:11]
	v_pk_mul_f32 v[12:13], v[18:19], v[12:13]
	s_nop 0
	v_pk_mul_f32 v[18:19], v[8:9], v[12:13]
	v_pk_fma_f32 v[12:13], v[8:9], v[12:13], v[8:9] neg_lo:[1,0,0] neg_hi:[1,0,0]
	v_and_b32_e32 v8, 0x7fffffff, v10
	v_cndmask_b32_e32 v18, v12, v18, vcc
	v_cmp_gt_f32_e32 vcc, 0, v9
	v_and_b32_e32 v9, 0x7fffffff, v11
	v_pk_fma_f32 v[8:9], v[8:9], s[28:29], 1.0 op_sel_hi:[1,0,0]
	v_cndmask_b32_e32 v19, v13, v19, vcc
	v_rcp_f32_e32 v8, v8
	v_rcp_f32_e32 v9, v9
	v_cmp_gt_f32_e32 vcc, 0, v10
	v_pk_fma_f32 v[12:13], v[8:9], s[30:31], v[122:123] op_sel_hi:[1,0,0]
	s_nop 0
	v_pk_fma_f32 v[12:13], v[8:9], v[12:13], s[52:53] op_sel_hi:[1,1,0]
	s_nop 0
	v_pk_fma_f32 v[12:13], v[8:9], v[12:13], s[54:55] op_sel_hi:[1,1,0]
	s_nop 0
	v_pk_fma_f32 v[12:13], v[8:9], v[12:13], s[56:57] op_sel_hi:[1,1,0]
	s_nop 0
	v_pk_mul_f32 v[8:9], v[8:9], v[12:13]
	v_pk_mul_f32 v[12:13], v[14:15], s[58:59] op_sel_hi:[1,0]
	s_nop 0
	v_exp_f32_e32 v12, v12
; __device__ __forceinline__ unsigned cvt_pk_bf16(float lo, float hi) { unsigned r; asm volatile("v_cvt_pk_bf16_f32 %0, %1, %2" : "=v"(r) : "v"(lo), "v"(hi)); return r; }
; #define PG8_BAR __builtin_amdgcn_s_barrier()
; #define GAS __attribute__((address_space(1)))
; template <class Epi, class Sched, bool ALIGN_EPI = false, bool SP2 = false>
; __device__ __forceinline__ void gemm_phase(PG8_LAS unsigned char* lds, const Gemm g, const Sched& S, const Epi& E) {
;     ...
;         if (!has_next) break;
; #pragma unroll
;         for (int a = 0; a < 2; ++a)
; #pragma unroll
;             for (int b = 0; b < 2; ++b)
; #pragma unroll
;                 for (int m = 0; m < 4; ++m)
; #pragma unroll
;                     for (int n = 0; n < 2; ++n) acc[a][b][m][n] = (f32x4){0.f, 0.f, 0.f, 0.f};
;         cur = nxt; cA = nA; cB = nB; ++ui;
;         if constexpr (Epi::PREFETCH) E.prefetch(cur, wr, fr, epre);
;         if constexpr (ALIGN_EPI) { if (wr == 1) PG8_BAR; }
;     __device__ __forceinline__ void operator()(const f32x4 (&acc)[2][2][4][2], const Unit& u, int wr, int wc, int fr, int fq, const float (&pre)[8]) const {
;     ...
;                     f32x4 v0 = acc[ai][bj][m][0], v1 = acc[ai][bj][m][1];
;                     if (RS == 1) { v0 = v0 * rsc; v1 = v1 * rsc; }
;                     if (RS == 2) { v0 = v0 * csc[bj][0]; v1 = v1 * csc[bj][1]; }
;                     if (ACT == 1) { const f32x2 a = gelu_pk((f32x2){v0[0], v0[1]}), b = gelu_pk((f32x2){v0[2], v0[3]}), c = gelu_pk((f32x2){v1[0], v1[1]}), d = gelu_pk((f32x2){v1[2], v1[3]});
;                         v0 = (f32x4){a.x, a.y, b.x, b.y}; v1 = (f32x4){c.x, c.y, d.x, d.y}; }
;                     v0 = v0 * sc; v1 = v1 * sc;
;                     if (STAT == 1) rs += (v0[0] * v0[0] + v0[1] * v0[1]) + (v0[2] * v0[2] + v0[3] * v0[3]) + (v1[0] * v1[0] + v1[1] * v1[1]) + (v1[2] * v1[2] + v1[3] * v1[3]);
;                     if (STAT == 2) {
; #pragma unroll
;                         for (int e = 0; e < 4; ++e) { cs[bj][0][e] += v0[e]; cq[bj][0][e] += v0[e] * v0[e]; cs[bj][1][e] += v1[e]; cq[bj][1][e] += v1[e] * v1[e]; } }
;                     u32x4 w; w.x = cvt_pk_bf16(v0[0], v0[1]); w.y = cvt_pk_bf16(v0[2], v0[3]); w.z = cvt_pk_bf16(v1[0], v1[1]); w.w = cvt_pk_bf16(v1[2], v1[3]);
;                     *(GAS u32x4*)(rowp + bj * 128) = w; }
	v_exp_f32_e32 v13, v13
	s_nop 0
	v_pk_mul_f32 v[8:9], v[12:13], v[8:9]
	s_nop 0
	v_pk_mul_f32 v[12:13], v[10:11], v[8:9]
	v_pk_fma_f32 v[8:9], v[10:11], v[8:9], v[10:11] neg_lo:[1,0,0] neg_hi:[1,0,0]
	s_nop 0
	v_cndmask_b32_e32 v12, v8, v12, vcc
	v_cmp_gt_f32_e32 vcc, 0, v11
	v_cvt_pk_bf16_f32 v8, v22, v23
	s_nop 1
	v_cndmask_b32_e32 v11, v9, v13, vcc
	v_cvt_pk_bf16_f32 v9, v20, v21
	v_cvt_pk_bf16_f32 v10, v18, v19
	v_cvt_pk_bf16_f32 v11, v12, v11
	v_add_co_u32_e32 v12, vcc, s4, v150
	s_nop 1
	v_addc_co_u32_e32 v13, vcc, 0, v151, vcc
	global_store_dwordx4 v[12:13], v[8:11], off
	v_pk_mul_f32 v[12:13], v[4:5], v[4:5]
	v_cmp_gt_f32_e32 vcc, 0, v4
	v_and_b32_e32 v9, 0x7fffffff, v5
	v_and_b32_e32 v8, 0x7fffffff, v4
	v_pk_fma_f32 v[8:9], v[8:9], s[28:29], 1.0 op_sel_hi:[1,0,0]
	v_pk_mul_f32 v[12:13], v[12:13], s[58:59] op_sel_hi:[1,0]
	v_rcp_f32_e32 v8, v8
	v_rcp_f32_e32 v9, v9
	v_exp_f32_e32 v12, v12
	v_exp_f32_e32 v13, v13
	v_pk_fma_f32 v[10:11], v[8:9], s[30:31], v[122:123] op_sel_hi:[1,0,0]
	s_nop 0
	v_pk_fma_f32 v[10:11], v[8:9], v[10:11], s[52:53] op_sel_hi:[1,1,0]
	s_nop 0
	v_pk_fma_f32 v[10:11], v[8:9], v[10:11], s[54:55] op_sel_hi:[1,1,0]
	s_nop 0
	v_pk_fma_f32 v[10:11], v[8:9], v[10:11], s[56:57] op_sel_hi:[1,1,0]
	s_nop 0
	v_pk_mul_f32 v[8:9], v[8:9], v[10:11]
	v_pk_mul_f32 v[10:11], v[6:7], v[6:7]
	v_pk_mul_f32 v[8:9], v[12:13], v[8:9]
	s_nop 0
	v_pk_mul_f32 v[12:13], v[4:5], v[8:9]
	v_pk_fma_f32 v[8:9], v[4:5], v[8:9], v[4:5] neg_lo:[1,0,0] neg_hi:[1,0,0]
	v_and_b32_e32 v4, 0x7fffffff, v6
	v_cndmask_b32_e32 v12, v8, v12, vcc
	v_cmp_gt_f32_e32 vcc, 0, v5
	v_and_b32_e32 v5, 0x7fffffff, v7
	v_pk_fma_f32 v[4:5], v[4:5], s[28:29], 1.0 op_sel_hi:[1,0,0]
	v_cndmask_b32_e32 v13, v9, v13, vcc
	v_rcp_f32_e32 v4, v4
	v_rcp_f32_e32 v5, v5
	v_cmp_gt_f32_e32 vcc, 0, v6
	v_pk_fma_f32 v[8:9], v[4:5], s[30:31], v[122:123] op_sel_hi:[1,0,0]
	s_nop 0
	v_pk_fma_f32 v[8:9], v[4:5], v[8:9], s[52:53] op_sel_hi:[1,1,0]
	s_nop 0
	v_pk_fma_f32 v[8:9], v[4:5], v[8:9], s[54:55] op_sel_hi:[1,1,0]
	s_nop 0
	v_pk_fma_f32 v[8:9], v[4:5], v[8:9], s[56:57] op_sel_hi:[1,1,0]
	s_nop 0
	v_pk_mul_f32 v[4:5], v[4:5], v[8:9]
	v_pk_mul_f32 v[8:9], v[10:11], s[58:59] op_sel_hi:[1,0]
	s_nop 0
	v_exp_f32_e32 v8, v8
	v_exp_f32_e32 v9, v9
	s_nop 0
	v_pk_mul_f32 v[4:5], v[8:9], v[4:5]
	s_nop 0
	v_pk_mul_f32 v[8:9], v[6:7], v[4:5]
	v_pk_fma_f32 v[4:5], v[6:7], v[4:5], v[6:7] neg_lo:[1,0,0] neg_hi:[1,0,0]
	s_nop 0
	v_cndmask_b32_e32 v10, v4, v8, vcc
	v_cmp_gt_f32_e32 vcc, 0, v7
	v_and_b32_e32 v4, 0x7fffffff, v0
	s_nop 0
	v_cndmask_b32_e32 v11, v5, v9, vcc
	v_and_b32_e32 v5, 0x7fffffff, v1
	v_pk_fma_f32 v[4:5], v[4:5], s[28:29], 1.0 op_sel_hi:[1,0,0]
	v_pk_mul_f32 v[8:9], v[0:1], v[0:1]
	v_rcp_f32_e32 v4, v4
	v_rcp_f32_e32 v5, v5
	v_pk_mul_f32 v[8:9], v[8:9], s[58:59] op_sel_hi:[1,0]
	v_cmp_gt_f32_e32 vcc, 0, v0
	v_exp_f32_e32 v8, v8
	v_pk_fma_f32 v[6:7], v[4:5], s[30:31], v[122:123] op_sel_hi:[1,0,0]
	v_exp_f32_e32 v9, v9
	v_pk_fma_f32 v[6:7], v[4:5], v[6:7], s[52:53] op_sel_hi:[1,1,0]
	s_nop 0
	v_pk_fma_f32 v[6:7], v[4:5], v[6:7], s[54:55] op_sel_hi:[1,1,0]
	s_nop 0
	v_pk_fma_f32 v[6:7], v[4:5], v[6:7], s[56:57] op_sel_hi:[1,1,0]
	s_nop 0
	v_pk_mul_f32 v[4:5], v[4:5], v[6:7]
	v_pk_mul_f32 v[6:7], v[2:3], v[2:3]
	v_pk_mul_f32 v[4:5], v[8:9], v[4:5]
	s_nop 0
	v_pk_mul_f32 v[8:9], v[0:1], v[4:5]
	v_pk_fma_f32 v[4:5], v[0:1], v[4:5], v[0:1] neg_lo:[1,0,0] neg_hi:[1,0,0]
	v_and_b32_e32 v0, 0x7fffffff, v2
	v_cndmask_b32_e32 v8, v4, v8, vcc
	v_cmp_gt_f32_e32 vcc, 0, v1
	v_and_b32_e32 v1, 0x7fffffff, v3
	v_pk_fma_f32 v[0:1], v[0:1], s[28:29], 1.0 op_sel_hi:[1,0,0]
	v_cndmask_b32_e32 v9, v5, v9, vcc
	v_rcp_f32_e32 v0, v0
	v_rcp_f32_e32 v1, v1
	v_cmp_gt_f32_e32 vcc, 0, v2
	v_pk_fma_f32 v[4:5], v[0:1], s[30:31], v[122:123] op_sel_hi:[1,0,0]
	s_nop 0
	v_pk_fma_f32 v[4:5], v[0:1], v[4:5], s[52:53] op_sel_hi:[1,1,0]
	s_nop 0
	v_pk_fma_f32 v[4:5], v[0:1], v[4:5], s[54:55] op_sel_hi:[1,1,0]
	s_nop 0
	v_pk_fma_f32 v[4:5], v[0:1], v[4:5], s[56:57] op_sel_hi:[1,1,0]
	s_nop 0
	v_pk_mul_f32 v[0:1], v[0:1], v[4:5]
	v_pk_mul_f32 v[4:5], v[6:7], s[58:59] op_sel_hi:[1,0]
	s_nop 0
	v_exp_f32_e32 v4, v4
	v_exp_f32_e32 v5, v5
	s_nop 0
	v_pk_mul_f32 v[0:1], v[4:5], v[0:1]
	s_nop 0
	v_pk_mul_f32 v[4:5], v[2:3], v[0:1]
	v_pk_fma_f32 v[0:1], v[2:3], v[0:1], v[2:3] neg_lo:[1,0,0] neg_hi:[1,0,0]
	s_nop 0
	v_cndmask_b32_e32 v4, v0, v4, vcc
	v_cmp_gt_f32_e32 vcc, 0, v3
	v_cvt_pk_bf16_f32 v0, v12, v13
	s_nop 1
	v_cndmask_b32_e32 v3, v1, v5, vcc
	s_andn2_b64 vcc, exec, s[96:97]
	v_cvt_pk_bf16_f32 v1, v10, v11
	v_cvt_pk_bf16_f32 v2, v8, v9
	v_cvt_pk_bf16_f32 v3, v4, v3
	global_store_dwordx4 v[16:17], v[0:3], off offset:256
	s_cbranch_vccnz .LBB0_109
	s_lshl_b32 s4, s90, 8
	s_ashr_i32 s5, s4, 31
	v_lshl_add_u64 v[0:1], s[4:5], 2, v[138:139]
	global_load_dword v172, v[0:1], off
	global_load_dword v158, v[0:1], off offset:64
	global_load_dword v156, v[0:1], off offset:128
	global_load_dword v154, v[0:1], off offset:192
	global_load_dword v152, v[0:1], off offset:512
	global_load_dword v148, v[0:1], off offset:576
	global_load_dword v146, v[0:1], off offset:640
	global_load_dword v144, v[0:1], off offset:704
	v_readlane_b32 s4, v254, 49
	v_readlane_b32 s5, v254, 50
	s_andn2_b64 vcc, exec, s[4:5]
	s_cmp_lg_u32 s4, 0
	s_cselect_b32 s100, 1, 0
	s_branch .LBB0_108

; #define PG8_STAGE(bufoff, gbase, voff) do { _Pragma("unroll") for (int _i = 0; _i < 2; ++_i) \
;         __builtin_amdgcn_global_load_lds((const unsigned*)((const char*)(gbase) + (voff)[_i]), (PG8_LAS unsigned*)(lds + (bufoff) + ldsw + _i * 8192), 16, 0, 0); } while (0)
; #define PG8_LDA(dst, b, h) do { _Pragma("unroll") for (int m = 0; m < 4; ++m) _Pragma("unroll") for (int k = 0; k < 2; ++k) dst[m][k] = *(const PG8_LAS bf16x8*)(lds + PG8_SA(b, h) + aoff + m * 2048 + k * 1024); } while (0)
; #define PG8_LDB(dst, b, h) do { _Pragma("unroll") for (int n = 0; n < 2; ++n) _Pragma("unroll") for (int k = 0; k < 2; ++k) dst[n][k] = *(const PG8_LAS bf16x8*)(lds + PG8_SB(b, h) + boff + n * 2048 + k * 1024); } while (0)
; #define PG8_WAIT_V(n) asm volatile("s_waitcnt vmcnt(" #n ")" ::: "memory")
; #define PG8_WAIT_L(n) asm volatile("s_waitcnt lgkmcnt(" #n ")" ::: "memory")
; #define PG8_BAR __builtin_amdgcn_s_barrier()
; template <class Epi, class Sched, bool ALIGN_EPI = false, bool SP2 = false>
; __device__ __forceinline__ void gemm_phase(PG8_LAS unsigned char* lds, const Gemm g, const Sched& S, const Epi& E) {
;     ...
;         const bool has_next = S.next(ui + 1, nxt);
;         const char* nA = has_next ? (const char*)g.A + (size_t)nxt.pm * tstep : cA; const char* nB = has_next ? (const char*)g.Bt + (size_t)nxt.pn * tstep : cB;
;         for (int t = 0; t < nt; t += 2) {
;             const bool last = (t == nt - 2);
;             const char* a1 = cA + (size_t)(t + 1) * kstep;
;             const char* a2 = last ? nA : cA + (size_t)(t + 2) * kstep; const char* b2 = last ? nB : cB + (size_t)(t + 2) * kstep;
;             const char* a3 = a2 + kstep; const char* b3 = b2 + kstep;
;             if (last && has_next) S.a_ready(nxt);
;             if constexpr (SP2) {
;             PG8_LDB(B0, 0, 0); PG8_LDB(B1, 0, 1); PG8_SCHED; PG8_LDA(At, 0, 0); PG8_STAGE(PG8_SA(1, 1), a1 + hstep, voffA);
;             PG8_WAIT_V(8); PG8_WAIT_L(0); PG8_BAR; PG8_MMA(0, 0, At, B0); PG8_MMA(0, 1, At, B1); PG8_BAR; PG8_SCHED;
;     ...
; #pragma unroll
;         for (int a = 0; a < 2; ++a)
; #pragma unroll
;             for (int b = 0; b < 2; ++b)
; #pragma unroll
;                 for (int m = 0; m < 4; ++m)
; #pragma unroll
;                     for (int n = 0; n < 2; ++n) acc[a][b][m][n] = (f32x4){0.f, 0.f, 0.f, 0.f};
;         cur = nxt; cA = nA; cB = nB; ++ui;
.LBB0_144:
	s_ashr_i32 s3, s2, 31
	s_lshl_b64 s[50:51], s[2:3], 19
	v_readlane_b32 s3, v254, 41
	s_add_u32 s94, s3, s50
	v_readlane_b32 s3, v254, 43
	s_addc_u32 s95, s3, s51
	s_and_b64 s[50:51], s[92:93], exec
	s_cselect_b32 s3, s95, s49
	s_cselect_b32 s45, s94, s48
	s_ashr_i32 s89, s88, 31
	s_lshl_b64 s[50:51], s[88:89], 19
	s_add_u32 s96, s62, s50
	s_addc_u32 s97, s63, s51
	s_and_b64 s[50:51], s[92:93], exec
	s_cselect_b32 s89, s97, s47
	s_cselect_b32 vcc_lo, s96, s46
	s_add_u32 vcc_hi, s46, 0x100
	s_addc_u32 s7, s47, 0
	s_add_u32 s46, s48, 0x40080
	v_mov_b32_e32 v0, 0
	s_addc_u32 s47, s49, 0
	s_mov_b32 s80, -2
	v_mov_b32_e32 v1, v0
	s_waitcnt lgkmcnt(0)
	v_mov_b32_e32 v2, v0
	v_mov_b32_e32 v3, v0
	v_mov_b32_e32 v4, v0
	v_mov_b32_e32 v5, v0
	v_mov_b32_e32 v6, v0
	v_mov_b32_e32 v7, v0
	v_mov_b32_e32 v16, v0
	v_mov_b32_e32 v17, v0
	v_mov_b32_e32 v18, v0
	v_mov_b32_e32 v19, v0
	v_mov_b32_e32 v20, v0
	v_mov_b32_e32 v21, v0
	v_mov_b32_e32 v22, v0
	v_mov_b32_e32 v23, v0
	v_mov_b32_e32 v34, v0
	v_mov_b32_e32 v35, v0
	v_mov_b32_e32 v36, v0
	v_mov_b32_e32 v37, v0
	v_mov_b32_e32 v38, v0
	v_mov_b32_e32 v39, v0
	v_mov_b32_e32 v40, v0
	v_mov_b32_e32 v41, v0
	v_mov_b32_e32 v58, v0
	v_mov_b32_e32 v59, v0
	v_mov_b32_e32 v60, v0
	v_mov_b32_e32 v61, v0
	v_mov_b32_e32 v62, v0
	v_mov_b32_e32 v63, v0
	v_mov_b32_e32 v64, v0
	v_mov_b32_e32 v65, v0
	v_mov_b32_e32 v8, v0
	v_mov_b32_e32 v9, v0
	v_mov_b32_e32 v10, v0
	v_mov_b32_e32 v11, v0
	v_mov_b32_e32 v12, v0
	v_mov_b32_e32 v13, v0
	v_mov_b32_e32 v14, v0
	v_mov_b32_e32 v15, v0
	v_mov_b32_e32 v24, v0
	v_mov_b32_e32 v25, v0
	v_mov_b32_e32 v26, v0
	v_mov_b32_e32 v27, v0
	v_mov_b32_e32 v28, v0
	v_mov_b32_e32 v29, v0
	v_mov_b32_e32 v30, v0
	v_mov_b32_e32 v31, v0
	v_mov_b32_e32 v42, v0
	v_mov_b32_e32 v43, v0
	v_mov_b32_e32 v44, v0
	v_mov_b32_e32 v45, v0
	v_mov_b32_e32 v46, v0
	v_mov_b32_e32 v47, v0
	v_mov_b32_e32 v48, v0
	v_mov_b32_e32 v49, v0
	v_mov_b32_e32 v74, v0
	v_mov_b32_e32 v75, v0
	v_mov_b32_e32 v76, v0
	v_mov_b32_e32 v77, v0
	v_mov_b32_e32 v78, v0
	v_mov_b32_e32 v79, v0
	v_mov_b32_e32 v80, v0
	v_mov_b32_e32 v81, v0
	v_mov_b32_e32 v82, v0
	v_mov_b32_e32 v83, v0
	v_mov_b32_e32 v84, v0
	v_mov_b32_e32 v85, v0
	v_mov_b32_e32 v86, v0
	v_mov_b32_e32 v87, v0
	v_mov_b32_e32 v88, v0
	v_mov_b32_e32 v89, v0
	v_mov_b32_e32 v98, v0
	v_mov_b32_e32 v99, v0
	v_mov_b32_e32 v100, v0
	v_mov_b32_e32 v101, v0
	v_mov_b32_e32 v102, v0
	v_mov_b32_e32 v103, v0
	v_mov_b32_e32 v104, v0
	v_mov_b32_e32 v105, v0
	v_mov_b32_e32 v114, v0
	v_mov_b32_e32 v115, v0
	v_mov_b32_e32 v116, v0
	v_mov_b32_e32 v117, v0
	v_mov_b32_e32 v118, v0
	v_mov_b32_e32 v119, v0
	v_mov_b32_e32 v120, v0
	v_mov_b32_e32 v121, v0
	v_mov_b32_e32 v130, v0
	v_mov_b32_e32 v131, v0
	v_mov_b32_e32 v132, v0
	v_mov_b32_e32 v133, v0
	v_mov_b32_e32 v134, v0
	v_mov_b32_e32 v135, v0
	v_mov_b32_e32 v136, v0
	v_mov_b32_e32 v137, v0
	v_mov_b32_e32 v90, v0
	v_mov_b32_e32 v91, v0
	v_mov_b32_e32 v92, v0
	v_mov_b32_e32 v93, v0
	v_mov_b32_e32 v94, v0
	v_mov_b32_e32 v95, v0
	v_mov_b32_e32 v96, v0
	v_mov_b32_e32 v97, v0
	v_mov_b32_e32 v106, v0
	v_mov_b32_e32 v107, v0
	v_mov_b32_e32 v108, v0
	v_mov_b32_e32 v109, v0
	v_mov_b32_e32 v110, v0
	v_mov_b32_e32 v111, v0
	v_mov_b32_e32 v112, v0
	v_mov_b32_e32 v113, v0
	v_mov_b32_e32 v122, v0
	v_mov_b32_e32 v123, v0
	v_mov_b32_e32 v124, v0
	v_mov_b32_e32 v125, v0
	v_mov_b32_e32 v126, v0
	v_mov_b32_e32 v127, v0
	v_mov_b32_e32 v128, v0
	v_mov_b32_e32 v129, v0
	v_mov_b32_e32 v138, v0
	v_mov_b32_e32 v139, v0
	v_mov_b32_e32 v140, v0
	v_mov_b32_e32 v141, v0
	v_mov_b32_e32 v142, v0
	v_mov_b32_e32 v143, v0
	v_mov_b32_e32 v144, v0
	v_mov_b32_e32 v145, v0
	s_cmp_eq_u32 s100, 0
	s_cbranch_scc1 .Lrb3_skip
	s_mov_b32 s100, 0
	s_barrier
.Lrb3_skip:
.LBB0_145:
	s_add_u32 s48, s46, 0xfffc0080
	s_addc_u32 s49, s47, -1
	s_add_i32 s61, 0, 0x10000
	s_cmp_eq_u32 s80, 12
	s_cselect_b32 s51, s3, s49
	s_cselect_b32 s50, s45, s48
	s_cselect_b32 s49, s89, s7
	s_cselect_b32 s48, vcc_lo, vcc_hi
	s_add_i32 s72, 0, 0x14000
	v_add_u32_e32 v70, s61, v176
	v_add_u32_e32 v174, s72, v176
	ds_read_b128 v[50:53], v70
	ds_read_b128 v[54:57], v70 offset:1024
	ds_read_b128 v[66:69], v70 offset:2048
	ds_read_b128 v[70:73], v70 offset:3072
	ds_read_b128 v[158:161], v174
	ds_read_b128 v[170:173], v174 offset:1024
	ds_read_b128 v[180:183], v174 offset:2048
	ds_read_b128 v[196:199], v174 offset:3072
	v_lshl_add_u64 v[174:175], s[46:47], 0, v[156:157]
	s_add_i32 m0, s5, 0xc000
	ds_read_b128 v[200:203], v178
	ds_read_b128 v[204:207], v178 offset:1024
	ds_read_b128 v[208:211], v178 offset:2048
	ds_read_b128 v[212:215], v178 offset:3072
	ds_read_b128 v[216:219], v178 offset:4096
	ds_read_b128 v[220:223], v178 offset:5120
	ds_read_b128 v[224:227], v178 offset:6144
	ds_read_b128 v[228:231], v178 offset:7168
	global_load_lds_dwordx4 v[174:175], off
	v_lshl_add_u64 v[174:175], s[46:47], 0, v[154:155]
	s_add_i32 m0, s5, 0xe000
	s_nop 0
	global_load_lds_dwordx4 v[174:175], off
	s_waitcnt vmcnt(8)
	s_waitcnt lgkmcnt(0)
	s_barrier
; #define PG8_STAGE(bufoff, gbase, voff) do { _Pragma("unroll") for (int _i = 0; _i < 2; ++_i) \
;         __builtin_amdgcn_global_load_lds((const unsigned*)((const char*)(gbase) + (voff)[_i]), (PG8_LAS unsigned*)(lds + (bufoff) + ldsw + _i * 8192), 16, 0, 0); } while (0)
; #define PG8_LDA(dst, b, h) do { _Pragma("unroll") for (int m = 0; m < 4; ++m) _Pragma("unroll") for (int k = 0; k < 2; ++k) dst[m][k] = *(const PG8_LAS bf16x8*)(lds + PG8_SA(b, h) + aoff + m * 2048 + k * 1024); } while (0)
; #define PG8_LDB(dst, b, h) do { _Pragma("unroll") for (int n = 0; n < 2; ++n) _Pragma("unroll") for (int k = 0; k < 2; ++k) dst[n][k] = *(const PG8_LAS bf16x8*)(lds + PG8_SB(b, h) + boff + n * 2048 + k * 1024); } while (0)
; #define PG8_MMA(ai, bj, At, Bt) do { __builtin_amdgcn_s_setprio(1); _Pragma("unroll") for (int m = 0; m < 4; ++m) _Pragma("unroll") for (int n = 0; n < 2; ++n) _Pragma("unroll") for (int k = 0; k < 2; ++k) \
;         acc[ai][bj][m][n] = __builtin_amdgcn_mfma_f32_16x16x32_bf16(Bt[n][k], At[m][k], acc[ai][bj][m][n], 0, 0, 0); __builtin_amdgcn_s_setprio(0); } while (0)
; #define PG8_WAIT_V(n) asm volatile("s_waitcnt vmcnt(" #n ")" ::: "memory")
; #define PG8_WAIT_L(n) asm volatile("s_waitcnt lgkmcnt(" #n ")" ::: "memory")
; #define PG8_BAR __builtin_amdgcn_s_barrier()
; #define PG8_SCHED __builtin_amdgcn_sched_barrier(0)
; template <class Epi, class Sched, bool ALIGN_EPI = false, bool SP2 = false>
; __device__ __forceinline__ void gemm_phase(PG8_LAS unsigned char* lds, const Gemm g, const Sched& S, const Epi& E) {
;     ...
;             PG8_LDB(B0, 0, 0); PG8_LDB(B1, 0, 1); PG8_SCHED; PG8_LDA(At, 0, 0); PG8_STAGE(PG8_SA(1, 1), a1 + hstep, voffA);
;             PG8_WAIT_V(8); PG8_WAIT_L(0); PG8_BAR; PG8_MMA(0, 0, At, B0); PG8_MMA(0, 1, At, B1); PG8_BAR; PG8_SCHED;
;             PG8_LDA(At, 0, 1); PG8_STAGE(PG8_SB(0, 0), b2, voffB); PG8_STAGE(PG8_SB(0, 1), b2 + hstep, voffB); PG8_STAGE(PG8_SA(0, 0), a2, voffA);
;             PG8_WAIT_V(8); PG8_WAIT_L(0); PG8_BAR; PG8_MMA(1, 0, At, B0); PG8_MMA(1, 1, At, B1); PG8_BAR; PG8_SCHED;
	v_mfma_f32_16x16x32_bf16 v[142:145], v[50:53], v[200:203], v[142:145]
	v_mfma_f32_16x16x32_bf16 v[138:141], v[66:69], v[200:203], v[138:141]
	v_mfma_f32_16x16x32_bf16 v[126:129], v[50:53], v[208:211], v[126:129]
	v_mfma_f32_16x16x32_bf16 v[122:125], v[66:69], v[208:211], v[122:125]
	v_mfma_f32_16x16x32_bf16 v[110:113], v[50:53], v[216:219], v[110:113]
	v_mfma_f32_16x16x32_bf16 v[106:109], v[66:69], v[216:219], v[106:109]
	v_mfma_f32_16x16x32_bf16 v[94:97], v[50:53], v[224:227], v[94:97]
	v_mfma_f32_16x16x32_bf16 v[90:93], v[66:69], v[224:227], v[90:93]
	v_mfma_f32_16x16x32_bf16 v[142:145], v[54:57], v[204:207], v[142:145]
	v_mfma_f32_16x16x32_bf16 v[138:141], v[70:73], v[204:207], v[138:141]
	v_mfma_f32_16x16x32_bf16 v[126:129], v[54:57], v[212:215], v[126:129]
	v_mfma_f32_16x16x32_bf16 v[122:125], v[70:73], v[212:215], v[122:125]
	v_mfma_f32_16x16x32_bf16 v[110:113], v[54:57], v[220:223], v[110:113]
	v_mfma_f32_16x16x32_bf16 v[106:109], v[70:73], v[220:223], v[106:109]
	v_mfma_f32_16x16x32_bf16 v[94:97], v[54:57], v[228:231], v[94:97]
	v_mfma_f32_16x16x32_bf16 v[90:93], v[70:73], v[228:231], v[90:93]
	v_mfma_f32_16x16x32_bf16 v[134:137], v[158:161], v[200:203], v[134:137]
	v_mfma_f32_16x16x32_bf16 v[130:133], v[180:183], v[200:203], v[130:133]
	v_mfma_f32_16x16x32_bf16 v[118:121], v[158:161], v[208:211], v[118:121]
	v_mfma_f32_16x16x32_bf16 v[114:117], v[180:183], v[208:211], v[114:117]
	v_mfma_f32_16x16x32_bf16 v[102:105], v[158:161], v[216:219], v[102:105]
	v_mfma_f32_16x16x32_bf16 v[98:101], v[180:183], v[216:219], v[98:101]
	v_mfma_f32_16x16x32_bf16 v[86:89], v[158:161], v[224:227], v[86:89]
	v_mfma_f32_16x16x32_bf16 v[82:85], v[180:183], v[224:227], v[82:85]
	v_mfma_f32_16x16x32_bf16 v[134:137], v[170:173], v[204:207], v[134:137]
	v_mfma_f32_16x16x32_bf16 v[130:133], v[196:199], v[204:207], v[130:133]
	v_mfma_f32_16x16x32_bf16 v[118:121], v[170:173], v[212:215], v[118:121]
	v_mfma_f32_16x16x32_bf16 v[114:117], v[196:199], v[212:215], v[114:117]
	v_mfma_f32_16x16x32_bf16 v[102:105], v[170:173], v[220:223], v[102:105]
	v_mfma_f32_16x16x32_bf16 v[98:101], v[196:199], v[220:223], v[98:101]
	v_mfma_f32_16x16x32_bf16 v[86:89], v[170:173], v[228:231], v[86:89]
	v_mfma_f32_16x16x32_bf16 v[82:85], v[196:199], v[228:231], v[82:85]
	s_barrier
	s_add_i32 s61, s61, s4
	v_lshl_add_u64 v[174:175], s[48:49], 0, v[148:149]
	s_mov_b32 m0, s61
	ds_read_b128 v[200:203], v178 offset:16384
	ds_read_b128 v[204:207], v178 offset:17408
	ds_read_b128 v[208:211], v178 offset:18432
	ds_read_b128 v[212:215], v178 offset:19456
	ds_read_b128 v[216:219], v178 offset:20480
	ds_read_b128 v[220:223], v178 offset:21504
	ds_read_b128 v[224:227], v178 offset:22528
	ds_read_b128 v[228:231], v178 offset:23552
	global_load_lds_dwordx4 v[174:175], off
	s_add_i32 m0, s61, 0x2000
	s_add_u32 s76, s48, 0x40000
	v_lshl_add_u64 v[184:185], s[48:49], 0, v[152:153]
	s_addc_u32 s77, s49, 0
	s_add_i32 s61, s72, s4
	global_load_lds_dwordx4 v[184:185], off
	v_lshl_add_u64 v[232:233], s[76:77], 0, v[148:149]
	s_mov_b32 m0, s61
	v_lshl_add_u64 v[234:235], s[50:51], 0, v[150:151]
	global_load_lds_dwordx4 v[232:233], off
	v_lshl_add_u64 v[232:233], s[76:77], 0, v[152:153]
	s_add_i32 m0, s61, 0x2000
	s_nop 0
	global_load_lds_dwordx4 v[232:233], off
	v_lshl_add_u64 v[232:233], s[50:51], 0, v[146:147]
	s_mov_b32 m0, s5
	s_nop 0
	global_load_lds_dwordx4 v[232:233], off
	s_mov_b32 m0, s91
	s_nop 0
	global_load_lds_dwordx4 v[234:235], off
	s_waitcnt vmcnt(8)
	s_waitcnt lgkmcnt(0)
	s_barrier
	v_mfma_f32_16x16x32_bf16 v[78:81], v[50:53], v[200:203], v[78:81]
	v_mfma_f32_16x16x32_bf16 v[74:77], v[66:69], v[200:203], v[74:77]
	v_mfma_f32_16x16x32_bf16 v[46:49], v[50:53], v[208:211], v[46:49]
	v_mfma_f32_16x16x32_bf16 v[42:45], v[66:69], v[208:211], v[42:45]
	v_mfma_f32_16x16x32_bf16 v[28:31], v[50:53], v[216:219], v[28:31]
	v_mfma_f32_16x16x32_bf16 v[24:27], v[66:69], v[216:219], v[24:27]
	v_mfma_f32_16x16x32_bf16 v[12:15], v[50:53], v[224:227], v[12:15]
	v_mfma_f32_16x16x32_bf16 v[8:11], v[66:69], v[224:227], v[8:11]
	v_mfma_f32_16x16x32_bf16 v[78:81], v[54:57], v[204:207], v[78:81]
	v_mfma_f32_16x16x32_bf16 v[74:77], v[70:73], v[204:207], v[74:77]
	v_mfma_f32_16x16x32_bf16 v[46:49], v[54:57], v[212:215], v[46:49]
	v_mfma_f32_16x16x32_bf16 v[42:45], v[70:73], v[212:215], v[42:45]
	v_mfma_f32_16x16x32_bf16 v[28:31], v[54:57], v[220:223], v[28:31]
	v_mfma_f32_16x16x32_bf16 v[24:27], v[70:73], v[220:223], v[24:27]
	v_mfma_f32_16x16x32_bf16 v[12:15], v[54:57], v[228:231], v[12:15]
	v_mfma_f32_16x16x32_bf16 v[8:11], v[70:73], v[228:231], v[8:11]
	v_mfma_f32_16x16x32_bf16 v[38:41], v[158:161], v[208:211], v[38:41]
	v_mfma_f32_16x16x32_bf16 v[34:37], v[180:183], v[208:211], v[34:37]
	v_mfma_f32_16x16x32_bf16 v[20:23], v[158:161], v[216:219], v[20:23]
	v_mfma_f32_16x16x32_bf16 v[16:19], v[180:183], v[216:219], v[16:19]
	v_mfma_f32_16x16x32_bf16 v[4:7], v[158:161], v[224:227], v[4:7]
	v_mfma_f32_16x16x32_bf16 v[0:3], v[180:183], v[224:227], v[0:3]
	v_mfma_f32_16x16x32_bf16 v[50:53], v[158:161], v[200:203], v[62:65]
	v_mfma_f32_16x16x32_bf16 v[54:57], v[180:183], v[200:203], v[58:61]
	v_mfma_f32_16x16x32_bf16 v[38:41], v[170:173], v[212:215], v[38:41]
	v_mfma_f32_16x16x32_bf16 v[34:37], v[196:199], v[212:215], v[34:37]
	v_mfma_f32_16x16x32_bf16 v[20:23], v[170:173], v[220:223], v[20:23]
	v_mfma_f32_16x16x32_bf16 v[16:19], v[196:199], v[220:223], v[16:19]
	v_mfma_f32_16x16x32_bf16 v[4:7], v[170:173], v[228:231], v[4:7]
	v_mfma_f32_16x16x32_bf16 v[0:3], v[196:199], v[228:231], v[0:3]
	v_mfma_f32_16x16x32_bf16 v[50:53], v[170:173], v[204:207], v[50:53]
	v_mfma_f32_16x16x32_bf16 v[54:57], v[196:199], v[204:207], v[54:57]
	s_barrier
; #define PG8_STAGE(bufoff, gbase, voff) do { _Pragma("unroll") for (int _i = 0; _i < 2; ++_i) \
;         __builtin_amdgcn_global_load_lds((const unsigned*)((const char*)(gbase) + (voff)[_i]), (PG8_LAS unsigned*)(lds + (bufoff) + ldsw + _i * 8192), 16, 0, 0); } while (0)
; #define PG8_LDA(dst, b, h) do { _Pragma("unroll") for (int m = 0; m < 4; ++m) _Pragma("unroll") for (int k = 0; k < 2; ++k) dst[m][k] = *(const PG8_LAS bf16x8*)(lds + PG8_SA(b, h) + aoff + m * 2048 + k * 1024); } while (0)
; #define PG8_LDB(dst, b, h) do { _Pragma("unroll") for (int n = 0; n < 2; ++n) _Pragma("unroll") for (int k = 0; k < 2; ++k) dst[n][k] = *(const PG8_LAS bf16x8*)(lds + PG8_SB(b, h) + boff + n * 2048 + k * 1024); } while (0)
; #define PG8_MMA(ai, bj, At, Bt) do { __builtin_amdgcn_s_setprio(1); _Pragma("unroll") for (int m = 0; m < 4; ++m) _Pragma("unroll") for (int n = 0; n < 2; ++n) _Pragma("unroll") for (int k = 0; k < 2; ++k) \
;         acc[ai][bj][m][n] = __builtin_amdgcn_mfma_f32_16x16x32_bf16(Bt[n][k], At[m][k], acc[ai][bj][m][n], 0, 0, 0); __builtin_amdgcn_s_setprio(0); } while (0)
; #define PG8_WAIT_V(n) asm volatile("s_waitcnt vmcnt(" #n ")" ::: "memory")
; #define PG8_WAIT_L(n) asm volatile("s_waitcnt lgkmcnt(" #n ")" ::: "memory")
; #define PG8_BAR __builtin_amdgcn_s_barrier()
; #define PG8_SCHED __builtin_amdgcn_sched_barrier(0)
; template <class Epi, class Sched, bool ALIGN_EPI = false, bool SP2 = false>
; __device__ __forceinline__ void gemm_phase(PG8_LAS unsigned char* lds, const Gemm g, const Sched& S, const Epi& E) {
;     ...
;             PG8_LDB(B0, 1, 0); PG8_LDB(B1, 1, 1); PG8_SCHED; PG8_LDA(At, 1, 0); PG8_STAGE(PG8_SA(0, 1), a2 + hstep, voffA);
;             PG8_WAIT_V(8); PG8_WAIT_L(0); PG8_BAR; PG8_MMA(0, 0, At, B0); PG8_MMA(0, 1, At, B1); PG8_BAR; PG8_SCHED;
	s_add_i32 s61, 0, 0x18000
	s_add_i32 s72, 0, 0x1c000
	v_add_u32_e32 v70, s61, v176
	v_add_u32_e32 v179, s72, v176
	ds_read_b128 v[58:61], v70
	ds_read_b128 v[62:65], v70 offset:1024
	ds_read_b128 v[66:69], v70 offset:2048
	ds_read_b128 v[70:73], v70 offset:3072
	ds_read_b128 v[158:161], v179
	ds_read_b128 v[170:173], v179 offset:1024
	ds_read_b128 v[180:183], v179 offset:2048
	ds_read_b128 v[196:199], v179 offset:3072
	s_add_u32 s50, s50, 0x40000
	s_addc_u32 s51, s51, 0
	s_mov_b32 m0, s8
	v_lshl_add_u64 v[236:237], s[50:51], 0, v[146:147]
	ds_read_b128 v[200:203], v178 offset:32768
	ds_read_b128 v[204:207], v178 offset:33792
	ds_read_b128 v[208:211], v178 offset:34816
	ds_read_b128 v[212:215], v178 offset:35840
	ds_read_b128 v[216:219], v178 offset:36864
	ds_read_b128 v[220:223], v178 offset:37888
	ds_read_b128 v[224:227], v178 offset:38912
	ds_read_b128 v[228:231], v178 offset:39936
	global_load_lds_dwordx4 v[236:237], off
	v_lshl_add_u64 v[236:237], s[50:51], 0, v[150:151]
	s_mov_b32 m0, s0
	s_nop 0
	global_load_lds_dwordx4 v[236:237], off
	s_waitcnt vmcnt(8)
	s_waitcnt lgkmcnt(0)
	s_barrier
	v_mfma_f32_16x16x32_bf16 v[142:145], v[58:61], v[200:203], v[142:145]
	v_mfma_f32_16x16x32_bf16 v[138:141], v[66:69], v[200:203], v[138:141]
	v_mfma_f32_16x16x32_bf16 v[126:129], v[58:61], v[208:211], v[126:129]
	v_mfma_f32_16x16x32_bf16 v[122:125], v[66:69], v[208:211], v[122:125]
	v_mfma_f32_16x16x32_bf16 v[110:113], v[58:61], v[216:219], v[110:113]
	v_mfma_f32_16x16x32_bf16 v[106:109], v[66:69], v[216:219], v[106:109]
	v_mfma_f32_16x16x32_bf16 v[94:97], v[58:61], v[224:227], v[94:97]
	v_mfma_f32_16x16x32_bf16 v[90:93], v[66:69], v[224:227], v[90:93]
	v_mfma_f32_16x16x32_bf16 v[142:145], v[62:65], v[204:207], v[142:145]
	v_mfma_f32_16x16x32_bf16 v[138:141], v[70:73], v[204:207], v[138:141]
	v_mfma_f32_16x16x32_bf16 v[126:129], v[62:65], v[212:215], v[126:129]
	v_mfma_f32_16x16x32_bf16 v[122:125], v[70:73], v[212:215], v[122:125]
	v_mfma_f32_16x16x32_bf16 v[110:113], v[62:65], v[220:223], v[110:113]
	v_mfma_f32_16x16x32_bf16 v[106:109], v[70:73], v[220:223], v[106:109]
	v_mfma_f32_16x16x32_bf16 v[94:97], v[62:65], v[228:231], v[94:97]
	v_mfma_f32_16x16x32_bf16 v[90:93], v[70:73], v[228:231], v[90:93]
	v_mfma_f32_16x16x32_bf16 v[134:137], v[158:161], v[200:203], v[134:137]
	v_mfma_f32_16x16x32_bf16 v[130:133], v[180:183], v[200:203], v[130:133]
	v_mfma_f32_16x16x32_bf16 v[118:121], v[158:161], v[208:211], v[118:121]
	v_mfma_f32_16x16x32_bf16 v[114:117], v[180:183], v[208:211], v[114:117]
	v_mfma_f32_16x16x32_bf16 v[102:105], v[158:161], v[216:219], v[102:105]
	v_mfma_f32_16x16x32_bf16 v[98:101], v[180:183], v[216:219], v[98:101]
	v_mfma_f32_16x16x32_bf16 v[86:89], v[158:161], v[224:227], v[86:89]
	v_mfma_f32_16x16x32_bf16 v[82:85], v[180:183], v[224:227], v[82:85]
	v_mfma_f32_16x16x32_bf16 v[134:137], v[170:173], v[204:207], v[134:137]
	v_mfma_f32_16x16x32_bf16 v[130:133], v[196:199], v[204:207], v[130:133]
	v_mfma_f32_16x16x32_bf16 v[118:121], v[170:173], v[212:215], v[118:121]
	v_mfma_f32_16x16x32_bf16 v[114:117], v[196:199], v[212:215], v[114:117]
	v_mfma_f32_16x16x32_bf16 v[102:105], v[170:173], v[220:223], v[102:105]
	v_mfma_f32_16x16x32_bf16 v[98:101], v[196:199], v[220:223], v[98:101]
	v_mfma_f32_16x16x32_bf16 v[86:89], v[170:173], v[228:231], v[86:89]
	v_mfma_f32_16x16x32_bf16 v[82:85], v[196:199], v[228:231], v[82:85]
	s_barrier
; #define PG8_STAGE(bufoff, gbase, voff) do { _Pragma("unroll") for (int _i = 0; _i < 2; ++_i) \
;         __builtin_amdgcn_global_load_lds((const unsigned*)((const char*)(gbase) + (voff)[_i]), (PG8_LAS unsigned*)(lds + (bufoff) + ldsw + _i * 8192), 16, 0, 0); } while (0)
; #define PG8_LDA(dst, b, h) do { _Pragma("unroll") for (int m = 0; m < 4; ++m) _Pragma("unroll") for (int k = 0; k < 2; ++k) dst[m][k] = *(const PG8_LAS bf16x8*)(lds + PG8_SA(b, h) + aoff + m * 2048 + k * 1024); } while (0)
; #define PG8_WAIT_V(n) asm volatile("s_waitcnt vmcnt(" #n ")" ::: "memory")
; template <class Epi, class Sched, bool ALIGN_EPI = false, bool SP2 = false>
; __device__ __forceinline__ void gemm_phase(PG8_LAS unsigned char* lds, const Gemm g, const Sched& S, const Epi& E) {
;     ...
;             PG8_LDA(At, 1, 1); PG8_STAGE(PG8_SB(1, 0), b3, voffB); PG8_STAGE(PG8_SB(1, 1), b3 + hstep, voffB); PG8_STAGE(PG8_SA(1, 0), a3, voffA);
;             PG8_WAIT_V(8); PG8_WAIT_L(0); PG8_BAR; PG8_MMA(1, 0, At, B0); PG8_MMA(1, 1, At, B1); PG8_BAR; PG8_SCHED;
;             } else {
;             PG8_LDB(B0, 0, 0); PG8_SCHED; PG8_LDA(At, 0, 0); PG8_STAGE(PG8_SA(1, 1), a1 + hstep, voffA);
;             PG8_WAIT_L(8); PG8_BAR; PG8_WAIT_L(0); PG8_MMA(0, 0, At, B0); PG8_BAR; PG8_SCHED;
;             PG8_LDB(B1, 0, 1); PG8_STAGE(PG8_SB(0, 0), b2, voffB);
;             PG8_BAR; PG8_WAIT_L(0); PG8_MMA(0, 1, At, B1); PG8_BAR;
;             PG8_LDA(At, 0, 1); PG8_STAGE(PG8_SA(0, 0), a2, voffA);
;             PG8_BAR; PG8_WAIT_L(0); PG8_MMA(1, 0, At, B0); PG8_BAR; PG8_SCHED;
;             PG8_STAGE(PG8_SB(0, 1), b2 + hstep, voffB);
;             PG8_WAIT_V(6); PG8_BAR; PG8_MMA(1, 1, At, B1); PG8_BAR;
;             PG8_LDB(B0, 1, 0); PG8_SCHED; PG8_LDA(At, 1, 0); PG8_STAGE(PG8_SA(0, 1), a2 + hstep, voffA);
;             PG8_WAIT_L(8); PG8_BAR; PG8_WAIT_L(0); PG8_MMA(0, 0, At, B0); PG8_BAR; PG8_SCHED;
;             PG8_LDB(B1, 1, 1); PG8_STAGE(PG8_SB(1, 0), b3, voffB);
;             PG8_BAR; PG8_WAIT_L(0); PG8_MMA(0, 1, At, B1); PG8_BAR;
;             PG8_LDA(At, 1, 1); PG8_STAGE(PG8_SA(1, 0), a3, voffA);
;             PG8_BAR; PG8_WAIT_L(0); PG8_MMA(1, 0, At, B0); PG8_BAR; PG8_SCHED;
;             PG8_STAGE(PG8_SB(1, 1), b3 + hstep, voffB);
;             PG8_WAIT_V(6); PG8_BAR; PG8_MMA(1, 1, At, B1); PG8_BAR;
;             }
;         }
;         if constexpr (ALIGN_EPI) { if (wr == 0) PG8_BAR; }
	s_add_i32 s50, s61, s4
	v_lshl_add_u64 v[174:175], v[174:175], 0, s[34:35]
	s_mov_b32 m0, s50
	ds_read_b128 v[200:203], v178 offset:49152
	ds_read_b128 v[204:207], v178 offset:50176
	ds_read_b128 v[208:211], v178 offset:51200
	ds_read_b128 v[212:215], v178 offset:52224
	ds_read_b128 v[216:219], v178 offset:53248
	ds_read_b128 v[220:223], v178 offset:54272
	ds_read_b128 v[224:227], v178 offset:55296
	ds_read_b128 v[228:231], v178 offset:56320
	global_load_lds_dwordx4 v[174:175], off
	s_add_i32 m0, s50, 0x2000
	s_add_u32 s48, s48, 0x40080
	v_lshl_add_u64 v[174:175], v[184:185], 0, s[34:35]
	s_addc_u32 s49, s49, 0
	s_add_i32 s50, s72, s4
	global_load_lds_dwordx4 v[174:175], off
	v_lshl_add_u64 v[174:175], s[48:49], 0, v[148:149]
	s_mov_b32 m0, s50
	s_nop 0
	global_load_lds_dwordx4 v[174:175], off
	v_lshl_add_u64 v[174:175], s[48:49], 0, v[152:153]
	s_add_i32 m0, s50, 0x2000
	s_nop 0
	global_load_lds_dwordx4 v[174:175], off
	v_lshl_add_u64 v[174:175], v[232:233], 0, s[34:35]
	s_mov_b32 m0, s9
	s_nop 0
	global_load_lds_dwordx4 v[174:175], off
	v_lshl_add_u64 v[174:175], v[234:235], 0, s[34:35]
	s_mov_b32 m0, s86
	s_nop 0
	global_load_lds_dwordx4 v[174:175], off
	s_waitcnt vmcnt(8)
	s_waitcnt lgkmcnt(0)
	s_barrier
	v_mfma_f32_16x16x32_bf16 v[78:81], v[58:61], v[200:203], v[78:81]
	v_mfma_f32_16x16x32_bf16 v[74:77], v[66:69], v[200:203], v[74:77]
	v_mfma_f32_16x16x32_bf16 v[46:49], v[58:61], v[208:211], v[46:49]
	v_mfma_f32_16x16x32_bf16 v[42:45], v[66:69], v[208:211], v[42:45]
	v_mfma_f32_16x16x32_bf16 v[28:31], v[58:61], v[216:219], v[28:31]
	v_mfma_f32_16x16x32_bf16 v[24:27], v[66:69], v[216:219], v[24:27]
	v_mfma_f32_16x16x32_bf16 v[12:15], v[58:61], v[224:227], v[12:15]
	v_mfma_f32_16x16x32_bf16 v[8:11], v[66:69], v[224:227], v[8:11]
	v_mfma_f32_16x16x32_bf16 v[78:81], v[62:65], v[204:207], v[78:81]
	v_mfma_f32_16x16x32_bf16 v[74:77], v[70:73], v[204:207], v[74:77]
	v_mfma_f32_16x16x32_bf16 v[46:49], v[62:65], v[212:215], v[46:49]
	v_mfma_f32_16x16x32_bf16 v[42:45], v[70:73], v[212:215], v[42:45]
	v_mfma_f32_16x16x32_bf16 v[28:31], v[62:65], v[220:223], v[28:31]
	v_mfma_f32_16x16x32_bf16 v[24:27], v[70:73], v[220:223], v[24:27]
	v_mfma_f32_16x16x32_bf16 v[12:15], v[62:65], v[228:231], v[12:15]
	v_mfma_f32_16x16x32_bf16 v[8:11], v[70:73], v[228:231], v[8:11]
	v_mfma_f32_16x16x32_bf16 v[50:53], v[158:161], v[200:203], v[50:53]
	v_mfma_f32_16x16x32_bf16 v[62:65], v[170:173], v[204:207], v[50:53]
	v_mfma_f32_16x16x32_bf16 v[50:53], v[180:183], v[200:203], v[54:57]
	v_mfma_f32_16x16x32_bf16 v[38:41], v[158:161], v[208:211], v[38:41]
	v_mfma_f32_16x16x32_bf16 v[34:37], v[180:183], v[208:211], v[34:37]
	v_mfma_f32_16x16x32_bf16 v[20:23], v[158:161], v[216:219], v[20:23]
	v_mfma_f32_16x16x32_bf16 v[16:19], v[180:183], v[216:219], v[16:19]
	v_mfma_f32_16x16x32_bf16 v[4:7], v[158:161], v[224:227], v[4:7]
	v_mfma_f32_16x16x32_bf16 v[0:3], v[180:183], v[224:227], v[0:3]
	v_mfma_f32_16x16x32_bf16 v[58:61], v[196:199], v[204:207], v[50:53]
	v_mfma_f32_16x16x32_bf16 v[38:41], v[170:173], v[212:215], v[38:41]
	v_mfma_f32_16x16x32_bf16 v[34:37], v[196:199], v[212:215], v[34:37]
	v_mfma_f32_16x16x32_bf16 v[20:23], v[170:173], v[220:223], v[20:23]
	v_mfma_f32_16x16x32_bf16 v[16:19], v[196:199], v[220:223], v[16:19]
	v_mfma_f32_16x16x32_bf16 v[4:7], v[170:173], v[228:231], v[4:7]
	v_mfma_f32_16x16x32_bf16 v[0:3], v[196:199], v[228:231], v[0:3]
	s_barrier
	s_add_i32 s80, s80, 2
	s_add_u32 vcc_hi, vcc_hi, 0x100
	s_addc_u32 s7, s7, 0
	s_add_u32 s46, s46, 0x100
	s_addc_u32 s47, s47, 0
	s_cmp_gt_u32 s80, 13
	s_cbranch_scc0 .LBB0_145
	v_readlane_b32 s46, v254, 51
	v_readlane_b32 s47, v254, 52
	s_and_b64 vcc, exec, s[46:47]
	s_cbranch_vccz .LBB0_148
	s_barrier

; #define PG8_BAR __builtin_amdgcn_s_barrier()
; template <class Epi, class Sched, bool ALIGN_EPI = false, bool SP2 = false>
; __device__ __forceinline__ void gemm_phase(PG8_LAS unsigned char* lds, const Gemm g, const Sched& S, const Epi& E) {
;     ...
;         if constexpr (ALIGN_EPI) { if (wr == 0) PG8_BAR; }
;         if constexpr (!Epi::AFTER_DRAIN) { if constexpr (Epi::PREFETCH) E(acc, cur, wr, wc, fr, fq, epre); else E(acc, cur, wr, wc, fr, fq); S.done(cur); }
;         if (!has_next) break;
; #pragma unroll
;         for (int a = 0; a < 2; ++a)
; #pragma unroll
;             for (int b = 0; b < 2; ++b)
; #pragma unroll
;                 for (int m = 0; m < 4; ++m)
; #pragma unroll
;                     for (int n = 0; n < 2; ++n) acc[a][b][m][n] = (f32x4){0.f, 0.f, 0.f, 0.f};
;         cur = nxt; cA = nA; cB = nB; ++ui;
;         if constexpr (Epi::PREFETCH) E.prefetch(cur, wr, fr, epre);
;         if constexpr (ALIGN_EPI) { if (wr == 1) PG8_BAR; }
.LBB0_180:
	s_or_b64 exec, exec, s[46:47]
	s_andn2_b64 vcc, exec, s[92:93]
	s_mov_b64 s[44:45], -1
	s_cbranch_vccnz .LBB0_136
	v_readlane_b32 s44, v254, 47
	v_readlane_b32 s45, v254, 48
	s_andn2_b64 vcc, exec, s[44:45]
	s_cmp_lg_u32 s44, 0
	s_cselect_b32 s100, 1, 0
	s_branch .LBB0_135

; #define GAS __attribute__((address_space(1)))
; template <bool HIN_F32, bool LAST>
; __device__ __forceinline__ void fin_phase(const float* x, float* out, bf16_t* HI, unsigned char* LO, float* rs, const bf16_t* f, const float* ss, const float* gpost, float coef, int gw, int NGW, int rend, int lane) {
;     f32x4 gpv[4];
; #pragma unroll
;     for (int j = 0; j < 4; ++j) gpv[j] = *(const GAS f32x4*)(gpost + 512 * (j >> 1) + 8 * lane + 4 * (j & 1));
;     FinStage S[3];
;     fin_load<HIN_F32>(S[0], x, HI, LO, f, ss, gw, NGW, lane);
;     if (gw + 2 * NGW < rend) fin_load<HIN_F32>(S[1], x, HI, LO, f, ss, gw + 2 * NGW, NGW, lane);
;     for (int base = gw; base < rend; base += 6 * NGW) {
.LBB0_269:
	s_cmp_ge_i32 s2, s51
	s_cbranch_scc1 .LBB0_294
	s_mov_b32 s101, 0
	v_and_b32_e32 v82, 64, v191
	v_add_u32_e32 v82, 64, v82
	v_xor_b32_e32 v83, 1, v191
	v_cmp_lt_i32_e32 vcc, v83, v82
	s_lshl_b64 s[46:47], s[2:3], 2
	s_add_u32 s7, s46, 0x900000
	v_cndmask_b32_e32 v83, v191, v83, vcc
	v_lshlrev_b32_e32 v184, 2, v83
	v_xor_b32_e32 v83, 2, v191
	v_cmp_lt_i32_e32 vcc, v83, v82
	s_waitcnt vmcnt(1)
	v_mov_b64_e32 v[136:137], v[48:49]
	v_mov_b64_e32 v[132:133], v[40:41]
	v_cndmask_b32_e32 v83, v191, v83, vcc
	v_lshlrev_b32_e32 v185, 2, v83
	v_xor_b32_e32 v83, 4, v191
	v_cmp_lt_i32_e32 vcc, v83, v82
	v_mov_b64_e32 v[128:129], v[30:31]
	v_mov_b64_e32 v[112:113], v[22:23]
	v_cndmask_b32_e32 v83, v191, v83, vcc
	v_lshlrev_b32_e32 v195, 2, v83
	v_xor_b32_e32 v83, 8, v191
	v_cmp_lt_i32_e32 vcc, v83, v82
	v_mov_b64_e32 v[140:141], v[44:45]
	v_mov_b64_e32 v[144:145], v[36:37]
	v_cndmask_b32_e32 v83, v191, v83, vcc
	v_lshlrev_b32_e32 v196, 2, v83
	v_xor_b32_e32 v83, 16, v191
	v_cmp_lt_i32_e32 vcc, v83, v82
	v_mov_b64_e32 v[116:117], v[26:27]
	v_mov_b64_e32 v[120:121], v[18:19]
	v_cndmask_b32_e32 v83, v191, v83, vcc
	v_lshlrev_b32_e32 v197, 2, v83
	v_xor_b32_e32 v83, 32, v191
	v_cmp_lt_i32_e32 vcc, v83, v82
	v_cmp_eq_u32_e64 s[40:41], 0, v193
	s_addc_u32 s82, s47, 0
	v_cndmask_b32_e32 v82, v191, v83, vcc
	v_lshlrev_b32_e32 v198, 2, v82
	v_lshlrev_b32_e32 v82, 1, v177
	v_mov_b32_e32 v83, v32
	v_lshl_add_u64 v[156:157], s[62:63], 0, v[82:83]
	v_lshl_add_u64 v[158:159], s[68:69], 0, v[82:83]
	v_lshl_add_u64 v[160:161], s[44:45], 0, v[152:153]
	v_lshl_or_b32 v170, v193, 4, s8
	v_mov_b32_e32 v171, s9
	s_waitcnt vmcnt(0)
	v_mov_b32_e32 v208, v176
	v_mov_b32_e32 v205, v173
	v_mov_b64_e32 v[134:135], v[46:47]
	v_mov_b64_e32 v[130:131], v[38:39]
	v_mov_b64_e32 v[126:127], v[28:29]
	v_mov_b64_e32 v[110:111], v[20:21]
	v_mov_b32_e32 v209, v175
	v_mov_b32_e32 v207, v174
	v_mov_b32_e32 v206, v172
	v_mov_b32_e32 v204, v149
	v_mov_b64_e32 v[138:139], v[42:43]
	v_mov_b64_e32 v[142:143], v[34:35]
	v_mov_b64_e32 v[114:115], v[24:25]
	v_mov_b64_e32 v[118:119], v[16:17]
	s_mov_b32 s83, s2
	s_branch .LBB0_273

; #define GAS __attribute__((address_space(1)))
; template <bool HIN_F32>
; __device__ __forceinline__ void fin_load(FinStage& S, const float* x, const bf16_t* HI, const unsigned char* LO, const bf16_t* f, const float* ss, int row0, int NGW, int lane) {
; #pragma unroll
;     for (int t = 0; t < 2; ++t) { const int row = row0 + t * NGW;
; #pragma unroll
;         for (int j = 0; j < 2; ++j) { const int idx = 512 * j + 8 * lane;
;             if (HIN_F32) { S.v[t][j][0] = __builtin_nontemporal_load((const GAS f32x4*)(x + (size_t)row * DM + idx)); S.v[t][j][1] = __builtin_nontemporal_load((const GAS f32x4*)(x + (size_t)row * DM + idx + 4)); }
;             else { S.hw[t][j] = __builtin_nontemporal_load((const GAS u32x4*)(HI + (size_t)row * DM + idx)); S.lw[t][j] = __builtin_nontemporal_load((const GAS unsigned*)(LO + (size_t)row * (DM / 2) + (idx >> 1))); }
;             S.fw[t][j] = __builtin_nontemporal_load((const GAS u32x4*)(f + (size_t)row * DM + idx)); }
;         S.sp[t] = *(const GAS float*)(ss + (size_t)row * 16 + (lane & 15)); }
; }
; template <bool HIN_F32, bool LAST>
; __device__ __forceinline__ void fin_phase(const float* x, float* out, bf16_t* HI, unsigned char* LO, float* rs, const bf16_t* f, const float* ss, const float* gpost, float coef, int gw, int NGW, int rend, int lane) {
;     ...
;     for (int base = gw; base < rend; base += 6 * NGW) {
; #pragma unroll
;         for (int u = 0; u < 3; ++u) {
;             const int rowc = base + 2 * NGW * u, rowl = rowc + 4 * NGW;
;             if (rowl < rend) fin_load<HIN_F32>(S[(u + 2) % 3], x, HI, LO, f, ss, rowl, NGW, lane);
;             if (rowc < rend) fin_compute<HIN_F32, LAST>(S[u], out, HI, LO, rs, gpv, coef, rowc, NGW, lane);
.LBB0_273:
	s_add_i32 s8, s73, s83
	s_cmp_lt_i32 s8, s51
	s_cselect_b64 s[76:77], -1, 0
	s_cmp_ge_i32 s8, s51
	s_cselect_b32 s101, 1, s101
	s_cbranch_scc1 .LBB0_275
	s_ashr_i32 s9, s8, 31
	s_lshl_b64 s[44:45], s[8:9], 9
	s_add_u32 s44, s0, s44
	s_addc_u32 s45, s50, s45
	s_lshl_b64 s[46:47], s[8:9], 11
	v_lshl_add_u64 v[86:87], v[156:157], 0, s[46:47]
	v_lshl_add_u64 v[82:83], s[44:45], 0, v[152:153]
	v_lshl_add_u64 v[88:89], v[158:159], 0, s[46:47]
	global_load_dword v199, v[82:83], off nt
	s_nop 0
	global_load_dwordx4 v[82:85], v[88:89], off nt
	global_load_dwordx4 v[94:97], v[86:87], off nt
	global_load_dwordx4 v[90:93], v[86:87], off offset:1024 nt
	v_lshl_add_u64 v[86:87], s[44:45], 0, v[154:155]
	s_lshl_b64 s[44:45], s[8:9], 6
	v_lshl_add_u64 v[98:99], v[150:151], 0, s[44:45]
	s_add_i32 s44, s85, s83
	s_ashr_i32 s45, s44, 31
	s_lshl_b64 s[46:47], s[44:45], 9
	s_add_u32 s46, s0, s46
	s_addc_u32 s47, s50, s47
	s_lshl_b64 s[48:49], s[44:45], 11
	global_load_dword v200, v[86:87], off nt
	global_load_dword v202, v[98:99], off
	s_nop 0
	global_load_dwordx4 v[86:89], v[88:89], off offset:1024 nt
	v_lshl_add_u64 v[102:103], v[156:157], 0, s[48:49]
	v_lshl_add_u64 v[98:99], s[46:47], 0, v[152:153]
	s_lshl_b64 s[44:45], s[44:45], 6
	v_lshl_add_u64 v[122:123], v[158:159], 0, s[48:49]
	global_load_dword v201, v[98:99], off nt
	s_nop 0
	global_load_dwordx4 v[98:101], v[122:123], off nt
	global_load_dwordx4 v[106:109], v[102:103], off nt
	s_nop 0
	global_load_dwordx4 v[102:105], v[102:103], off offset:1024 nt
	v_lshl_add_u64 v[124:125], s[46:47], 0, v[154:155]
	v_lshl_add_u64 v[210:211], v[150:151], 0, s[44:45]
	global_load_dword v203, v[124:125], off nt
	s_nop 0
	global_load_dword v210, v[210:211], off
	s_nop 0
	global_load_dwordx4 v[122:125], v[122:123], off offset:1024 nt
.LBB0_275:
	s_waitcnt vmcnt(48)
	s_cmp_eq_u32 s101, 0
	s_cbranch_scc1 .Lfin_mid_S_go
	s_waitcnt vmcnt(0)

; #define GAS __attribute__((address_space(1)))
; template <bool HIN_F32>
; __device__ __forceinline__ void fin_load(FinStage& S, const float* x, const bf16_t* HI, const unsigned char* LO, const bf16_t* f, const float* ss, int row0, int NGW, int lane) {
; #pragma unroll
;     for (int t = 0; t < 2; ++t) { const int row = row0 + t * NGW;
; #pragma unroll
;         for (int j = 0; j < 2; ++j) { const int idx = 512 * j + 8 * lane;
;             if (HIN_F32) { S.v[t][j][0] = __builtin_nontemporal_load((const GAS f32x4*)(x + (size_t)row * DM + idx)); S.v[t][j][1] = __builtin_nontemporal_load((const GAS f32x4*)(x + (size_t)row * DM + idx + 4)); }
;             else { S.hw[t][j] = __builtin_nontemporal_load((const GAS u32x4*)(HI + (size_t)row * DM + idx)); S.lw[t][j] = __builtin_nontemporal_load((const GAS unsigned*)(LO + (size_t)row * (DM / 2) + (idx >> 1))); }
;             S.fw[t][j] = __builtin_nontemporal_load((const GAS u32x4*)(f + (size_t)row * DM + idx)); }
;         S.sp[t] = *(const GAS float*)(ss + (size_t)row * 16 + (lane & 15)); }
; }
; template <bool HIN_F32, bool LAST>
; __device__ __forceinline__ void fin_phase(const float* x, float* out, bf16_t* HI, unsigned char* LO, float* rs, const bf16_t* f, const float* ss, const float* gpost, float coef, int gw, int NGW, int rend, int lane) {
;     ...
;     for (int base = gw; base < rend; base += 6 * NGW) {
; #pragma unroll
;         for (int u = 0; u < 3; ++u) {
;             const int rowc = base + 2 * NGW * u, rowl = rowc + 4 * NGW;
;             if (rowl < rend) fin_load<HIN_F32>(S[(u + 2) % 3], x, HI, LO, f, ss, rowl, NGW, lane);
;             if (rowc < rend) fin_compute<HIN_F32, LAST>(S[u], out, HI, LO, rs, gpv, coef, rowc, NGW, lane);
.LBB0_279:
	s_or_b64 exec, exec, s[46:47]
	s_add_i32 s78, s84, s83
	s_cmp_ge_i32 s78, s51
	s_cselect_b64 s[80:81], -1, 0
	s_cselect_b32 s101, 1, s101
	s_and_b64 vcc, exec, s[80:81]
	s_cbranch_vccnz .LBB0_283
	s_ashr_i32 s79, s78, 31
	s_lshl_b64 s[44:45], s[78:79], 9
	s_add_u32 s44, s0, s44
	s_addc_u32 s45, s50, s45
	v_lshl_add_u64 v[110:111], s[44:45], 0, v[152:153]
	v_lshl_add_u64 v[128:129], s[44:45], 0, v[154:155]
	s_lshl_b64 s[44:45], s[78:79], 6
	v_readlane_b32 s9, v253, 47
	v_lshl_add_u64 v[130:131], v[150:151], 0, s[44:45]
	s_add_i32 s44, s9, s83
	s_lshl_b64 s[46:47], s[78:79], 11
	s_ashr_i32 s45, s44, 31
	v_lshl_add_u64 v[114:115], v[156:157], 0, s[46:47]
	v_lshl_add_u64 v[126:127], v[158:159], 0, s[46:47]
	s_lshl_b64 s[46:47], s[44:45], 9
	s_add_u32 s46, s0, s46
	s_addc_u32 s47, s50, s47
	s_lshl_b64 s[48:49], s[44:45], 11
	global_load_dword v204, v[110:111], off nt
	s_nop 0
	global_load_dwordx4 v[110:113], v[126:127], off nt
	global_load_dwordx4 v[118:121], v[114:115], off nt
	s_nop 0
	global_load_dwordx4 v[114:117], v[114:115], off offset:1024 nt
	s_nop 0
	global_load_dword v206, v[128:129], off nt
	global_load_dword v205, v[130:131], off
	s_nop 0
	global_load_dwordx4 v[126:129], v[126:127], off offset:1024 nt
	v_lshl_add_u64 v[134:135], v[156:157], 0, s[48:49]
	v_lshl_add_u64 v[130:131], s[46:47], 0, v[152:153]
	v_lshl_add_u64 v[136:137], v[158:159], 0, s[48:49]
	global_load_dword v207, v[130:131], off nt
	s_nop 0
	global_load_dwordx4 v[130:133], v[136:137], off nt
	global_load_dwordx4 v[142:145], v[134:135], off nt
	global_load_dwordx4 v[138:141], v[134:135], off offset:1024 nt
	v_lshl_add_u64 v[134:135], s[46:47], 0, v[154:155]
	s_lshl_b64 s[44:45], s[44:45], 6
	s_waitcnt lgkmcnt(0)
	v_lshl_add_u64 v[212:213], v[150:151], 0, s[44:45]
	global_load_dword v209, v[134:135], off nt
	global_load_dword v208, v[212:213], off
	s_nop 0
	global_load_dwordx4 v[134:137], v[136:137], off offset:1024 nt
	v_readlane_b32 s79, v253, 32
	v_readlane_b32 s73, v253, 4
	v_readlane_b32 s72, v253, 3
	v_readlane_b32 s61, v253, 49
	s_add_i32 s44, s72, s83
	s_cmp_ge_i32 s44, s51
	s_cbranch_scc0 .LBB0_284
.LBB0_281:
	s_add_i32 s44, s79, s83
	s_cmp_ge_i32 s44, s51
	s_cselect_b32 s101, 1, s101
	s_cbranch_scc1 .LBB0_289

; template <bool HIN_F32, bool LAST>
; __device__ __forceinline__ void fin_phase(const float* x, float* out, bf16_t* HI, unsigned char* LO, float* rs, const bf16_t* f, const float* ss, const float* gpost, float coef, int gw, int NGW, int rend, int lane) {
;     ...
;     for (int base = gw; base < rend; base += 6 * NGW) {
; #pragma unroll
;         for (int u = 0; u < 3; ++u) {
;             const int rowc = base + 2 * NGW * u, rowl = rowc + 4 * NGW;
;             if (rowl < rend) fin_load<HIN_F32>(S[(u + 2) % 3], x, HI, LO, f, ss, rowl, NGW, lane);
;             if (rowc < rend) fin_compute<HIN_F32, LAST>(S[u], out, HI, LO, rs, gpv, coef, rowc, NGW, lane);
.LBB0_288:
	s_or_b64 exec, exec, s[46:47]
	s_add_i32 s44, s79, s83
	s_cmp_ge_i32 s44, s51
	s_cselect_b32 s101, 1, s101
	s_cbranch_scc0 .LBB0_282

; #define PG8_STAGE(bufoff, gbase, voff) do { _Pragma("unroll") for (int _i = 0; _i < 2; ++_i) \
;         __builtin_amdgcn_global_load_lds((const unsigned*)((const char*)(gbase) + (voff)[_i]), (PG8_LAS unsigned*)(lds + (bufoff) + ldsw + _i * 8192), 16, 0, 0); } while (0)
; #define PG8_LDA(dst, b, h) do { _Pragma("unroll") for (int m = 0; m < 4; ++m) _Pragma("unroll") for (int k = 0; k < 2; ++k) dst[m][k] = *(const PG8_LAS bf16x8*)(lds + PG8_SA(b, h) + aoff + m * 2048 + k * 1024); } while (0)
; #define PG8_LDB(dst, b, h) do { _Pragma("unroll") for (int n = 0; n < 2; ++n) _Pragma("unroll") for (int k = 0; k < 2; ++k) dst[n][k] = *(const PG8_LAS bf16x8*)(lds + PG8_SB(b, h) + boff + n * 2048 + k * 1024); } while (0)
; #define PG8_WAIT_V(n) asm volatile("s_waitcnt vmcnt(" #n ")" ::: "memory")
; #define PG8_WAIT_L(n) asm volatile("s_waitcnt lgkmcnt(" #n ")" ::: "memory")
; #define PG8_BAR __builtin_amdgcn_s_barrier()
; #define PG8_SCHED __builtin_amdgcn_sched_barrier(0)
; template <class Epi, class Sched, bool ALIGN_EPI = false, bool SP2 = false>
; __device__ __forceinline__ void gemm_phase(PG8_LAS unsigned char* lds, const Gemm g, const Sched& S, const Epi& E) {
;     ...
;         for (int t = 0; t < nt; t += 2) {
;             const bool last = (t == nt - 2);
;             const char* a1 = cA + (size_t)(t + 1) * kstep;
;             const char* a2 = last ? nA : cA + (size_t)(t + 2) * kstep; const char* b2 = last ? nB : cB + (size_t)(t + 2) * kstep;
;             const char* a3 = a2 + kstep; const char* b3 = b2 + kstep;
;             if (last && has_next) S.a_ready(nxt);
;             if constexpr (SP2) {
;             PG8_LDB(B0, 0, 0); PG8_LDB(B1, 0, 1); PG8_SCHED; PG8_LDA(At, 0, 0); PG8_STAGE(PG8_SA(1, 1), a1 + hstep, voffA);
;             PG8_WAIT_V(8); PG8_WAIT_L(0); PG8_BAR; PG8_MMA(0, 0, At, B0); PG8_MMA(0, 1, At, B1); PG8_BAR; PG8_SCHED;
;     ...
; #pragma unroll
;         for (int a = 0; a < 2; ++a)
; #pragma unroll
;             for (int b = 0; b < 2; ++b)
; #pragma unroll
;                 for (int m = 0; m < 4; ++m)
; #pragma unroll
;                     for (int n = 0; n < 2; ++n) acc[a][b][m][n] = (f32x4){0.f, 0.f, 0.f, 0.f};
;         cur = nxt; cA = nA; cB = nB; ++ui;
;         if constexpr (Epi::PREFETCH) E.prefetch(cur, wr, fr, epre);
;         if constexpr (ALIGN_EPI) { if (wr == 1) PG8_BAR; }
.LBB0_368:
	s_add_u32 s90, s44, 0x100
	s_addc_u32 s91, s45, 0
	s_add_u32 s44, s46, 0x80
	v_mov_b32_e32 v0, 0
	s_addc_u32 s45, s47, 0
	s_mov_b32 s46, 0
	v_mov_b32_e32 v1, v0
	v_mov_b32_e32 v2, v0
	v_mov_b32_e32 v3, v0
	v_mov_b32_e32 v4, v0
	s_waitcnt lgkmcnt(0)
	v_mov_b32_e32 v5, v0
	v_mov_b32_e32 v6, v0
	v_mov_b32_e32 v7, v0
	v_mov_b32_e32 v16, v0
	v_mov_b32_e32 v17, v0
	v_mov_b32_e32 v18, v0
	v_mov_b32_e32 v19, v0
	v_mov_b32_e32 v20, v0
	v_mov_b32_e32 v21, v0
	v_mov_b32_e32 v22, v0
	v_mov_b32_e32 v23, v0
	v_mov_b32_e32 v34, v0
	v_mov_b32_e32 v35, v0
	v_mov_b32_e32 v36, v0
	v_mov_b32_e32 v37, v0
	v_mov_b32_e32 v38, v0
	v_mov_b32_e32 v39, v0
	v_mov_b32_e32 v40, v0
	v_mov_b32_e32 v41, v0
	v_mov_b32_e32 v50, v0
	v_mov_b32_e32 v51, v0
	v_mov_b32_e32 v52, v0
	v_mov_b32_e32 v53, v0
	v_mov_b32_e32 v54, v0
	v_mov_b32_e32 v55, v0
	v_mov_b32_e32 v56, v0
	v_mov_b32_e32 v57, v0
	v_mov_b32_e32 v8, v0
	v_mov_b32_e32 v9, v0
	v_mov_b32_e32 v10, v0
	v_mov_b32_e32 v11, v0
	v_mov_b32_e32 v12, v0
	v_mov_b32_e32 v13, v0
	v_mov_b32_e32 v14, v0
	v_mov_b32_e32 v15, v0
	v_mov_b32_e32 v24, v0
	v_mov_b32_e32 v25, v0
	v_mov_b32_e32 v26, v0
	v_mov_b32_e32 v27, v0
	v_mov_b32_e32 v28, v0
	v_mov_b32_e32 v29, v0
	v_mov_b32_e32 v30, v0
	v_mov_b32_e32 v31, v0
	v_mov_b32_e32 v42, v0
	v_mov_b32_e32 v43, v0
	v_mov_b32_e32 v44, v0
	v_mov_b32_e32 v45, v0
	v_mov_b32_e32 v46, v0
	v_mov_b32_e32 v47, v0
	v_mov_b32_e32 v48, v0
	v_mov_b32_e32 v49, v0
	v_mov_b32_e32 v58, v0
	v_mov_b32_e32 v59, v0
	v_mov_b32_e32 v60, v0
	v_mov_b32_e32 v61, v0
	v_mov_b32_e32 v62, v0
	v_mov_b32_e32 v63, v0
	v_mov_b32_e32 v64, v0
	v_mov_b32_e32 v65, v0
	v_mov_b32_e32 v66, v0
	v_mov_b32_e32 v67, v0
	v_mov_b32_e32 v68, v0
	v_mov_b32_e32 v69, v0
	v_mov_b32_e32 v70, v0
	v_mov_b32_e32 v71, v0
	v_mov_b32_e32 v72, v0
	v_mov_b32_e32 v73, v0
	v_mov_b32_e32 v82, v0
	v_mov_b32_e32 v83, v0
	v_mov_b32_e32 v84, v0
	v_mov_b32_e32 v85, v0
	v_mov_b32_e32 v86, v0
	v_mov_b32_e32 v87, v0
	v_mov_b32_e32 v88, v0
	v_mov_b32_e32 v89, v0
	v_mov_b32_e32 v98, v0
	v_mov_b32_e32 v99, v0
	v_mov_b32_e32 v100, v0
	v_mov_b32_e32 v101, v0
	v_mov_b32_e32 v102, v0
	v_mov_b32_e32 v103, v0
	v_mov_b32_e32 v104, v0
	v_mov_b32_e32 v105, v0
	v_mov_b32_e32 v114, v0
	v_mov_b32_e32 v115, v0
	v_mov_b32_e32 v116, v0
	v_mov_b32_e32 v117, v0
	v_mov_b32_e32 v118, v0
	v_mov_b32_e32 v119, v0
	v_mov_b32_e32 v120, v0
	v_mov_b32_e32 v121, v0
	v_mov_b32_e32 v74, v0
	v_mov_b32_e32 v75, v0
	v_mov_b32_e32 v76, v0
	v_mov_b32_e32 v77, v0
	v_mov_b32_e32 v78, v0
	v_mov_b32_e32 v79, v0
	v_mov_b32_e32 v80, v0
	v_mov_b32_e32 v81, v0
	v_mov_b32_e32 v90, v0
	v_mov_b32_e32 v91, v0
	v_mov_b32_e32 v92, v0
	v_mov_b32_e32 v93, v0
	v_mov_b32_e32 v94, v0
	v_mov_b32_e32 v95, v0
	v_mov_b32_e32 v96, v0
	v_mov_b32_e32 v97, v0
	v_mov_b32_e32 v106, v0
	v_mov_b32_e32 v107, v0
	v_mov_b32_e32 v108, v0
	v_mov_b32_e32 v109, v0
	v_mov_b32_e32 v110, v0
	v_mov_b32_e32 v111, v0
	v_mov_b32_e32 v112, v0
	v_mov_b32_e32 v113, v0
	v_mov_b32_e32 v122, v0
	v_mov_b32_e32 v123, v0
	v_mov_b32_e32 v124, v0
	v_mov_b32_e32 v125, v0
	v_mov_b32_e32 v126, v0
	v_mov_b32_e32 v127, v0
	v_mov_b32_e32 v128, v0
	v_mov_b32_e32 v129, v0
	s_cmp_eq_u32 s100, 0
	s_cbranch_scc1 .Lrb4_skip
	s_mov_b32 s100, 0
	s_barrier
.Lrb4_skip:
.LBB0_369:
	s_add_i32 s92, s46, 2
	s_add_u32 s61, s44, 0x80
	s_addc_u32 s47, s45, 0
	s_add_i32 s72, 0, 0x10000
	s_cmp_eq_u32 s87, s46
	s_cselect_b32 s47, s43, s47
	s_cselect_b32 s46, s42, s61
	v_add_u32_e32 v149, s72, v146
	s_cselect_b32 s95, s77, s91
	s_cselect_b32 s94, s76, s90
	s_add_i32 s61, 0, 0x14000
	ds_read_b128 v[142:145], v149
	ds_read_b128 v[150:153], v149 offset:1024
	ds_read_b128 v[154:157], v149 offset:2048
	ds_read_b128 v[158:161], v149 offset:3072
	v_add_u32_e32 v149, s61, v146
	ds_read_b128 v[170:173], v149
	ds_read_b128 v[174:177], v149 offset:1024
	ds_read_b128 v[178:181], v149 offset:2048
	ds_read_b128 v[182:185], v149 offset:3072
	v_lshl_add_u64 v[228:229], s[44:45], 0, v[140:141]
	s_add_i32 m0, s51, 0xc000
	ds_read_b128 v[196:199], v148
	ds_read_b128 v[200:203], v148 offset:1024
	ds_read_b128 v[204:207], v148 offset:2048
	ds_read_b128 v[208:211], v148 offset:3072
	ds_read_b128 v[212:215], v148 offset:4096
	ds_read_b128 v[216:219], v148 offset:5120
	ds_read_b128 v[220:223], v148 offset:6144
	ds_read_b128 v[224:227], v148 offset:7168
	global_load_lds_dwordx4 v[228:229], off
	v_lshl_add_u64 v[228:229], s[44:45], 0, v[138:139]
	s_add_i32 m0, s51, 0xe000
	s_nop 0
	global_load_lds_dwordx4 v[228:229], off
	s_waitcnt vmcnt(8)
	s_waitcnt lgkmcnt(0)
	s_barrier
	v_mfma_f32_16x16x32_bf16 v[126:129], v[142:145], v[196:199], v[126:129]
	v_mfma_f32_16x16x32_bf16 v[122:125], v[154:157], v[196:199], v[122:125]
	v_mfma_f32_16x16x32_bf16 v[110:113], v[142:145], v[204:207], v[110:113]
	v_mfma_f32_16x16x32_bf16 v[106:109], v[154:157], v[204:207], v[106:109]
	v_mfma_f32_16x16x32_bf16 v[94:97], v[142:145], v[212:215], v[94:97]
	v_mfma_f32_16x16x32_bf16 v[90:93], v[154:157], v[212:215], v[90:93]
	v_mfma_f32_16x16x32_bf16 v[78:81], v[142:145], v[220:223], v[78:81]
	v_mfma_f32_16x16x32_bf16 v[74:77], v[154:157], v[220:223], v[74:77]
	v_mfma_f32_16x16x32_bf16 v[126:129], v[150:153], v[200:203], v[126:129]
	v_mfma_f32_16x16x32_bf16 v[122:125], v[158:161], v[200:203], v[122:125]
	v_mfma_f32_16x16x32_bf16 v[110:113], v[150:153], v[208:211], v[110:113]
	v_mfma_f32_16x16x32_bf16 v[106:109], v[158:161], v[208:211], v[106:109]
	v_mfma_f32_16x16x32_bf16 v[94:97], v[150:153], v[216:219], v[94:97]
	v_mfma_f32_16x16x32_bf16 v[90:93], v[158:161], v[216:219], v[90:93]
	v_mfma_f32_16x16x32_bf16 v[78:81], v[150:153], v[224:227], v[78:81]
	v_mfma_f32_16x16x32_bf16 v[74:77], v[158:161], v[224:227], v[74:77]
	v_mfma_f32_16x16x32_bf16 v[118:121], v[170:173], v[196:199], v[118:121]
	v_mfma_f32_16x16x32_bf16 v[114:117], v[178:181], v[196:199], v[114:117]
	v_mfma_f32_16x16x32_bf16 v[102:105], v[170:173], v[204:207], v[102:105]
	v_mfma_f32_16x16x32_bf16 v[98:101], v[178:181], v[204:207], v[98:101]
	v_mfma_f32_16x16x32_bf16 v[86:89], v[170:173], v[212:215], v[86:89]
	v_mfma_f32_16x16x32_bf16 v[82:85], v[178:181], v[212:215], v[82:85]
	v_mfma_f32_16x16x32_bf16 v[70:73], v[170:173], v[220:223], v[70:73]
	v_mfma_f32_16x16x32_bf16 v[66:69], v[178:181], v[220:223], v[66:69]
	v_mfma_f32_16x16x32_bf16 v[118:121], v[174:177], v[200:203], v[118:121]
	v_mfma_f32_16x16x32_bf16 v[114:117], v[182:185], v[200:203], v[114:117]
	v_mfma_f32_16x16x32_bf16 v[102:105], v[174:177], v[208:211], v[102:105]
	v_mfma_f32_16x16x32_bf16 v[98:101], v[182:185], v[208:211], v[98:101]
	v_mfma_f32_16x16x32_bf16 v[86:89], v[174:177], v[216:219], v[86:89]
	v_mfma_f32_16x16x32_bf16 v[82:85], v[182:185], v[216:219], v[82:85]
	v_mfma_f32_16x16x32_bf16 v[70:73], v[174:177], v[224:227], v[70:73]
	v_mfma_f32_16x16x32_bf16 v[66:69], v[182:185], v[224:227], v[66:69]
	s_barrier
; #define PG8_STAGE(bufoff, gbase, voff) do { _Pragma("unroll") for (int _i = 0; _i < 2; ++_i) \
;         __builtin_amdgcn_global_load_lds((const unsigned*)((const char*)(gbase) + (voff)[_i]), (PG8_LAS unsigned*)(lds + (bufoff) + ldsw + _i * 8192), 16, 0, 0); } while (0)
; #define PG8_LDA(dst, b, h) do { _Pragma("unroll") for (int m = 0; m < 4; ++m) _Pragma("unroll") for (int k = 0; k < 2; ++k) dst[m][k] = *(const PG8_LAS bf16x8*)(lds + PG8_SA(b, h) + aoff + m * 2048 + k * 1024); } while (0)
; #define PG8_LDB(dst, b, h) do { _Pragma("unroll") for (int n = 0; n < 2; ++n) _Pragma("unroll") for (int k = 0; k < 2; ++k) dst[n][k] = *(const PG8_LAS bf16x8*)(lds + PG8_SB(b, h) + boff + n * 2048 + k * 1024); } while (0)
; #define PG8_MMA(ai, bj, At, Bt) do { __builtin_amdgcn_s_setprio(1); _Pragma("unroll") for (int m = 0; m < 4; ++m) _Pragma("unroll") for (int n = 0; n < 2; ++n) _Pragma("unroll") for (int k = 0; k < 2; ++k) \
;         acc[ai][bj][m][n] = __builtin_amdgcn_mfma_f32_16x16x32_bf16(Bt[n][k], At[m][k], acc[ai][bj][m][n], 0, 0, 0); __builtin_amdgcn_s_setprio(0); } while (0)
; #define PG8_WAIT_V(n) asm volatile("s_waitcnt vmcnt(" #n ")" ::: "memory")
; #define PG8_WAIT_L(n) asm volatile("s_waitcnt lgkmcnt(" #n ")" ::: "memory")
; #define PG8_BAR __builtin_amdgcn_s_barrier()
; #define PG8_SCHED __builtin_amdgcn_sched_barrier(0)
; template <class Epi, class Sched, bool ALIGN_EPI = false, bool SP2 = false>
; __device__ __forceinline__ void gemm_phase(PG8_LAS unsigned char* lds, const Gemm g, const Sched& S, const Epi& E) {
;     ...
;             PG8_WAIT_V(8); PG8_WAIT_L(0); PG8_BAR; PG8_MMA(0, 0, At, B0); PG8_MMA(0, 1, At, B1); PG8_BAR; PG8_SCHED;
;             PG8_LDA(At, 0, 1); PG8_STAGE(PG8_SB(0, 0), b2, voffB); PG8_STAGE(PG8_SB(0, 1), b2 + hstep, voffB); PG8_STAGE(PG8_SA(0, 0), a2, voffA);
;             PG8_WAIT_V(8); PG8_WAIT_L(0); PG8_BAR; PG8_MMA(1, 0, At, B0); PG8_MMA(1, 1, At, B1); PG8_BAR; PG8_SCHED;
;             PG8_LDB(B0, 1, 0); PG8_LDB(B1, 1, 1); PG8_SCHED; PG8_LDA(At, 1, 0); PG8_STAGE(PG8_SA(0, 1), a2 + hstep, voffA);
;             PG8_WAIT_V(8); PG8_WAIT_L(0); PG8_BAR; PG8_MMA(0, 0, At, B0); PG8_MMA(0, 1, At, B1); PG8_BAR; PG8_SCHED;
	s_add_i32 s72, s72, s50
	v_lshl_add_u64 v[228:229], s[94:95], 0, v[132:133]
	s_mov_b32 m0, s72
	ds_read_b128 v[196:199], v148 offset:16384
	ds_read_b128 v[200:203], v148 offset:17408
	ds_read_b128 v[204:207], v148 offset:18432
	ds_read_b128 v[208:211], v148 offset:19456
	ds_read_b128 v[212:215], v148 offset:20480
	ds_read_b128 v[216:219], v148 offset:21504
	ds_read_b128 v[220:223], v148 offset:22528
	ds_read_b128 v[224:227], v148 offset:23552
	global_load_lds_dwordx4 v[228:229], off
	s_add_i32 m0, s72, 0x2000
	v_lshl_add_u64 v[230:231], s[94:95], 0, v[136:137]
	s_add_u32 s94, s94, s8
	s_addc_u32 s95, s95, 0
	s_add_i32 s61, s61, s50
	global_load_lds_dwordx4 v[230:231], off
	v_lshl_add_u64 v[232:233], s[94:95], 0, v[132:133]
	s_mov_b32 m0, s61
	v_lshl_add_u64 v[234:235], s[94:95], 0, v[136:137]
	global_load_lds_dwordx4 v[232:233], off
	s_add_i32 m0, s61, 0x2000
	v_lshl_add_u64 v[236:237], s[46:47], 0, v[130:131]
	global_load_lds_dwordx4 v[234:235], off
	s_mov_b32 m0, s51
	v_lshl_add_u64 v[238:239], s[46:47], 0, v[134:135]
	global_load_lds_dwordx4 v[236:237], off
	s_mov_b32 m0, s78
	s_nop 0
	global_load_lds_dwordx4 v[238:239], off
	s_waitcnt vmcnt(8)
	s_waitcnt lgkmcnt(0)
	s_barrier
	v_mfma_f32_16x16x32_bf16 v[62:65], v[142:145], v[196:199], v[62:65]
	v_mfma_f32_16x16x32_bf16 v[58:61], v[154:157], v[196:199], v[58:61]
	v_mfma_f32_16x16x32_bf16 v[46:49], v[142:145], v[204:207], v[46:49]
	v_mfma_f32_16x16x32_bf16 v[42:45], v[154:157], v[204:207], v[42:45]
	v_mfma_f32_16x16x32_bf16 v[28:31], v[142:145], v[212:215], v[28:31]
	v_mfma_f32_16x16x32_bf16 v[24:27], v[154:157], v[212:215], v[24:27]
	v_mfma_f32_16x16x32_bf16 v[12:15], v[142:145], v[220:223], v[12:15]
	v_mfma_f32_16x16x32_bf16 v[8:11], v[154:157], v[220:223], v[8:11]
	v_mfma_f32_16x16x32_bf16 v[62:65], v[150:153], v[200:203], v[62:65]
	v_mfma_f32_16x16x32_bf16 v[58:61], v[158:161], v[200:203], v[58:61]
	v_mfma_f32_16x16x32_bf16 v[46:49], v[150:153], v[208:211], v[46:49]
	v_mfma_f32_16x16x32_bf16 v[42:45], v[158:161], v[208:211], v[42:45]
	v_mfma_f32_16x16x32_bf16 v[28:31], v[150:153], v[216:219], v[28:31]
	v_mfma_f32_16x16x32_bf16 v[24:27], v[158:161], v[216:219], v[24:27]
	v_mfma_f32_16x16x32_bf16 v[12:15], v[150:153], v[224:227], v[12:15]
	v_mfma_f32_16x16x32_bf16 v[8:11], v[158:161], v[224:227], v[8:11]
	v_mfma_f32_16x16x32_bf16 v[54:57], v[170:173], v[196:199], v[54:57]
	v_mfma_f32_16x16x32_bf16 v[50:53], v[178:181], v[196:199], v[50:53]
	v_mfma_f32_16x16x32_bf16 v[38:41], v[170:173], v[204:207], v[38:41]
	v_mfma_f32_16x16x32_bf16 v[34:37], v[178:181], v[204:207], v[34:37]
	v_mfma_f32_16x16x32_bf16 v[20:23], v[170:173], v[212:215], v[20:23]
	v_mfma_f32_16x16x32_bf16 v[16:19], v[178:181], v[212:215], v[16:19]
	v_mfma_f32_16x16x32_bf16 v[4:7], v[170:173], v[220:223], v[4:7]
	v_mfma_f32_16x16x32_bf16 v[0:3], v[178:181], v[220:223], v[0:3]
	v_mfma_f32_16x16x32_bf16 v[54:57], v[174:177], v[200:203], v[54:57]
	v_mfma_f32_16x16x32_bf16 v[50:53], v[182:185], v[200:203], v[50:53]
	v_mfma_f32_16x16x32_bf16 v[38:41], v[174:177], v[208:211], v[38:41]
	v_mfma_f32_16x16x32_bf16 v[34:37], v[182:185], v[208:211], v[34:37]
	v_mfma_f32_16x16x32_bf16 v[20:23], v[174:177], v[216:219], v[20:23]
	v_mfma_f32_16x16x32_bf16 v[16:19], v[182:185], v[216:219], v[16:19]
	v_mfma_f32_16x16x32_bf16 v[4:7], v[174:177], v[224:227], v[4:7]
	v_mfma_f32_16x16x32_bf16 v[0:3], v[182:185], v[224:227], v[0:3]
	s_barrier
	s_add_i32 s61, 0, 0x18000
	v_add_u32_e32 v149, s61, v146
	s_add_i32 s72, 0, 0x1c000
	ds_read_b128 v[142:145], v149
	ds_read_b128 v[150:153], v149 offset:1024
	ds_read_b128 v[154:157], v149 offset:2048
	ds_read_b128 v[158:161], v149 offset:3072
	v_add_u32_e32 v149, s72, v146
	ds_read_b128 v[170:173], v149
	ds_read_b128 v[174:177], v149 offset:1024
	ds_read_b128 v[178:181], v149 offset:2048
	ds_read_b128 v[182:185], v149 offset:3072
	s_add_u32 s46, s46, s8
	s_addc_u32 s47, s47, 0
	s_mov_b32 m0, s79
	v_lshl_add_u64 v[240:241], s[46:47], 0, v[130:131]
	ds_read_b128 v[196:199], v148 offset:32768
	ds_read_b128 v[200:203], v148 offset:33792
	ds_read_b128 v[204:207], v148 offset:34816
	ds_read_b128 v[208:211], v148 offset:35840
	ds_read_b128 v[212:215], v148 offset:36864
	ds_read_b128 v[216:219], v148 offset:37888
	ds_read_b128 v[220:223], v148 offset:38912
	ds_read_b128 v[224:227], v148 offset:39936
	global_load_lds_dwordx4 v[240:241], off
	v_lshl_add_u64 v[240:241], s[46:47], 0, v[134:135]
	s_mov_b32 m0, s80
	s_nop 0
	global_load_lds_dwordx4 v[240:241], off
	s_waitcnt vmcnt(8)
	s_waitcnt lgkmcnt(0)
	s_barrier
; #define PG8_STAGE(bufoff, gbase, voff) do { _Pragma("unroll") for (int _i = 0; _i < 2; ++_i) \
;         __builtin_amdgcn_global_load_lds((const unsigned*)((const char*)(gbase) + (voff)[_i]), (PG8_LAS unsigned*)(lds + (bufoff) + ldsw + _i * 8192), 16, 0, 0); } while (0)
; #define PG8_WAIT_V(n) asm volatile("s_waitcnt vmcnt(" #n ")" ::: "memory")
; #define PG8_WAIT_L(n) asm volatile("s_waitcnt lgkmcnt(" #n ")" ::: "memory")
; template <class Epi, class Sched, bool ALIGN_EPI = false, bool SP2 = false>
; __device__ __forceinline__ void gemm_phase(PG8_LAS unsigned char* lds, const Gemm g, const Sched& S, const Epi& E) {
;     ...
;             PG8_WAIT_V(8); PG8_WAIT_L(0); PG8_BAR; PG8_MMA(0, 0, At, B0); PG8_MMA(0, 1, At, B1); PG8_BAR; PG8_SCHED;
;             PG8_LDA(At, 1, 1); PG8_STAGE(PG8_SB(1, 0), b3, voffB); PG8_STAGE(PG8_SB(1, 1), b3 + hstep, voffB); PG8_STAGE(PG8_SA(1, 0), a3, voffA);
;             PG8_WAIT_V(8); PG8_WAIT_L(0); PG8_BAR; PG8_MMA(1, 0, At, B0); PG8_MMA(1, 1, At, B1); PG8_BAR; PG8_SCHED;
;             } else {
;             PG8_LDB(B0, 0, 0); PG8_SCHED; PG8_LDA(At, 0, 0); PG8_STAGE(PG8_SA(1, 1), a1 + hstep, voffA);
;             PG8_WAIT_L(8); PG8_BAR; PG8_WAIT_L(0); PG8_MMA(0, 0, At, B0); PG8_BAR; PG8_SCHED;
;             PG8_LDB(B1, 0, 1); PG8_STAGE(PG8_SB(0, 0), b2, voffB);
;             PG8_BAR; PG8_WAIT_L(0); PG8_MMA(0, 1, At, B1); PG8_BAR;
;             PG8_LDA(At, 0, 1); PG8_STAGE(PG8_SA(0, 0), a2, voffA);
;             PG8_BAR; PG8_WAIT_L(0); PG8_MMA(1, 0, At, B0); PG8_BAR; PG8_SCHED;
;             PG8_STAGE(PG8_SB(0, 1), b2 + hstep, voffB);
;             PG8_WAIT_V(6); PG8_BAR; PG8_MMA(1, 1, At, B1); PG8_BAR;
;             PG8_LDB(B0, 1, 0); PG8_SCHED; PG8_LDA(At, 1, 0); PG8_STAGE(PG8_SA(0, 1), a2 + hstep, voffA);
;             PG8_WAIT_L(8); PG8_BAR; PG8_WAIT_L(0); PG8_MMA(0, 0, At, B0); PG8_BAR; PG8_SCHED;
;             PG8_LDB(B1, 1, 1); PG8_STAGE(PG8_SB(1, 0), b3, voffB);
;             PG8_BAR; PG8_WAIT_L(0); PG8_MMA(0, 1, At, B1); PG8_BAR;
;             PG8_LDA(At, 1, 1); PG8_STAGE(PG8_SA(1, 0), a3, voffA);
;             PG8_BAR; PG8_WAIT_L(0); PG8_MMA(1, 0, At, B0); PG8_BAR; PG8_SCHED;
;             PG8_STAGE(PG8_SB(1, 1), b3 + hstep, voffB);
;             PG8_WAIT_V(6); PG8_BAR; PG8_MMA(1, 1, At, B1); PG8_BAR;
;             }
;         }
;         if constexpr (ALIGN_EPI) { if (wr == 0) PG8_BAR; }
	v_mfma_f32_16x16x32_bf16 v[126:129], v[142:145], v[196:199], v[126:129]
	v_mfma_f32_16x16x32_bf16 v[122:125], v[154:157], v[196:199], v[122:125]
	v_mfma_f32_16x16x32_bf16 v[110:113], v[142:145], v[204:207], v[110:113]
	v_mfma_f32_16x16x32_bf16 v[106:109], v[154:157], v[204:207], v[106:109]
	v_mfma_f32_16x16x32_bf16 v[94:97], v[142:145], v[212:215], v[94:97]
	v_mfma_f32_16x16x32_bf16 v[90:93], v[154:157], v[212:215], v[90:93]
	v_mfma_f32_16x16x32_bf16 v[78:81], v[142:145], v[220:223], v[78:81]
	v_mfma_f32_16x16x32_bf16 v[74:77], v[154:157], v[220:223], v[74:77]
	v_mfma_f32_16x16x32_bf16 v[126:129], v[150:153], v[200:203], v[126:129]
	v_mfma_f32_16x16x32_bf16 v[122:125], v[158:161], v[200:203], v[122:125]
	v_mfma_f32_16x16x32_bf16 v[110:113], v[150:153], v[208:211], v[110:113]
	v_mfma_f32_16x16x32_bf16 v[106:109], v[158:161], v[208:211], v[106:109]
	v_mfma_f32_16x16x32_bf16 v[94:97], v[150:153], v[216:219], v[94:97]
	v_mfma_f32_16x16x32_bf16 v[90:93], v[158:161], v[216:219], v[90:93]
	v_mfma_f32_16x16x32_bf16 v[78:81], v[150:153], v[224:227], v[78:81]
	v_mfma_f32_16x16x32_bf16 v[74:77], v[158:161], v[224:227], v[74:77]
	v_mfma_f32_16x16x32_bf16 v[118:121], v[170:173], v[196:199], v[118:121]
	v_mfma_f32_16x16x32_bf16 v[114:117], v[178:181], v[196:199], v[114:117]
	v_mfma_f32_16x16x32_bf16 v[102:105], v[170:173], v[204:207], v[102:105]
	v_mfma_f32_16x16x32_bf16 v[98:101], v[178:181], v[204:207], v[98:101]
	v_mfma_f32_16x16x32_bf16 v[86:89], v[170:173], v[212:215], v[86:89]
	v_mfma_f32_16x16x32_bf16 v[82:85], v[178:181], v[212:215], v[82:85]
	v_mfma_f32_16x16x32_bf16 v[70:73], v[170:173], v[220:223], v[70:73]
	v_mfma_f32_16x16x32_bf16 v[66:69], v[178:181], v[220:223], v[66:69]
	v_mfma_f32_16x16x32_bf16 v[118:121], v[174:177], v[200:203], v[118:121]
	v_mfma_f32_16x16x32_bf16 v[114:117], v[182:185], v[200:203], v[114:117]
	v_mfma_f32_16x16x32_bf16 v[102:105], v[174:177], v[208:211], v[102:105]
	v_mfma_f32_16x16x32_bf16 v[98:101], v[182:185], v[208:211], v[98:101]
	v_mfma_f32_16x16x32_bf16 v[86:89], v[174:177], v[216:219], v[86:89]
	v_mfma_f32_16x16x32_bf16 v[82:85], v[182:185], v[216:219], v[82:85]
	v_mfma_f32_16x16x32_bf16 v[70:73], v[174:177], v[224:227], v[70:73]
	v_mfma_f32_16x16x32_bf16 v[66:69], v[182:185], v[224:227], v[66:69]
	s_barrier
	s_add_i32 s46, s61, s50
	v_lshl_add_u64 v[228:229], v[228:229], 0, s[34:35]
	s_mov_b32 m0, s46
	ds_read_b128 v[196:199], v148 offset:49152
	ds_read_b128 v[200:203], v148 offset:50176
	ds_read_b128 v[204:207], v148 offset:51200
	ds_read_b128 v[208:211], v148 offset:52224
	ds_read_b128 v[212:215], v148 offset:53248
	ds_read_b128 v[216:219], v148 offset:54272
	ds_read_b128 v[220:223], v148 offset:55296
	ds_read_b128 v[224:227], v148 offset:56320
	global_load_lds_dwordx4 v[228:229], off
	v_lshl_add_u64 v[228:229], v[230:231], 0, s[34:35]
	s_add_i32 m0, s46, 0x2000
	s_add_i32 s46, s72, s50
	global_load_lds_dwordx4 v[228:229], off
	v_lshl_add_u64 v[228:229], v[232:233], 0, s[34:35]
	s_mov_b32 m0, s46
	s_nop 0
	global_load_lds_dwordx4 v[228:229], off
	v_lshl_add_u64 v[228:229], v[234:235], 0, s[34:35]
	s_add_i32 m0, s46, 0x2000
	s_nop 0
	global_load_lds_dwordx4 v[228:229], off
	v_lshl_add_u64 v[228:229], v[236:237], 0, s[34:35]
	s_mov_b32 m0, s85
	s_nop 0
	global_load_lds_dwordx4 v[228:229], off
	v_lshl_add_u64 v[228:229], v[238:239], 0, s[34:35]
	s_mov_b32 m0, s86
	s_nop 0
	global_load_lds_dwordx4 v[228:229], off
	s_waitcnt vmcnt(8)
	s_waitcnt lgkmcnt(0)
	s_barrier
	v_mfma_f32_16x16x32_bf16 v[62:65], v[142:145], v[196:199], v[62:65]
	v_mfma_f32_16x16x32_bf16 v[58:61], v[154:157], v[196:199], v[58:61]
	v_mfma_f32_16x16x32_bf16 v[46:49], v[142:145], v[204:207], v[46:49]
	v_mfma_f32_16x16x32_bf16 v[42:45], v[154:157], v[204:207], v[42:45]
	v_mfma_f32_16x16x32_bf16 v[28:31], v[142:145], v[212:215], v[28:31]
	v_mfma_f32_16x16x32_bf16 v[24:27], v[154:157], v[212:215], v[24:27]
	v_mfma_f32_16x16x32_bf16 v[12:15], v[142:145], v[220:223], v[12:15]
	v_mfma_f32_16x16x32_bf16 v[8:11], v[154:157], v[220:223], v[8:11]
	v_mfma_f32_16x16x32_bf16 v[62:65], v[150:153], v[200:203], v[62:65]
	v_mfma_f32_16x16x32_bf16 v[58:61], v[158:161], v[200:203], v[58:61]
	v_mfma_f32_16x16x32_bf16 v[46:49], v[150:153], v[208:211], v[46:49]
	v_mfma_f32_16x16x32_bf16 v[42:45], v[158:161], v[208:211], v[42:45]
	v_mfma_f32_16x16x32_bf16 v[28:31], v[150:153], v[216:219], v[28:31]
	v_mfma_f32_16x16x32_bf16 v[24:27], v[158:161], v[216:219], v[24:27]
	v_mfma_f32_16x16x32_bf16 v[12:15], v[150:153], v[224:227], v[12:15]
	v_mfma_f32_16x16x32_bf16 v[8:11], v[158:161], v[224:227], v[8:11]
	v_mfma_f32_16x16x32_bf16 v[54:57], v[170:173], v[196:199], v[54:57]
	v_mfma_f32_16x16x32_bf16 v[50:53], v[178:181], v[196:199], v[50:53]
	v_mfma_f32_16x16x32_bf16 v[38:41], v[170:173], v[204:207], v[38:41]
	v_mfma_f32_16x16x32_bf16 v[34:37], v[178:181], v[204:207], v[34:37]
	v_mfma_f32_16x16x32_bf16 v[20:23], v[170:173], v[212:215], v[20:23]
	v_mfma_f32_16x16x32_bf16 v[16:19], v[178:181], v[212:215], v[16:19]
	v_mfma_f32_16x16x32_bf16 v[4:7], v[170:173], v[220:223], v[4:7]
	v_mfma_f32_16x16x32_bf16 v[0:3], v[178:181], v[220:223], v[0:3]
	v_mfma_f32_16x16x32_bf16 v[54:57], v[174:177], v[200:203], v[54:57]
	v_mfma_f32_16x16x32_bf16 v[50:53], v[182:185], v[200:203], v[50:53]
	v_mfma_f32_16x16x32_bf16 v[38:41], v[174:177], v[208:211], v[38:41]
	v_mfma_f32_16x16x32_bf16 v[34:37], v[182:185], v[208:211], v[34:37]
	v_mfma_f32_16x16x32_bf16 v[20:23], v[174:177], v[216:219], v[20:23]
	v_mfma_f32_16x16x32_bf16 v[16:19], v[182:185], v[216:219], v[16:19]
	v_mfma_f32_16x16x32_bf16 v[4:7], v[174:177], v[224:227], v[4:7]
	v_mfma_f32_16x16x32_bf16 v[0:3], v[182:185], v[224:227], v[0:3]
	s_barrier
	s_add_u32 s90, s90, 0x100
	s_addc_u32 s91, s91, 0
	s_add_u32 s44, s44, 0x100
	s_addc_u32 s45, s45, 0
	s_cmp_ge_u32 s92, s82
	s_mov_b32 s46, s92
	s_cbranch_scc0 .LBB0_369
	s_and_b64 vcc, exec, s[40:41]
	s_cbranch_vccz .LBB0_372
	s_barrier

; #define PG8_BAR __builtin_amdgcn_s_barrier()
; template <class Epi, class Sched, bool ALIGN_EPI = false, bool SP2 = false>
; __device__ __forceinline__ void gemm_phase(PG8_LAS unsigned char* lds, const Gemm g, const Sched& S, const Epi& E) {
;     ...
;         if (!has_next) break;
; #pragma unroll
;         for (int a = 0; a < 2; ++a)
; #pragma unroll
;             for (int b = 0; b < 2; ++b)
; #pragma unroll
;                 for (int m = 0; m < 4; ++m)
; #pragma unroll
;                     for (int n = 0; n < 2; ++n) acc[a][b][m][n] = (f32x4){0.f, 0.f, 0.f, 0.f};
;         cur = nxt; cA = nA; cB = nB; ++ui;
;         if constexpr (Epi::PREFETCH) E.prefetch(cur, wr, fr, epre);
;         if constexpr (ALIGN_EPI) { if (wr == 1) PG8_BAR; }
;     }
.LBB0_388:
	s_or_b64 exec, exec, s[44:45]
	s_and_b64 vcc, exec, s[4:5]
	s_mov_b64 s[4:5], -1
	s_cbranch_vccnz .LBB0_356
	s_andn2_b64 vcc, exec, s[38:39]
	s_cmp_lg_u32 s38, 0
	s_cselect_b32 s100, 1, 0
	s_branch .LBB0_355

; #define PG8_STAGE(bufoff, gbase, voff) do { _Pragma("unroll") for (int _i = 0; _i < 2; ++_i) \
;         __builtin_amdgcn_global_load_lds((const unsigned*)((const char*)(gbase) + (voff)[_i]), (PG8_LAS unsigned*)(lds + (bufoff) + ldsw + _i * 8192), 16, 0, 0); } while (0)
; #define PG8_LDA(dst, b, h) do { _Pragma("unroll") for (int m = 0; m < 4; ++m) _Pragma("unroll") for (int k = 0; k < 2; ++k) dst[m][k] = *(const PG8_LAS bf16x8*)(lds + PG8_SA(b, h) + aoff + m * 2048 + k * 1024); } while (0)
; #define PG8_LDB(dst, b, h) do { _Pragma("unroll") for (int n = 0; n < 2; ++n) _Pragma("unroll") for (int k = 0; k < 2; ++k) dst[n][k] = *(const PG8_LAS bf16x8*)(lds + PG8_SB(b, h) + boff + n * 2048 + k * 1024); } while (0)
; #define PG8_WAIT_V(n) asm volatile("s_waitcnt vmcnt(" #n ")" ::: "memory")
; #define PG8_WAIT_L(n) asm volatile("s_waitcnt lgkmcnt(" #n ")" ::: "memory")
; #define PG8_BAR __builtin_amdgcn_s_barrier()
; #define PG8_SCHED __builtin_amdgcn_sched_barrier(0)
; template <class Epi, class Sched, bool ALIGN_EPI = false, bool SP2 = false>
; __device__ __forceinline__ void gemm_phase(PG8_LAS unsigned char* lds, const Gemm g, const Sched& S, const Epi& E) {
;     ...
;         for (int t = 0; t < nt; t += 2) {
;             const bool last = (t == nt - 2);
;             const char* a1 = cA + (size_t)(t + 1) * kstep;
;             const char* a2 = last ? nA : cA + (size_t)(t + 2) * kstep; const char* b2 = last ? nB : cB + (size_t)(t + 2) * kstep;
;             const char* a3 = a2 + kstep; const char* b3 = b2 + kstep;
;             if (last && has_next) S.a_ready(nxt);
;             if constexpr (SP2) {
;             PG8_LDB(B0, 0, 0); PG8_LDB(B1, 0, 1); PG8_SCHED; PG8_LDA(At, 0, 0); PG8_STAGE(PG8_SA(1, 1), a1 + hstep, voffA);
;             PG8_WAIT_V(8); PG8_WAIT_L(0); PG8_BAR; PG8_MMA(0, 0, At, B0); PG8_MMA(0, 1, At, B1); PG8_BAR; PG8_SCHED;
;     ...
; #pragma unroll
;         for (int a = 0; a < 2; ++a)
; #pragma unroll
;             for (int b = 0; b < 2; ++b)
; #pragma unroll
;                 for (int m = 0; m < 4; ++m)
; #pragma unroll
;                     for (int n = 0; n < 2; ++n) acc[a][b][m][n] = (f32x4){0.f, 0.f, 0.f, 0.f};
;         cur = nxt; cA = nA; cB = nB; ++ui;
;         if constexpr (Epi::PREFETCH) E.prefetch(cur, wr, fr, epre);
;         if constexpr (ALIGN_EPI) { if (wr == 1) PG8_BAR; }
.LBB0_410:
	s_add_u32 s48, s44, 0x100
	s_addc_u32 s49, s45, 0
	s_add_u32 s44, s46, 0x80
	v_mov_b32_e32 v0, 0
	s_addc_u32 s45, s47, 0
	s_mov_b32 s46, 0
	v_mov_b32_e32 v1, v0
	v_mov_b32_e32 v2, v0
	v_mov_b32_e32 v3, v0
	v_mov_b32_e32 v4, v0
	s_waitcnt lgkmcnt(0)
	v_mov_b32_e32 v5, v0
	v_mov_b32_e32 v6, v0
	v_mov_b32_e32 v7, v0
	v_mov_b32_e32 v16, v0
	v_mov_b32_e32 v17, v0
	v_mov_b32_e32 v18, v0
	v_mov_b32_e32 v19, v0
	v_mov_b32_e32 v20, v0
	v_mov_b32_e32 v21, v0
	v_mov_b32_e32 v22, v0
	v_mov_b32_e32 v23, v0
	v_mov_b32_e32 v34, v0
	v_mov_b32_e32 v35, v0
	v_mov_b32_e32 v36, v0
	v_mov_b32_e32 v37, v0
	v_mov_b32_e32 v38, v0
	v_mov_b32_e32 v39, v0
	v_mov_b32_e32 v40, v0
	v_mov_b32_e32 v41, v0
	v_mov_b32_e32 v50, v0
	v_mov_b32_e32 v51, v0
	v_mov_b32_e32 v52, v0
	v_mov_b32_e32 v53, v0
	v_mov_b32_e32 v54, v0
	v_mov_b32_e32 v55, v0
	v_mov_b32_e32 v56, v0
	v_mov_b32_e32 v57, v0
	v_mov_b32_e32 v8, v0
	v_mov_b32_e32 v9, v0
	v_mov_b32_e32 v10, v0
	v_mov_b32_e32 v11, v0
	v_mov_b32_e32 v12, v0
	v_mov_b32_e32 v13, v0
	v_mov_b32_e32 v14, v0
	v_mov_b32_e32 v15, v0
	v_mov_b32_e32 v24, v0
	v_mov_b32_e32 v25, v0
	v_mov_b32_e32 v26, v0
	v_mov_b32_e32 v27, v0
	v_mov_b32_e32 v28, v0
	v_mov_b32_e32 v29, v0
	v_mov_b32_e32 v30, v0
	v_mov_b32_e32 v31, v0
	v_mov_b32_e32 v42, v0
	v_mov_b32_e32 v43, v0
	v_mov_b32_e32 v44, v0
	v_mov_b32_e32 v45, v0
	v_mov_b32_e32 v46, v0
	v_mov_b32_e32 v47, v0
	v_mov_b32_e32 v48, v0
	v_mov_b32_e32 v49, v0
	v_mov_b32_e32 v58, v0
	v_mov_b32_e32 v59, v0
	v_mov_b32_e32 v60, v0
	v_mov_b32_e32 v61, v0
	v_mov_b32_e32 v62, v0
	v_mov_b32_e32 v63, v0
	v_mov_b32_e32 v64, v0
	v_mov_b32_e32 v65, v0
	v_mov_b32_e32 v66, v0
	v_mov_b32_e32 v67, v0
	v_mov_b32_e32 v68, v0
	v_mov_b32_e32 v69, v0
	v_mov_b32_e32 v70, v0
	v_mov_b32_e32 v71, v0
	v_mov_b32_e32 v72, v0
	v_mov_b32_e32 v73, v0
	v_mov_b32_e32 v82, v0
	v_mov_b32_e32 v83, v0
	v_mov_b32_e32 v84, v0
	v_mov_b32_e32 v85, v0
	v_mov_b32_e32 v86, v0
	v_mov_b32_e32 v87, v0
	v_mov_b32_e32 v88, v0
	v_mov_b32_e32 v89, v0
	v_mov_b32_e32 v98, v0
	v_mov_b32_e32 v99, v0
	v_mov_b32_e32 v100, v0
	v_mov_b32_e32 v101, v0
	v_mov_b32_e32 v102, v0
	v_mov_b32_e32 v103, v0
	v_mov_b32_e32 v104, v0
	v_mov_b32_e32 v105, v0
	v_mov_b32_e32 v114, v0
	v_mov_b32_e32 v115, v0
	v_mov_b32_e32 v116, v0
	v_mov_b32_e32 v117, v0
	v_mov_b32_e32 v118, v0
	v_mov_b32_e32 v119, v0
	v_mov_b32_e32 v120, v0
	v_mov_b32_e32 v121, v0
	v_mov_b32_e32 v74, v0
	v_mov_b32_e32 v75, v0
	v_mov_b32_e32 v76, v0
	v_mov_b32_e32 v77, v0
	v_mov_b32_e32 v78, v0
	v_mov_b32_e32 v79, v0
	v_mov_b32_e32 v80, v0
	v_mov_b32_e32 v81, v0
	v_mov_b32_e32 v90, v0
	v_mov_b32_e32 v91, v0
	v_mov_b32_e32 v92, v0
	v_mov_b32_e32 v93, v0
	v_mov_b32_e32 v94, v0
	v_mov_b32_e32 v95, v0
	v_mov_b32_e32 v96, v0
	v_mov_b32_e32 v97, v0
	v_mov_b32_e32 v106, v0
	v_mov_b32_e32 v107, v0
	v_mov_b32_e32 v108, v0
	v_mov_b32_e32 v109, v0
	v_mov_b32_e32 v110, v0
	v_mov_b32_e32 v111, v0
	v_mov_b32_e32 v112, v0
	v_mov_b32_e32 v113, v0
	v_mov_b32_e32 v122, v0
	v_mov_b32_e32 v123, v0
	v_mov_b32_e32 v124, v0
	v_mov_b32_e32 v125, v0
	v_mov_b32_e32 v126, v0
	v_mov_b32_e32 v127, v0
	v_mov_b32_e32 v128, v0
	v_mov_b32_e32 v129, v0
	s_cmp_eq_u32 s100, 0
	s_cbranch_scc1 .Lrb5_skip
	s_mov_b32 s100, 0
	s_barrier
.Lrb5_skip:
.LBB0_411:
	s_add_i32 vcc_lo, s46, 2
	s_add_u32 s38, s44, 0x80
	s_addc_u32 s39, s45, 0
	s_add_i32 vcc_hi, 0, 0x10000
	s_cmp_eq_u32 s92, s46
	s_cselect_b32 s47, s79, s39
	s_cselect_b32 s46, s78, s38
	v_add_u32_e32 v149, vcc_hi, v146
	s_cselect_b32 s39, s81, s49
	s_cselect_b32 s38, s80, s48
	s_add_i32 s61, 0, 0x14000
	ds_read_b128 v[142:145], v149
	ds_read_b128 v[150:153], v149 offset:1024
	ds_read_b128 v[154:157], v149 offset:2048
	ds_read_b128 v[158:161], v149 offset:3072
	v_add_u32_e32 v149, s61, v146
	ds_read_b128 v[170:173], v149
	ds_read_b128 v[174:177], v149 offset:1024
	ds_read_b128 v[178:181], v149 offset:2048
	ds_read_b128 v[182:185], v149 offset:3072
	v_lshl_add_u64 v[228:229], s[44:45], 0, v[140:141]
	s_add_i32 m0, s82, 0xc000
	ds_read_b128 v[196:199], v148
	ds_read_b128 v[200:203], v148 offset:1024
	ds_read_b128 v[204:207], v148 offset:2048
	ds_read_b128 v[208:211], v148 offset:3072
	ds_read_b128 v[212:215], v148 offset:4096
	ds_read_b128 v[216:219], v148 offset:5120
	ds_read_b128 v[220:223], v148 offset:6144
	ds_read_b128 v[224:227], v148 offset:7168
	global_load_lds_dwordx4 v[228:229], off
	v_lshl_add_u64 v[228:229], s[44:45], 0, v[138:139]
	s_add_i32 m0, s82, 0xe000
	s_nop 0
	global_load_lds_dwordx4 v[228:229], off
	s_waitcnt vmcnt(8)
	s_waitcnt lgkmcnt(0)
	s_barrier
; #define PG8_STAGE(bufoff, gbase, voff) do { _Pragma("unroll") for (int _i = 0; _i < 2; ++_i) \
;         __builtin_amdgcn_global_load_lds((const unsigned*)((const char*)(gbase) + (voff)[_i]), (PG8_LAS unsigned*)(lds + (bufoff) + ldsw + _i * 8192), 16, 0, 0); } while (0)
; #define PG8_LDA(dst, b, h) do { _Pragma("unroll") for (int m = 0; m < 4; ++m) _Pragma("unroll") for (int k = 0; k < 2; ++k) dst[m][k] = *(const PG8_LAS bf16x8*)(lds + PG8_SA(b, h) + aoff + m * 2048 + k * 1024); } while (0)
; #define PG8_MMA(ai, bj, At, Bt) do { __builtin_amdgcn_s_setprio(1); _Pragma("unroll") for (int m = 0; m < 4; ++m) _Pragma("unroll") for (int n = 0; n < 2; ++n) _Pragma("unroll") for (int k = 0; k < 2; ++k) \
;         acc[ai][bj][m][n] = __builtin_amdgcn_mfma_f32_16x16x32_bf16(Bt[n][k], At[m][k], acc[ai][bj][m][n], 0, 0, 0); __builtin_amdgcn_s_setprio(0); } while (0)
; #define PG8_WAIT_V(n) asm volatile("s_waitcnt vmcnt(" #n ")" ::: "memory")
; #define PG8_WAIT_L(n) asm volatile("s_waitcnt lgkmcnt(" #n ")" ::: "memory")
; #define PG8_BAR __builtin_amdgcn_s_barrier()
; #define PG8_SCHED __builtin_amdgcn_sched_barrier(0)
; template <class Epi, class Sched, bool ALIGN_EPI = false, bool SP2 = false>
; __device__ __forceinline__ void gemm_phase(PG8_LAS unsigned char* lds, const Gemm g, const Sched& S, const Epi& E) {
;     ...
;             PG8_WAIT_V(8); PG8_WAIT_L(0); PG8_BAR; PG8_MMA(0, 0, At, B0); PG8_MMA(0, 1, At, B1); PG8_BAR; PG8_SCHED;
;             PG8_LDA(At, 0, 1); PG8_STAGE(PG8_SB(0, 0), b2, voffB); PG8_STAGE(PG8_SB(0, 1), b2 + hstep, voffB); PG8_STAGE(PG8_SA(0, 0), a2, voffA);
;             PG8_WAIT_V(8); PG8_WAIT_L(0); PG8_BAR; PG8_MMA(1, 0, At, B0); PG8_MMA(1, 1, At, B1); PG8_BAR; PG8_SCHED;
	v_mfma_f32_16x16x32_bf16 v[126:129], v[142:145], v[196:199], v[126:129]
	v_mfma_f32_16x16x32_bf16 v[122:125], v[154:157], v[196:199], v[122:125]
	v_mfma_f32_16x16x32_bf16 v[110:113], v[142:145], v[204:207], v[110:113]
	v_mfma_f32_16x16x32_bf16 v[106:109], v[154:157], v[204:207], v[106:109]
	v_mfma_f32_16x16x32_bf16 v[94:97], v[142:145], v[212:215], v[94:97]
	v_mfma_f32_16x16x32_bf16 v[90:93], v[154:157], v[212:215], v[90:93]
	v_mfma_f32_16x16x32_bf16 v[78:81], v[142:145], v[220:223], v[78:81]
	v_mfma_f32_16x16x32_bf16 v[74:77], v[154:157], v[220:223], v[74:77]
	v_mfma_f32_16x16x32_bf16 v[126:129], v[150:153], v[200:203], v[126:129]
	v_mfma_f32_16x16x32_bf16 v[122:125], v[158:161], v[200:203], v[122:125]
	v_mfma_f32_16x16x32_bf16 v[110:113], v[150:153], v[208:211], v[110:113]
	v_mfma_f32_16x16x32_bf16 v[106:109], v[158:161], v[208:211], v[106:109]
	v_mfma_f32_16x16x32_bf16 v[94:97], v[150:153], v[216:219], v[94:97]
	v_mfma_f32_16x16x32_bf16 v[90:93], v[158:161], v[216:219], v[90:93]
	v_mfma_f32_16x16x32_bf16 v[78:81], v[150:153], v[224:227], v[78:81]
	v_mfma_f32_16x16x32_bf16 v[74:77], v[158:161], v[224:227], v[74:77]
	v_mfma_f32_16x16x32_bf16 v[118:121], v[170:173], v[196:199], v[118:121]
	v_mfma_f32_16x16x32_bf16 v[114:117], v[178:181], v[196:199], v[114:117]
	v_mfma_f32_16x16x32_bf16 v[102:105], v[170:173], v[204:207], v[102:105]
	v_mfma_f32_16x16x32_bf16 v[98:101], v[178:181], v[204:207], v[98:101]
	v_mfma_f32_16x16x32_bf16 v[86:89], v[170:173], v[212:215], v[86:89]
	v_mfma_f32_16x16x32_bf16 v[82:85], v[178:181], v[212:215], v[82:85]
	v_mfma_f32_16x16x32_bf16 v[70:73], v[170:173], v[220:223], v[70:73]
	v_mfma_f32_16x16x32_bf16 v[66:69], v[178:181], v[220:223], v[66:69]
	v_mfma_f32_16x16x32_bf16 v[118:121], v[174:177], v[200:203], v[118:121]
	v_mfma_f32_16x16x32_bf16 v[114:117], v[182:185], v[200:203], v[114:117]
	v_mfma_f32_16x16x32_bf16 v[102:105], v[174:177], v[208:211], v[102:105]
	v_mfma_f32_16x16x32_bf16 v[98:101], v[182:185], v[208:211], v[98:101]
	v_mfma_f32_16x16x32_bf16 v[86:89], v[174:177], v[216:219], v[86:89]
	v_mfma_f32_16x16x32_bf16 v[82:85], v[182:185], v[216:219], v[82:85]
	v_mfma_f32_16x16x32_bf16 v[70:73], v[174:177], v[224:227], v[70:73]
	v_mfma_f32_16x16x32_bf16 v[66:69], v[182:185], v[224:227], v[66:69]
	s_barrier
	s_add_i32 vcc_hi, vcc_hi, s51
	v_lshl_add_u64 v[228:229], s[38:39], 0, v[132:133]
	s_mov_b32 m0, vcc_hi
	ds_read_b128 v[196:199], v148 offset:16384
	ds_read_b128 v[200:203], v148 offset:17408
	ds_read_b128 v[204:207], v148 offset:18432
	ds_read_b128 v[208:211], v148 offset:19456
	ds_read_b128 v[212:215], v148 offset:20480
	ds_read_b128 v[216:219], v148 offset:21504
	ds_read_b128 v[220:223], v148 offset:22528
	ds_read_b128 v[224:227], v148 offset:23552
	global_load_lds_dwordx4 v[228:229], off
	s_add_i32 m0, vcc_hi, 0x2000
	v_lshl_add_u64 v[230:231], s[38:39], 0, v[136:137]
	s_add_u32 s38, s38, s8
	s_addc_u32 s39, s39, 0
	s_add_i32 s61, s61, s51
	global_load_lds_dwordx4 v[230:231], off
	v_lshl_add_u64 v[232:233], s[38:39], 0, v[132:133]
	s_mov_b32 m0, s61
	v_lshl_add_u64 v[234:235], s[38:39], 0, v[136:137]
	global_load_lds_dwordx4 v[232:233], off
	s_add_i32 m0, s61, 0x2000
	v_lshl_add_u64 v[236:237], s[46:47], 0, v[130:131]
	global_load_lds_dwordx4 v[234:235], off
	s_mov_b32 m0, s82
	v_lshl_add_u64 v[238:239], s[46:47], 0, v[134:135]
	global_load_lds_dwordx4 v[236:237], off
	s_mov_b32 m0, s83
	s_nop 0
	global_load_lds_dwordx4 v[238:239], off
	s_waitcnt vmcnt(8)
	s_waitcnt lgkmcnt(0)
	s_barrier
	v_mfma_f32_16x16x32_bf16 v[62:65], v[142:145], v[196:199], v[62:65]
	v_mfma_f32_16x16x32_bf16 v[58:61], v[154:157], v[196:199], v[58:61]
	v_mfma_f32_16x16x32_bf16 v[46:49], v[142:145], v[204:207], v[46:49]
	v_mfma_f32_16x16x32_bf16 v[42:45], v[154:157], v[204:207], v[42:45]
	v_mfma_f32_16x16x32_bf16 v[28:31], v[142:145], v[212:215], v[28:31]
	v_mfma_f32_16x16x32_bf16 v[24:27], v[154:157], v[212:215], v[24:27]
	v_mfma_f32_16x16x32_bf16 v[12:15], v[142:145], v[220:223], v[12:15]
	v_mfma_f32_16x16x32_bf16 v[8:11], v[154:157], v[220:223], v[8:11]
	v_mfma_f32_16x16x32_bf16 v[62:65], v[150:153], v[200:203], v[62:65]
	v_mfma_f32_16x16x32_bf16 v[58:61], v[158:161], v[200:203], v[58:61]
	v_mfma_f32_16x16x32_bf16 v[46:49], v[150:153], v[208:211], v[46:49]
	v_mfma_f32_16x16x32_bf16 v[42:45], v[158:161], v[208:211], v[42:45]
	v_mfma_f32_16x16x32_bf16 v[28:31], v[150:153], v[216:219], v[28:31]
	v_mfma_f32_16x16x32_bf16 v[24:27], v[158:161], v[216:219], v[24:27]
	v_mfma_f32_16x16x32_bf16 v[12:15], v[150:153], v[224:227], v[12:15]
	v_mfma_f32_16x16x32_bf16 v[8:11], v[158:161], v[224:227], v[8:11]
	v_mfma_f32_16x16x32_bf16 v[54:57], v[170:173], v[196:199], v[54:57]
	v_mfma_f32_16x16x32_bf16 v[50:53], v[178:181], v[196:199], v[50:53]
	v_mfma_f32_16x16x32_bf16 v[38:41], v[170:173], v[204:207], v[38:41]
	v_mfma_f32_16x16x32_bf16 v[34:37], v[178:181], v[204:207], v[34:37]
	v_mfma_f32_16x16x32_bf16 v[20:23], v[170:173], v[212:215], v[20:23]
	v_mfma_f32_16x16x32_bf16 v[16:19], v[178:181], v[212:215], v[16:19]
	v_mfma_f32_16x16x32_bf16 v[4:7], v[170:173], v[220:223], v[4:7]
	v_mfma_f32_16x16x32_bf16 v[0:3], v[178:181], v[220:223], v[0:3]
	v_mfma_f32_16x16x32_bf16 v[54:57], v[174:177], v[200:203], v[54:57]
	v_mfma_f32_16x16x32_bf16 v[50:53], v[182:185], v[200:203], v[50:53]
	v_mfma_f32_16x16x32_bf16 v[38:41], v[174:177], v[208:211], v[38:41]
	v_mfma_f32_16x16x32_bf16 v[34:37], v[182:185], v[208:211], v[34:37]
	v_mfma_f32_16x16x32_bf16 v[20:23], v[174:177], v[216:219], v[20:23]
	v_mfma_f32_16x16x32_bf16 v[16:19], v[182:185], v[216:219], v[16:19]
	v_mfma_f32_16x16x32_bf16 v[4:7], v[174:177], v[224:227], v[4:7]
	v_mfma_f32_16x16x32_bf16 v[0:3], v[182:185], v[224:227], v[0:3]
	s_barrier
; #define PG8_STAGE(bufoff, gbase, voff) do { _Pragma("unroll") for (int _i = 0; _i < 2; ++_i) \
;         __builtin_amdgcn_global_load_lds((const unsigned*)((const char*)(gbase) + (voff)[_i]), (PG8_LAS unsigned*)(lds + (bufoff) + ldsw + _i * 8192), 16, 0, 0); } while (0)
; #define PG8_BAR __builtin_amdgcn_s_barrier()
; template <class Epi, class Sched, bool ALIGN_EPI = false, bool SP2 = false>
; __device__ __forceinline__ void gemm_phase(PG8_LAS unsigned char* lds, const Gemm g, const Sched& S, const Epi& E) {
;     ...
;             PG8_LDB(B0, 1, 0); PG8_LDB(B1, 1, 1); PG8_SCHED; PG8_LDA(At, 1, 0); PG8_STAGE(PG8_SA(0, 1), a2 + hstep, voffA);
;             PG8_WAIT_V(8); PG8_WAIT_L(0); PG8_BAR; PG8_MMA(0, 0, At, B0); PG8_MMA(0, 1, At, B1); PG8_BAR; PG8_SCHED;
;             PG8_LDA(At, 1, 1); PG8_STAGE(PG8_SB(1, 0), b3, voffB); PG8_STAGE(PG8_SB(1, 1), b3 + hstep, voffB); PG8_STAGE(PG8_SA(1, 0), a3, voffA);
;             PG8_WAIT_V(8); PG8_WAIT_L(0); PG8_BAR; PG8_MMA(1, 0, At, B0); PG8_MMA(1, 1, At, B1); PG8_BAR; PG8_SCHED;
;             } else {
;             PG8_LDB(B0, 0, 0); PG8_SCHED; PG8_LDA(At, 0, 0); PG8_STAGE(PG8_SA(1, 1), a1 + hstep, voffA);
;             PG8_WAIT_L(8); PG8_BAR; PG8_WAIT_L(0); PG8_MMA(0, 0, At, B0); PG8_BAR; PG8_SCHED;
;             PG8_LDB(B1, 0, 1); PG8_STAGE(PG8_SB(0, 0), b2, voffB);
;             PG8_BAR; PG8_WAIT_L(0); PG8_MMA(0, 1, At, B1); PG8_BAR;
;             PG8_LDA(At, 0, 1); PG8_STAGE(PG8_SA(0, 0), a2, voffA);
;             PG8_BAR; PG8_WAIT_L(0); PG8_MMA(1, 0, At, B0); PG8_BAR; PG8_SCHED;
;             PG8_STAGE(PG8_SB(0, 1), b2 + hstep, voffB);
;             PG8_WAIT_V(6); PG8_BAR; PG8_MMA(1, 1, At, B1); PG8_BAR;
;             PG8_LDB(B0, 1, 0); PG8_SCHED; PG8_LDA(At, 1, 0); PG8_STAGE(PG8_SA(0, 1), a2 + hstep, voffA);
;             PG8_WAIT_L(8); PG8_BAR; PG8_WAIT_L(0); PG8_MMA(0, 0, At, B0); PG8_BAR; PG8_SCHED;
;             PG8_LDB(B1, 1, 1); PG8_STAGE(PG8_SB(1, 0), b3, voffB);
;             PG8_BAR; PG8_WAIT_L(0); PG8_MMA(0, 1, At, B1); PG8_BAR;
;             PG8_LDA(At, 1, 1); PG8_STAGE(PG8_SA(1, 0), a3, voffA);
;             PG8_BAR; PG8_WAIT_L(0); PG8_MMA(1, 0, At, B0); PG8_BAR; PG8_SCHED;
;             PG8_STAGE(PG8_SB(1, 1), b3 + hstep, voffB);
;             PG8_WAIT_V(6); PG8_BAR; PG8_MMA(1, 1, At, B1); PG8_BAR;
;             }
;         }
;         if constexpr (ALIGN_EPI) { if (wr == 0) PG8_BAR; }
	s_add_i32 s61, 0, 0x18000
	v_add_u32_e32 v149, s61, v146
	s_add_i32 vcc_hi, 0, 0x1c000
	ds_read_b128 v[142:145], v149
	ds_read_b128 v[150:153], v149 offset:1024
	ds_read_b128 v[154:157], v149 offset:2048
	ds_read_b128 v[158:161], v149 offset:3072
	v_add_u32_e32 v149, vcc_hi, v146
	ds_read_b128 v[170:173], v149
	ds_read_b128 v[174:177], v149 offset:1024
	ds_read_b128 v[178:181], v149 offset:2048
	ds_read_b128 v[182:185], v149 offset:3072
	s_add_u32 s38, s46, s8
	s_addc_u32 s39, s47, 0
	s_mov_b32 m0, s87
	v_lshl_add_u64 v[240:241], s[38:39], 0, v[130:131]
	ds_read_b128 v[196:199], v148 offset:32768
	ds_read_b128 v[200:203], v148 offset:33792
	ds_read_b128 v[204:207], v148 offset:34816
	ds_read_b128 v[208:211], v148 offset:35840
	ds_read_b128 v[212:215], v148 offset:36864
	ds_read_b128 v[216:219], v148 offset:37888
	ds_read_b128 v[220:223], v148 offset:38912
	ds_read_b128 v[224:227], v148 offset:39936
	global_load_lds_dwordx4 v[240:241], off
	v_lshl_add_u64 v[240:241], s[38:39], 0, v[134:135]
	s_mov_b32 m0, s88
	s_nop 0
	global_load_lds_dwordx4 v[240:241], off
	s_waitcnt vmcnt(8)
	s_waitcnt lgkmcnt(0)
	s_barrier
	v_mfma_f32_16x16x32_bf16 v[126:129], v[142:145], v[196:199], v[126:129]
	v_mfma_f32_16x16x32_bf16 v[122:125], v[154:157], v[196:199], v[122:125]
	v_mfma_f32_16x16x32_bf16 v[110:113], v[142:145], v[204:207], v[110:113]
	v_mfma_f32_16x16x32_bf16 v[106:109], v[154:157], v[204:207], v[106:109]
	v_mfma_f32_16x16x32_bf16 v[94:97], v[142:145], v[212:215], v[94:97]
	v_mfma_f32_16x16x32_bf16 v[90:93], v[154:157], v[212:215], v[90:93]
	v_mfma_f32_16x16x32_bf16 v[78:81], v[142:145], v[220:223], v[78:81]
	v_mfma_f32_16x16x32_bf16 v[74:77], v[154:157], v[220:223], v[74:77]
	v_mfma_f32_16x16x32_bf16 v[126:129], v[150:153], v[200:203], v[126:129]
	v_mfma_f32_16x16x32_bf16 v[122:125], v[158:161], v[200:203], v[122:125]
	v_mfma_f32_16x16x32_bf16 v[110:113], v[150:153], v[208:211], v[110:113]
	v_mfma_f32_16x16x32_bf16 v[106:109], v[158:161], v[208:211], v[106:109]
	v_mfma_f32_16x16x32_bf16 v[94:97], v[150:153], v[216:219], v[94:97]
	v_mfma_f32_16x16x32_bf16 v[90:93], v[158:161], v[216:219], v[90:93]
	v_mfma_f32_16x16x32_bf16 v[78:81], v[150:153], v[224:227], v[78:81]
	v_mfma_f32_16x16x32_bf16 v[74:77], v[158:161], v[224:227], v[74:77]
	v_mfma_f32_16x16x32_bf16 v[118:121], v[170:173], v[196:199], v[118:121]
	v_mfma_f32_16x16x32_bf16 v[114:117], v[178:181], v[196:199], v[114:117]
	v_mfma_f32_16x16x32_bf16 v[102:105], v[170:173], v[204:207], v[102:105]
	v_mfma_f32_16x16x32_bf16 v[98:101], v[178:181], v[204:207], v[98:101]
	v_mfma_f32_16x16x32_bf16 v[86:89], v[170:173], v[212:215], v[86:89]
	v_mfma_f32_16x16x32_bf16 v[82:85], v[178:181], v[212:215], v[82:85]
	v_mfma_f32_16x16x32_bf16 v[70:73], v[170:173], v[220:223], v[70:73]
	v_mfma_f32_16x16x32_bf16 v[66:69], v[178:181], v[220:223], v[66:69]
	v_mfma_f32_16x16x32_bf16 v[118:121], v[174:177], v[200:203], v[118:121]
	v_mfma_f32_16x16x32_bf16 v[114:117], v[182:185], v[200:203], v[114:117]
	v_mfma_f32_16x16x32_bf16 v[102:105], v[174:177], v[208:211], v[102:105]
	v_mfma_f32_16x16x32_bf16 v[98:101], v[182:185], v[208:211], v[98:101]
	v_mfma_f32_16x16x32_bf16 v[86:89], v[174:177], v[216:219], v[86:89]
	v_mfma_f32_16x16x32_bf16 v[82:85], v[182:185], v[216:219], v[82:85]
	v_mfma_f32_16x16x32_bf16 v[70:73], v[174:177], v[224:227], v[70:73]
	v_mfma_f32_16x16x32_bf16 v[66:69], v[182:185], v[224:227], v[66:69]
	s_barrier
	s_add_i32 s38, s61, s51
	v_lshl_add_u64 v[228:229], v[228:229], 0, s[34:35]
	s_mov_b32 m0, s38
	ds_read_b128 v[196:199], v148 offset:49152
	ds_read_b128 v[200:203], v148 offset:50176
	ds_read_b128 v[204:207], v148 offset:51200
	ds_read_b128 v[208:211], v148 offset:52224
	ds_read_b128 v[212:215], v148 offset:53248
	ds_read_b128 v[216:219], v148 offset:54272
	ds_read_b128 v[220:223], v148 offset:55296
	ds_read_b128 v[224:227], v148 offset:56320
	global_load_lds_dwordx4 v[228:229], off
	v_lshl_add_u64 v[228:229], v[230:231], 0, s[34:35]
	s_add_i32 m0, s38, 0x2000
	s_add_i32 s38, vcc_hi, s51
	global_load_lds_dwordx4 v[228:229], off
	v_lshl_add_u64 v[228:229], v[232:233], 0, s[34:35]
	s_mov_b32 m0, s38
	s_nop 0
	global_load_lds_dwordx4 v[228:229], off
	v_lshl_add_u64 v[228:229], v[234:235], 0, s[34:35]
	s_add_i32 m0, s38, 0x2000
	s_nop 0
	global_load_lds_dwordx4 v[228:229], off
	v_lshl_add_u64 v[228:229], v[236:237], 0, s[34:35]
	s_mov_b32 m0, s90
	s_nop 0
	global_load_lds_dwordx4 v[228:229], off
	v_lshl_add_u64 v[228:229], v[238:239], 0, s[34:35]
	s_mov_b32 m0, s91
	s_nop 0
	global_load_lds_dwordx4 v[228:229], off
	s_waitcnt vmcnt(8)
	s_waitcnt lgkmcnt(0)
	s_barrier
	v_mfma_f32_16x16x32_bf16 v[62:65], v[142:145], v[196:199], v[62:65]
	v_mfma_f32_16x16x32_bf16 v[58:61], v[154:157], v[196:199], v[58:61]
	v_mfma_f32_16x16x32_bf16 v[46:49], v[142:145], v[204:207], v[46:49]
	v_mfma_f32_16x16x32_bf16 v[42:45], v[154:157], v[204:207], v[42:45]
	v_mfma_f32_16x16x32_bf16 v[28:31], v[142:145], v[212:215], v[28:31]
	v_mfma_f32_16x16x32_bf16 v[24:27], v[154:157], v[212:215], v[24:27]
	v_mfma_f32_16x16x32_bf16 v[12:15], v[142:145], v[220:223], v[12:15]
	v_mfma_f32_16x16x32_bf16 v[8:11], v[154:157], v[220:223], v[8:11]
	v_mfma_f32_16x16x32_bf16 v[62:65], v[150:153], v[200:203], v[62:65]
	v_mfma_f32_16x16x32_bf16 v[58:61], v[158:161], v[200:203], v[58:61]
	v_mfma_f32_16x16x32_bf16 v[46:49], v[150:153], v[208:211], v[46:49]
	v_mfma_f32_16x16x32_bf16 v[42:45], v[158:161], v[208:211], v[42:45]
	v_mfma_f32_16x16x32_bf16 v[28:31], v[150:153], v[216:219], v[28:31]
	v_mfma_f32_16x16x32_bf16 v[24:27], v[158:161], v[216:219], v[24:27]
	v_mfma_f32_16x16x32_bf16 v[12:15], v[150:153], v[224:227], v[12:15]
	v_mfma_f32_16x16x32_bf16 v[8:11], v[158:161], v[224:227], v[8:11]
	v_mfma_f32_16x16x32_bf16 v[54:57], v[170:173], v[196:199], v[54:57]
	v_mfma_f32_16x16x32_bf16 v[50:53], v[178:181], v[196:199], v[50:53]
	v_mfma_f32_16x16x32_bf16 v[38:41], v[170:173], v[204:207], v[38:41]
	v_mfma_f32_16x16x32_bf16 v[34:37], v[178:181], v[204:207], v[34:37]
	v_mfma_f32_16x16x32_bf16 v[20:23], v[170:173], v[212:215], v[20:23]
	v_mfma_f32_16x16x32_bf16 v[16:19], v[178:181], v[212:215], v[16:19]
	v_mfma_f32_16x16x32_bf16 v[4:7], v[170:173], v[220:223], v[4:7]
	v_mfma_f32_16x16x32_bf16 v[0:3], v[178:181], v[220:223], v[0:3]
	v_mfma_f32_16x16x32_bf16 v[54:57], v[174:177], v[200:203], v[54:57]
	v_mfma_f32_16x16x32_bf16 v[50:53], v[182:185], v[200:203], v[50:53]
	v_mfma_f32_16x16x32_bf16 v[38:41], v[174:177], v[208:211], v[38:41]
	v_mfma_f32_16x16x32_bf16 v[34:37], v[182:185], v[208:211], v[34:37]
	v_mfma_f32_16x16x32_bf16 v[20:23], v[174:177], v[216:219], v[20:23]
	v_mfma_f32_16x16x32_bf16 v[16:19], v[182:185], v[216:219], v[16:19]
	v_mfma_f32_16x16x32_bf16 v[4:7], v[174:177], v[224:227], v[4:7]
	v_mfma_f32_16x16x32_bf16 v[0:3], v[182:185], v[224:227], v[0:3]
	s_barrier
	s_add_u32 s48, s48, 0x100
	s_addc_u32 s49, s49, 0
	s_add_u32 s44, s44, 0x100
	s_addc_u32 s45, s45, 0
	s_cmp_ge_u32 vcc_lo, s85
	s_mov_b32 s46, vcc_lo
	s_cbranch_scc0 .LBB0_411
	s_and_b64 vcc, exec, s[42:43]
	s_cbranch_vccz .LBB0_414
	s_barrier

; #define PG8_BAR __builtin_amdgcn_s_barrier()
; template <class Epi, class Sched, bool ALIGN_EPI = false, bool SP2 = false>
; __device__ __forceinline__ void gemm_phase(PG8_LAS unsigned char* lds, const Gemm g, const Sched& S, const Epi& E) {
;     ...
;         if (!has_next) break;
; #pragma unroll
;         for (int a = 0; a < 2; ++a)
; #pragma unroll
;             for (int b = 0; b < 2; ++b)
; #pragma unroll
;                 for (int m = 0; m < 4; ++m)
; #pragma unroll
;                     for (int n = 0; n < 2; ++n) acc[a][b][m][n] = (f32x4){0.f, 0.f, 0.f, 0.f};
;         cur = nxt; cA = nA; cB = nB; ++ui;
;         if constexpr (Epi::PREFETCH) E.prefetch(cur, wr, fr, epre);
;         if constexpr (ALIGN_EPI) { if (wr == 1) PG8_BAR; }
;     }
.LBB0_430:
	s_or_b64 exec, exec, s[44:45]
	s_and_b64 vcc, exec, s[4:5]
	s_mov_b64 s[4:5], -1
	s_cbranch_vccnz .LBB0_405
	s_andn2_b64 vcc, exec, s[40:41]
	s_cmp_lg_u32 s40, 0
	s_cselect_b32 s100, 1, 0
	s_branch .LBB0_404

; #define PG8_STAGE(bufoff, gbase, voff) do { _Pragma("unroll") for (int _i = 0; _i < 2; ++_i) \
;         __builtin_amdgcn_global_load_lds((const unsigned*)((const char*)(gbase) + (voff)[_i]), (PG8_LAS unsigned*)(lds + (bufoff) + ldsw + _i * 8192), 16, 0, 0); } while (0)
; #define PG8_LDA(dst, b, h) do { _Pragma("unroll") for (int m = 0; m < 4; ++m) _Pragma("unroll") for (int k = 0; k < 2; ++k) dst[m][k] = *(const PG8_LAS bf16x8*)(lds + PG8_SA(b, h) + aoff + m * 2048 + k * 1024); } while (0)
; #define PG8_LDB(dst, b, h) do { _Pragma("unroll") for (int n = 0; n < 2; ++n) _Pragma("unroll") for (int k = 0; k < 2; ++k) dst[n][k] = *(const PG8_LAS bf16x8*)(lds + PG8_SB(b, h) + boff + n * 2048 + k * 1024); } while (0)
; #define PG8_WAIT_V(n) asm volatile("s_waitcnt vmcnt(" #n ")" ::: "memory")
; #define PG8_WAIT_L(n) asm volatile("s_waitcnt lgkmcnt(" #n ")" ::: "memory")
; #define PG8_BAR __builtin_amdgcn_s_barrier()
; #define PG8_SCHED __builtin_amdgcn_sched_barrier(0)
; template <class Epi, class Sched, bool ALIGN_EPI = false, bool SP2 = false>
; __device__ __forceinline__ void gemm_phase(PG8_LAS unsigned char* lds, const Gemm g, const Sched& S, const Epi& E) {
;     ...
;         const bool has_next = S.next(ui + 1, nxt);
;         const char* nA = has_next ? (const char*)g.A + (size_t)nxt.pm * tstep : cA; const char* nB = has_next ? (const char*)g.Bt + (size_t)nxt.pn * tstep : cB;
;         for (int t = 0; t < nt; t += 2) {
;             const bool last = (t == nt - 2);
;             const char* a1 = cA + (size_t)(t + 1) * kstep;
;             const char* a2 = last ? nA : cA + (size_t)(t + 2) * kstep; const char* b2 = last ? nB : cB + (size_t)(t + 2) * kstep;
;             const char* a3 = a2 + kstep; const char* b3 = b2 + kstep;
;             if (last && has_next) S.a_ready(nxt);
;             if constexpr (SP2) {
;             PG8_LDB(B0, 0, 0); PG8_LDB(B1, 0, 1); PG8_SCHED; PG8_LDA(At, 0, 0); PG8_STAGE(PG8_SA(1, 1), a1 + hstep, voffA);
;             PG8_WAIT_V(8); PG8_WAIT_L(0); PG8_BAR; PG8_MMA(0, 0, At, B0); PG8_MMA(0, 1, At, B1); PG8_BAR; PG8_SCHED;
;     ...
; #pragma unroll
;         for (int a = 0; a < 2; ++a)
; #pragma unroll
;             for (int b = 0; b < 2; ++b)
; #pragma unroll
;                 for (int m = 0; m < 4; ++m)
; #pragma unroll
;                     for (int n = 0; n < 2; ++n) acc[a][b][m][n] = (f32x4){0.f, 0.f, 0.f, 0.f};
.LBB0_443:
	s_ashr_i32 s43, s42, 31
	s_lshl_b64 s[38:39], s[42:43], 19
	s_add_u32 s76, s62, s38
	s_addc_u32 s77, s63, s39
	s_and_b64 s[38:39], s[80:81], exec
	s_cselect_b32 s43, s77, s51
	s_cselect_b32 s45, s76, s50
	s_ashr_i32 s41, s40, 31
	s_lshl_b64 s[38:39], s[40:41], 19
	s_add_u32 s78, s87, s38
	s_addc_u32 s79, s88, s39
	s_and_b64 s[38:39], s[80:81], exec
	s_cselect_b32 s41, s79, s49
	s_cselect_b32 s96, s78, s48
	s_add_u32 s97, s48, 0x100
	s_addc_u32 vcc_lo, s49, 0
	s_add_u32 s48, s50, 0x40080
	v_mov_b32_e32 v0, 0
	s_addc_u32 s49, s51, 0
	s_mov_b32 vcc_hi, -2
	v_mov_b32_e32 v1, v0
	v_mov_b32_e32 v2, v0
	v_mov_b32_e32 v3, v0
	v_mov_b32_e32 v4, v0
	v_mov_b32_e32 v5, v0
	v_mov_b32_e32 v6, v0
	v_mov_b32_e32 v7, v0
	v_mov_b32_e32 v16, v0
	v_mov_b32_e32 v17, v0
	v_mov_b32_e32 v18, v0
	v_mov_b32_e32 v19, v0
	v_mov_b32_e32 v20, v0
	v_mov_b32_e32 v21, v0
	v_mov_b32_e32 v22, v0
	v_mov_b32_e32 v23, v0
	v_mov_b32_e32 v34, v0
	v_mov_b32_e32 v35, v0
	v_mov_b32_e32 v36, v0
	v_mov_b32_e32 v37, v0
	v_mov_b32_e32 v38, v0
	v_mov_b32_e32 v39, v0
	v_mov_b32_e32 v40, v0
	v_mov_b32_e32 v41, v0
	v_mov_b32_e32 v50, v0
	v_mov_b32_e32 v51, v0
	v_mov_b32_e32 v52, v0
	v_mov_b32_e32 v53, v0
	v_mov_b32_e32 v54, v0
	v_mov_b32_e32 v55, v0
	v_mov_b32_e32 v56, v0
	v_mov_b32_e32 v57, v0
	v_mov_b32_e32 v8, v0
	v_mov_b32_e32 v9, v0
	v_mov_b32_e32 v10, v0
	v_mov_b32_e32 v11, v0
	v_mov_b32_e32 v12, v0
	v_mov_b32_e32 v13, v0
	v_mov_b32_e32 v14, v0
	v_mov_b32_e32 v15, v0
	v_mov_b32_e32 v24, v0
	v_mov_b32_e32 v25, v0
	v_mov_b32_e32 v26, v0
	v_mov_b32_e32 v27, v0
	v_mov_b32_e32 v28, v0
	v_mov_b32_e32 v29, v0
	v_mov_b32_e32 v30, v0
	v_mov_b32_e32 v31, v0
	v_mov_b32_e32 v42, v0
	v_mov_b32_e32 v43, v0
	v_mov_b32_e32 v44, v0
	v_mov_b32_e32 v45, v0
	v_mov_b32_e32 v46, v0
	v_mov_b32_e32 v47, v0
	v_mov_b32_e32 v48, v0
	v_mov_b32_e32 v49, v0
	v_mov_b32_e32 v58, v0
	v_mov_b32_e32 v59, v0
	v_mov_b32_e32 v60, v0
	v_mov_b32_e32 v61, v0
	v_mov_b32_e32 v62, v0
	v_mov_b32_e32 v63, v0
	v_mov_b32_e32 v64, v0
	v_mov_b32_e32 v65, v0
	v_mov_b32_e32 v66, v0
	v_mov_b32_e32 v67, v0
	v_mov_b32_e32 v68, v0
	v_mov_b32_e32 v69, v0
	v_mov_b32_e32 v70, v0
	v_mov_b32_e32 v71, v0
	v_mov_b32_e32 v72, v0
	v_mov_b32_e32 v73, v0
	v_mov_b32_e32 v82, v0
	v_mov_b32_e32 v83, v0
	v_mov_b32_e32 v84, v0
	v_mov_b32_e32 v85, v0
	v_mov_b32_e32 v86, v0
	v_mov_b32_e32 v87, v0
	v_mov_b32_e32 v88, v0
	v_mov_b32_e32 v89, v0
	v_mov_b32_e32 v98, v0
	v_mov_b32_e32 v99, v0
	v_mov_b32_e32 v100, v0
	v_mov_b32_e32 v101, v0
	v_mov_b32_e32 v102, v0
	v_mov_b32_e32 v103, v0
	v_mov_b32_e32 v104, v0
	v_mov_b32_e32 v105, v0
	v_mov_b32_e32 v114, v0
	v_mov_b32_e32 v115, v0
	v_mov_b32_e32 v116, v0
	v_mov_b32_e32 v117, v0
	v_mov_b32_e32 v118, v0
	v_mov_b32_e32 v119, v0
	v_mov_b32_e32 v120, v0
	v_mov_b32_e32 v121, v0
	v_mov_b32_e32 v74, v0
	v_mov_b32_e32 v75, v0
	v_mov_b32_e32 v76, v0
	v_mov_b32_e32 v77, v0
	v_mov_b32_e32 v78, v0
	v_mov_b32_e32 v79, v0
	v_mov_b32_e32 v80, v0
	v_mov_b32_e32 v81, v0
	v_mov_b32_e32 v90, v0
	v_mov_b32_e32 v91, v0
	v_mov_b32_e32 v92, v0
	v_mov_b32_e32 v93, v0
	v_mov_b32_e32 v94, v0
	v_mov_b32_e32 v95, v0
	v_mov_b32_e32 v96, v0
	v_mov_b32_e32 v97, v0
	v_mov_b32_e32 v106, v0
	v_mov_b32_e32 v107, v0
	v_mov_b32_e32 v108, v0
	v_mov_b32_e32 v109, v0
	v_mov_b32_e32 v110, v0
	v_mov_b32_e32 v111, v0
	v_mov_b32_e32 v112, v0
	v_mov_b32_e32 v113, v0
	v_mov_b32_e32 v122, v0
	v_mov_b32_e32 v123, v0
	v_mov_b32_e32 v124, v0
	v_mov_b32_e32 v125, v0
	v_mov_b32_e32 v126, v0
	v_mov_b32_e32 v127, v0
	v_mov_b32_e32 v128, v0
	v_mov_b32_e32 v129, v0
	s_cmp_eq_u32 s100, 0
	s_cbranch_scc1 .Lrb6_skip
	s_mov_b32 s100, 0
	s_barrier
.Lrb6_skip:
.LBB0_444:
	s_add_u32 s38, s48, 0xfffc0080
	s_addc_u32 s39, s49, -1
	s_add_i32 s61, 0, 0x10000
	s_cmp_eq_u32 vcc_hi, 12
	s_cselect_b32 s83, s43, s39
	s_cselect_b32 s82, s45, s38
	v_add_u32_e32 v151, s61, v145
	s_cselect_b32 s51, s41, vcc_lo
	s_cselect_b32 s50, s96, s97
	s_add_i32 s72, 0, 0x14000
	ds_read_b128 v[170:173], v151
	ds_read_b128 v[174:177], v151 offset:1024
	ds_read_b128 v[178:181], v151 offset:2048
	ds_read_b128 v[182:185], v151 offset:3072
	v_add_u32_e32 v151, s72, v145
	ds_read_b128 v[196:199], v151
	ds_read_b128 v[200:203], v151 offset:1024
	ds_read_b128 v[204:207], v151 offset:2048
	ds_read_b128 v[208:211], v151 offset:3072
	v_lshl_add_u64 v[160:161], s[48:49], 0, v[142:143]
	s_add_i32 m0, s47, 0xc000
	ds_read_b128 v[212:215], v149
	ds_read_b128 v[216:219], v149 offset:1024
	ds_read_b128 v[220:223], v149 offset:2048
	ds_read_b128 v[224:227], v149 offset:3072
	ds_read_b128 v[228:231], v149 offset:4096
	ds_read_b128 v[232:235], v149 offset:5120
	ds_read_b128 v[236:239], v149 offset:6144
	ds_read_b128 v[240:243], v149 offset:7168
	global_load_lds_dwordx4 v[160:161], off
	v_lshl_add_u64 v[160:161], s[48:49], 0, v[140:141]
	s_add_i32 m0, s47, 0xe000
	s_nop 0
	global_load_lds_dwordx4 v[160:161], off
	s_waitcnt vmcnt(8)
	s_waitcnt lgkmcnt(0)
	s_barrier
; #define PG8_STAGE(bufoff, gbase, voff) do { _Pragma("unroll") for (int _i = 0; _i < 2; ++_i) \
;         __builtin_amdgcn_global_load_lds((const unsigned*)((const char*)(gbase) + (voff)[_i]), (PG8_LAS unsigned*)(lds + (bufoff) + ldsw + _i * 8192), 16, 0, 0); } while (0)
; #define PG8_LDA(dst, b, h) do { _Pragma("unroll") for (int m = 0; m < 4; ++m) _Pragma("unroll") for (int k = 0; k < 2; ++k) dst[m][k] = *(const PG8_LAS bf16x8*)(lds + PG8_SA(b, h) + aoff + m * 2048 + k * 1024); } while (0)
; #define PG8_MMA(ai, bj, At, Bt) do { __builtin_amdgcn_s_setprio(1); _Pragma("unroll") for (int m = 0; m < 4; ++m) _Pragma("unroll") for (int n = 0; n < 2; ++n) _Pragma("unroll") for (int k = 0; k < 2; ++k) \
;         acc[ai][bj][m][n] = __builtin_amdgcn_mfma_f32_16x16x32_bf16(Bt[n][k], At[m][k], acc[ai][bj][m][n], 0, 0, 0); __builtin_amdgcn_s_setprio(0); } while (0)
; #define PG8_WAIT_V(n) asm volatile("s_waitcnt vmcnt(" #n ")" ::: "memory")
; #define PG8_WAIT_L(n) asm volatile("s_waitcnt lgkmcnt(" #n ")" ::: "memory")
; #define PG8_BAR __builtin_amdgcn_s_barrier()
; #define PG8_SCHED __builtin_amdgcn_sched_barrier(0)
; template <class Epi, class Sched, bool ALIGN_EPI = false, bool SP2 = false>
; __device__ __forceinline__ void gemm_phase(PG8_LAS unsigned char* lds, const Gemm g, const Sched& S, const Epi& E) {
;     ...
;             PG8_WAIT_V(8); PG8_WAIT_L(0); PG8_BAR; PG8_MMA(0, 0, At, B0); PG8_MMA(0, 1, At, B1); PG8_BAR; PG8_SCHED;
;             PG8_LDA(At, 0, 1); PG8_STAGE(PG8_SB(0, 0), b2, voffB); PG8_STAGE(PG8_SB(0, 1), b2 + hstep, voffB); PG8_STAGE(PG8_SA(0, 0), a2, voffA);
;             PG8_WAIT_V(8); PG8_WAIT_L(0); PG8_BAR; PG8_MMA(1, 0, At, B0); PG8_MMA(1, 1, At, B1); PG8_BAR; PG8_SCHED;
	v_mfma_f32_16x16x32_bf16 v[126:129], v[170:173], v[212:215], v[126:129]
	v_mfma_f32_16x16x32_bf16 v[122:125], v[178:181], v[212:215], v[122:125]
	v_mfma_f32_16x16x32_bf16 v[110:113], v[170:173], v[220:223], v[110:113]
	v_mfma_f32_16x16x32_bf16 v[106:109], v[178:181], v[220:223], v[106:109]
	v_mfma_f32_16x16x32_bf16 v[94:97], v[170:173], v[228:231], v[94:97]
	v_mfma_f32_16x16x32_bf16 v[90:93], v[178:181], v[228:231], v[90:93]
	v_mfma_f32_16x16x32_bf16 v[78:81], v[170:173], v[236:239], v[78:81]
	v_mfma_f32_16x16x32_bf16 v[74:77], v[178:181], v[236:239], v[74:77]
	v_mfma_f32_16x16x32_bf16 v[126:129], v[174:177], v[216:219], v[126:129]
	v_mfma_f32_16x16x32_bf16 v[122:125], v[182:185], v[216:219], v[122:125]
	v_mfma_f32_16x16x32_bf16 v[110:113], v[174:177], v[224:227], v[110:113]
	v_mfma_f32_16x16x32_bf16 v[106:109], v[182:185], v[224:227], v[106:109]
	v_mfma_f32_16x16x32_bf16 v[94:97], v[174:177], v[232:235], v[94:97]
	v_mfma_f32_16x16x32_bf16 v[90:93], v[182:185], v[232:235], v[90:93]
	v_mfma_f32_16x16x32_bf16 v[78:81], v[174:177], v[240:243], v[78:81]
	v_mfma_f32_16x16x32_bf16 v[74:77], v[182:185], v[240:243], v[74:77]
	v_mfma_f32_16x16x32_bf16 v[118:121], v[196:199], v[212:215], v[118:121]
	v_mfma_f32_16x16x32_bf16 v[114:117], v[204:207], v[212:215], v[114:117]
	v_mfma_f32_16x16x32_bf16 v[102:105], v[196:199], v[220:223], v[102:105]
	v_mfma_f32_16x16x32_bf16 v[98:101], v[204:207], v[220:223], v[98:101]
	v_mfma_f32_16x16x32_bf16 v[86:89], v[196:199], v[228:231], v[86:89]
	v_mfma_f32_16x16x32_bf16 v[82:85], v[204:207], v[228:231], v[82:85]
	v_mfma_f32_16x16x32_bf16 v[70:73], v[196:199], v[236:239], v[70:73]
	v_mfma_f32_16x16x32_bf16 v[66:69], v[204:207], v[236:239], v[66:69]
	v_mfma_f32_16x16x32_bf16 v[118:121], v[200:203], v[216:219], v[118:121]
	v_mfma_f32_16x16x32_bf16 v[114:117], v[208:211], v[216:219], v[114:117]
	v_mfma_f32_16x16x32_bf16 v[102:105], v[200:203], v[224:227], v[102:105]
	v_mfma_f32_16x16x32_bf16 v[98:101], v[208:211], v[224:227], v[98:101]
	v_mfma_f32_16x16x32_bf16 v[86:89], v[200:203], v[232:235], v[86:89]
	v_mfma_f32_16x16x32_bf16 v[82:85], v[208:211], v[232:235], v[82:85]
	v_mfma_f32_16x16x32_bf16 v[70:73], v[200:203], v[240:243], v[70:73]
	v_mfma_f32_16x16x32_bf16 v[66:69], v[208:211], v[240:243], v[66:69]
	s_barrier
	s_add_i32 s38, s61, s89
	v_lshl_add_u64 v[160:161], s[50:51], 0, v[134:135]
	s_mov_b32 m0, s38
	ds_read_b128 v[212:215], v149 offset:16384
	ds_read_b128 v[216:219], v149 offset:17408
	ds_read_b128 v[220:223], v149 offset:18432
	ds_read_b128 v[224:227], v149 offset:19456
	ds_read_b128 v[228:231], v149 offset:20480
	ds_read_b128 v[232:235], v149 offset:21504
	ds_read_b128 v[236:239], v149 offset:22528
	ds_read_b128 v[240:243], v149 offset:23552
	global_load_lds_dwordx4 v[160:161], off
	s_add_i32 m0, s38, 0x2000
	s_add_u32 s38, s50, 0x40000
	v_lshl_add_u64 v[244:245], s[50:51], 0, v[130:131]
	s_addc_u32 s39, s51, 0
	s_add_i32 s61, s72, s89
	global_load_lds_dwordx4 v[244:245], off
	v_lshl_add_u64 v[246:247], s[38:39], 0, v[134:135]
	s_mov_b32 m0, s61
	v_lshl_add_u64 v[248:249], s[82:83], 0, v[132:133]
	global_load_lds_dwordx4 v[246:247], off
	v_lshl_add_u64 v[246:247], s[38:39], 0, v[130:131]
	s_add_i32 m0, s61, 0x2000
	s_nop 0
	global_load_lds_dwordx4 v[246:247], off
	v_lshl_add_u64 v[246:247], s[82:83], 0, v[136:137]
	s_mov_b32 m0, s47
	s_nop 0
	global_load_lds_dwordx4 v[246:247], off
	s_mov_b32 m0, s90
	s_nop 0
	global_load_lds_dwordx4 v[248:249], off
	s_waitcnt vmcnt(8)
	s_waitcnt lgkmcnt(0)
	s_barrier
	v_mfma_f32_16x16x32_bf16 v[62:65], v[170:173], v[212:215], v[62:65]
	v_mfma_f32_16x16x32_bf16 v[58:61], v[178:181], v[212:215], v[58:61]
	v_mfma_f32_16x16x32_bf16 v[46:49], v[170:173], v[220:223], v[46:49]
	v_mfma_f32_16x16x32_bf16 v[42:45], v[178:181], v[220:223], v[42:45]
	v_mfma_f32_16x16x32_bf16 v[28:31], v[170:173], v[228:231], v[28:31]
	v_mfma_f32_16x16x32_bf16 v[24:27], v[178:181], v[228:231], v[24:27]
	v_mfma_f32_16x16x32_bf16 v[12:15], v[170:173], v[236:239], v[12:15]
	v_mfma_f32_16x16x32_bf16 v[8:11], v[178:181], v[236:239], v[8:11]
	v_mfma_f32_16x16x32_bf16 v[62:65], v[174:177], v[216:219], v[62:65]
	v_mfma_f32_16x16x32_bf16 v[58:61], v[182:185], v[216:219], v[58:61]
	v_mfma_f32_16x16x32_bf16 v[46:49], v[174:177], v[224:227], v[46:49]
	v_mfma_f32_16x16x32_bf16 v[42:45], v[182:185], v[224:227], v[42:45]
	v_mfma_f32_16x16x32_bf16 v[28:31], v[174:177], v[232:235], v[28:31]
	v_mfma_f32_16x16x32_bf16 v[24:27], v[182:185], v[232:235], v[24:27]
	v_mfma_f32_16x16x32_bf16 v[12:15], v[174:177], v[240:243], v[12:15]
	v_mfma_f32_16x16x32_bf16 v[8:11], v[182:185], v[240:243], v[8:11]
	v_mfma_f32_16x16x32_bf16 v[54:57], v[196:199], v[212:215], v[54:57]
	v_mfma_f32_16x16x32_bf16 v[50:53], v[204:207], v[212:215], v[50:53]
	v_mfma_f32_16x16x32_bf16 v[38:41], v[196:199], v[220:223], v[38:41]
	v_mfma_f32_16x16x32_bf16 v[34:37], v[204:207], v[220:223], v[34:37]
	v_mfma_f32_16x16x32_bf16 v[20:23], v[196:199], v[228:231], v[20:23]
	v_mfma_f32_16x16x32_bf16 v[16:19], v[204:207], v[228:231], v[16:19]
	v_mfma_f32_16x16x32_bf16 v[4:7], v[196:199], v[236:239], v[4:7]
	v_mfma_f32_16x16x32_bf16 v[0:3], v[204:207], v[236:239], v[0:3]
	v_mfma_f32_16x16x32_bf16 v[54:57], v[200:203], v[216:219], v[54:57]
	v_mfma_f32_16x16x32_bf16 v[50:53], v[208:211], v[216:219], v[50:53]
	v_mfma_f32_16x16x32_bf16 v[38:41], v[200:203], v[224:227], v[38:41]
	v_mfma_f32_16x16x32_bf16 v[34:37], v[208:211], v[224:227], v[34:37]
	v_mfma_f32_16x16x32_bf16 v[20:23], v[200:203], v[232:235], v[20:23]
	v_mfma_f32_16x16x32_bf16 v[16:19], v[208:211], v[232:235], v[16:19]
	v_mfma_f32_16x16x32_bf16 v[4:7], v[200:203], v[240:243], v[4:7]
	v_mfma_f32_16x16x32_bf16 v[0:3], v[208:211], v[240:243], v[0:3]
	s_barrier
; #define PG8_STAGE(bufoff, gbase, voff) do { _Pragma("unroll") for (int _i = 0; _i < 2; ++_i) \
;         __builtin_amdgcn_global_load_lds((const unsigned*)((const char*)(gbase) + (voff)[_i]), (PG8_LAS unsigned*)(lds + (bufoff) + ldsw + _i * 8192), 16, 0, 0); } while (0)
; #define PG8_LDA(dst, b, h) do { _Pragma("unroll") for (int m = 0; m < 4; ++m) _Pragma("unroll") for (int k = 0; k < 2; ++k) dst[m][k] = *(const PG8_LAS bf16x8*)(lds + PG8_SA(b, h) + aoff + m * 2048 + k * 1024); } while (0)
; #define PG8_LDB(dst, b, h) do { _Pragma("unroll") for (int n = 0; n < 2; ++n) _Pragma("unroll") for (int k = 0; k < 2; ++k) dst[n][k] = *(const PG8_LAS bf16x8*)(lds + PG8_SB(b, h) + boff + n * 2048 + k * 1024); } while (0)
; #define PG8_MMA(ai, bj, At, Bt) do { __builtin_amdgcn_s_setprio(1); _Pragma("unroll") for (int m = 0; m < 4; ++m) _Pragma("unroll") for (int n = 0; n < 2; ++n) _Pragma("unroll") for (int k = 0; k < 2; ++k) \
;         acc[ai][bj][m][n] = __builtin_amdgcn_mfma_f32_16x16x32_bf16(Bt[n][k], At[m][k], acc[ai][bj][m][n], 0, 0, 0); __builtin_amdgcn_s_setprio(0); } while (0)
; #define PG8_WAIT_V(n) asm volatile("s_waitcnt vmcnt(" #n ")" ::: "memory")
; #define PG8_WAIT_L(n) asm volatile("s_waitcnt lgkmcnt(" #n ")" ::: "memory")
; #define PG8_BAR __builtin_amdgcn_s_barrier()
; #define PG8_SCHED __builtin_amdgcn_sched_barrier(0)
; template <class Epi, class Sched, bool ALIGN_EPI = false, bool SP2 = false>
; __device__ __forceinline__ void gemm_phase(PG8_LAS unsigned char* lds, const Gemm g, const Sched& S, const Epi& E) {
;     ...
;             PG8_WAIT_V(8); PG8_WAIT_L(0); PG8_BAR; PG8_MMA(1, 0, At, B0); PG8_MMA(1, 1, At, B1); PG8_BAR; PG8_SCHED;
;             PG8_LDB(B0, 1, 0); PG8_LDB(B1, 1, 1); PG8_SCHED; PG8_LDA(At, 1, 0); PG8_STAGE(PG8_SA(0, 1), a2 + hstep, voffA);
;             PG8_WAIT_V(8); PG8_WAIT_L(0); PG8_BAR; PG8_MMA(0, 0, At, B0); PG8_MMA(0, 1, At, B1); PG8_BAR; PG8_SCHED;
	s_add_i32 s61, 0, 0x18000
	v_add_u32_e32 v151, s61, v145
	s_add_i32 s72, 0, 0x1c000
	ds_read_b128 v[170:173], v151
	ds_read_b128 v[174:177], v151 offset:1024
	ds_read_b128 v[178:181], v151 offset:2048
	ds_read_b128 v[182:185], v151 offset:3072
	v_add_u32_e32 v151, s72, v145
	ds_read_b128 v[196:199], v151
	ds_read_b128 v[200:203], v151 offset:1024
	ds_read_b128 v[204:207], v151 offset:2048
	ds_read_b128 v[208:211], v151 offset:3072
	s_add_u32 s38, s82, 0x40000
	s_addc_u32 s39, s83, 0
	s_mov_b32 m0, s91
	v_lshl_add_u64 v[250:251], s[38:39], 0, v[136:137]
	ds_read_b128 v[212:215], v149 offset:32768
	ds_read_b128 v[216:219], v149 offset:33792
	ds_read_b128 v[220:223], v149 offset:34816
	ds_read_b128 v[224:227], v149 offset:35840
	ds_read_b128 v[228:231], v149 offset:36864
	ds_read_b128 v[232:235], v149 offset:37888
	ds_read_b128 v[236:239], v149 offset:38912
	ds_read_b128 v[240:243], v149 offset:39936
	global_load_lds_dwordx4 v[250:251], off
	v_lshl_add_u64 v[250:251], s[38:39], 0, v[132:133]
	s_mov_b32 m0, s92
	s_nop 0
	global_load_lds_dwordx4 v[250:251], off
	s_waitcnt vmcnt(8)
	s_waitcnt lgkmcnt(0)
	s_barrier
	v_mfma_f32_16x16x32_bf16 v[126:129], v[170:173], v[212:215], v[126:129]
	v_mfma_f32_16x16x32_bf16 v[122:125], v[178:181], v[212:215], v[122:125]
	v_mfma_f32_16x16x32_bf16 v[110:113], v[170:173], v[220:223], v[110:113]
	v_mfma_f32_16x16x32_bf16 v[106:109], v[178:181], v[220:223], v[106:109]
	v_mfma_f32_16x16x32_bf16 v[94:97], v[170:173], v[228:231], v[94:97]
	v_mfma_f32_16x16x32_bf16 v[90:93], v[178:181], v[228:231], v[90:93]
	v_mfma_f32_16x16x32_bf16 v[78:81], v[170:173], v[236:239], v[78:81]
	v_mfma_f32_16x16x32_bf16 v[74:77], v[178:181], v[236:239], v[74:77]
	v_mfma_f32_16x16x32_bf16 v[126:129], v[174:177], v[216:219], v[126:129]
	v_mfma_f32_16x16x32_bf16 v[122:125], v[182:185], v[216:219], v[122:125]
	v_mfma_f32_16x16x32_bf16 v[110:113], v[174:177], v[224:227], v[110:113]
	v_mfma_f32_16x16x32_bf16 v[106:109], v[182:185], v[224:227], v[106:109]
	v_mfma_f32_16x16x32_bf16 v[94:97], v[174:177], v[232:235], v[94:97]
	v_mfma_f32_16x16x32_bf16 v[90:93], v[182:185], v[232:235], v[90:93]
	v_mfma_f32_16x16x32_bf16 v[78:81], v[174:177], v[240:243], v[78:81]
	v_mfma_f32_16x16x32_bf16 v[74:77], v[182:185], v[240:243], v[74:77]
	v_mfma_f32_16x16x32_bf16 v[118:121], v[196:199], v[212:215], v[118:121]
	v_mfma_f32_16x16x32_bf16 v[114:117], v[204:207], v[212:215], v[114:117]
	v_mfma_f32_16x16x32_bf16 v[102:105], v[196:199], v[220:223], v[102:105]
	v_mfma_f32_16x16x32_bf16 v[98:101], v[204:207], v[220:223], v[98:101]
	v_mfma_f32_16x16x32_bf16 v[86:89], v[196:199], v[228:231], v[86:89]
	v_mfma_f32_16x16x32_bf16 v[82:85], v[204:207], v[228:231], v[82:85]
	v_mfma_f32_16x16x32_bf16 v[70:73], v[196:199], v[236:239], v[70:73]
	v_mfma_f32_16x16x32_bf16 v[66:69], v[204:207], v[236:239], v[66:69]
	v_mfma_f32_16x16x32_bf16 v[118:121], v[200:203], v[216:219], v[118:121]
	v_mfma_f32_16x16x32_bf16 v[114:117], v[208:211], v[216:219], v[114:117]
	v_mfma_f32_16x16x32_bf16 v[102:105], v[200:203], v[224:227], v[102:105]
	v_mfma_f32_16x16x32_bf16 v[98:101], v[208:211], v[224:227], v[98:101]
	v_mfma_f32_16x16x32_bf16 v[86:89], v[200:203], v[232:235], v[86:89]
	v_mfma_f32_16x16x32_bf16 v[82:85], v[208:211], v[232:235], v[82:85]
	v_mfma_f32_16x16x32_bf16 v[70:73], v[200:203], v[240:243], v[70:73]
	v_mfma_f32_16x16x32_bf16 v[66:69], v[208:211], v[240:243], v[66:69]
	s_barrier
	s_add_i32 s38, s61, s89
	v_lshl_add_u64 v[160:161], v[160:161], 0, s[34:35]
	s_mov_b32 m0, s38
	ds_read_b128 v[212:215], v149 offset:49152
	ds_read_b128 v[216:219], v149 offset:50176
	ds_read_b128 v[220:223], v149 offset:51200
	ds_read_b128 v[224:227], v149 offset:52224
	ds_read_b128 v[228:231], v149 offset:53248
	ds_read_b128 v[232:235], v149 offset:54272
	ds_read_b128 v[236:239], v149 offset:55296
	ds_read_b128 v[240:243], v149 offset:56320
	global_load_lds_dwordx4 v[160:161], off
	s_add_i32 m0, s38, 0x2000
	s_add_u32 s38, s50, 0x40080
	v_lshl_add_u64 v[160:161], v[244:245], 0, s[34:35]
	s_addc_u32 s39, s51, 0
	s_add_i32 s50, s72, s89
	global_load_lds_dwordx4 v[160:161], off
	v_lshl_add_u64 v[160:161], s[38:39], 0, v[134:135]
	s_mov_b32 m0, s50
	s_nop 0
	global_load_lds_dwordx4 v[160:161], off
	v_lshl_add_u64 v[160:161], s[38:39], 0, v[130:131]
	s_add_i32 m0, s50, 0x2000
	s_nop 0
	global_load_lds_dwordx4 v[160:161], off
	v_lshl_add_u64 v[160:161], v[246:247], 0, s[34:35]
	s_mov_b32 m0, s93
	s_nop 0
	global_load_lds_dwordx4 v[160:161], off
	v_lshl_add_u64 v[160:161], v[248:249], 0, s[34:35]
	s_mov_b32 m0, s94
	s_nop 0
	global_load_lds_dwordx4 v[160:161], off
	s_waitcnt vmcnt(8)
	s_waitcnt lgkmcnt(0)
	s_barrier
; __device__ __forceinline__ unsigned cvt_pk_bf16(float lo, float hi) { unsigned r; asm volatile("v_cvt_pk_bf16_f32 %0, %1, %2" : "=v"(r) : "v"(lo), "v"(hi)); return r; }
; #define PG8_STAGE(bufoff, gbase, voff) do { _Pragma("unroll") for (int _i = 0; _i < 2; ++_i) \
;         __builtin_amdgcn_global_load_lds((const unsigned*)((const char*)(gbase) + (voff)[_i]), (PG8_LAS unsigned*)(lds + (bufoff) + ldsw + _i * 8192), 16, 0, 0); } while (0)
; #define PG8_LDA(dst, b, h) do { _Pragma("unroll") for (int m = 0; m < 4; ++m) _Pragma("unroll") for (int k = 0; k < 2; ++k) dst[m][k] = *(const PG8_LAS bf16x8*)(lds + PG8_SA(b, h) + aoff + m * 2048 + k * 1024); } while (0)
; #define PG8_WAIT_V(n) asm volatile("s_waitcnt vmcnt(" #n ")" ::: "memory")
; #define PG8_WAIT_L(n) asm volatile("s_waitcnt lgkmcnt(" #n ")" ::: "memory")
; template <class Epi, class Sched, bool ALIGN_EPI = false, bool SP2 = false>
; __device__ __forceinline__ void gemm_phase(PG8_LAS unsigned char* lds, const Gemm g, const Sched& S, const Epi& E) {
;     ...
;             PG8_WAIT_V(8); PG8_WAIT_L(0); PG8_BAR; PG8_MMA(0, 0, At, B0); PG8_MMA(0, 1, At, B1); PG8_BAR; PG8_SCHED;
;             PG8_LDA(At, 1, 1); PG8_STAGE(PG8_SB(1, 0), b3, voffB); PG8_STAGE(PG8_SB(1, 1), b3 + hstep, voffB); PG8_STAGE(PG8_SA(1, 0), a3, voffA);
;             PG8_WAIT_V(8); PG8_WAIT_L(0); PG8_BAR; PG8_MMA(1, 0, At, B0); PG8_MMA(1, 1, At, B1); PG8_BAR; PG8_SCHED;
;     __device__ __forceinline__ void operator()(const f32x4 (&acc)[2][2][4][2], const Unit& u, int wr, int wc, int fr, int fq, const float (&pre)[8]) const {
;         const int row0 = u.pm * 256 + wr * 64 + fr, col0 = u.pn * 128 + wc * 32 + 8 * fq;
; #pragma unroll
;         for (int ai = 0; ai < 2; ++ai)
; #pragma unroll
;             for (int m = 0; m < 4; ++m) {
;                 const float rsc = pre[ai * 4 + m];
;                 const f32x4 g0 = acc[ai][0][m][0] * rsc, g1 = acc[ai][0][m][1] * rsc, u0 = acc[ai][1][m][0] * rsc, u1 = acc[ai][1][m][1] * rsc;
;                 u32x4 w; w.x = cvt_pk_bf16(silu_mul(g0[0], u0[0]), silu_mul(g0[1], u0[1])); w.y = cvt_pk_bf16(silu_mul(g0[2], u0[2]), silu_mul(g0[3], u0[3]));
;                 w.z = cvt_pk_bf16(silu_mul(g1[0], u1[0]), silu_mul(g1[1], u1[1])); w.w = cvt_pk_bf16(silu_mul(g1[2], u1[2]), silu_mul(g1[3], u1[3]));
;                 *(GAS u32x4*)(O + (size_t)(row0 + ai * 128 + m * 16) * DFF + col0) = w; }
	v_mfma_f32_16x16x32_bf16 v[62:65], v[170:173], v[212:215], v[62:65]
	v_mfma_f32_16x16x32_bf16 v[58:61], v[178:181], v[212:215], v[58:61]
	v_mfma_f32_16x16x32_bf16 v[46:49], v[170:173], v[220:223], v[46:49]
	v_mfma_f32_16x16x32_bf16 v[42:45], v[178:181], v[220:223], v[42:45]
	v_mfma_f32_16x16x32_bf16 v[28:31], v[170:173], v[228:231], v[28:31]
	v_mfma_f32_16x16x32_bf16 v[24:27], v[178:181], v[228:231], v[24:27]
	v_mfma_f32_16x16x32_bf16 v[12:15], v[170:173], v[236:239], v[12:15]
	v_mfma_f32_16x16x32_bf16 v[8:11], v[178:181], v[236:239], v[8:11]
	v_mfma_f32_16x16x32_bf16 v[62:65], v[174:177], v[216:219], v[62:65]
	v_mfma_f32_16x16x32_bf16 v[58:61], v[182:185], v[216:219], v[58:61]
	v_mfma_f32_16x16x32_bf16 v[46:49], v[174:177], v[224:227], v[46:49]
	v_mfma_f32_16x16x32_bf16 v[42:45], v[182:185], v[224:227], v[42:45]
	v_mfma_f32_16x16x32_bf16 v[28:31], v[174:177], v[232:235], v[28:31]
	v_mfma_f32_16x16x32_bf16 v[24:27], v[182:185], v[232:235], v[24:27]
	v_mfma_f32_16x16x32_bf16 v[12:15], v[174:177], v[240:243], v[12:15]
	v_mfma_f32_16x16x32_bf16 v[8:11], v[182:185], v[240:243], v[8:11]
	v_mfma_f32_16x16x32_bf16 v[54:57], v[196:199], v[212:215], v[54:57]
	v_mfma_f32_16x16x32_bf16 v[50:53], v[204:207], v[212:215], v[50:53]
	v_mfma_f32_16x16x32_bf16 v[38:41], v[196:199], v[220:223], v[38:41]
	v_mfma_f32_16x16x32_bf16 v[34:37], v[204:207], v[220:223], v[34:37]
	v_mfma_f32_16x16x32_bf16 v[20:23], v[196:199], v[228:231], v[20:23]
	v_mfma_f32_16x16x32_bf16 v[16:19], v[204:207], v[228:231], v[16:19]
	v_mfma_f32_16x16x32_bf16 v[4:7], v[196:199], v[236:239], v[4:7]
	v_mfma_f32_16x16x32_bf16 v[0:3], v[204:207], v[236:239], v[0:3]
	v_mfma_f32_16x16x32_bf16 v[54:57], v[200:203], v[216:219], v[54:57]
	v_mfma_f32_16x16x32_bf16 v[50:53], v[208:211], v[216:219], v[50:53]
	v_mfma_f32_16x16x32_bf16 v[38:41], v[200:203], v[224:227], v[38:41]
	v_mfma_f32_16x16x32_bf16 v[34:37], v[208:211], v[224:227], v[34:37]
	v_mfma_f32_16x16x32_bf16 v[20:23], v[200:203], v[232:235], v[20:23]
	v_mfma_f32_16x16x32_bf16 v[16:19], v[208:211], v[232:235], v[16:19]
	v_mfma_f32_16x16x32_bf16 v[4:7], v[200:203], v[240:243], v[4:7]
	v_mfma_f32_16x16x32_bf16 v[0:3], v[208:211], v[240:243], v[0:3]
	s_barrier
	s_add_i32 vcc_hi, vcc_hi, 2
	s_add_u32 s97, s97, 0x100
	s_addc_u32 vcc_lo, vcc_lo, 0
	s_add_u32 s48, s48, 0x100
	s_addc_u32 s49, s49, 0
	s_cmp_gt_u32 vcc_hi, 13
	s_cbranch_scc0 .LBB0_444
	s_and_b64 vcc, exec, s[4:5]
	s_cbranch_vccz .LBB0_447
	s_barrier
.LBB0_447:
	v_pk_mul_f32 v[126:127], v[158:159], v[126:127] op_sel_hi:[0,1]
	v_mul_f32_e32 v153, 0xbfb8aa3b, v126
	v_exp_f32_e32 v153, v153
	v_pk_mul_f32 v[118:119], v[158:159], v[118:119] op_sel_hi:[0,1]
	v_pk_mul_f32 v[128:129], v[158:159], v[128:129] op_sel_hi:[0,1]
	v_pk_mul_f32 v[120:121], v[158:159], v[120:121] op_sel_hi:[0,1]
	v_add_f32_e32 v153, 1.0, v153
	v_rcp_f32_e32 v153, v153
	v_pk_mul_f32 v[122:123], v[158:159], v[122:123] op_sel_hi:[0,1]
	v_pk_mul_f32 v[114:115], v[158:159], v[114:115] op_sel_hi:[0,1]
	v_pk_mul_f32 v[124:125], v[158:159], v[124:125] op_sel_hi:[0,1]
	v_mul_f32_e32 v126, v126, v153
	v_mul_f32_e32 v118, v126, v118
	v_mul_f32_e32 v126, 0xbfb8aa3b, v127
	v_exp_f32_e32 v126, v126
	v_pk_mul_f32 v[116:117], v[158:159], v[116:117] op_sel_hi:[0,1]
	v_lshl_or_b32 v160, s44, 7, v147
	v_lshl_add_u32 v151, s46, 8, v33
	v_add_f32_e32 v126, 1.0, v126
	v_rcp_f32_e32 v126, v126
	v_ashrrev_i32_e32 v161, 31, v160
	v_pk_mul_f32 v[110:111], v[156:157], v[110:111] op_sel_hi:[0,1]
	v_pk_mul_f32 v[102:103], v[156:157], v[102:103] op_sel_hi:[0,1]
	v_mul_f32_e32 v126, v127, v126
	v_mul_f32_e32 v119, v126, v119
	v_cvt_pk_bf16_f32 v118, v118, v119
	v_mul_f32_e32 v119, 0xbfb8aa3b, v128
	v_exp_f32_e32 v119, v119
	v_pk_mul_f32 v[112:113], v[156:157], v[112:113] op_sel_hi:[0,1]
	v_pk_mul_f32 v[104:105], v[156:157], v[104:105] op_sel_hi:[0,1]
	v_pk_mul_f32 v[106:107], v[156:157], v[106:107] op_sel_hi:[0,1]
	v_add_f32_e32 v119, 1.0, v119
	v_rcp_f32_e32 v119, v119
	v_pk_mul_f32 v[108:109], v[156:157], v[108:109] op_sel_hi:[0,1]
	v_pk_mul_f32 v[94:95], v[154:155], v[94:95] op_sel_hi:[0,1]
	v_pk_mul_f32 v[86:87], v[154:155], v[86:87] op_sel_hi:[0,1]
	v_mul_f32_e32 v119, v128, v119
	v_mul_f32_e32 v119, v119, v120
	v_mul_f32_e32 v120, 0xbfb8aa3b, v129
	v_exp_f32_e32 v120, v120
	v_pk_mul_f32 v[96:97], v[154:155], v[96:97] op_sel_hi:[0,1]
	v_pk_mul_f32 v[88:89], v[154:155], v[88:89] op_sel_hi:[0,1]
	v_pk_mul_f32 v[90:91], v[154:155], v[90:91] op_sel_hi:[0,1]
	v_add_f32_e32 v120, 1.0, v120
	v_rcp_f32_e32 v120, v120
	v_pk_mul_f32 v[92:93], v[154:155], v[92:93] op_sel_hi:[0,1]
	v_pk_mul_f32 v[78:79], v[152:153], v[78:79] op_sel_hi:[0,1]
	v_pk_mul_f32 v[70:71], v[152:153], v[70:71] op_sel_hi:[0,1]
	v_mul_f32_e32 v120, v129, v120
	v_mul_f32_e32 v120, v120, v121
	v_cvt_pk_bf16_f32 v119, v119, v120
	v_mul_f32_e32 v120, 0xbfb8aa3b, v122
	v_exp_f32_e32 v120, v120
	v_pk_mul_f32 v[80:81], v[152:153], v[80:81] op_sel_hi:[0,1]
	v_pk_mul_f32 v[72:73], v[152:153], v[72:73] op_sel_hi:[0,1]
	v_pk_mul_f32 v[74:75], v[152:153], v[74:75] op_sel_hi:[0,1]
	v_add_f32_e32 v120, 1.0, v120
	v_rcp_f32_e32 v120, v120
	v_pk_mul_f32 v[76:77], v[152:153], v[76:77] op_sel_hi:[0,1]
	v_pk_mul_f32 v[62:63], v[150:151], v[62:63] op_sel_hi:[0,1]
	v_pk_mul_f32 v[54:55], v[150:151], v[54:55] op_sel_hi:[0,1]
	v_mul_f32_e32 v120, v122, v120
	v_mul_f32_e32 v114, v120, v114
	v_mul_f32_e32 v120, 0xbfb8aa3b, v123
	v_exp_f32_e32 v120, v120
	v_pk_mul_f32 v[64:65], v[150:151], v[64:65] op_sel_hi:[0,1]
	v_pk_mul_f32 v[56:57], v[150:151], v[56:57] op_sel_hi:[0,1]
	v_pk_mul_f32 v[58:59], v[150:151], v[58:59] op_sel_hi:[0,1]
	v_add_f32_e32 v120, 1.0, v120
	v_rcp_f32_e32 v120, v120
; __device__ __forceinline__ unsigned cvt_pk_bf16(float lo, float hi) { unsigned r; asm volatile("v_cvt_pk_bf16_f32 %0, %1, %2" : "=v"(r) : "v"(lo), "v"(hi)); return r; }
; #define GAS __attribute__((address_space(1)))
; __device__ __forceinline__ float silu_mul(float g, float u) { const float e = __builtin_amdgcn_exp2f(-1.4426950408889634f * g); return g * __builtin_amdgcn_rcpf(1.0f + e) * u; }
;     __device__ __forceinline__ void prefetch(const Unit& u, int wr, int fr, float (&pre)[8]) const {
; #pragma unroll
;         for (int i = 0; i < 8; ++i) pre[i] = *(const GAS float*)(rs + u.pm * 256 + wr * 64 + fr + (i >> 2) * 128 + (i & 3) * 16);
;     }
;     __device__ __forceinline__ void operator()(const f32x4 (&acc)[2][2][4][2], const Unit& u, int wr, int wc, int fr, int fq, const float (&pre)[8]) const {
;         const int row0 = u.pm * 256 + wr * 64 + fr, col0 = u.pn * 128 + wc * 32 + 8 * fq;
; #pragma unroll
;         for (int ai = 0; ai < 2; ++ai)
; #pragma unroll
;             for (int m = 0; m < 4; ++m) {
;                 const float rsc = pre[ai * 4 + m];
;                 const f32x4 g0 = acc[ai][0][m][0] * rsc, g1 = acc[ai][0][m][1] * rsc, u0 = acc[ai][1][m][0] * rsc, u1 = acc[ai][1][m][1] * rsc;
;                 u32x4 w; w.x = cvt_pk_bf16(silu_mul(g0[0], u0[0]), silu_mul(g0[1], u0[1])); w.y = cvt_pk_bf16(silu_mul(g0[2], u0[2]), silu_mul(g0[3], u0[3]));
;                 w.z = cvt_pk_bf16(silu_mul(g1[0], u1[0]), silu_mul(g1[1], u1[1])); w.w = cvt_pk_bf16(silu_mul(g1[2], u1[2]), silu_mul(g1[3], u1[3]));
;                 *(GAS u32x4*)(O + (size_t)(row0 + ai * 128 + m * 16) * DFF + col0) = w; }
	v_pk_mul_f32 v[60:61], v[150:151], v[60:61] op_sel_hi:[0,1]
	v_pk_mul_f32 v[46:47], v[148:149], v[46:47] op_sel_hi:[0,1]
	v_pk_mul_f32 v[38:39], v[148:149], v[38:39] op_sel_hi:[0,1]
	v_mul_f32_e32 v120, v123, v120
	v_mul_f32_e32 v115, v120, v115
	v_cvt_pk_bf16_f32 v120, v114, v115
	v_mul_f32_e32 v114, 0xbfb8aa3b, v124
	v_mul_f32_e32 v115, 0xbfb8aa3b, v125
	v_exp_f32_e32 v114, v114
	v_exp_f32_e32 v115, v115
	v_pk_mul_f32 v[48:49], v[148:149], v[48:49] op_sel_hi:[0,1]
	v_pk_mul_f32 v[40:41], v[148:149], v[40:41] op_sel_hi:[0,1]
	v_add_f32_e32 v114, 1.0, v114
	v_add_f32_e32 v115, 1.0, v115
	v_rcp_f32_e32 v114, v114
	v_rcp_f32_e32 v115, v115
	v_pk_mul_f32 v[42:43], v[148:149], v[42:43] op_sel_hi:[0,1]
	v_pk_mul_f32 v[44:45], v[148:149], v[44:45] op_sel_hi:[0,1]
	v_mul_f32_e32 v114, v124, v114
	v_mul_f32_e32 v115, v125, v115
	v_mul_f32_e32 v114, v114, v116
	v_mul_f32_e32 v115, v115, v117
	v_cvt_pk_bf16_f32 v121, v114, v115
	v_mov_b64_e32 v[114:115], s[64:65]
	v_mad_i64_i32 v[122:123], s[38:39], v151, s29, v[114:115]
	v_lshlrev_b64 v[116:117], 1, v[160:161]
	v_lshl_add_u64 v[122:123], v[122:123], 0, v[116:117]
	global_store_dwordx4 v[122:123], v[118:121], off
	v_pk_mul_f32 v[28:29], v[146:147], v[28:29] op_sel_hi:[0,1]
	v_pk_mul_f32 v[20:21], v[146:147], v[20:21] op_sel_hi:[0,1]
	v_pk_mul_f32 v[118:119], v[156:157], v[100:101] op_sel_hi:[0,1]
	v_pk_mul_f32 v[100:101], v[156:157], v[98:99] op_sel_hi:[0,1]
	v_mul_f32_e32 v98, 0xbfb8aa3b, v110
	v_mul_f32_e32 v99, 0xbfb8aa3b, v111
	v_exp_f32_e32 v98, v98
	v_exp_f32_e32 v99, v99
	v_pk_mul_f32 v[30:31], v[146:147], v[30:31] op_sel_hi:[0,1]
	v_pk_mul_f32 v[22:23], v[146:147], v[22:23] op_sel_hi:[0,1]
	v_add_f32_e32 v98, 1.0, v98
	v_add_f32_e32 v99, 1.0, v99
	v_rcp_f32_e32 v98, v98
	v_rcp_f32_e32 v99, v99
	v_pk_mul_f32 v[24:25], v[146:147], v[24:25] op_sel_hi:[0,1]
	v_pk_mul_f32 v[26:27], v[146:147], v[26:27] op_sel_hi:[0,1]
	v_mul_f32_e32 v98, v110, v98
	v_mul_f32_e32 v99, v111, v99
	v_mul_f32_e32 v98, v98, v102
	v_mul_f32_e32 v99, v99, v103
	v_cvt_pk_bf16_f32 v98, v98, v99
	v_mul_f32_e32 v99, 0xbfb8aa3b, v112
	v_mul_f32_e32 v102, 0xbfb8aa3b, v113
	v_exp_f32_e32 v99, v99
	v_exp_f32_e32 v102, v102
	v_pk_mul_f32 v[12:13], v[144:145], v[12:13] op_sel_hi:[0,1]
	v_pk_mul_f32 v[4:5], v[144:145], v[4:5] op_sel_hi:[0,1]
	v_add_f32_e32 v99, 1.0, v99
	v_add_f32_e32 v102, 1.0, v102
	v_rcp_f32_e32 v99, v99
	v_rcp_f32_e32 v102, v102
	v_pk_mul_f32 v[14:15], v[144:145], v[14:15] op_sel_hi:[0,1]
	v_pk_mul_f32 v[6:7], v[144:145], v[6:7] op_sel_hi:[0,1]
	v_mul_f32_e32 v99, v112, v99
	v_mul_f32_e32 v102, v113, v102
	v_mul_f32_e32 v99, v99, v104
	v_mul_f32_e32 v102, v102, v105
	v_cvt_pk_bf16_f32 v99, v99, v102
	v_mul_f32_e32 v102, 0xbfb8aa3b, v106
	v_exp_f32_e32 v102, v102
	v_pk_mul_f32 v[8:9], v[144:145], v[8:9] op_sel_hi:[0,1]
	v_pk_mul_f32 v[10:11], v[144:145], v[10:11] op_sel_hi:[0,1]
	s_mov_b64 s[44:45], -1
	v_add_f32_e32 v102, 1.0, v102
	v_rcp_f32_e32 v102, v102
	s_andn2_b64 vcc, exec, s[80:81]
	v_mul_f32_e32 v102, v106, v102
	v_mul_f32_e32 v100, v102, v100
	v_mul_f32_e32 v102, 0xbfb8aa3b, v107
	v_exp_f32_e32 v102, v102
	s_nop 0
	v_add_f32_e32 v102, 1.0, v102
	v_rcp_f32_e32 v102, v102
	s_nop 0
	v_mul_f32_e32 v102, v107, v102
	v_mul_f32_e32 v101, v102, v101
	v_cvt_pk_bf16_f32 v100, v100, v101
	v_mul_f32_e32 v101, 0xbfb8aa3b, v108
	v_mul_f32_e32 v102, 0xbfb8aa3b, v109
	v_exp_f32_e32 v101, v101
	v_exp_f32_e32 v102, v102
	v_add_f32_e32 v101, 1.0, v101
	v_add_f32_e32 v102, 1.0, v102
	v_rcp_f32_e32 v101, v101
	v_rcp_f32_e32 v102, v102
	v_mul_f32_e32 v101, v108, v101
	v_mul_f32_e32 v102, v109, v102
	v_mul_f32_e32 v101, v101, v118
	v_mul_f32_e32 v102, v102, v119
	v_cvt_pk_bf16_f32 v101, v101, v102
	v_or_b32_e32 v102, 16, v151
	v_mad_i64_i32 v[102:103], s[38:39], v102, s29, v[114:115]
	v_lshl_add_u64 v[102:103], v[102:103], 0, v[116:117]
	global_store_dwordx4 v[102:103], v[98:101], off
	s_nop 1
	v_pk_mul_f32 v[98:99], v[154:155], v[84:85] op_sel_hi:[0,1]
	v_pk_mul_f32 v[84:85], v[154:155], v[82:83] op_sel_hi:[0,1]
	v_mul_f32_e32 v82, 0xbfb8aa3b, v94
	v_mul_f32_e32 v83, 0xbfb8aa3b, v95
	v_exp_f32_e32 v82, v82
	v_exp_f32_e32 v83, v83
	v_add_f32_e32 v82, 1.0, v82
	v_add_f32_e32 v83, 1.0, v83
	v_rcp_f32_e32 v82, v82
	v_rcp_f32_e32 v83, v83
	v_mul_f32_e32 v82, v94, v82
	v_mul_f32_e32 v83, v95, v83
	v_mul_f32_e32 v82, v82, v86
	v_mul_f32_e32 v83, v83, v87
	v_cvt_pk_bf16_f32 v82, v82, v83
	v_mul_f32_e32 v83, 0xbfb8aa3b, v96
	v_mul_f32_e32 v86, 0xbfb8aa3b, v97
	v_exp_f32_e32 v83, v83
	v_exp_f32_e32 v86, v86
	v_add_f32_e32 v83, 1.0, v83
	v_add_f32_e32 v86, 1.0, v86
	v_rcp_f32_e32 v83, v83
	v_rcp_f32_e32 v86, v86
	v_mul_f32_e32 v83, v96, v83
	v_mul_f32_e32 v86, v97, v86
	v_mul_f32_e32 v83, v83, v88
	v_mul_f32_e32 v86, v86, v89
	v_cvt_pk_bf16_f32 v83, v83, v86
	v_mul_f32_e32 v86, 0xbfb8aa3b, v90
	v_exp_f32_e32 v86, v86
	s_nop 0
	v_add_f32_e32 v86, 1.0, v86
	v_rcp_f32_e32 v86, v86
	s_nop 0
	v_mul_f32_e32 v86, v90, v86
	v_mul_f32_e32 v84, v86, v84
	v_mul_f32_e32 v86, 0xbfb8aa3b, v91
	v_exp_f32_e32 v86, v86
	s_nop 0
	v_add_f32_e32 v86, 1.0, v86
	v_rcp_f32_e32 v86, v86
	s_nop 0
	v_mul_f32_e32 v86, v91, v86
	v_mul_f32_e32 v85, v86, v85
	v_cvt_pk_bf16_f32 v84, v84, v85
	v_mul_f32_e32 v85, 0xbfb8aa3b, v92
	v_mul_f32_e32 v86, 0xbfb8aa3b, v93
	v_exp_f32_e32 v85, v85
	v_exp_f32_e32 v86, v86
	v_add_f32_e32 v85, 1.0, v85
	v_add_f32_e32 v86, 1.0, v86
	v_rcp_f32_e32 v85, v85
	v_rcp_f32_e32 v86, v86
	v_mul_f32_e32 v85, v92, v85
	v_mul_f32_e32 v86, v93, v86
	v_mul_f32_e32 v85, v85, v98
	v_mul_f32_e32 v86, v86, v99
	v_cvt_pk_bf16_f32 v85, v85, v86
	v_or_b32_e32 v86, 32, v151
	v_mad_i64_i32 v[86:87], s[38:39], v86, s29, v[114:115]
; __device__ __forceinline__ unsigned cvt_pk_bf16(float lo, float hi) { unsigned r; asm volatile("v_cvt_pk_bf16_f32 %0, %1, %2" : "=v"(r) : "v"(lo), "v"(hi)); return r; }
; #define GAS __attribute__((address_space(1)))
; __device__ __forceinline__ float silu_mul(float g, float u) { const float e = __builtin_amdgcn_exp2f(-1.4426950408889634f * g); return g * __builtin_amdgcn_rcpf(1.0f + e) * u; }
;     __device__ __forceinline__ void prefetch(const Unit& u, int wr, int fr, float (&pre)[8]) const {
; #pragma unroll
;         for (int i = 0; i < 8; ++i) pre[i] = *(const GAS float*)(rs + u.pm * 256 + wr * 64 + fr + (i >> 2) * 128 + (i & 3) * 16);
;     }
;     __device__ __forceinline__ void operator()(const f32x4 (&acc)[2][2][4][2], const Unit& u, int wr, int wc, int fr, int fq, const float (&pre)[8]) const {
;         const int row0 = u.pm * 256 + wr * 64 + fr, col0 = u.pn * 128 + wc * 32 + 8 * fq;
; #pragma unroll
;         for (int ai = 0; ai < 2; ++ai)
; #pragma unroll
;             for (int m = 0; m < 4; ++m) {
;                 const float rsc = pre[ai * 4 + m];
;                 const f32x4 g0 = acc[ai][0][m][0] * rsc, g1 = acc[ai][0][m][1] * rsc, u0 = acc[ai][1][m][0] * rsc, u1 = acc[ai][1][m][1] * rsc;
;                 u32x4 w; w.x = cvt_pk_bf16(silu_mul(g0[0], u0[0]), silu_mul(g0[1], u0[1])); w.y = cvt_pk_bf16(silu_mul(g0[2], u0[2]), silu_mul(g0[3], u0[3]));
;                 w.z = cvt_pk_bf16(silu_mul(g1[0], u1[0]), silu_mul(g1[1], u1[1])); w.w = cvt_pk_bf16(silu_mul(g1[2], u1[2]), silu_mul(g1[3], u1[3]));
;                 *(GAS u32x4*)(O + (size_t)(row0 + ai * 128 + m * 16) * DFF + col0) = w; }
	v_lshl_add_u64 v[86:87], v[86:87], 0, v[116:117]
	global_store_dwordx4 v[86:87], v[82:85], off
	s_nop 1
	v_pk_mul_f32 v[82:83], v[152:153], v[68:69] op_sel_hi:[0,1]
	v_pk_mul_f32 v[68:69], v[152:153], v[66:67] op_sel_hi:[0,1]
	v_mul_f32_e32 v66, 0xbfb8aa3b, v78
	v_mul_f32_e32 v67, 0xbfb8aa3b, v79
	v_exp_f32_e32 v66, v66
	v_exp_f32_e32 v67, v67
	v_add_f32_e32 v66, 1.0, v66
	v_add_f32_e32 v67, 1.0, v67
	v_rcp_f32_e32 v66, v66
	v_rcp_f32_e32 v67, v67
	v_mul_f32_e32 v66, v78, v66
	v_mul_f32_e32 v67, v79, v67
	v_mul_f32_e32 v66, v66, v70
	v_mul_f32_e32 v67, v67, v71
	v_cvt_pk_bf16_f32 v66, v66, v67
	v_mul_f32_e32 v67, 0xbfb8aa3b, v80
	v_mul_f32_e32 v70, 0xbfb8aa3b, v81
	v_exp_f32_e32 v67, v67
	v_exp_f32_e32 v70, v70
	v_add_f32_e32 v67, 1.0, v67
	v_add_f32_e32 v70, 1.0, v70
	v_rcp_f32_e32 v67, v67
	v_rcp_f32_e32 v70, v70
	v_mul_f32_e32 v67, v80, v67
	v_mul_f32_e32 v70, v81, v70
	v_mul_f32_e32 v67, v67, v72
	v_mul_f32_e32 v70, v70, v73
	v_cvt_pk_bf16_f32 v67, v67, v70
	v_mul_f32_e32 v70, 0xbfb8aa3b, v74
	v_exp_f32_e32 v70, v70
	s_nop 0
	v_add_f32_e32 v70, 1.0, v70
	v_rcp_f32_e32 v70, v70
	s_nop 0
	v_mul_f32_e32 v70, v74, v70
	v_mul_f32_e32 v68, v70, v68
	v_mul_f32_e32 v70, 0xbfb8aa3b, v75
	v_exp_f32_e32 v70, v70
	s_nop 0
	v_add_f32_e32 v70, 1.0, v70
	v_rcp_f32_e32 v70, v70
	s_nop 0
	v_mul_f32_e32 v70, v75, v70
	v_mul_f32_e32 v69, v70, v69
	v_cvt_pk_bf16_f32 v68, v68, v69
	v_mul_f32_e32 v69, 0xbfb8aa3b, v76
	v_mul_f32_e32 v70, 0xbfb8aa3b, v77
	v_exp_f32_e32 v69, v69
	v_exp_f32_e32 v70, v70
	v_add_f32_e32 v69, 1.0, v69
	v_add_f32_e32 v70, 1.0, v70
	v_rcp_f32_e32 v69, v69
	v_rcp_f32_e32 v70, v70
	v_mul_f32_e32 v69, v76, v69
	v_mul_f32_e32 v70, v77, v70
	v_mul_f32_e32 v69, v69, v82
	v_mul_f32_e32 v70, v70, v83
	v_cvt_pk_bf16_f32 v69, v69, v70
	v_or_b32_e32 v70, 48, v151
	v_mad_i64_i32 v[70:71], s[38:39], v70, s29, v[114:115]
	v_lshl_add_u64 v[70:71], v[70:71], 0, v[116:117]
	global_store_dwordx4 v[70:71], v[66:69], off
	s_nop 1
	v_pk_mul_f32 v[66:67], v[150:151], v[52:53] op_sel_hi:[0,1]
	v_pk_mul_f32 v[52:53], v[150:151], v[50:51] op_sel_hi:[0,1]
	v_mul_f32_e32 v50, 0xbfb8aa3b, v62
	v_mul_f32_e32 v51, 0xbfb8aa3b, v63
	v_exp_f32_e32 v50, v50
	v_exp_f32_e32 v51, v51
	v_add_u32_e32 v68, 0x80, v151
	v_add_f32_e32 v50, 1.0, v50
	v_add_f32_e32 v51, 1.0, v51
	v_rcp_f32_e32 v50, v50
	v_rcp_f32_e32 v51, v51
	v_mul_f32_e32 v50, v62, v50
	v_mul_f32_e32 v51, v63, v51
	v_mul_f32_e32 v50, v50, v54
	v_mul_f32_e32 v51, v51, v55
	v_cvt_pk_bf16_f32 v50, v50, v51
	v_mul_f32_e32 v51, 0xbfb8aa3b, v64
	v_mul_f32_e32 v54, 0xbfb8aa3b, v65
	v_exp_f32_e32 v51, v51
	v_exp_f32_e32 v54, v54
	v_add_f32_e32 v51, 1.0, v51
	v_add_f32_e32 v54, 1.0, v54
	v_rcp_f32_e32 v51, v51
	v_rcp_f32_e32 v54, v54
	v_mul_f32_e32 v51, v64, v51
	v_mul_f32_e32 v54, v65, v54
	v_mul_f32_e32 v51, v51, v56
	v_mul_f32_e32 v54, v54, v57
	v_cvt_pk_bf16_f32 v51, v51, v54
	v_mul_f32_e32 v54, 0xbfb8aa3b, v58
	v_exp_f32_e32 v54, v54
	s_nop 0
	v_add_f32_e32 v54, 1.0, v54
	v_rcp_f32_e32 v54, v54
	s_nop 0
	v_mul_f32_e32 v54, v58, v54
	v_mul_f32_e32 v52, v54, v52
	v_mul_f32_e32 v54, 0xbfb8aa3b, v59
	v_exp_f32_e32 v54, v54
	s_nop 0
	v_add_f32_e32 v54, 1.0, v54
	v_rcp_f32_e32 v54, v54
	s_nop 0
	v_mul_f32_e32 v54, v59, v54
	v_mul_f32_e32 v53, v54, v53
	v_cvt_pk_bf16_f32 v52, v52, v53
	v_mul_f32_e32 v53, 0xbfb8aa3b, v60
	v_mul_f32_e32 v54, 0xbfb8aa3b, v61
	v_exp_f32_e32 v53, v53
	v_exp_f32_e32 v54, v54
	v_add_f32_e32 v53, 1.0, v53
	v_add_f32_e32 v54, 1.0, v54
	v_rcp_f32_e32 v53, v53
	v_rcp_f32_e32 v54, v54
	v_mul_f32_e32 v53, v60, v53
	v_mul_f32_e32 v54, v61, v54
	v_mul_f32_e32 v53, v53, v66
	v_mul_f32_e32 v54, v54, v67
	v_cvt_pk_bf16_f32 v53, v53, v54
	v_mad_i64_i32 v[54:55], s[38:39], v68, s29, v[114:115]
	v_lshl_add_u64 v[54:55], v[54:55], 0, v[116:117]
	global_store_dwordx4 v[54:55], v[50:53], off
	s_nop 1
	v_pk_mul_f32 v[50:51], v[148:149], v[36:37] op_sel_hi:[0,1]
	v_pk_mul_f32 v[36:37], v[148:149], v[34:35] op_sel_hi:[0,1]
	v_mul_f32_e32 v34, 0xbfb8aa3b, v46
	v_mul_f32_e32 v35, 0xbfb8aa3b, v47
	v_exp_f32_e32 v34, v34
	v_exp_f32_e32 v35, v35
	v_add_f32_e32 v34, 1.0, v34
	v_add_f32_e32 v35, 1.0, v35
	v_rcp_f32_e32 v34, v34
	v_rcp_f32_e32 v35, v35
	v_mul_f32_e32 v34, v46, v34
	v_mul_f32_e32 v35, v47, v35
	v_mul_f32_e32 v34, v34, v38
	v_mul_f32_e32 v35, v35, v39
	v_cvt_pk_bf16_f32 v34, v34, v35
	v_mul_f32_e32 v35, 0xbfb8aa3b, v48
	v_mul_f32_e32 v38, 0xbfb8aa3b, v49
	v_exp_f32_e32 v35, v35
	v_exp_f32_e32 v38, v38
	v_add_f32_e32 v35, 1.0, v35
	v_add_f32_e32 v38, 1.0, v38
	v_rcp_f32_e32 v35, v35
	v_rcp_f32_e32 v38, v38
	v_mul_f32_e32 v35, v48, v35
	v_mul_f32_e32 v38, v49, v38
	v_mul_f32_e32 v35, v35, v40
	v_mul_f32_e32 v38, v38, v41
	v_cvt_pk_bf16_f32 v35, v35, v38
	v_mul_f32_e32 v38, 0xbfb8aa3b, v42
	v_exp_f32_e32 v38, v38
	s_nop 0
	v_add_f32_e32 v38, 1.0, v38
	v_rcp_f32_e32 v38, v38
	s_nop 0
	v_mul_f32_e32 v38, v42, v38
	v_mul_f32_e32 v36, v38, v36
	v_mul_f32_e32 v38, 0xbfb8aa3b, v43
; __device__ __forceinline__ unsigned cvt_pk_bf16(float lo, float hi) { unsigned r; asm volatile("v_cvt_pk_bf16_f32 %0, %1, %2" : "=v"(r) : "v"(lo), "v"(hi)); return r; }
; #define PG8_BAR __builtin_amdgcn_s_barrier()
; #define GAS __attribute__((address_space(1)))
; template <class Epi, class Sched, bool ALIGN_EPI = false, bool SP2 = false>
; __device__ __forceinline__ void gemm_phase(PG8_LAS unsigned char* lds, const Gemm g, const Sched& S, const Epi& E) {
;     ...
;         if (!has_next) break;
; #pragma unroll
;         for (int a = 0; a < 2; ++a)
; #pragma unroll
;             for (int b = 0; b < 2; ++b)
; #pragma unroll
;                 for (int m = 0; m < 4; ++m)
; #pragma unroll
;                     for (int n = 0; n < 2; ++n) acc[a][b][m][n] = (f32x4){0.f, 0.f, 0.f, 0.f};
;         cur = nxt; cA = nA; cB = nB; ++ui;
;         if constexpr (Epi::PREFETCH) E.prefetch(cur, wr, fr, epre);
;         if constexpr (ALIGN_EPI) { if (wr == 1) PG8_BAR; }
; __device__ __forceinline__ float silu_mul(float g, float u) { const float e = __builtin_amdgcn_exp2f(-1.4426950408889634f * g); return g * __builtin_amdgcn_rcpf(1.0f + e) * u; }
;     __device__ __forceinline__ void prefetch(const Unit& u, int wr, int fr, float (&pre)[8]) const {
; #pragma unroll
;         for (int i = 0; i < 8; ++i) pre[i] = *(const GAS float*)(rs + u.pm * 256 + wr * 64 + fr + (i >> 2) * 128 + (i & 3) * 16);
;     }
;     __device__ __forceinline__ void operator()(const f32x4 (&acc)[2][2][4][2], const Unit& u, int wr, int wc, int fr, int fq, const float (&pre)[8]) const {
;         const int row0 = u.pm * 256 + wr * 64 + fr, col0 = u.pn * 128 + wc * 32 + 8 * fq;
; #pragma unroll
;         for (int ai = 0; ai < 2; ++ai)
; #pragma unroll
;             for (int m = 0; m < 4; ++m) {
;                 const float rsc = pre[ai * 4 + m];
;                 const f32x4 g0 = acc[ai][0][m][0] * rsc, g1 = acc[ai][0][m][1] * rsc, u0 = acc[ai][1][m][0] * rsc, u1 = acc[ai][1][m][1] * rsc;
;                 u32x4 w; w.x = cvt_pk_bf16(silu_mul(g0[0], u0[0]), silu_mul(g0[1], u0[1])); w.y = cvt_pk_bf16(silu_mul(g0[2], u0[2]), silu_mul(g0[3], u0[3]));
;                 w.z = cvt_pk_bf16(silu_mul(g1[0], u1[0]), silu_mul(g1[1], u1[1])); w.w = cvt_pk_bf16(silu_mul(g1[2], u1[2]), silu_mul(g1[3], u1[3]));
;                 *(GAS u32x4*)(O + (size_t)(row0 + ai * 128 + m * 16) * DFF + col0) = w; }
	v_exp_f32_e32 v38, v38
	s_nop 0
	v_add_f32_e32 v38, 1.0, v38
	v_rcp_f32_e32 v38, v38
	s_nop 0
	v_mul_f32_e32 v38, v43, v38
	v_mul_f32_e32 v37, v38, v37
	v_cvt_pk_bf16_f32 v36, v36, v37
	v_mul_f32_e32 v37, 0xbfb8aa3b, v44
	v_mul_f32_e32 v38, 0xbfb8aa3b, v45
	v_exp_f32_e32 v37, v37
	v_exp_f32_e32 v38, v38
	v_add_f32_e32 v37, 1.0, v37
	v_add_f32_e32 v38, 1.0, v38
	v_rcp_f32_e32 v37, v37
	v_rcp_f32_e32 v38, v38
	v_mul_f32_e32 v37, v44, v37
	v_mul_f32_e32 v38, v45, v38
	v_mul_f32_e32 v37, v37, v50
	v_mul_f32_e32 v38, v38, v51
	v_cvt_pk_bf16_f32 v37, v37, v38
	v_add_u32_e32 v38, 0x90, v151
	v_mad_i64_i32 v[38:39], s[38:39], v38, s29, v[114:115]
	v_lshl_add_u64 v[38:39], v[38:39], 0, v[116:117]
	global_store_dwordx4 v[38:39], v[34:37], off
	s_nop 1
	v_pk_mul_f32 v[34:35], v[146:147], v[18:19] op_sel_hi:[0,1]
	v_pk_mul_f32 v[18:19], v[146:147], v[16:17] op_sel_hi:[0,1]
	v_mul_f32_e32 v16, 0xbfb8aa3b, v28
	v_mul_f32_e32 v17, 0xbfb8aa3b, v29
	v_exp_f32_e32 v16, v16
	v_exp_f32_e32 v17, v17
	v_add_f32_e32 v16, 1.0, v16
	v_add_f32_e32 v17, 1.0, v17
	v_rcp_f32_e32 v16, v16
	v_rcp_f32_e32 v17, v17
	v_mul_f32_e32 v16, v28, v16
	v_mul_f32_e32 v17, v29, v17
	v_mul_f32_e32 v16, v16, v20
	v_mul_f32_e32 v17, v17, v21
	v_cvt_pk_bf16_f32 v16, v16, v17
	v_mul_f32_e32 v17, 0xbfb8aa3b, v30
	v_mul_f32_e32 v20, 0xbfb8aa3b, v31
	v_exp_f32_e32 v17, v17
	v_exp_f32_e32 v20, v20
	v_add_f32_e32 v17, 1.0, v17
	v_add_f32_e32 v20, 1.0, v20
	v_rcp_f32_e32 v17, v17
	v_rcp_f32_e32 v20, v20
	v_mul_f32_e32 v17, v30, v17
	v_mul_f32_e32 v20, v31, v20
	v_mul_f32_e32 v17, v17, v22
	v_mul_f32_e32 v20, v20, v23
	v_cvt_pk_bf16_f32 v17, v17, v20
	v_mul_f32_e32 v20, 0xbfb8aa3b, v24
	v_exp_f32_e32 v20, v20
	s_nop 0
	v_add_f32_e32 v20, 1.0, v20
	v_rcp_f32_e32 v20, v20
	s_nop 0
	v_mul_f32_e32 v20, v24, v20
	v_mul_f32_e32 v18, v20, v18
	v_mul_f32_e32 v20, 0xbfb8aa3b, v25
	v_exp_f32_e32 v20, v20
	s_nop 0
	v_add_f32_e32 v20, 1.0, v20
	v_rcp_f32_e32 v20, v20
	s_nop 0
	v_mul_f32_e32 v20, v25, v20
	v_mul_f32_e32 v19, v20, v19
	v_cvt_pk_bf16_f32 v18, v18, v19
	v_mul_f32_e32 v19, 0xbfb8aa3b, v26
	v_mul_f32_e32 v20, 0xbfb8aa3b, v27
	v_exp_f32_e32 v19, v19
	v_exp_f32_e32 v20, v20
	v_add_f32_e32 v19, 1.0, v19
	v_add_f32_e32 v20, 1.0, v20
	v_rcp_f32_e32 v19, v19
	v_rcp_f32_e32 v20, v20
	v_mul_f32_e32 v19, v26, v19
	v_mul_f32_e32 v20, v27, v20
	v_mul_f32_e32 v19, v19, v34
	v_mul_f32_e32 v20, v20, v35
	v_cvt_pk_bf16_f32 v19, v19, v20
	v_add_u32_e32 v20, 0xa0, v151
	v_mad_i64_i32 v[20:21], s[38:39], v20, s29, v[114:115]
	v_lshl_add_u64 v[20:21], v[20:21], 0, v[116:117]
	global_store_dwordx4 v[20:21], v[16:19], off
	s_nop 1
	v_pk_mul_f32 v[16:17], v[144:145], v[2:3] op_sel_hi:[0,1]
	v_pk_mul_f32 v[2:3], v[144:145], v[0:1] op_sel_hi:[0,1]
	v_mul_f32_e32 v0, 0xbfb8aa3b, v12
	v_mul_f32_e32 v1, 0xbfb8aa3b, v13
	v_exp_f32_e32 v0, v0
	v_exp_f32_e32 v1, v1
	v_add_f32_e32 v0, 1.0, v0
	v_add_f32_e32 v1, 1.0, v1
	v_rcp_f32_e32 v0, v0
	v_rcp_f32_e32 v1, v1
	v_mul_f32_e32 v0, v12, v0
	v_mul_f32_e32 v1, v13, v1
	v_mul_f32_e32 v0, v0, v4
	v_mul_f32_e32 v1, v1, v5
	v_cvt_pk_bf16_f32 v0, v0, v1
	v_mul_f32_e32 v1, 0xbfb8aa3b, v14
	v_mul_f32_e32 v4, 0xbfb8aa3b, v15
	v_exp_f32_e32 v1, v1
	v_exp_f32_e32 v4, v4
	v_add_f32_e32 v1, 1.0, v1
	v_add_f32_e32 v4, 1.0, v4
	v_rcp_f32_e32 v1, v1
	v_rcp_f32_e32 v4, v4
	v_mul_f32_e32 v1, v14, v1
	v_mul_f32_e32 v4, v15, v4
	v_mul_f32_e32 v1, v1, v6
	v_mul_f32_e32 v4, v4, v7
	v_cvt_pk_bf16_f32 v1, v1, v4
	v_mul_f32_e32 v4, 0xbfb8aa3b, v8
	v_exp_f32_e32 v4, v4
	s_nop 0
	v_add_f32_e32 v4, 1.0, v4
	v_rcp_f32_e32 v4, v4
	s_nop 0
	v_mul_f32_e32 v4, v8, v4
	v_mul_f32_e32 v2, v4, v2
	v_mul_f32_e32 v4, 0xbfb8aa3b, v9
	v_exp_f32_e32 v4, v4
	s_nop 0
	v_add_f32_e32 v4, 1.0, v4
	v_rcp_f32_e32 v4, v4
	s_nop 0
	v_mul_f32_e32 v4, v9, v4
	v_mul_f32_e32 v3, v4, v3
	v_cvt_pk_bf16_f32 v2, v2, v3
	v_mul_f32_e32 v3, 0xbfb8aa3b, v10
	v_mul_f32_e32 v4, 0xbfb8aa3b, v11
	v_exp_f32_e32 v3, v3
	v_exp_f32_e32 v4, v4
	v_add_f32_e32 v3, 1.0, v3
	v_add_f32_e32 v4, 1.0, v4
	v_rcp_f32_e32 v3, v3
	v_rcp_f32_e32 v4, v4
	v_mul_f32_e32 v3, v10, v3
	v_mul_f32_e32 v4, v11, v4
	v_mul_f32_e32 v3, v3, v16
	v_mul_f32_e32 v4, v4, v17
	v_cvt_pk_bf16_f32 v3, v3, v4
	v_add_u32_e32 v4, 0xb0, v151
	v_mad_i64_i32 v[4:5], s[38:39], v4, s29, v[114:115]
	v_lshl_add_u64 v[4:5], v[4:5], 0, v[116:117]
	global_store_dwordx4 v[4:5], v[0:3], off
	s_cbranch_vccnz .LBB0_439
	s_lshl_b32 s38, s42, 8
	s_ashr_i32 s39, s38, 31
	v_lshl_add_u64 v[0:1], s[38:39], 2, v[138:139]
	global_load_dword v158, v[0:1], off
	global_load_dword v156, v[0:1], off offset:64
	global_load_dword v154, v[0:1], off offset:128
	global_load_dword v152, v[0:1], off offset:192
	global_load_dword v150, v[0:1], off offset:512
	global_load_dword v148, v[0:1], off offset:576
	global_load_dword v146, v[0:1], off offset:640
	global_load_dword v144, v[0:1], off offset:704
	s_andn2_b64 vcc, exec, s[2:3]
	s_cmp_lg_u32 s2, 0
	s_cselect_b32 s100, 1, 0
	s_branch .LBB0_438

; #define PG8_STAGE(bufoff, gbase, voff) do { _Pragma("unroll") for (int _i = 0; _i < 2; ++_i) \
;         __builtin_amdgcn_global_load_lds((const unsigned*)((const char*)(gbase) + (voff)[_i]), (PG8_LAS unsigned*)(lds + (bufoff) + ldsw + _i * 8192), 16, 0, 0); } while (0)
; #define PG8_LDA(dst, b, h) do { _Pragma("unroll") for (int m = 0; m < 4; ++m) _Pragma("unroll") for (int k = 0; k < 2; ++k) dst[m][k] = *(const PG8_LAS bf16x8*)(lds + PG8_SA(b, h) + aoff + m * 2048 + k * 1024); } while (0)
; #define PG8_LDB(dst, b, h) do { _Pragma("unroll") for (int n = 0; n < 2; ++n) _Pragma("unroll") for (int k = 0; k < 2; ++k) dst[n][k] = *(const PG8_LAS bf16x8*)(lds + PG8_SB(b, h) + boff + n * 2048 + k * 1024); } while (0)
; #define PG8_WAIT_V(n) asm volatile("s_waitcnt vmcnt(" #n ")" ::: "memory")
; #define PG8_WAIT_L(n) asm volatile("s_waitcnt lgkmcnt(" #n ")" ::: "memory")
; #define PG8_BAR __builtin_amdgcn_s_barrier()
; #define PG8_SCHED __builtin_amdgcn_sched_barrier(0)
; template <class Epi, class Sched, bool ALIGN_EPI = false, bool SP2 = false>
; __device__ __forceinline__ void gemm_phase(PG8_LAS unsigned char* lds, const Gemm g, const Sched& S, const Epi& E) {
;     ...
;         for (int t = 0; t < nt; t += 2) {
;             const bool last = (t == nt - 2);
;             const char* a1 = cA + (size_t)(t + 1) * kstep;
;             const char* a2 = last ? nA : cA + (size_t)(t + 2) * kstep; const char* b2 = last ? nB : cB + (size_t)(t + 2) * kstep;
;             const char* a3 = a2 + kstep; const char* b3 = b2 + kstep;
;             if (last && has_next) S.a_ready(nxt);
;             if constexpr (SP2) {
;             PG8_LDB(B0, 0, 0); PG8_LDB(B1, 0, 1); PG8_SCHED; PG8_LDA(At, 0, 0); PG8_STAGE(PG8_SA(1, 1), a1 + hstep, voffA);
;             PG8_WAIT_V(8); PG8_WAIT_L(0); PG8_BAR; PG8_MMA(0, 0, At, B0); PG8_MMA(0, 1, At, B1); PG8_BAR; PG8_SCHED;
;     ...
; #pragma unroll
;         for (int a = 0; a < 2; ++a)
; #pragma unroll
;             for (int b = 0; b < 2; ++b)
; #pragma unroll
;                 for (int m = 0; m < 4; ++m)
; #pragma unroll
;                     for (int n = 0; n < 2; ++n) acc[a][b][m][n] = (f32x4){0.f, 0.f, 0.f, 0.f};
;         cur = nxt; cA = nA; cB = nB; ++ui;
;         if constexpr (Epi::PREFETCH) E.prefetch(cur, wr, fr, epre);
;         if constexpr (ALIGN_EPI) { if (wr == 1) PG8_BAR; }
.LBB0_545:
	s_add_u32 s0, s44, 0x100
	s_addc_u32 s9, s45, 0
	s_add_u32 s44, s46, 0x80
	v_mov_b32_e32 v0, 0
	s_addc_u32 s45, s47, 0
	s_mov_b32 s46, 0
	v_mov_b32_e32 v1, v0
	v_mov_b32_e32 v2, v0
	v_mov_b32_e32 v3, v0
	v_mov_b32_e32 v4, v0
	s_waitcnt lgkmcnt(0)
	v_mov_b32_e32 v5, v0
	v_mov_b32_e32 v6, v0
	v_mov_b32_e32 v7, v0
	v_mov_b32_e32 v16, v0
	v_mov_b32_e32 v17, v0
	v_mov_b32_e32 v18, v0
	v_mov_b32_e32 v19, v0
	v_mov_b32_e32 v20, v0
	v_mov_b32_e32 v21, v0
	v_mov_b32_e32 v22, v0
	v_mov_b32_e32 v23, v0
	v_mov_b32_e32 v34, v0
	v_mov_b32_e32 v35, v0
	v_mov_b32_e32 v36, v0
	v_mov_b32_e32 v37, v0
	v_mov_b32_e32 v38, v0
	v_mov_b32_e32 v39, v0
	v_mov_b32_e32 v40, v0
	v_mov_b32_e32 v41, v0
	v_mov_b32_e32 v50, v0
	v_mov_b32_e32 v51, v0
	v_mov_b32_e32 v52, v0
	v_mov_b32_e32 v53, v0
	v_mov_b32_e32 v54, v0
	v_mov_b32_e32 v55, v0
	v_mov_b32_e32 v56, v0
	v_mov_b32_e32 v57, v0
	v_mov_b32_e32 v8, v0
	v_mov_b32_e32 v9, v0
	v_mov_b32_e32 v10, v0
	v_mov_b32_e32 v11, v0
	v_mov_b32_e32 v12, v0
	v_mov_b32_e32 v13, v0
	v_mov_b32_e32 v14, v0
	v_mov_b32_e32 v15, v0
	v_mov_b32_e32 v24, v0
	v_mov_b32_e32 v25, v0
	v_mov_b32_e32 v26, v0
	v_mov_b32_e32 v27, v0
	v_mov_b32_e32 v28, v0
	v_mov_b32_e32 v29, v0
	v_mov_b32_e32 v30, v0
	v_mov_b32_e32 v31, v0
	v_mov_b32_e32 v42, v0
	v_mov_b32_e32 v43, v0
	v_mov_b32_e32 v44, v0
	v_mov_b32_e32 v45, v0
	v_mov_b32_e32 v46, v0
	v_mov_b32_e32 v47, v0
	v_mov_b32_e32 v48, v0
	v_mov_b32_e32 v49, v0
	v_mov_b32_e32 v58, v0
	v_mov_b32_e32 v59, v0
	v_mov_b32_e32 v60, v0
	v_mov_b32_e32 v61, v0
	v_mov_b32_e32 v62, v0
	v_mov_b32_e32 v63, v0
	v_mov_b32_e32 v64, v0
	v_mov_b32_e32 v65, v0
	v_mov_b32_e32 v66, v0
	v_mov_b32_e32 v67, v0
	v_mov_b32_e32 v68, v0
	v_mov_b32_e32 v69, v0
	v_mov_b32_e32 v70, v0
	v_mov_b32_e32 v71, v0
	v_mov_b32_e32 v72, v0
	v_mov_b32_e32 v73, v0
	v_mov_b32_e32 v82, v0
	v_mov_b32_e32 v83, v0
	v_mov_b32_e32 v84, v0
	v_mov_b32_e32 v85, v0
	v_mov_b32_e32 v86, v0
	v_mov_b32_e32 v87, v0
	v_mov_b32_e32 v88, v0
	v_mov_b32_e32 v89, v0
	v_mov_b32_e32 v98, v0
	v_mov_b32_e32 v99, v0
	v_mov_b32_e32 v100, v0
	v_mov_b32_e32 v101, v0
	v_mov_b32_e32 v102, v0
	v_mov_b32_e32 v103, v0
	v_mov_b32_e32 v104, v0
	v_mov_b32_e32 v105, v0
	v_mov_b32_e32 v114, v0
	v_mov_b32_e32 v115, v0
	v_mov_b32_e32 v116, v0
	v_mov_b32_e32 v117, v0
	v_mov_b32_e32 v118, v0
	v_mov_b32_e32 v119, v0
	v_mov_b32_e32 v120, v0
	v_mov_b32_e32 v121, v0
	v_mov_b32_e32 v74, v0
	v_mov_b32_e32 v75, v0
	v_mov_b32_e32 v76, v0
	v_mov_b32_e32 v77, v0
	v_mov_b32_e32 v78, v0
	v_mov_b32_e32 v79, v0
	v_mov_b32_e32 v80, v0
	v_mov_b32_e32 v81, v0
	v_mov_b32_e32 v90, v0
	v_mov_b32_e32 v91, v0
	v_mov_b32_e32 v92, v0
	v_mov_b32_e32 v93, v0
	v_mov_b32_e32 v94, v0
	v_mov_b32_e32 v95, v0
	v_mov_b32_e32 v96, v0
	v_mov_b32_e32 v97, v0
	v_mov_b32_e32 v106, v0
	v_mov_b32_e32 v107, v0
	v_mov_b32_e32 v108, v0
	v_mov_b32_e32 v109, v0
	v_mov_b32_e32 v110, v0
	v_mov_b32_e32 v111, v0
	v_mov_b32_e32 v112, v0
	v_mov_b32_e32 v113, v0
	v_mov_b32_e32 v122, v0
	v_mov_b32_e32 v123, v0
	v_mov_b32_e32 v124, v0
	v_mov_b32_e32 v125, v0
	v_mov_b32_e32 v126, v0
	v_mov_b32_e32 v127, v0
	v_mov_b32_e32 v128, v0
	v_mov_b32_e32 v129, v0
	s_cmp_eq_u32 s100, 0
	s_cbranch_scc1 .Lrb7_skip
	s_mov_b32 s100, 0
	s_barrier
.Lrb7_skip:
.LBB0_546:
	s_add_i32 s48, s46, 2
	s_add_u32 s49, s44, 0x80
	s_addc_u32 s47, s45, 0
	s_add_i32 s61, 0, 0x10000
	s_cmp_eq_u32 s87, s46
	s_cselect_b32 s47, s43, s47
	s_cselect_b32 s46, s42, s49
	v_add_u32_e32 v149, s61, v146
	s_cselect_b32 s93, s77, s9
	s_cselect_b32 s92, s76, s0
	s_add_i32 s49, 0, 0x14000
	ds_read_b128 v[142:145], v149
	ds_read_b128 v[150:153], v149 offset:1024
	ds_read_b128 v[154:157], v149 offset:2048
	ds_read_b128 v[158:161], v149 offset:3072
	v_add_u32_e32 v149, s49, v146
	ds_read_b128 v[170:173], v149
	ds_read_b128 v[174:177], v149 offset:1024
	ds_read_b128 v[178:181], v149 offset:2048
	ds_read_b128 v[182:185], v149 offset:3072
	v_lshl_add_u64 v[228:229], s[44:45], 0, v[140:141]
	s_add_i32 m0, s78, 0xc000
	ds_read_b128 v[196:199], v148
	ds_read_b128 v[200:203], v148 offset:1024
	ds_read_b128 v[204:207], v148 offset:2048
	ds_read_b128 v[208:211], v148 offset:3072
	ds_read_b128 v[212:215], v148 offset:4096
	ds_read_b128 v[216:219], v148 offset:5120
	ds_read_b128 v[220:223], v148 offset:6144
	ds_read_b128 v[224:227], v148 offset:7168
	global_load_lds_dwordx4 v[228:229], off
	v_lshl_add_u64 v[228:229], s[44:45], 0, v[138:139]
	s_add_i32 m0, s78, 0xe000
	s_nop 0
	global_load_lds_dwordx4 v[228:229], off
	s_waitcnt vmcnt(8)
	s_waitcnt lgkmcnt(0)
	s_barrier
	v_mfma_f32_16x16x32_bf16 v[126:129], v[142:145], v[196:199], v[126:129]
	v_mfma_f32_16x16x32_bf16 v[122:125], v[154:157], v[196:199], v[122:125]
	v_mfma_f32_16x16x32_bf16 v[110:113], v[142:145], v[204:207], v[110:113]
	v_mfma_f32_16x16x32_bf16 v[106:109], v[154:157], v[204:207], v[106:109]
	v_mfma_f32_16x16x32_bf16 v[94:97], v[142:145], v[212:215], v[94:97]
	v_mfma_f32_16x16x32_bf16 v[90:93], v[154:157], v[212:215], v[90:93]
	v_mfma_f32_16x16x32_bf16 v[78:81], v[142:145], v[220:223], v[78:81]
	v_mfma_f32_16x16x32_bf16 v[74:77], v[154:157], v[220:223], v[74:77]
	v_mfma_f32_16x16x32_bf16 v[126:129], v[150:153], v[200:203], v[126:129]
	v_mfma_f32_16x16x32_bf16 v[122:125], v[158:161], v[200:203], v[122:125]
	v_mfma_f32_16x16x32_bf16 v[110:113], v[150:153], v[208:211], v[110:113]
	v_mfma_f32_16x16x32_bf16 v[106:109], v[158:161], v[208:211], v[106:109]
	v_mfma_f32_16x16x32_bf16 v[94:97], v[150:153], v[216:219], v[94:97]
	v_mfma_f32_16x16x32_bf16 v[90:93], v[158:161], v[216:219], v[90:93]
	v_mfma_f32_16x16x32_bf16 v[78:81], v[150:153], v[224:227], v[78:81]
	v_mfma_f32_16x16x32_bf16 v[74:77], v[158:161], v[224:227], v[74:77]
	v_mfma_f32_16x16x32_bf16 v[118:121], v[170:173], v[196:199], v[118:121]
	v_mfma_f32_16x16x32_bf16 v[114:117], v[178:181], v[196:199], v[114:117]
	v_mfma_f32_16x16x32_bf16 v[102:105], v[170:173], v[204:207], v[102:105]
	v_mfma_f32_16x16x32_bf16 v[98:101], v[178:181], v[204:207], v[98:101]
	v_mfma_f32_16x16x32_bf16 v[86:89], v[170:173], v[212:215], v[86:89]
	v_mfma_f32_16x16x32_bf16 v[82:85], v[178:181], v[212:215], v[82:85]
	v_mfma_f32_16x16x32_bf16 v[70:73], v[170:173], v[220:223], v[70:73]
	v_mfma_f32_16x16x32_bf16 v[66:69], v[178:181], v[220:223], v[66:69]
	v_mfma_f32_16x16x32_bf16 v[118:121], v[174:177], v[200:203], v[118:121]
	v_mfma_f32_16x16x32_bf16 v[114:117], v[182:185], v[200:203], v[114:117]
	v_mfma_f32_16x16x32_bf16 v[102:105], v[174:177], v[208:211], v[102:105]
	v_mfma_f32_16x16x32_bf16 v[98:101], v[182:185], v[208:211], v[98:101]
	v_mfma_f32_16x16x32_bf16 v[86:89], v[174:177], v[216:219], v[86:89]
	v_mfma_f32_16x16x32_bf16 v[82:85], v[182:185], v[216:219], v[82:85]
	v_mfma_f32_16x16x32_bf16 v[70:73], v[174:177], v[224:227], v[70:73]
	v_mfma_f32_16x16x32_bf16 v[66:69], v[182:185], v[224:227], v[66:69]
	s_barrier
; #define PG8_STAGE(bufoff, gbase, voff) do { _Pragma("unroll") for (int _i = 0; _i < 2; ++_i) \
;         __builtin_amdgcn_global_load_lds((const unsigned*)((const char*)(gbase) + (voff)[_i]), (PG8_LAS unsigned*)(lds + (bufoff) + ldsw + _i * 8192), 16, 0, 0); } while (0)
; #define PG8_LDA(dst, b, h) do { _Pragma("unroll") for (int m = 0; m < 4; ++m) _Pragma("unroll") for (int k = 0; k < 2; ++k) dst[m][k] = *(const PG8_LAS bf16x8*)(lds + PG8_SA(b, h) + aoff + m * 2048 + k * 1024); } while (0)
; #define PG8_LDB(dst, b, h) do { _Pragma("unroll") for (int n = 0; n < 2; ++n) _Pragma("unroll") for (int k = 0; k < 2; ++k) dst[n][k] = *(const PG8_LAS bf16x8*)(lds + PG8_SB(b, h) + boff + n * 2048 + k * 1024); } while (0)
; #define PG8_MMA(ai, bj, At, Bt) do { __builtin_amdgcn_s_setprio(1); _Pragma("unroll") for (int m = 0; m < 4; ++m) _Pragma("unroll") for (int n = 0; n < 2; ++n) _Pragma("unroll") for (int k = 0; k < 2; ++k) \
;         acc[ai][bj][m][n] = __builtin_amdgcn_mfma_f32_16x16x32_bf16(Bt[n][k], At[m][k], acc[ai][bj][m][n], 0, 0, 0); __builtin_amdgcn_s_setprio(0); } while (0)
; #define PG8_WAIT_V(n) asm volatile("s_waitcnt vmcnt(" #n ")" ::: "memory")
; #define PG8_WAIT_L(n) asm volatile("s_waitcnt lgkmcnt(" #n ")" ::: "memory")
; #define PG8_BAR __builtin_amdgcn_s_barrier()
; #define PG8_SCHED __builtin_amdgcn_sched_barrier(0)
; template <class Epi, class Sched, bool ALIGN_EPI = false, bool SP2 = false>
; __device__ __forceinline__ void gemm_phase(PG8_LAS unsigned char* lds, const Gemm g, const Sched& S, const Epi& E) {
;     ...
;             PG8_WAIT_V(8); PG8_WAIT_L(0); PG8_BAR; PG8_MMA(0, 0, At, B0); PG8_MMA(0, 1, At, B1); PG8_BAR; PG8_SCHED;
;             PG8_LDA(At, 0, 1); PG8_STAGE(PG8_SB(0, 0), b2, voffB); PG8_STAGE(PG8_SB(0, 1), b2 + hstep, voffB); PG8_STAGE(PG8_SA(0, 0), a2, voffA);
;             PG8_WAIT_V(8); PG8_WAIT_L(0); PG8_BAR; PG8_MMA(1, 0, At, B0); PG8_MMA(1, 1, At, B1); PG8_BAR; PG8_SCHED;
;             PG8_LDB(B0, 1, 0); PG8_LDB(B1, 1, 1); PG8_SCHED; PG8_LDA(At, 1, 0); PG8_STAGE(PG8_SA(0, 1), a2 + hstep, voffA);
;             PG8_WAIT_V(8); PG8_WAIT_L(0); PG8_BAR; PG8_MMA(0, 0, At, B0); PG8_MMA(0, 1, At, B1); PG8_BAR; PG8_SCHED;
	s_add_i32 s61, s61, s51
	v_lshl_add_u64 v[228:229], s[92:93], 0, v[132:133]
	s_mov_b32 m0, s61
	ds_read_b128 v[196:199], v148 offset:16384
	ds_read_b128 v[200:203], v148 offset:17408
	ds_read_b128 v[204:207], v148 offset:18432
	ds_read_b128 v[208:211], v148 offset:19456
	ds_read_b128 v[212:215], v148 offset:20480
	ds_read_b128 v[216:219], v148 offset:21504
	ds_read_b128 v[220:223], v148 offset:22528
	ds_read_b128 v[224:227], v148 offset:23552
	global_load_lds_dwordx4 v[228:229], off
	s_add_i32 m0, s61, 0x2000
	v_lshl_add_u64 v[230:231], s[92:93], 0, v[136:137]
	s_add_u32 s92, s92, s8
	s_addc_u32 s93, s93, 0
	s_add_i32 s49, s49, s51
	global_load_lds_dwordx4 v[230:231], off
	v_lshl_add_u64 v[232:233], s[92:93], 0, v[132:133]
	s_mov_b32 m0, s49
	v_lshl_add_u64 v[234:235], s[92:93], 0, v[136:137]
	global_load_lds_dwordx4 v[232:233], off
	s_add_i32 m0, s49, 0x2000
	v_lshl_add_u64 v[236:237], s[46:47], 0, v[130:131]
	global_load_lds_dwordx4 v[234:235], off
	s_mov_b32 m0, s78
	v_lshl_add_u64 v[238:239], s[46:47], 0, v[134:135]
	global_load_lds_dwordx4 v[236:237], off
	s_mov_b32 m0, s79
	s_nop 0
	global_load_lds_dwordx4 v[238:239], off
	s_waitcnt vmcnt(8)
	s_waitcnt lgkmcnt(0)
	s_barrier
	v_mfma_f32_16x16x32_bf16 v[62:65], v[142:145], v[196:199], v[62:65]
	v_mfma_f32_16x16x32_bf16 v[58:61], v[154:157], v[196:199], v[58:61]
	v_mfma_f32_16x16x32_bf16 v[46:49], v[142:145], v[204:207], v[46:49]
	v_mfma_f32_16x16x32_bf16 v[42:45], v[154:157], v[204:207], v[42:45]
	v_mfma_f32_16x16x32_bf16 v[28:31], v[142:145], v[212:215], v[28:31]
	v_mfma_f32_16x16x32_bf16 v[24:27], v[154:157], v[212:215], v[24:27]
	v_mfma_f32_16x16x32_bf16 v[12:15], v[142:145], v[220:223], v[12:15]
	v_mfma_f32_16x16x32_bf16 v[8:11], v[154:157], v[220:223], v[8:11]
	v_mfma_f32_16x16x32_bf16 v[62:65], v[150:153], v[200:203], v[62:65]
	v_mfma_f32_16x16x32_bf16 v[58:61], v[158:161], v[200:203], v[58:61]
	v_mfma_f32_16x16x32_bf16 v[46:49], v[150:153], v[208:211], v[46:49]
	v_mfma_f32_16x16x32_bf16 v[42:45], v[158:161], v[208:211], v[42:45]
	v_mfma_f32_16x16x32_bf16 v[28:31], v[150:153], v[216:219], v[28:31]
	v_mfma_f32_16x16x32_bf16 v[24:27], v[158:161], v[216:219], v[24:27]
	v_mfma_f32_16x16x32_bf16 v[12:15], v[150:153], v[224:227], v[12:15]
	v_mfma_f32_16x16x32_bf16 v[8:11], v[158:161], v[224:227], v[8:11]
	v_mfma_f32_16x16x32_bf16 v[54:57], v[170:173], v[196:199], v[54:57]
	v_mfma_f32_16x16x32_bf16 v[50:53], v[178:181], v[196:199], v[50:53]
	v_mfma_f32_16x16x32_bf16 v[38:41], v[170:173], v[204:207], v[38:41]
	v_mfma_f32_16x16x32_bf16 v[34:37], v[178:181], v[204:207], v[34:37]
	v_mfma_f32_16x16x32_bf16 v[20:23], v[170:173], v[212:215], v[20:23]
	v_mfma_f32_16x16x32_bf16 v[16:19], v[178:181], v[212:215], v[16:19]
	v_mfma_f32_16x16x32_bf16 v[4:7], v[170:173], v[220:223], v[4:7]
	v_mfma_f32_16x16x32_bf16 v[0:3], v[178:181], v[220:223], v[0:3]
	v_mfma_f32_16x16x32_bf16 v[54:57], v[174:177], v[200:203], v[54:57]
	v_mfma_f32_16x16x32_bf16 v[50:53], v[182:185], v[200:203], v[50:53]
	v_mfma_f32_16x16x32_bf16 v[38:41], v[174:177], v[208:211], v[38:41]
	v_mfma_f32_16x16x32_bf16 v[34:37], v[182:185], v[208:211], v[34:37]
	v_mfma_f32_16x16x32_bf16 v[20:23], v[174:177], v[216:219], v[20:23]
	v_mfma_f32_16x16x32_bf16 v[16:19], v[182:185], v[216:219], v[16:19]
	v_mfma_f32_16x16x32_bf16 v[4:7], v[174:177], v[224:227], v[4:7]
	v_mfma_f32_16x16x32_bf16 v[0:3], v[182:185], v[224:227], v[0:3]
	s_barrier
	s_add_i32 s49, 0, 0x18000
	v_add_u32_e32 v149, s49, v146
	s_add_i32 s61, 0, 0x1c000
	ds_read_b128 v[142:145], v149
	ds_read_b128 v[150:153], v149 offset:1024
	ds_read_b128 v[154:157], v149 offset:2048
	ds_read_b128 v[158:161], v149 offset:3072
	v_add_u32_e32 v149, s61, v146
	ds_read_b128 v[170:173], v149
	ds_read_b128 v[174:177], v149 offset:1024
	ds_read_b128 v[178:181], v149 offset:2048
	ds_read_b128 v[182:185], v149 offset:3072
	s_add_u32 s46, s46, s8
	s_addc_u32 s47, s47, 0
	s_mov_b32 m0, s80
	v_lshl_add_u64 v[240:241], s[46:47], 0, v[130:131]
	ds_read_b128 v[196:199], v148 offset:32768
	ds_read_b128 v[200:203], v148 offset:33792
	ds_read_b128 v[204:207], v148 offset:34816
	ds_read_b128 v[208:211], v148 offset:35840
	ds_read_b128 v[212:215], v148 offset:36864
	ds_read_b128 v[216:219], v148 offset:37888
	ds_read_b128 v[220:223], v148 offset:38912
	ds_read_b128 v[224:227], v148 offset:39936
	global_load_lds_dwordx4 v[240:241], off
	v_lshl_add_u64 v[240:241], s[46:47], 0, v[134:135]
	s_mov_b32 m0, s81
	s_nop 0
	global_load_lds_dwordx4 v[240:241], off
	s_waitcnt vmcnt(8)
	s_waitcnt lgkmcnt(0)
	s_barrier
; #define PG8_STAGE(bufoff, gbase, voff) do { _Pragma("unroll") for (int _i = 0; _i < 2; ++_i) \
;         __builtin_amdgcn_global_load_lds((const unsigned*)((const char*)(gbase) + (voff)[_i]), (PG8_LAS unsigned*)(lds + (bufoff) + ldsw + _i * 8192), 16, 0, 0); } while (0)
; #define PG8_WAIT_V(n) asm volatile("s_waitcnt vmcnt(" #n ")" ::: "memory")
; #define PG8_WAIT_L(n) asm volatile("s_waitcnt lgkmcnt(" #n ")" ::: "memory")
; template <class Epi, class Sched, bool ALIGN_EPI = false, bool SP2 = false>
; __device__ __forceinline__ void gemm_phase(PG8_LAS unsigned char* lds, const Gemm g, const Sched& S, const Epi& E) {
;     ...
;             PG8_WAIT_V(8); PG8_WAIT_L(0); PG8_BAR; PG8_MMA(0, 0, At, B0); PG8_MMA(0, 1, At, B1); PG8_BAR; PG8_SCHED;
;             PG8_LDA(At, 1, 1); PG8_STAGE(PG8_SB(1, 0), b3, voffB); PG8_STAGE(PG8_SB(1, 1), b3 + hstep, voffB); PG8_STAGE(PG8_SA(1, 0), a3, voffA);
;             PG8_WAIT_V(8); PG8_WAIT_L(0); PG8_BAR; PG8_MMA(1, 0, At, B0); PG8_MMA(1, 1, At, B1); PG8_BAR; PG8_SCHED;
;             } else {
;             PG8_LDB(B0, 0, 0); PG8_SCHED; PG8_LDA(At, 0, 0); PG8_STAGE(PG8_SA(1, 1), a1 + hstep, voffA);
;             PG8_WAIT_L(8); PG8_BAR; PG8_WAIT_L(0); PG8_MMA(0, 0, At, B0); PG8_BAR; PG8_SCHED;
;             PG8_LDB(B1, 0, 1); PG8_STAGE(PG8_SB(0, 0), b2, voffB);
;             PG8_BAR; PG8_WAIT_L(0); PG8_MMA(0, 1, At, B1); PG8_BAR;
;             PG8_LDA(At, 0, 1); PG8_STAGE(PG8_SA(0, 0), a2, voffA);
;             PG8_BAR; PG8_WAIT_L(0); PG8_MMA(1, 0, At, B0); PG8_BAR; PG8_SCHED;
;             PG8_STAGE(PG8_SB(0, 1), b2 + hstep, voffB);
;             PG8_WAIT_V(6); PG8_BAR; PG8_MMA(1, 1, At, B1); PG8_BAR;
;             PG8_LDB(B0, 1, 0); PG8_SCHED; PG8_LDA(At, 1, 0); PG8_STAGE(PG8_SA(0, 1), a2 + hstep, voffA);
;             PG8_WAIT_L(8); PG8_BAR; PG8_WAIT_L(0); PG8_MMA(0, 0, At, B0); PG8_BAR; PG8_SCHED;
;             PG8_LDB(B1, 1, 1); PG8_STAGE(PG8_SB(1, 0), b3, voffB);
;             PG8_BAR; PG8_WAIT_L(0); PG8_MMA(0, 1, At, B1); PG8_BAR;
;             PG8_LDA(At, 1, 1); PG8_STAGE(PG8_SA(1, 0), a3, voffA);
;             PG8_BAR; PG8_WAIT_L(0); PG8_MMA(1, 0, At, B0); PG8_BAR; PG8_SCHED;
;             PG8_STAGE(PG8_SB(1, 1), b3 + hstep, voffB);
;             PG8_WAIT_V(6); PG8_BAR; PG8_MMA(1, 1, At, B1); PG8_BAR;
;             }
;         }
;         if constexpr (ALIGN_EPI) { if (wr == 0) PG8_BAR; }
	v_mfma_f32_16x16x32_bf16 v[126:129], v[142:145], v[196:199], v[126:129]
	v_mfma_f32_16x16x32_bf16 v[122:125], v[154:157], v[196:199], v[122:125]
	v_mfma_f32_16x16x32_bf16 v[110:113], v[142:145], v[204:207], v[110:113]
	v_mfma_f32_16x16x32_bf16 v[106:109], v[154:157], v[204:207], v[106:109]
	v_mfma_f32_16x16x32_bf16 v[94:97], v[142:145], v[212:215], v[94:97]
	v_mfma_f32_16x16x32_bf16 v[90:93], v[154:157], v[212:215], v[90:93]
	v_mfma_f32_16x16x32_bf16 v[78:81], v[142:145], v[220:223], v[78:81]
	v_mfma_f32_16x16x32_bf16 v[74:77], v[154:157], v[220:223], v[74:77]
	v_mfma_f32_16x16x32_bf16 v[126:129], v[150:153], v[200:203], v[126:129]
	v_mfma_f32_16x16x32_bf16 v[122:125], v[158:161], v[200:203], v[122:125]
	v_mfma_f32_16x16x32_bf16 v[110:113], v[150:153], v[208:211], v[110:113]
	v_mfma_f32_16x16x32_bf16 v[106:109], v[158:161], v[208:211], v[106:109]
	v_mfma_f32_16x16x32_bf16 v[94:97], v[150:153], v[216:219], v[94:97]
	v_mfma_f32_16x16x32_bf16 v[90:93], v[158:161], v[216:219], v[90:93]
	v_mfma_f32_16x16x32_bf16 v[78:81], v[150:153], v[224:227], v[78:81]
	v_mfma_f32_16x16x32_bf16 v[74:77], v[158:161], v[224:227], v[74:77]
	v_mfma_f32_16x16x32_bf16 v[118:121], v[170:173], v[196:199], v[118:121]
	v_mfma_f32_16x16x32_bf16 v[114:117], v[178:181], v[196:199], v[114:117]
	v_mfma_f32_16x16x32_bf16 v[102:105], v[170:173], v[204:207], v[102:105]
	v_mfma_f32_16x16x32_bf16 v[98:101], v[178:181], v[204:207], v[98:101]
	v_mfma_f32_16x16x32_bf16 v[86:89], v[170:173], v[212:215], v[86:89]
	v_mfma_f32_16x16x32_bf16 v[82:85], v[178:181], v[212:215], v[82:85]
	v_mfma_f32_16x16x32_bf16 v[70:73], v[170:173], v[220:223], v[70:73]
	v_mfma_f32_16x16x32_bf16 v[66:69], v[178:181], v[220:223], v[66:69]
	v_mfma_f32_16x16x32_bf16 v[118:121], v[174:177], v[200:203], v[118:121]
	v_mfma_f32_16x16x32_bf16 v[114:117], v[182:185], v[200:203], v[114:117]
	v_mfma_f32_16x16x32_bf16 v[102:105], v[174:177], v[208:211], v[102:105]
	v_mfma_f32_16x16x32_bf16 v[98:101], v[182:185], v[208:211], v[98:101]
	v_mfma_f32_16x16x32_bf16 v[86:89], v[174:177], v[216:219], v[86:89]
	v_mfma_f32_16x16x32_bf16 v[82:85], v[182:185], v[216:219], v[82:85]
	v_mfma_f32_16x16x32_bf16 v[70:73], v[174:177], v[224:227], v[70:73]
	v_mfma_f32_16x16x32_bf16 v[66:69], v[182:185], v[224:227], v[66:69]
	s_barrier
	s_add_i32 s46, s49, s51
	v_lshl_add_u64 v[228:229], v[228:229], 0, s[34:35]
	s_mov_b32 m0, s46
	ds_read_b128 v[196:199], v148 offset:49152
	ds_read_b128 v[200:203], v148 offset:50176
	ds_read_b128 v[204:207], v148 offset:51200
	ds_read_b128 v[208:211], v148 offset:52224
	ds_read_b128 v[212:215], v148 offset:53248
	ds_read_b128 v[216:219], v148 offset:54272
	ds_read_b128 v[220:223], v148 offset:55296
	ds_read_b128 v[224:227], v148 offset:56320
	global_load_lds_dwordx4 v[228:229], off
	v_lshl_add_u64 v[228:229], v[230:231], 0, s[34:35]
	s_add_i32 m0, s46, 0x2000
	s_add_i32 s46, s61, s51
	global_load_lds_dwordx4 v[228:229], off
	v_lshl_add_u64 v[228:229], v[232:233], 0, s[34:35]
	s_mov_b32 m0, s46
	s_nop 0
	global_load_lds_dwordx4 v[228:229], off
	v_lshl_add_u64 v[228:229], v[234:235], 0, s[34:35]
	s_add_i32 m0, s46, 0x2000
	s_nop 0
	global_load_lds_dwordx4 v[228:229], off
	v_lshl_add_u64 v[228:229], v[236:237], 0, s[34:35]
	s_mov_b32 m0, s83
	s_nop 0
	global_load_lds_dwordx4 v[228:229], off
	v_lshl_add_u64 v[228:229], v[238:239], 0, s[34:35]
	s_mov_b32 m0, s84
	s_nop 0
	global_load_lds_dwordx4 v[228:229], off
	s_waitcnt vmcnt(8)
	s_waitcnt lgkmcnt(0)
	s_barrier
	v_mfma_f32_16x16x32_bf16 v[62:65], v[142:145], v[196:199], v[62:65]
	v_mfma_f32_16x16x32_bf16 v[58:61], v[154:157], v[196:199], v[58:61]
	v_mfma_f32_16x16x32_bf16 v[46:49], v[142:145], v[204:207], v[46:49]
	v_mfma_f32_16x16x32_bf16 v[42:45], v[154:157], v[204:207], v[42:45]
	v_mfma_f32_16x16x32_bf16 v[28:31], v[142:145], v[212:215], v[28:31]
	v_mfma_f32_16x16x32_bf16 v[24:27], v[154:157], v[212:215], v[24:27]
	v_mfma_f32_16x16x32_bf16 v[12:15], v[142:145], v[220:223], v[12:15]
	v_mfma_f32_16x16x32_bf16 v[8:11], v[154:157], v[220:223], v[8:11]
	v_mfma_f32_16x16x32_bf16 v[62:65], v[150:153], v[200:203], v[62:65]
	v_mfma_f32_16x16x32_bf16 v[58:61], v[158:161], v[200:203], v[58:61]
	v_mfma_f32_16x16x32_bf16 v[46:49], v[150:153], v[208:211], v[46:49]
	v_mfma_f32_16x16x32_bf16 v[42:45], v[158:161], v[208:211], v[42:45]
	v_mfma_f32_16x16x32_bf16 v[28:31], v[150:153], v[216:219], v[28:31]
	v_mfma_f32_16x16x32_bf16 v[24:27], v[158:161], v[216:219], v[24:27]
	v_mfma_f32_16x16x32_bf16 v[12:15], v[150:153], v[224:227], v[12:15]
	v_mfma_f32_16x16x32_bf16 v[8:11], v[158:161], v[224:227], v[8:11]
	v_mfma_f32_16x16x32_bf16 v[54:57], v[170:173], v[196:199], v[54:57]
	v_mfma_f32_16x16x32_bf16 v[50:53], v[178:181], v[196:199], v[50:53]
	v_mfma_f32_16x16x32_bf16 v[38:41], v[170:173], v[204:207], v[38:41]
	v_mfma_f32_16x16x32_bf16 v[34:37], v[178:181], v[204:207], v[34:37]
	v_mfma_f32_16x16x32_bf16 v[20:23], v[170:173], v[212:215], v[20:23]
	v_mfma_f32_16x16x32_bf16 v[16:19], v[178:181], v[212:215], v[16:19]
	v_mfma_f32_16x16x32_bf16 v[4:7], v[170:173], v[220:223], v[4:7]
	v_mfma_f32_16x16x32_bf16 v[0:3], v[178:181], v[220:223], v[0:3]
	v_mfma_f32_16x16x32_bf16 v[54:57], v[174:177], v[200:203], v[54:57]
	v_mfma_f32_16x16x32_bf16 v[50:53], v[182:185], v[200:203], v[50:53]
	v_mfma_f32_16x16x32_bf16 v[38:41], v[174:177], v[208:211], v[38:41]
	v_mfma_f32_16x16x32_bf16 v[34:37], v[182:185], v[208:211], v[34:37]
	v_mfma_f32_16x16x32_bf16 v[20:23], v[174:177], v[216:219], v[20:23]
	v_mfma_f32_16x16x32_bf16 v[16:19], v[182:185], v[216:219], v[16:19]
	v_mfma_f32_16x16x32_bf16 v[4:7], v[174:177], v[224:227], v[4:7]
	v_mfma_f32_16x16x32_bf16 v[0:3], v[182:185], v[224:227], v[0:3]
	s_barrier
	s_add_u32 s0, s0, 0x100
	s_addc_u32 s9, s9, 0
	s_add_u32 s44, s44, 0x100
	s_addc_u32 s45, s45, 0
	s_cmp_ge_u32 s48, s85
	s_mov_b32 s46, s48
	s_cbranch_scc0 .LBB0_546
	s_and_b64 vcc, exec, s[40:41]
	s_cbranch_vccz .LBB0_549
	s_barrier

; #define PG8_STAGE(bufoff, gbase, voff) do { _Pragma("unroll") for (int _i = 0; _i < 2; ++_i) \
;         __builtin_amdgcn_global_load_lds((const unsigned*)((const char*)(gbase) + (voff)[_i]), (PG8_LAS unsigned*)(lds + (bufoff) + ldsw + _i * 8192), 16, 0, 0); } while (0)
; #define PG8_LDA(dst, b, h) do { _Pragma("unroll") for (int m = 0; m < 4; ++m) _Pragma("unroll") for (int k = 0; k < 2; ++k) dst[m][k] = *(const PG8_LAS bf16x8*)(lds + PG8_SA(b, h) + aoff + m * 2048 + k * 1024); } while (0)
; #define PG8_LDB(dst, b, h) do { _Pragma("unroll") for (int n = 0; n < 2; ++n) _Pragma("unroll") for (int k = 0; k < 2; ++k) dst[n][k] = *(const PG8_LAS bf16x8*)(lds + PG8_SB(b, h) + boff + n * 2048 + k * 1024); } while (0)
; #define PG8_WAIT_V(n) asm volatile("s_waitcnt vmcnt(" #n ")" ::: "memory")
; #define PG8_WAIT_L(n) asm volatile("s_waitcnt lgkmcnt(" #n ")" ::: "memory")
; #define PG8_BAR __builtin_amdgcn_s_barrier()
; #define PG8_SCHED __builtin_amdgcn_sched_barrier(0)
; template <class Epi, class Sched, bool ALIGN_EPI = false, bool SP2 = false>
; __device__ __forceinline__ void gemm_phase(PG8_LAS unsigned char* lds, const Gemm g, const Sched& S, const Epi& E) {
;     ...
;         const bool has_next = S.next(ui + 1, nxt);
;         const char* nA = has_next ? (const char*)g.A + (size_t)nxt.pm * tstep : cA; const char* nB = has_next ? (const char*)g.Bt + (size_t)nxt.pn * tstep : cB;
;         for (int t = 0; t < nt; t += 2) {
;             const bool last = (t == nt - 2);
;             const char* a1 = cA + (size_t)(t + 1) * kstep;
;             const char* a2 = last ? nA : cA + (size_t)(t + 2) * kstep; const char* b2 = last ? nB : cB + (size_t)(t + 2) * kstep;
;             const char* a3 = a2 + kstep; const char* b3 = b2 + kstep;
;             if (last && has_next) S.a_ready(nxt);
;             if constexpr (SP2) {
;             PG8_LDB(B0, 0, 0); PG8_LDB(B1, 0, 1); PG8_SCHED; PG8_LDA(At, 0, 0); PG8_STAGE(PG8_SA(1, 1), a1 + hstep, voffA);
;             PG8_WAIT_V(8); PG8_WAIT_L(0); PG8_BAR; PG8_MMA(0, 0, At, B0); PG8_MMA(0, 1, At, B1); PG8_BAR; PG8_SCHED;
;     ...
; #pragma unroll
;         for (int a = 0; a < 2; ++a)
; #pragma unroll
;             for (int b = 0; b < 2; ++b)
; #pragma unroll
;                 for (int m = 0; m < 4; ++m)
; #pragma unroll
;                     for (int n = 0; n < 2; ++n) acc[a][b][m][n] = (f32x4){0.f, 0.f, 0.f, 0.f};
.LBB0_579:
	s_ashr_i32 s9, s8, 31
	s_lshl_b64 s[38:39], s[8:9], 19
	s_add_u32 s38, s62, s38
	s_addc_u32 s39, s63, s39
	s_and_b64 s[40:41], s[42:43], exec
	s_cselect_b32 s9, s39, s49
	s_cselect_b32 s66, s38, s48
	s_ashr_i32 s7, s6, 31
	s_lshl_b64 s[40:41], s[6:7], 19
	s_add_u32 s40, s61, s40
	s_addc_u32 s41, s68, s41
	s_and_b64 s[50:51], s[42:43], exec
	s_cselect_b32 s7, s41, s47
	s_cselect_b32 s67, s40, s46
	s_add_u32 s79, s46, 0x100
	s_addc_u32 s80, s47, 0
	s_add_u32 s46, s48, 0x40080
	v_mov_b32_e32 v0, 0
	s_addc_u32 s47, s49, 0
	s_mov_b32 s81, -2
	v_mov_b32_e32 v1, v0
	v_mov_b32_e32 v2, v0
	v_mov_b32_e32 v3, v0
	v_mov_b32_e32 v4, v0
	v_mov_b32_e32 v5, v0
	v_mov_b32_e32 v6, v0
	v_mov_b32_e32 v7, v0
	v_mov_b32_e32 v16, v0
	v_mov_b32_e32 v17, v0
	v_mov_b32_e32 v18, v0
	v_mov_b32_e32 v19, v0
	v_mov_b32_e32 v20, v0
	v_mov_b32_e32 v21, v0
	v_mov_b32_e32 v22, v0
	v_mov_b32_e32 v23, v0
	v_mov_b32_e32 v34, v0
	v_mov_b32_e32 v35, v0
	v_mov_b32_e32 v36, v0
	v_mov_b32_e32 v37, v0
	v_mov_b32_e32 v38, v0
	v_mov_b32_e32 v39, v0
	v_mov_b32_e32 v40, v0
	v_mov_b32_e32 v41, v0
	v_mov_b32_e32 v50, v0
	v_mov_b32_e32 v51, v0
	v_mov_b32_e32 v52, v0
	v_mov_b32_e32 v53, v0
	v_mov_b32_e32 v54, v0
	v_mov_b32_e32 v55, v0
	v_mov_b32_e32 v56, v0
	v_mov_b32_e32 v57, v0
	v_mov_b32_e32 v8, v0
	v_mov_b32_e32 v9, v0
	v_mov_b32_e32 v10, v0
	v_mov_b32_e32 v11, v0
	v_mov_b32_e32 v12, v0
	v_mov_b32_e32 v13, v0
	v_mov_b32_e32 v14, v0
	v_mov_b32_e32 v15, v0
	v_mov_b32_e32 v24, v0
	v_mov_b32_e32 v25, v0
	v_mov_b32_e32 v26, v0
	v_mov_b32_e32 v27, v0
	v_mov_b32_e32 v28, v0
	v_mov_b32_e32 v29, v0
	v_mov_b32_e32 v30, v0
	v_mov_b32_e32 v31, v0
	v_mov_b32_e32 v42, v0
	v_mov_b32_e32 v43, v0
	v_mov_b32_e32 v44, v0
	v_mov_b32_e32 v45, v0
	v_mov_b32_e32 v46, v0
	v_mov_b32_e32 v47, v0
	v_mov_b32_e32 v48, v0
	v_mov_b32_e32 v49, v0
	v_mov_b32_e32 v58, v0
	v_mov_b32_e32 v59, v0
	v_mov_b32_e32 v60, v0
	v_mov_b32_e32 v61, v0
	v_mov_b32_e32 v62, v0
	v_mov_b32_e32 v63, v0
	v_mov_b32_e32 v64, v0
	v_mov_b32_e32 v65, v0
	v_mov_b32_e32 v66, v0
	v_mov_b32_e32 v67, v0
	v_mov_b32_e32 v68, v0
	v_mov_b32_e32 v69, v0
	v_mov_b32_e32 v70, v0
	v_mov_b32_e32 v71, v0
	v_mov_b32_e32 v72, v0
	v_mov_b32_e32 v73, v0
	v_mov_b32_e32 v82, v0
	v_mov_b32_e32 v83, v0
	v_mov_b32_e32 v84, v0
	v_mov_b32_e32 v85, v0
	v_mov_b32_e32 v86, v0
	v_mov_b32_e32 v87, v0
	v_mov_b32_e32 v88, v0
	v_mov_b32_e32 v89, v0
	v_mov_b32_e32 v98, v0
	v_mov_b32_e32 v99, v0
	v_mov_b32_e32 v100, v0
	v_mov_b32_e32 v101, v0
	v_mov_b32_e32 v102, v0
	v_mov_b32_e32 v103, v0
	v_mov_b32_e32 v104, v0
	v_mov_b32_e32 v105, v0
	v_mov_b32_e32 v114, v0
	v_mov_b32_e32 v115, v0
	v_mov_b32_e32 v116, v0
	v_mov_b32_e32 v117, v0
	v_mov_b32_e32 v118, v0
	v_mov_b32_e32 v119, v0
	v_mov_b32_e32 v120, v0
	v_mov_b32_e32 v121, v0
	v_mov_b32_e32 v74, v0
	v_mov_b32_e32 v75, v0
	v_mov_b32_e32 v76, v0
	v_mov_b32_e32 v77, v0
	v_mov_b32_e32 v78, v0
	v_mov_b32_e32 v79, v0
	v_mov_b32_e32 v80, v0
	v_mov_b32_e32 v81, v0
	v_mov_b32_e32 v90, v0
	v_mov_b32_e32 v91, v0
	v_mov_b32_e32 v92, v0
	v_mov_b32_e32 v93, v0
	v_mov_b32_e32 v94, v0
	v_mov_b32_e32 v95, v0
	v_mov_b32_e32 v96, v0
	v_mov_b32_e32 v97, v0
	v_mov_b32_e32 v106, v0
	v_mov_b32_e32 v107, v0
	v_mov_b32_e32 v108, v0
	v_mov_b32_e32 v109, v0
	v_mov_b32_e32 v110, v0
	v_mov_b32_e32 v111, v0
	v_mov_b32_e32 v112, v0
	v_mov_b32_e32 v113, v0
	v_mov_b32_e32 v122, v0
	v_mov_b32_e32 v123, v0
	v_mov_b32_e32 v124, v0
	v_mov_b32_e32 v125, v0
	v_mov_b32_e32 v126, v0
	v_mov_b32_e32 v127, v0
	v_mov_b32_e32 v128, v0
	v_mov_b32_e32 v129, v0
	s_cmp_eq_u32 s100, 0
	s_cbranch_scc1 .Lrb8_skip
	s_mov_b32 s100, 0
	s_barrier
.Lrb8_skip:
.LBB0_580:
	s_add_u32 s48, s46, 0xfffc0080
	s_addc_u32 s49, s47, -1
	s_add_i32 s82, 0, 0x10000
	s_cmp_eq_u32 s81, 12
	s_cselect_b32 s51, s9, s49
	s_cselect_b32 s50, s66, s48
	v_add_u32_e32 v151, s82, v145
	s_cselect_b32 s49, s7, s80
	s_cselect_b32 s48, s67, s79
	s_add_i32 s84, 0, 0x14000
	ds_read_b128 v[170:173], v151
	ds_read_b128 v[174:177], v151 offset:1024
	ds_read_b128 v[178:181], v151 offset:2048
	ds_read_b128 v[182:185], v151 offset:3072
	v_add_u32_e32 v151, s84, v145
	ds_read_b128 v[196:199], v151
	ds_read_b128 v[200:203], v151 offset:1024
	ds_read_b128 v[204:207], v151 offset:2048
	ds_read_b128 v[208:211], v151 offset:3072
	v_lshl_add_u64 v[160:161], s[46:47], 0, v[142:143]
	s_add_i32 m0, s71, 0xc000
	ds_read_b128 v[212:215], v149
	ds_read_b128 v[216:219], v149 offset:1024
	ds_read_b128 v[220:223], v149 offset:2048
	ds_read_b128 v[224:227], v149 offset:3072
	ds_read_b128 v[228:231], v149 offset:4096
	ds_read_b128 v[232:235], v149 offset:5120
	ds_read_b128 v[236:239], v149 offset:6144
	ds_read_b128 v[240:243], v149 offset:7168
	global_load_lds_dwordx4 v[160:161], off
	v_lshl_add_u64 v[160:161], s[46:47], 0, v[140:141]
	s_add_i32 m0, s71, 0xe000
	s_nop 0
	global_load_lds_dwordx4 v[160:161], off
	s_waitcnt vmcnt(8)
	s_waitcnt lgkmcnt(0)
	s_barrier
; #define PG8_STAGE(bufoff, gbase, voff) do { _Pragma("unroll") for (int _i = 0; _i < 2; ++_i) \
;         __builtin_amdgcn_global_load_lds((const unsigned*)((const char*)(gbase) + (voff)[_i]), (PG8_LAS unsigned*)(lds + (bufoff) + ldsw + _i * 8192), 16, 0, 0); } while (0)
; #define PG8_LDA(dst, b, h) do { _Pragma("unroll") for (int m = 0; m < 4; ++m) _Pragma("unroll") for (int k = 0; k < 2; ++k) dst[m][k] = *(const PG8_LAS bf16x8*)(lds + PG8_SA(b, h) + aoff + m * 2048 + k * 1024); } while (0)
; #define PG8_MMA(ai, bj, At, Bt) do { __builtin_amdgcn_s_setprio(1); _Pragma("unroll") for (int m = 0; m < 4; ++m) _Pragma("unroll") for (int n = 0; n < 2; ++n) _Pragma("unroll") for (int k = 0; k < 2; ++k) \
;         acc[ai][bj][m][n] = __builtin_amdgcn_mfma_f32_16x16x32_bf16(Bt[n][k], At[m][k], acc[ai][bj][m][n], 0, 0, 0); __builtin_amdgcn_s_setprio(0); } while (0)
; #define PG8_WAIT_V(n) asm volatile("s_waitcnt vmcnt(" #n ")" ::: "memory")
; #define PG8_WAIT_L(n) asm volatile("s_waitcnt lgkmcnt(" #n ")" ::: "memory")
; #define PG8_BAR __builtin_amdgcn_s_barrier()
; #define PG8_SCHED __builtin_amdgcn_sched_barrier(0)
; template <class Epi, class Sched, bool ALIGN_EPI = false, bool SP2 = false>
; __device__ __forceinline__ void gemm_phase(PG8_LAS unsigned char* lds, const Gemm g, const Sched& S, const Epi& E) {
;     ...
;             PG8_WAIT_V(8); PG8_WAIT_L(0); PG8_BAR; PG8_MMA(0, 0, At, B0); PG8_MMA(0, 1, At, B1); PG8_BAR; PG8_SCHED;
;             PG8_LDA(At, 0, 1); PG8_STAGE(PG8_SB(0, 0), b2, voffB); PG8_STAGE(PG8_SB(0, 1), b2 + hstep, voffB); PG8_STAGE(PG8_SA(0, 0), a2, voffA);
;             PG8_WAIT_V(8); PG8_WAIT_L(0); PG8_BAR; PG8_MMA(1, 0, At, B0); PG8_MMA(1, 1, At, B1); PG8_BAR; PG8_SCHED;
	v_mfma_f32_16x16x32_bf16 v[126:129], v[170:173], v[212:215], v[126:129]
	v_mfma_f32_16x16x32_bf16 v[122:125], v[178:181], v[212:215], v[122:125]
	v_mfma_f32_16x16x32_bf16 v[110:113], v[170:173], v[220:223], v[110:113]
	v_mfma_f32_16x16x32_bf16 v[106:109], v[178:181], v[220:223], v[106:109]
	v_mfma_f32_16x16x32_bf16 v[94:97], v[170:173], v[228:231], v[94:97]
	v_mfma_f32_16x16x32_bf16 v[90:93], v[178:181], v[228:231], v[90:93]
	v_mfma_f32_16x16x32_bf16 v[78:81], v[170:173], v[236:239], v[78:81]
	v_mfma_f32_16x16x32_bf16 v[74:77], v[178:181], v[236:239], v[74:77]
	v_mfma_f32_16x16x32_bf16 v[126:129], v[174:177], v[216:219], v[126:129]
	v_mfma_f32_16x16x32_bf16 v[122:125], v[182:185], v[216:219], v[122:125]
	v_mfma_f32_16x16x32_bf16 v[110:113], v[174:177], v[224:227], v[110:113]
	v_mfma_f32_16x16x32_bf16 v[106:109], v[182:185], v[224:227], v[106:109]
	v_mfma_f32_16x16x32_bf16 v[94:97], v[174:177], v[232:235], v[94:97]
	v_mfma_f32_16x16x32_bf16 v[90:93], v[182:185], v[232:235], v[90:93]
	v_mfma_f32_16x16x32_bf16 v[78:81], v[174:177], v[240:243], v[78:81]
	v_mfma_f32_16x16x32_bf16 v[74:77], v[182:185], v[240:243], v[74:77]
	v_mfma_f32_16x16x32_bf16 v[118:121], v[196:199], v[212:215], v[118:121]
	v_mfma_f32_16x16x32_bf16 v[114:117], v[204:207], v[212:215], v[114:117]
	v_mfma_f32_16x16x32_bf16 v[102:105], v[196:199], v[220:223], v[102:105]
	v_mfma_f32_16x16x32_bf16 v[98:101], v[204:207], v[220:223], v[98:101]
	v_mfma_f32_16x16x32_bf16 v[86:89], v[196:199], v[228:231], v[86:89]
	v_mfma_f32_16x16x32_bf16 v[82:85], v[204:207], v[228:231], v[82:85]
	v_mfma_f32_16x16x32_bf16 v[70:73], v[196:199], v[236:239], v[70:73]
	v_mfma_f32_16x16x32_bf16 v[66:69], v[204:207], v[236:239], v[66:69]
	v_mfma_f32_16x16x32_bf16 v[118:121], v[200:203], v[216:219], v[118:121]
	v_mfma_f32_16x16x32_bf16 v[114:117], v[208:211], v[216:219], v[114:117]
	v_mfma_f32_16x16x32_bf16 v[102:105], v[200:203], v[224:227], v[102:105]
	v_mfma_f32_16x16x32_bf16 v[98:101], v[208:211], v[224:227], v[98:101]
	v_mfma_f32_16x16x32_bf16 v[86:89], v[200:203], v[232:235], v[86:89]
	v_mfma_f32_16x16x32_bf16 v[82:85], v[208:211], v[232:235], v[82:85]
	v_mfma_f32_16x16x32_bf16 v[70:73], v[200:203], v[240:243], v[70:73]
	v_mfma_f32_16x16x32_bf16 v[66:69], v[208:211], v[240:243], v[66:69]
	s_barrier
	s_add_i32 s82, s82, s69
	v_lshl_add_u64 v[160:161], s[48:49], 0, v[134:135]
	s_mov_b32 m0, s82
	ds_read_b128 v[212:215], v149 offset:16384
	ds_read_b128 v[216:219], v149 offset:17408
	ds_read_b128 v[220:223], v149 offset:18432
	ds_read_b128 v[224:227], v149 offset:19456
	ds_read_b128 v[228:231], v149 offset:20480
	ds_read_b128 v[232:235], v149 offset:21504
	ds_read_b128 v[236:239], v149 offset:22528
	ds_read_b128 v[240:243], v149 offset:23552
	global_load_lds_dwordx4 v[160:161], off
	s_add_i32 m0, s82, 0x2000
	s_add_u32 s82, s48, 0x40000
	v_lshl_add_u64 v[244:245], s[48:49], 0, v[130:131]
	s_addc_u32 s83, s49, 0
	s_add_i32 s84, s84, s69
	global_load_lds_dwordx4 v[244:245], off
	v_lshl_add_u64 v[246:247], s[82:83], 0, v[134:135]
	s_mov_b32 m0, s84
	v_lshl_add_u64 v[248:249], s[50:51], 0, v[132:133]
	global_load_lds_dwordx4 v[246:247], off
	v_lshl_add_u64 v[246:247], s[82:83], 0, v[130:131]
	s_add_i32 m0, s84, 0x2000
	s_nop 0
	global_load_lds_dwordx4 v[246:247], off
	v_lshl_add_u64 v[246:247], s[50:51], 0, v[136:137]
	s_mov_b32 m0, s71
	s_nop 0
	global_load_lds_dwordx4 v[246:247], off
	s_mov_b32 m0, s72
	s_nop 0
	global_load_lds_dwordx4 v[248:249], off
	s_waitcnt vmcnt(8)
	s_waitcnt lgkmcnt(0)
	s_barrier
	v_mfma_f32_16x16x32_bf16 v[62:65], v[170:173], v[212:215], v[62:65]
	v_mfma_f32_16x16x32_bf16 v[58:61], v[178:181], v[212:215], v[58:61]
	v_mfma_f32_16x16x32_bf16 v[46:49], v[170:173], v[220:223], v[46:49]
	v_mfma_f32_16x16x32_bf16 v[42:45], v[178:181], v[220:223], v[42:45]
	v_mfma_f32_16x16x32_bf16 v[28:31], v[170:173], v[228:231], v[28:31]
	v_mfma_f32_16x16x32_bf16 v[24:27], v[178:181], v[228:231], v[24:27]
	v_mfma_f32_16x16x32_bf16 v[12:15], v[170:173], v[236:239], v[12:15]
	v_mfma_f32_16x16x32_bf16 v[8:11], v[178:181], v[236:239], v[8:11]
	v_mfma_f32_16x16x32_bf16 v[62:65], v[174:177], v[216:219], v[62:65]
	v_mfma_f32_16x16x32_bf16 v[58:61], v[182:185], v[216:219], v[58:61]
	v_mfma_f32_16x16x32_bf16 v[46:49], v[174:177], v[224:227], v[46:49]
	v_mfma_f32_16x16x32_bf16 v[42:45], v[182:185], v[224:227], v[42:45]
	v_mfma_f32_16x16x32_bf16 v[28:31], v[174:177], v[232:235], v[28:31]
	v_mfma_f32_16x16x32_bf16 v[24:27], v[182:185], v[232:235], v[24:27]
	v_mfma_f32_16x16x32_bf16 v[12:15], v[174:177], v[240:243], v[12:15]
	v_mfma_f32_16x16x32_bf16 v[8:11], v[182:185], v[240:243], v[8:11]
	v_mfma_f32_16x16x32_bf16 v[54:57], v[196:199], v[212:215], v[54:57]
	v_mfma_f32_16x16x32_bf16 v[50:53], v[204:207], v[212:215], v[50:53]
	v_mfma_f32_16x16x32_bf16 v[38:41], v[196:199], v[220:223], v[38:41]
	v_mfma_f32_16x16x32_bf16 v[34:37], v[204:207], v[220:223], v[34:37]
	v_mfma_f32_16x16x32_bf16 v[20:23], v[196:199], v[228:231], v[20:23]
	v_mfma_f32_16x16x32_bf16 v[16:19], v[204:207], v[228:231], v[16:19]
	v_mfma_f32_16x16x32_bf16 v[4:7], v[196:199], v[236:239], v[4:7]
	v_mfma_f32_16x16x32_bf16 v[0:3], v[204:207], v[236:239], v[0:3]
	v_mfma_f32_16x16x32_bf16 v[54:57], v[200:203], v[216:219], v[54:57]
	v_mfma_f32_16x16x32_bf16 v[50:53], v[208:211], v[216:219], v[50:53]
	v_mfma_f32_16x16x32_bf16 v[38:41], v[200:203], v[224:227], v[38:41]
	v_mfma_f32_16x16x32_bf16 v[34:37], v[208:211], v[224:227], v[34:37]
	v_mfma_f32_16x16x32_bf16 v[20:23], v[200:203], v[232:235], v[20:23]
	v_mfma_f32_16x16x32_bf16 v[16:19], v[208:211], v[232:235], v[16:19]
	v_mfma_f32_16x16x32_bf16 v[4:7], v[200:203], v[240:243], v[4:7]
	v_mfma_f32_16x16x32_bf16 v[0:3], v[208:211], v[240:243], v[0:3]
	s_barrier
; #define PG8_STAGE(bufoff, gbase, voff) do { _Pragma("unroll") for (int _i = 0; _i < 2; ++_i) \
;         __builtin_amdgcn_global_load_lds((const unsigned*)((const char*)(gbase) + (voff)[_i]), (PG8_LAS unsigned*)(lds + (bufoff) + ldsw + _i * 8192), 16, 0, 0); } while (0)
; #define PG8_LDA(dst, b, h) do { _Pragma("unroll") for (int m = 0; m < 4; ++m) _Pragma("unroll") for (int k = 0; k < 2; ++k) dst[m][k] = *(const PG8_LAS bf16x8*)(lds + PG8_SA(b, h) + aoff + m * 2048 + k * 1024); } while (0)
; #define PG8_LDB(dst, b, h) do { _Pragma("unroll") for (int n = 0; n < 2; ++n) _Pragma("unroll") for (int k = 0; k < 2; ++k) dst[n][k] = *(const PG8_LAS bf16x8*)(lds + PG8_SB(b, h) + boff + n * 2048 + k * 1024); } while (0)
; #define PG8_MMA(ai, bj, At, Bt) do { __builtin_amdgcn_s_setprio(1); _Pragma("unroll") for (int m = 0; m < 4; ++m) _Pragma("unroll") for (int n = 0; n < 2; ++n) _Pragma("unroll") for (int k = 0; k < 2; ++k) \
;         acc[ai][bj][m][n] = __builtin_amdgcn_mfma_f32_16x16x32_bf16(Bt[n][k], At[m][k], acc[ai][bj][m][n], 0, 0, 0); __builtin_amdgcn_s_setprio(0); } while (0)
; #define PG8_WAIT_V(n) asm volatile("s_waitcnt vmcnt(" #n ")" ::: "memory")
; #define PG8_WAIT_L(n) asm volatile("s_waitcnt lgkmcnt(" #n ")" ::: "memory")
; #define PG8_BAR __builtin_amdgcn_s_barrier()
; #define PG8_SCHED __builtin_amdgcn_sched_barrier(0)
; template <class Epi, class Sched, bool ALIGN_EPI = false, bool SP2 = false>
; __device__ __forceinline__ void gemm_phase(PG8_LAS unsigned char* lds, const Gemm g, const Sched& S, const Epi& E) {
;     ...
;             PG8_WAIT_V(8); PG8_WAIT_L(0); PG8_BAR; PG8_MMA(1, 0, At, B0); PG8_MMA(1, 1, At, B1); PG8_BAR; PG8_SCHED;
;             PG8_LDB(B0, 1, 0); PG8_LDB(B1, 1, 1); PG8_SCHED; PG8_LDA(At, 1, 0); PG8_STAGE(PG8_SA(0, 1), a2 + hstep, voffA);
;             PG8_WAIT_V(8); PG8_WAIT_L(0); PG8_BAR; PG8_MMA(0, 0, At, B0); PG8_MMA(0, 1, At, B1); PG8_BAR; PG8_SCHED;
	s_add_i32 s82, 0, 0x18000
	v_add_u32_e32 v151, s82, v145
	s_add_i32 s83, 0, 0x1c000
	ds_read_b128 v[170:173], v151
	ds_read_b128 v[174:177], v151 offset:1024
	ds_read_b128 v[178:181], v151 offset:2048
	ds_read_b128 v[182:185], v151 offset:3072
	v_add_u32_e32 v151, s83, v145
	ds_read_b128 v[196:199], v151
	ds_read_b128 v[200:203], v151 offset:1024
	ds_read_b128 v[204:207], v151 offset:2048
	ds_read_b128 v[208:211], v151 offset:3072
	s_add_u32 s50, s50, 0x40000
	s_addc_u32 s51, s51, 0
	s_mov_b32 m0, s73
	v_lshl_add_u64 v[250:251], s[50:51], 0, v[136:137]
	ds_read_b128 v[212:215], v149 offset:32768
	ds_read_b128 v[216:219], v149 offset:33792
	ds_read_b128 v[220:223], v149 offset:34816
	ds_read_b128 v[224:227], v149 offset:35840
	ds_read_b128 v[228:231], v149 offset:36864
	ds_read_b128 v[232:235], v149 offset:37888
	ds_read_b128 v[236:239], v149 offset:38912
	ds_read_b128 v[240:243], v149 offset:39936
	global_load_lds_dwordx4 v[250:251], off
	v_lshl_add_u64 v[250:251], s[50:51], 0, v[132:133]
	s_mov_b32 m0, s76
	s_nop 0
	global_load_lds_dwordx4 v[250:251], off
	s_waitcnt vmcnt(8)
	s_waitcnt lgkmcnt(0)
	s_barrier
	v_mfma_f32_16x16x32_bf16 v[126:129], v[170:173], v[212:215], v[126:129]
	v_mfma_f32_16x16x32_bf16 v[122:125], v[178:181], v[212:215], v[122:125]
	v_mfma_f32_16x16x32_bf16 v[110:113], v[170:173], v[220:223], v[110:113]
	v_mfma_f32_16x16x32_bf16 v[106:109], v[178:181], v[220:223], v[106:109]
	v_mfma_f32_16x16x32_bf16 v[94:97], v[170:173], v[228:231], v[94:97]
	v_mfma_f32_16x16x32_bf16 v[90:93], v[178:181], v[228:231], v[90:93]
	v_mfma_f32_16x16x32_bf16 v[78:81], v[170:173], v[236:239], v[78:81]
	v_mfma_f32_16x16x32_bf16 v[74:77], v[178:181], v[236:239], v[74:77]
	v_mfma_f32_16x16x32_bf16 v[126:129], v[174:177], v[216:219], v[126:129]
	v_mfma_f32_16x16x32_bf16 v[122:125], v[182:185], v[216:219], v[122:125]
	v_mfma_f32_16x16x32_bf16 v[110:113], v[174:177], v[224:227], v[110:113]
	v_mfma_f32_16x16x32_bf16 v[106:109], v[182:185], v[224:227], v[106:109]
	v_mfma_f32_16x16x32_bf16 v[94:97], v[174:177], v[232:235], v[94:97]
	v_mfma_f32_16x16x32_bf16 v[90:93], v[182:185], v[232:235], v[90:93]
	v_mfma_f32_16x16x32_bf16 v[78:81], v[174:177], v[240:243], v[78:81]
	v_mfma_f32_16x16x32_bf16 v[74:77], v[182:185], v[240:243], v[74:77]
	v_mfma_f32_16x16x32_bf16 v[118:121], v[196:199], v[212:215], v[118:121]
	v_mfma_f32_16x16x32_bf16 v[114:117], v[204:207], v[212:215], v[114:117]
	v_mfma_f32_16x16x32_bf16 v[102:105], v[196:199], v[220:223], v[102:105]
	v_mfma_f32_16x16x32_bf16 v[98:101], v[204:207], v[220:223], v[98:101]
	v_mfma_f32_16x16x32_bf16 v[86:89], v[196:199], v[228:231], v[86:89]
	v_mfma_f32_16x16x32_bf16 v[82:85], v[204:207], v[228:231], v[82:85]
	v_mfma_f32_16x16x32_bf16 v[70:73], v[196:199], v[236:239], v[70:73]
	v_mfma_f32_16x16x32_bf16 v[66:69], v[204:207], v[236:239], v[66:69]
	v_mfma_f32_16x16x32_bf16 v[118:121], v[200:203], v[216:219], v[118:121]
	v_mfma_f32_16x16x32_bf16 v[114:117], v[208:211], v[216:219], v[114:117]
	v_mfma_f32_16x16x32_bf16 v[102:105], v[200:203], v[224:227], v[102:105]
	v_mfma_f32_16x16x32_bf16 v[98:101], v[208:211], v[224:227], v[98:101]
	v_mfma_f32_16x16x32_bf16 v[86:89], v[200:203], v[232:235], v[86:89]
	v_mfma_f32_16x16x32_bf16 v[82:85], v[208:211], v[232:235], v[82:85]
	v_mfma_f32_16x16x32_bf16 v[70:73], v[200:203], v[240:243], v[70:73]
	v_mfma_f32_16x16x32_bf16 v[66:69], v[208:211], v[240:243], v[66:69]
	s_barrier
	s_add_i32 s50, s82, s69
	v_lshl_add_u64 v[160:161], v[160:161], 0, s[34:35]
	s_mov_b32 m0, s50
	ds_read_b128 v[212:215], v149 offset:49152
	ds_read_b128 v[216:219], v149 offset:50176
	ds_read_b128 v[220:223], v149 offset:51200
	ds_read_b128 v[224:227], v149 offset:52224
	ds_read_b128 v[228:231], v149 offset:53248
	ds_read_b128 v[232:235], v149 offset:54272
	ds_read_b128 v[236:239], v149 offset:55296
	ds_read_b128 v[240:243], v149 offset:56320
	global_load_lds_dwordx4 v[160:161], off
	s_add_i32 m0, s50, 0x2000
	s_add_u32 s48, s48, 0x40080
	v_lshl_add_u64 v[160:161], v[244:245], 0, s[34:35]
	s_addc_u32 s49, s49, 0
	s_add_i32 s50, s83, s69
	global_load_lds_dwordx4 v[160:161], off
	v_lshl_add_u64 v[160:161], s[48:49], 0, v[134:135]
	s_mov_b32 m0, s50
	s_nop 0
	global_load_lds_dwordx4 v[160:161], off
	v_lshl_add_u64 v[160:161], s[48:49], 0, v[130:131]
	s_add_i32 m0, s50, 0x2000
	s_nop 0
	global_load_lds_dwordx4 v[160:161], off
	v_lshl_add_u64 v[160:161], v[246:247], 0, s[34:35]
	s_mov_b32 m0, s77
	s_nop 0
	global_load_lds_dwordx4 v[160:161], off
	v_lshl_add_u64 v[160:161], v[248:249], 0, s[34:35]
	s_mov_b32 m0, s78
	s_nop 0
	global_load_lds_dwordx4 v[160:161], off
	s_waitcnt vmcnt(8)
	s_waitcnt lgkmcnt(0)
	s_barrier
; __device__ __forceinline__ unsigned cvt_pk_bf16(float lo, float hi) { unsigned r; asm volatile("v_cvt_pk_bf16_f32 %0, %1, %2" : "=v"(r) : "v"(lo), "v"(hi)); return r; }
; #define PG8_STAGE(bufoff, gbase, voff) do { _Pragma("unroll") for (int _i = 0; _i < 2; ++_i) \
;         __builtin_amdgcn_global_load_lds((const unsigned*)((const char*)(gbase) + (voff)[_i]), (PG8_LAS unsigned*)(lds + (bufoff) + ldsw + _i * 8192), 16, 0, 0); } while (0)
; #define PG8_LDA(dst, b, h) do { _Pragma("unroll") for (int m = 0; m < 4; ++m) _Pragma("unroll") for (int k = 0; k < 2; ++k) dst[m][k] = *(const PG8_LAS bf16x8*)(lds + PG8_SA(b, h) + aoff + m * 2048 + k * 1024); } while (0)
; #define PG8_WAIT_V(n) asm volatile("s_waitcnt vmcnt(" #n ")" ::: "memory")
; #define PG8_WAIT_L(n) asm volatile("s_waitcnt lgkmcnt(" #n ")" ::: "memory")
; template <class Epi, class Sched, bool ALIGN_EPI = false, bool SP2 = false>
; __device__ __forceinline__ void gemm_phase(PG8_LAS unsigned char* lds, const Gemm g, const Sched& S, const Epi& E) {
;     ...
;             PG8_WAIT_V(8); PG8_WAIT_L(0); PG8_BAR; PG8_MMA(0, 0, At, B0); PG8_MMA(0, 1, At, B1); PG8_BAR; PG8_SCHED;
;             PG8_LDA(At, 1, 1); PG8_STAGE(PG8_SB(1, 0), b3, voffB); PG8_STAGE(PG8_SB(1, 1), b3 + hstep, voffB); PG8_STAGE(PG8_SA(1, 0), a3, voffA);
;             PG8_WAIT_V(8); PG8_WAIT_L(0); PG8_BAR; PG8_MMA(1, 0, At, B0); PG8_MMA(1, 1, At, B1); PG8_BAR; PG8_SCHED;
;     __device__ __forceinline__ void operator()(const f32x4 (&acc)[2][2][4][2], const Unit& u, int wr, int wc, int fr, int fq, const float (&pre)[8]) const {
;         const int row0 = u.pm * 256 + wr * 64 + fr, col0 = u.pn * 128 + wc * 32 + 8 * fq;
; #pragma unroll
;         for (int ai = 0; ai < 2; ++ai)
; #pragma unroll
;             for (int m = 0; m < 4; ++m) {
;                 const float rsc = pre[ai * 4 + m];
;                 const f32x4 g0 = acc[ai][0][m][0] * rsc, g1 = acc[ai][0][m][1] * rsc, u0 = acc[ai][1][m][0] * rsc, u1 = acc[ai][1][m][1] * rsc;
;                 u32x4 w; w.x = cvt_pk_bf16(silu_mul(g0[0], u0[0]), silu_mul(g0[1], u0[1])); w.y = cvt_pk_bf16(silu_mul(g0[2], u0[2]), silu_mul(g0[3], u0[3]));
;                 w.z = cvt_pk_bf16(silu_mul(g1[0], u1[0]), silu_mul(g1[1], u1[1])); w.w = cvt_pk_bf16(silu_mul(g1[2], u1[2]), silu_mul(g1[3], u1[3]));
;                 *(GAS u32x4*)(O + (size_t)(row0 + ai * 128 + m * 16) * DFF + col0) = w; }
	v_mfma_f32_16x16x32_bf16 v[62:65], v[170:173], v[212:215], v[62:65]
	v_mfma_f32_16x16x32_bf16 v[58:61], v[178:181], v[212:215], v[58:61]
	v_mfma_f32_16x16x32_bf16 v[46:49], v[170:173], v[220:223], v[46:49]
	v_mfma_f32_16x16x32_bf16 v[42:45], v[178:181], v[220:223], v[42:45]
	v_mfma_f32_16x16x32_bf16 v[28:31], v[170:173], v[228:231], v[28:31]
	v_mfma_f32_16x16x32_bf16 v[24:27], v[178:181], v[228:231], v[24:27]
	v_mfma_f32_16x16x32_bf16 v[12:15], v[170:173], v[236:239], v[12:15]
	v_mfma_f32_16x16x32_bf16 v[8:11], v[178:181], v[236:239], v[8:11]
	v_mfma_f32_16x16x32_bf16 v[62:65], v[174:177], v[216:219], v[62:65]
	v_mfma_f32_16x16x32_bf16 v[58:61], v[182:185], v[216:219], v[58:61]
	v_mfma_f32_16x16x32_bf16 v[46:49], v[174:177], v[224:227], v[46:49]
	v_mfma_f32_16x16x32_bf16 v[42:45], v[182:185], v[224:227], v[42:45]
	v_mfma_f32_16x16x32_bf16 v[28:31], v[174:177], v[232:235], v[28:31]
	v_mfma_f32_16x16x32_bf16 v[24:27], v[182:185], v[232:235], v[24:27]
	v_mfma_f32_16x16x32_bf16 v[12:15], v[174:177], v[240:243], v[12:15]
	v_mfma_f32_16x16x32_bf16 v[8:11], v[182:185], v[240:243], v[8:11]
	v_mfma_f32_16x16x32_bf16 v[54:57], v[196:199], v[212:215], v[54:57]
	v_mfma_f32_16x16x32_bf16 v[50:53], v[204:207], v[212:215], v[50:53]
	v_mfma_f32_16x16x32_bf16 v[38:41], v[196:199], v[220:223], v[38:41]
	v_mfma_f32_16x16x32_bf16 v[34:37], v[204:207], v[220:223], v[34:37]
	v_mfma_f32_16x16x32_bf16 v[20:23], v[196:199], v[228:231], v[20:23]
	v_mfma_f32_16x16x32_bf16 v[16:19], v[204:207], v[228:231], v[16:19]
	v_mfma_f32_16x16x32_bf16 v[4:7], v[196:199], v[236:239], v[4:7]
	v_mfma_f32_16x16x32_bf16 v[0:3], v[204:207], v[236:239], v[0:3]
	v_mfma_f32_16x16x32_bf16 v[54:57], v[200:203], v[216:219], v[54:57]
	v_mfma_f32_16x16x32_bf16 v[50:53], v[208:211], v[216:219], v[50:53]
	v_mfma_f32_16x16x32_bf16 v[38:41], v[200:203], v[224:227], v[38:41]
	v_mfma_f32_16x16x32_bf16 v[34:37], v[208:211], v[224:227], v[34:37]
	v_mfma_f32_16x16x32_bf16 v[20:23], v[200:203], v[232:235], v[20:23]
	v_mfma_f32_16x16x32_bf16 v[16:19], v[208:211], v[232:235], v[16:19]
	v_mfma_f32_16x16x32_bf16 v[4:7], v[200:203], v[240:243], v[4:7]
	v_mfma_f32_16x16x32_bf16 v[0:3], v[208:211], v[240:243], v[0:3]
	s_barrier
	s_add_i32 s81, s81, 2
	s_add_u32 s79, s79, 0x100
	s_addc_u32 s80, s80, 0
	s_add_u32 s46, s46, 0x100
	s_addc_u32 s47, s47, 0
	s_cmp_gt_u32 s81, 13
	s_cbranch_scc0 .LBB0_580
	s_and_b64 vcc, exec, s[4:5]
	s_cbranch_vccz .LBB0_583
	s_barrier
.LBB0_583:
	v_pk_mul_f32 v[126:127], v[158:159], v[126:127] op_sel_hi:[0,1]
	v_mul_f32_e32 v153, 0xbfb8aa3b, v126
	v_exp_f32_e32 v153, v153
	v_pk_mul_f32 v[118:119], v[158:159], v[118:119] op_sel_hi:[0,1]
	v_pk_mul_f32 v[128:129], v[158:159], v[128:129] op_sel_hi:[0,1]
	v_pk_mul_f32 v[120:121], v[158:159], v[120:121] op_sel_hi:[0,1]
	v_add_f32_e32 v153, 1.0, v153
	v_rcp_f32_e32 v153, v153
	v_pk_mul_f32 v[122:123], v[158:159], v[122:123] op_sel_hi:[0,1]
	v_pk_mul_f32 v[114:115], v[158:159], v[114:115] op_sel_hi:[0,1]
	v_pk_mul_f32 v[124:125], v[158:159], v[124:125] op_sel_hi:[0,1]
	v_mul_f32_e32 v126, v126, v153
	v_mul_f32_e32 v118, v126, v118
	v_mul_f32_e32 v126, 0xbfb8aa3b, v127
	v_exp_f32_e32 v126, v126
	v_pk_mul_f32 v[116:117], v[158:159], v[116:117] op_sel_hi:[0,1]
	v_lshl_or_b32 v160, s45, 7, v147
	v_lshl_add_u32 v151, s44, 8, v33
	v_add_f32_e32 v126, 1.0, v126
	v_rcp_f32_e32 v126, v126
	v_ashrrev_i32_e32 v161, 31, v160
	v_pk_mul_f32 v[110:111], v[156:157], v[110:111] op_sel_hi:[0,1]
	v_pk_mul_f32 v[102:103], v[156:157], v[102:103] op_sel_hi:[0,1]
	v_mul_f32_e32 v126, v127, v126
	v_mul_f32_e32 v119, v126, v119
	v_cvt_pk_bf16_f32 v118, v118, v119
	v_mul_f32_e32 v119, 0xbfb8aa3b, v128
	v_exp_f32_e32 v119, v119
	v_pk_mul_f32 v[112:113], v[156:157], v[112:113] op_sel_hi:[0,1]
	v_pk_mul_f32 v[104:105], v[156:157], v[104:105] op_sel_hi:[0,1]
	v_pk_mul_f32 v[106:107], v[156:157], v[106:107] op_sel_hi:[0,1]
	v_add_f32_e32 v119, 1.0, v119
	v_rcp_f32_e32 v119, v119
	v_pk_mul_f32 v[108:109], v[156:157], v[108:109] op_sel_hi:[0,1]
	v_pk_mul_f32 v[94:95], v[154:155], v[94:95] op_sel_hi:[0,1]
	v_pk_mul_f32 v[86:87], v[154:155], v[86:87] op_sel_hi:[0,1]
	v_mul_f32_e32 v119, v128, v119
	v_mul_f32_e32 v119, v119, v120
	v_mul_f32_e32 v120, 0xbfb8aa3b, v129
	v_exp_f32_e32 v120, v120
	v_pk_mul_f32 v[96:97], v[154:155], v[96:97] op_sel_hi:[0,1]
	v_pk_mul_f32 v[88:89], v[154:155], v[88:89] op_sel_hi:[0,1]
	v_pk_mul_f32 v[90:91], v[154:155], v[90:91] op_sel_hi:[0,1]
	v_add_f32_e32 v120, 1.0, v120
	v_rcp_f32_e32 v120, v120
	v_pk_mul_f32 v[92:93], v[154:155], v[92:93] op_sel_hi:[0,1]
	v_pk_mul_f32 v[78:79], v[152:153], v[78:79] op_sel_hi:[0,1]
	v_pk_mul_f32 v[70:71], v[152:153], v[70:71] op_sel_hi:[0,1]
	v_mul_f32_e32 v120, v129, v120
	v_mul_f32_e32 v120, v120, v121
	v_cvt_pk_bf16_f32 v119, v119, v120
	v_mul_f32_e32 v120, 0xbfb8aa3b, v122
	v_exp_f32_e32 v120, v120
	v_pk_mul_f32 v[80:81], v[152:153], v[80:81] op_sel_hi:[0,1]
	v_pk_mul_f32 v[72:73], v[152:153], v[72:73] op_sel_hi:[0,1]
	v_pk_mul_f32 v[74:75], v[152:153], v[74:75] op_sel_hi:[0,1]
	v_add_f32_e32 v120, 1.0, v120
	v_rcp_f32_e32 v120, v120
	v_pk_mul_f32 v[76:77], v[152:153], v[76:77] op_sel_hi:[0,1]
	v_pk_mul_f32 v[62:63], v[150:151], v[62:63] op_sel_hi:[0,1]
	v_pk_mul_f32 v[54:55], v[150:151], v[54:55] op_sel_hi:[0,1]
	v_mul_f32_e32 v120, v122, v120
	v_mul_f32_e32 v114, v120, v114
	v_mul_f32_e32 v120, 0xbfb8aa3b, v123
	v_exp_f32_e32 v120, v120
	v_pk_mul_f32 v[64:65], v[150:151], v[64:65] op_sel_hi:[0,1]
	v_pk_mul_f32 v[56:57], v[150:151], v[56:57] op_sel_hi:[0,1]
	v_pk_mul_f32 v[58:59], v[150:151], v[58:59] op_sel_hi:[0,1]
	v_add_f32_e32 v120, 1.0, v120
	v_rcp_f32_e32 v120, v120
; __device__ __forceinline__ unsigned cvt_pk_bf16(float lo, float hi) { unsigned r; asm volatile("v_cvt_pk_bf16_f32 %0, %1, %2" : "=v"(r) : "v"(lo), "v"(hi)); return r; }
; #define GAS __attribute__((address_space(1)))
; __device__ __forceinline__ float silu_mul(float g, float u) { const float e = __builtin_amdgcn_exp2f(-1.4426950408889634f * g); return g * __builtin_amdgcn_rcpf(1.0f + e) * u; }
;     __device__ __forceinline__ void prefetch(const Unit& u, int wr, int fr, float (&pre)[8]) const {
; #pragma unroll
;         for (int i = 0; i < 8; ++i) pre[i] = *(const GAS float*)(rs + u.pm * 256 + wr * 64 + fr + (i >> 2) * 128 + (i & 3) * 16);
;     }
;     __device__ __forceinline__ void operator()(const f32x4 (&acc)[2][2][4][2], const Unit& u, int wr, int wc, int fr, int fq, const float (&pre)[8]) const {
;         const int row0 = u.pm * 256 + wr * 64 + fr, col0 = u.pn * 128 + wc * 32 + 8 * fq;
; #pragma unroll
;         for (int ai = 0; ai < 2; ++ai)
; #pragma unroll
;             for (int m = 0; m < 4; ++m) {
;                 const float rsc = pre[ai * 4 + m];
;                 const f32x4 g0 = acc[ai][0][m][0] * rsc, g1 = acc[ai][0][m][1] * rsc, u0 = acc[ai][1][m][0] * rsc, u1 = acc[ai][1][m][1] * rsc;
;                 u32x4 w; w.x = cvt_pk_bf16(silu_mul(g0[0], u0[0]), silu_mul(g0[1], u0[1])); w.y = cvt_pk_bf16(silu_mul(g0[2], u0[2]), silu_mul(g0[3], u0[3]));
;                 w.z = cvt_pk_bf16(silu_mul(g1[0], u1[0]), silu_mul(g1[1], u1[1])); w.w = cvt_pk_bf16(silu_mul(g1[2], u1[2]), silu_mul(g1[3], u1[3]));
;                 *(GAS u32x4*)(O + (size_t)(row0 + ai * 128 + m * 16) * DFF + col0) = w; }
	v_pk_mul_f32 v[60:61], v[150:151], v[60:61] op_sel_hi:[0,1]
	v_pk_mul_f32 v[46:47], v[148:149], v[46:47] op_sel_hi:[0,1]
	v_pk_mul_f32 v[38:39], v[148:149], v[38:39] op_sel_hi:[0,1]
	v_mul_f32_e32 v120, v123, v120
	v_mul_f32_e32 v115, v120, v115
	v_cvt_pk_bf16_f32 v120, v114, v115
	v_mul_f32_e32 v114, 0xbfb8aa3b, v124
	v_mul_f32_e32 v115, 0xbfb8aa3b, v125
	v_exp_f32_e32 v114, v114
	v_exp_f32_e32 v115, v115
	v_pk_mul_f32 v[48:49], v[148:149], v[48:49] op_sel_hi:[0,1]
	v_pk_mul_f32 v[40:41], v[148:149], v[40:41] op_sel_hi:[0,1]
	v_add_f32_e32 v114, 1.0, v114
	v_add_f32_e32 v115, 1.0, v115
	v_rcp_f32_e32 v114, v114
	v_rcp_f32_e32 v115, v115
	v_pk_mul_f32 v[42:43], v[148:149], v[42:43] op_sel_hi:[0,1]
	v_pk_mul_f32 v[44:45], v[148:149], v[44:45] op_sel_hi:[0,1]
	v_mul_f32_e32 v114, v124, v114
	v_mul_f32_e32 v115, v125, v115
	v_mul_f32_e32 v114, v114, v116
	v_mul_f32_e32 v115, v115, v117
	v_cvt_pk_bf16_f32 v121, v114, v115
	v_mov_b64_e32 v[114:115], s[64:65]
	v_mad_i64_i32 v[122:123], s[44:45], v151, s29, v[114:115]
	v_lshlrev_b64 v[116:117], 1, v[160:161]
	v_lshl_add_u64 v[122:123], v[122:123], 0, v[116:117]
	global_store_dwordx4 v[122:123], v[118:121], off
	v_pk_mul_f32 v[28:29], v[146:147], v[28:29] op_sel_hi:[0,1]
	v_pk_mul_f32 v[20:21], v[146:147], v[20:21] op_sel_hi:[0,1]
	v_pk_mul_f32 v[118:119], v[156:157], v[100:101] op_sel_hi:[0,1]
	v_pk_mul_f32 v[100:101], v[156:157], v[98:99] op_sel_hi:[0,1]
	v_mul_f32_e32 v98, 0xbfb8aa3b, v110
	v_mul_f32_e32 v99, 0xbfb8aa3b, v111
	v_exp_f32_e32 v98, v98
	v_exp_f32_e32 v99, v99
	v_pk_mul_f32 v[30:31], v[146:147], v[30:31] op_sel_hi:[0,1]
	v_pk_mul_f32 v[22:23], v[146:147], v[22:23] op_sel_hi:[0,1]
	v_add_f32_e32 v98, 1.0, v98
	v_add_f32_e32 v99, 1.0, v99
	v_rcp_f32_e32 v98, v98
	v_rcp_f32_e32 v99, v99
	v_pk_mul_f32 v[24:25], v[146:147], v[24:25] op_sel_hi:[0,1]
	v_pk_mul_f32 v[26:27], v[146:147], v[26:27] op_sel_hi:[0,1]
	v_mul_f32_e32 v98, v110, v98
	v_mul_f32_e32 v99, v111, v99
	v_mul_f32_e32 v98, v98, v102
	v_mul_f32_e32 v99, v99, v103
	v_cvt_pk_bf16_f32 v98, v98, v99
	v_mul_f32_e32 v99, 0xbfb8aa3b, v112
	v_mul_f32_e32 v102, 0xbfb8aa3b, v113
	v_exp_f32_e32 v99, v99
	v_exp_f32_e32 v102, v102
	v_pk_mul_f32 v[12:13], v[144:145], v[12:13] op_sel_hi:[0,1]
	v_pk_mul_f32 v[4:5], v[144:145], v[4:5] op_sel_hi:[0,1]
	v_add_f32_e32 v99, 1.0, v99
	v_add_f32_e32 v102, 1.0, v102
	v_rcp_f32_e32 v99, v99
	v_rcp_f32_e32 v102, v102
	v_pk_mul_f32 v[14:15], v[144:145], v[14:15] op_sel_hi:[0,1]
	v_pk_mul_f32 v[6:7], v[144:145], v[6:7] op_sel_hi:[0,1]
	v_mul_f32_e32 v99, v112, v99
	v_mul_f32_e32 v102, v113, v102
	v_mul_f32_e32 v99, v99, v104
	v_mul_f32_e32 v102, v102, v105
	v_cvt_pk_bf16_f32 v99, v99, v102
	v_mul_f32_e32 v102, 0xbfb8aa3b, v106
	v_exp_f32_e32 v102, v102
	v_pk_mul_f32 v[8:9], v[144:145], v[8:9] op_sel_hi:[0,1]
	v_pk_mul_f32 v[10:11], v[144:145], v[10:11] op_sel_hi:[0,1]
	s_andn2_b64 vcc, exec, s[42:43]
	v_add_f32_e32 v102, 1.0, v102
	v_rcp_f32_e32 v102, v102
	s_nop 0
	v_mul_f32_e32 v102, v106, v102
	v_mul_f32_e32 v100, v102, v100
	v_mul_f32_e32 v102, 0xbfb8aa3b, v107
	v_exp_f32_e32 v102, v102
	s_nop 0
	v_add_f32_e32 v102, 1.0, v102
	v_rcp_f32_e32 v102, v102
	s_nop 0
	v_mul_f32_e32 v102, v107, v102
	v_mul_f32_e32 v101, v102, v101
	v_cvt_pk_bf16_f32 v100, v100, v101
	v_mul_f32_e32 v101, 0xbfb8aa3b, v108
	v_mul_f32_e32 v102, 0xbfb8aa3b, v109
	v_exp_f32_e32 v101, v101
	v_exp_f32_e32 v102, v102
	v_add_f32_e32 v101, 1.0, v101
	v_add_f32_e32 v102, 1.0, v102
	v_rcp_f32_e32 v101, v101
	v_rcp_f32_e32 v102, v102
	v_mul_f32_e32 v101, v108, v101
	v_mul_f32_e32 v102, v109, v102
	v_mul_f32_e32 v101, v101, v118
	v_mul_f32_e32 v102, v102, v119
	v_cvt_pk_bf16_f32 v101, v101, v102
	v_or_b32_e32 v102, 16, v151
	v_mad_i64_i32 v[102:103], s[44:45], v102, s29, v[114:115]
	v_lshl_add_u64 v[102:103], v[102:103], 0, v[116:117]
	global_store_dwordx4 v[102:103], v[98:101], off
	s_nop 1
	v_pk_mul_f32 v[98:99], v[154:155], v[84:85] op_sel_hi:[0,1]
	v_pk_mul_f32 v[84:85], v[154:155], v[82:83] op_sel_hi:[0,1]
	v_mul_f32_e32 v82, 0xbfb8aa3b, v94
	v_mul_f32_e32 v83, 0xbfb8aa3b, v95
	v_exp_f32_e32 v82, v82
	v_exp_f32_e32 v83, v83
	v_add_f32_e32 v82, 1.0, v82
	v_add_f32_e32 v83, 1.0, v83
	v_rcp_f32_e32 v82, v82
	v_rcp_f32_e32 v83, v83
	v_mul_f32_e32 v82, v94, v82
	v_mul_f32_e32 v83, v95, v83
	v_mul_f32_e32 v82, v82, v86
	v_mul_f32_e32 v83, v83, v87
	v_cvt_pk_bf16_f32 v82, v82, v83
	v_mul_f32_e32 v83, 0xbfb8aa3b, v96
	v_mul_f32_e32 v86, 0xbfb8aa3b, v97
	v_exp_f32_e32 v83, v83
	v_exp_f32_e32 v86, v86
	v_add_f32_e32 v83, 1.0, v83
	v_add_f32_e32 v86, 1.0, v86
	v_rcp_f32_e32 v83, v83
	v_rcp_f32_e32 v86, v86
	v_mul_f32_e32 v83, v96, v83
	v_mul_f32_e32 v86, v97, v86
	v_mul_f32_e32 v83, v83, v88
	v_mul_f32_e32 v86, v86, v89
	v_cvt_pk_bf16_f32 v83, v83, v86
	v_mul_f32_e32 v86, 0xbfb8aa3b, v90
	v_exp_f32_e32 v86, v86
	s_nop 0
	v_add_f32_e32 v86, 1.0, v86
	v_rcp_f32_e32 v86, v86
	s_nop 0
	v_mul_f32_e32 v86, v90, v86
	v_mul_f32_e32 v84, v86, v84
	v_mul_f32_e32 v86, 0xbfb8aa3b, v91
	v_exp_f32_e32 v86, v86
	s_nop 0
	v_add_f32_e32 v86, 1.0, v86
	v_rcp_f32_e32 v86, v86
	s_nop 0
	v_mul_f32_e32 v86, v91, v86
	v_mul_f32_e32 v85, v86, v85
	v_cvt_pk_bf16_f32 v84, v84, v85
	v_mul_f32_e32 v85, 0xbfb8aa3b, v92
	v_mul_f32_e32 v86, 0xbfb8aa3b, v93
	v_exp_f32_e32 v85, v85
	v_exp_f32_e32 v86, v86
	v_add_f32_e32 v85, 1.0, v85
	v_add_f32_e32 v86, 1.0, v86
	v_rcp_f32_e32 v85, v85
	v_rcp_f32_e32 v86, v86
	v_mul_f32_e32 v85, v92, v85
	v_mul_f32_e32 v86, v93, v86
	v_mul_f32_e32 v85, v85, v98
	v_mul_f32_e32 v86, v86, v99
	v_cvt_pk_bf16_f32 v85, v85, v86
	v_or_b32_e32 v86, 32, v151
	v_mad_i64_i32 v[86:87], s[44:45], v86, s29, v[114:115]
	v_lshl_add_u64 v[86:87], v[86:87], 0, v[116:117]
; __device__ __forceinline__ unsigned cvt_pk_bf16(float lo, float hi) { unsigned r; asm volatile("v_cvt_pk_bf16_f32 %0, %1, %2" : "=v"(r) : "v"(lo), "v"(hi)); return r; }
; #define GAS __attribute__((address_space(1)))
; __device__ __forceinline__ float silu_mul(float g, float u) { const float e = __builtin_amdgcn_exp2f(-1.4426950408889634f * g); return g * __builtin_amdgcn_rcpf(1.0f + e) * u; }
;     __device__ __forceinline__ void prefetch(const Unit& u, int wr, int fr, float (&pre)[8]) const {
; #pragma unroll
;         for (int i = 0; i < 8; ++i) pre[i] = *(const GAS float*)(rs + u.pm * 256 + wr * 64 + fr + (i >> 2) * 128 + (i & 3) * 16);
;     }
;     __device__ __forceinline__ void operator()(const f32x4 (&acc)[2][2][4][2], const Unit& u, int wr, int wc, int fr, int fq, const float (&pre)[8]) const {
;         const int row0 = u.pm * 256 + wr * 64 + fr, col0 = u.pn * 128 + wc * 32 + 8 * fq;
; #pragma unroll
;         for (int ai = 0; ai < 2; ++ai)
; #pragma unroll
;             for (int m = 0; m < 4; ++m) {
;                 const float rsc = pre[ai * 4 + m];
;                 const f32x4 g0 = acc[ai][0][m][0] * rsc, g1 = acc[ai][0][m][1] * rsc, u0 = acc[ai][1][m][0] * rsc, u1 = acc[ai][1][m][1] * rsc;
;                 u32x4 w; w.x = cvt_pk_bf16(silu_mul(g0[0], u0[0]), silu_mul(g0[1], u0[1])); w.y = cvt_pk_bf16(silu_mul(g0[2], u0[2]), silu_mul(g0[3], u0[3]));
;                 w.z = cvt_pk_bf16(silu_mul(g1[0], u1[0]), silu_mul(g1[1], u1[1])); w.w = cvt_pk_bf16(silu_mul(g1[2], u1[2]), silu_mul(g1[3], u1[3]));
;                 *(GAS u32x4*)(O + (size_t)(row0 + ai * 128 + m * 16) * DFF + col0) = w; }
	global_store_dwordx4 v[86:87], v[82:85], off
	s_nop 1
	v_pk_mul_f32 v[82:83], v[152:153], v[68:69] op_sel_hi:[0,1]
	v_pk_mul_f32 v[68:69], v[152:153], v[66:67] op_sel_hi:[0,1]
	v_mul_f32_e32 v66, 0xbfb8aa3b, v78
	v_mul_f32_e32 v67, 0xbfb8aa3b, v79
	v_exp_f32_e32 v66, v66
	v_exp_f32_e32 v67, v67
	v_add_f32_e32 v66, 1.0, v66
	v_add_f32_e32 v67, 1.0, v67
	v_rcp_f32_e32 v66, v66
	v_rcp_f32_e32 v67, v67
	v_mul_f32_e32 v66, v78, v66
	v_mul_f32_e32 v67, v79, v67
	v_mul_f32_e32 v66, v66, v70
	v_mul_f32_e32 v67, v67, v71
	v_cvt_pk_bf16_f32 v66, v66, v67
	v_mul_f32_e32 v67, 0xbfb8aa3b, v80
	v_mul_f32_e32 v70, 0xbfb8aa3b, v81
	v_exp_f32_e32 v67, v67
	v_exp_f32_e32 v70, v70
	v_add_f32_e32 v67, 1.0, v67
	v_add_f32_e32 v70, 1.0, v70
	v_rcp_f32_e32 v67, v67
	v_rcp_f32_e32 v70, v70
	v_mul_f32_e32 v67, v80, v67
	v_mul_f32_e32 v70, v81, v70
	v_mul_f32_e32 v67, v67, v72
	v_mul_f32_e32 v70, v70, v73
	v_cvt_pk_bf16_f32 v67, v67, v70
	v_mul_f32_e32 v70, 0xbfb8aa3b, v74
	v_exp_f32_e32 v70, v70
	s_nop 0
	v_add_f32_e32 v70, 1.0, v70
	v_rcp_f32_e32 v70, v70
	s_nop 0
	v_mul_f32_e32 v70, v74, v70
	v_mul_f32_e32 v68, v70, v68
	v_mul_f32_e32 v70, 0xbfb8aa3b, v75
	v_exp_f32_e32 v70, v70
	s_nop 0
	v_add_f32_e32 v70, 1.0, v70
	v_rcp_f32_e32 v70, v70
	s_nop 0
	v_mul_f32_e32 v70, v75, v70
	v_mul_f32_e32 v69, v70, v69
	v_cvt_pk_bf16_f32 v68, v68, v69
	v_mul_f32_e32 v69, 0xbfb8aa3b, v76
	v_mul_f32_e32 v70, 0xbfb8aa3b, v77
	v_exp_f32_e32 v69, v69
	v_exp_f32_e32 v70, v70
	v_add_f32_e32 v69, 1.0, v69
	v_add_f32_e32 v70, 1.0, v70
	v_rcp_f32_e32 v69, v69
	v_rcp_f32_e32 v70, v70
	v_mul_f32_e32 v69, v76, v69
	v_mul_f32_e32 v70, v77, v70
	v_mul_f32_e32 v69, v69, v82
	v_mul_f32_e32 v70, v70, v83
	v_cvt_pk_bf16_f32 v69, v69, v70
	v_or_b32_e32 v70, 48, v151
	v_mad_i64_i32 v[70:71], s[44:45], v70, s29, v[114:115]
	v_lshl_add_u64 v[70:71], v[70:71], 0, v[116:117]
	global_store_dwordx4 v[70:71], v[66:69], off
	s_nop 1
	v_pk_mul_f32 v[66:67], v[150:151], v[52:53] op_sel_hi:[0,1]
	v_pk_mul_f32 v[52:53], v[150:151], v[50:51] op_sel_hi:[0,1]
	v_mul_f32_e32 v50, 0xbfb8aa3b, v62
	v_mul_f32_e32 v51, 0xbfb8aa3b, v63
	v_exp_f32_e32 v50, v50
	v_exp_f32_e32 v51, v51
	v_add_u32_e32 v68, 0x80, v151
	v_add_f32_e32 v50, 1.0, v50
	v_add_f32_e32 v51, 1.0, v51
	v_rcp_f32_e32 v50, v50
	v_rcp_f32_e32 v51, v51
	v_mul_f32_e32 v50, v62, v50
	v_mul_f32_e32 v51, v63, v51
	v_mul_f32_e32 v50, v50, v54
	v_mul_f32_e32 v51, v51, v55
	v_cvt_pk_bf16_f32 v50, v50, v51
	v_mul_f32_e32 v51, 0xbfb8aa3b, v64
	v_mul_f32_e32 v54, 0xbfb8aa3b, v65
	v_exp_f32_e32 v51, v51
	v_exp_f32_e32 v54, v54
	v_add_f32_e32 v51, 1.0, v51
	v_add_f32_e32 v54, 1.0, v54
	v_rcp_f32_e32 v51, v51
	v_rcp_f32_e32 v54, v54
	v_mul_f32_e32 v51, v64, v51
	v_mul_f32_e32 v54, v65, v54
	v_mul_f32_e32 v51, v51, v56
	v_mul_f32_e32 v54, v54, v57
	v_cvt_pk_bf16_f32 v51, v51, v54
	v_mul_f32_e32 v54, 0xbfb8aa3b, v58
	v_exp_f32_e32 v54, v54
	s_nop 0
	v_add_f32_e32 v54, 1.0, v54
	v_rcp_f32_e32 v54, v54
	s_nop 0
	v_mul_f32_e32 v54, v58, v54
	v_mul_f32_e32 v52, v54, v52
	v_mul_f32_e32 v54, 0xbfb8aa3b, v59
	v_exp_f32_e32 v54, v54
	s_nop 0
	v_add_f32_e32 v54, 1.0, v54
	v_rcp_f32_e32 v54, v54
	s_nop 0
	v_mul_f32_e32 v54, v59, v54
	v_mul_f32_e32 v53, v54, v53
	v_cvt_pk_bf16_f32 v52, v52, v53
	v_mul_f32_e32 v53, 0xbfb8aa3b, v60
	v_mul_f32_e32 v54, 0xbfb8aa3b, v61
	v_exp_f32_e32 v53, v53
	v_exp_f32_e32 v54, v54
	v_add_f32_e32 v53, 1.0, v53
	v_add_f32_e32 v54, 1.0, v54
	v_rcp_f32_e32 v53, v53
	v_rcp_f32_e32 v54, v54
	v_mul_f32_e32 v53, v60, v53
	v_mul_f32_e32 v54, v61, v54
	v_mul_f32_e32 v53, v53, v66
	v_mul_f32_e32 v54, v54, v67
	v_cvt_pk_bf16_f32 v53, v53, v54
	v_mad_i64_i32 v[54:55], s[44:45], v68, s29, v[114:115]
	v_lshl_add_u64 v[54:55], v[54:55], 0, v[116:117]
	global_store_dwordx4 v[54:55], v[50:53], off
	s_nop 1
	v_pk_mul_f32 v[50:51], v[148:149], v[36:37] op_sel_hi:[0,1]
	v_pk_mul_f32 v[36:37], v[148:149], v[34:35] op_sel_hi:[0,1]
	v_mul_f32_e32 v34, 0xbfb8aa3b, v46
	v_mul_f32_e32 v35, 0xbfb8aa3b, v47
	v_exp_f32_e32 v34, v34
	v_exp_f32_e32 v35, v35
	v_add_f32_e32 v34, 1.0, v34
	v_add_f32_e32 v35, 1.0, v35
	v_rcp_f32_e32 v34, v34
	v_rcp_f32_e32 v35, v35
	v_mul_f32_e32 v34, v46, v34
	v_mul_f32_e32 v35, v47, v35
	v_mul_f32_e32 v34, v34, v38
	v_mul_f32_e32 v35, v35, v39
	v_cvt_pk_bf16_f32 v34, v34, v35
	v_mul_f32_e32 v35, 0xbfb8aa3b, v48
	v_mul_f32_e32 v38, 0xbfb8aa3b, v49
	v_exp_f32_e32 v35, v35
	v_exp_f32_e32 v38, v38
	v_add_f32_e32 v35, 1.0, v35
	v_add_f32_e32 v38, 1.0, v38
	v_rcp_f32_e32 v35, v35
	v_rcp_f32_e32 v38, v38
	v_mul_f32_e32 v35, v48, v35
	v_mul_f32_e32 v38, v49, v38
	v_mul_f32_e32 v35, v35, v40
	v_mul_f32_e32 v38, v38, v41
	v_cvt_pk_bf16_f32 v35, v35, v38
	v_mul_f32_e32 v38, 0xbfb8aa3b, v42
	v_exp_f32_e32 v38, v38
	s_nop 0
	v_add_f32_e32 v38, 1.0, v38
	v_rcp_f32_e32 v38, v38
	s_nop 0
	v_mul_f32_e32 v38, v42, v38
	v_mul_f32_e32 v36, v38, v36
	v_mul_f32_e32 v38, 0xbfb8aa3b, v43
	v_exp_f32_e32 v38, v38
	s_nop 0
; __device__ __forceinline__ unsigned cvt_pk_bf16(float lo, float hi) { unsigned r; asm volatile("v_cvt_pk_bf16_f32 %0, %1, %2" : "=v"(r) : "v"(lo), "v"(hi)); return r; }
; #define PG8_BAR __builtin_amdgcn_s_barrier()
; #define GAS __attribute__((address_space(1)))
; __device__ __forceinline__ float silu_mul(float g, float u) { const float e = __builtin_amdgcn_exp2f(-1.4426950408889634f * g); return g * __builtin_amdgcn_rcpf(1.0f + e) * u; }
; template <class Epi, class Sched, bool ALIGN_EPI = false, bool SP2 = false>
; __device__ __forceinline__ void gemm_phase(PG8_LAS unsigned char* lds, const Gemm g, const Sched& S, const Epi& E) {
;     ...
;         if constexpr (Epi::PREFETCH) E.prefetch(cur, wr, fr, epre);
;         if constexpr (ALIGN_EPI) { if (wr == 1) PG8_BAR; }
;     __device__ __forceinline__ void operator()(const f32x4 (&acc)[2][2][4][2], const Unit& u, int wr, int wc, int fr, int fq, const float (&pre)[8]) const {
;         const int row0 = u.pm * 256 + wr * 64 + fr, col0 = u.pn * 128 + wc * 32 + 8 * fq;
; #pragma unroll
;         for (int ai = 0; ai < 2; ++ai)
; #pragma unroll
;             for (int m = 0; m < 4; ++m) {
;                 const float rsc = pre[ai * 4 + m];
;                 const f32x4 g0 = acc[ai][0][m][0] * rsc, g1 = acc[ai][0][m][1] * rsc, u0 = acc[ai][1][m][0] * rsc, u1 = acc[ai][1][m][1] * rsc;
;                 u32x4 w; w.x = cvt_pk_bf16(silu_mul(g0[0], u0[0]), silu_mul(g0[1], u0[1])); w.y = cvt_pk_bf16(silu_mul(g0[2], u0[2]), silu_mul(g0[3], u0[3]));
;                 w.z = cvt_pk_bf16(silu_mul(g1[0], u1[0]), silu_mul(g1[1], u1[1])); w.w = cvt_pk_bf16(silu_mul(g1[2], u1[2]), silu_mul(g1[3], u1[3]));
;                 *(GAS u32x4*)(O + (size_t)(row0 + ai * 128 + m * 16) * DFF + col0) = w; }
	v_add_f32_e32 v38, 1.0, v38
	v_rcp_f32_e32 v38, v38
	s_nop 0
	v_mul_f32_e32 v38, v43, v38
	v_mul_f32_e32 v37, v38, v37
	v_cvt_pk_bf16_f32 v36, v36, v37
	v_mul_f32_e32 v37, 0xbfb8aa3b, v44
	v_mul_f32_e32 v38, 0xbfb8aa3b, v45
	v_exp_f32_e32 v37, v37
	v_exp_f32_e32 v38, v38
	v_add_f32_e32 v37, 1.0, v37
	v_add_f32_e32 v38, 1.0, v38
	v_rcp_f32_e32 v37, v37
	v_rcp_f32_e32 v38, v38
	v_mul_f32_e32 v37, v44, v37
	v_mul_f32_e32 v38, v45, v38
	v_mul_f32_e32 v37, v37, v50
	v_mul_f32_e32 v38, v38, v51
	v_cvt_pk_bf16_f32 v37, v37, v38
	v_add_u32_e32 v38, 0x90, v151
	v_mad_i64_i32 v[38:39], s[44:45], v38, s29, v[114:115]
	v_lshl_add_u64 v[38:39], v[38:39], 0, v[116:117]
	global_store_dwordx4 v[38:39], v[34:37], off
	s_nop 1
	v_pk_mul_f32 v[34:35], v[146:147], v[18:19] op_sel_hi:[0,1]
	v_pk_mul_f32 v[18:19], v[146:147], v[16:17] op_sel_hi:[0,1]
	v_mul_f32_e32 v16, 0xbfb8aa3b, v28
	v_mul_f32_e32 v17, 0xbfb8aa3b, v29
	v_exp_f32_e32 v16, v16
	v_exp_f32_e32 v17, v17
	v_add_f32_e32 v16, 1.0, v16
	v_add_f32_e32 v17, 1.0, v17
	v_rcp_f32_e32 v16, v16
	v_rcp_f32_e32 v17, v17
	v_mul_f32_e32 v16, v28, v16
	v_mul_f32_e32 v17, v29, v17
	v_mul_f32_e32 v16, v16, v20
	v_mul_f32_e32 v17, v17, v21
	v_cvt_pk_bf16_f32 v16, v16, v17
	v_mul_f32_e32 v17, 0xbfb8aa3b, v30
	v_mul_f32_e32 v20, 0xbfb8aa3b, v31
	v_exp_f32_e32 v17, v17
	v_exp_f32_e32 v20, v20
	v_add_f32_e32 v17, 1.0, v17
	v_add_f32_e32 v20, 1.0, v20
	v_rcp_f32_e32 v17, v17
	v_rcp_f32_e32 v20, v20
	v_mul_f32_e32 v17, v30, v17
	v_mul_f32_e32 v20, v31, v20
	v_mul_f32_e32 v17, v17, v22
	v_mul_f32_e32 v20, v20, v23
	v_cvt_pk_bf16_f32 v17, v17, v20
	v_mul_f32_e32 v20, 0xbfb8aa3b, v24
	v_exp_f32_e32 v20, v20
	s_nop 0
	v_add_f32_e32 v20, 1.0, v20
	v_rcp_f32_e32 v20, v20
	s_nop 0
	v_mul_f32_e32 v20, v24, v20
	v_mul_f32_e32 v18, v20, v18
	v_mul_f32_e32 v20, 0xbfb8aa3b, v25
	v_exp_f32_e32 v20, v20
	s_nop 0
	v_add_f32_e32 v20, 1.0, v20
	v_rcp_f32_e32 v20, v20
	s_nop 0
	v_mul_f32_e32 v20, v25, v20
	v_mul_f32_e32 v19, v20, v19
	v_cvt_pk_bf16_f32 v18, v18, v19
	v_mul_f32_e32 v19, 0xbfb8aa3b, v26
	v_mul_f32_e32 v20, 0xbfb8aa3b, v27
	v_exp_f32_e32 v19, v19
	v_exp_f32_e32 v20, v20
	v_add_f32_e32 v19, 1.0, v19
	v_add_f32_e32 v20, 1.0, v20
	v_rcp_f32_e32 v19, v19
	v_rcp_f32_e32 v20, v20
	v_mul_f32_e32 v19, v26, v19
	v_mul_f32_e32 v20, v27, v20
	v_mul_f32_e32 v19, v19, v34
	v_mul_f32_e32 v20, v20, v35
	v_cvt_pk_bf16_f32 v19, v19, v20
	v_add_u32_e32 v20, 0xa0, v151
	v_mad_i64_i32 v[20:21], s[44:45], v20, s29, v[114:115]
	v_lshl_add_u64 v[20:21], v[20:21], 0, v[116:117]
	global_store_dwordx4 v[20:21], v[16:19], off
	s_nop 1
	v_pk_mul_f32 v[16:17], v[144:145], v[2:3] op_sel_hi:[0,1]
	v_pk_mul_f32 v[2:3], v[144:145], v[0:1] op_sel_hi:[0,1]
	v_mul_f32_e32 v0, 0xbfb8aa3b, v12
	v_mul_f32_e32 v1, 0xbfb8aa3b, v13
	v_exp_f32_e32 v0, v0
	v_exp_f32_e32 v1, v1
	v_add_f32_e32 v0, 1.0, v0
	v_add_f32_e32 v1, 1.0, v1
	v_rcp_f32_e32 v0, v0
	v_rcp_f32_e32 v1, v1
	v_mul_f32_e32 v0, v12, v0
	v_mul_f32_e32 v1, v13, v1
	v_mul_f32_e32 v0, v0, v4
	v_mul_f32_e32 v1, v1, v5
	v_cvt_pk_bf16_f32 v0, v0, v1
	v_mul_f32_e32 v1, 0xbfb8aa3b, v14
	v_mul_f32_e32 v4, 0xbfb8aa3b, v15
	v_exp_f32_e32 v1, v1
	v_exp_f32_e32 v4, v4
	v_add_f32_e32 v1, 1.0, v1
	v_add_f32_e32 v4, 1.0, v4
	v_rcp_f32_e32 v1, v1
	v_rcp_f32_e32 v4, v4
	v_mul_f32_e32 v1, v14, v1
	v_mul_f32_e32 v4, v15, v4
	v_mul_f32_e32 v1, v1, v6
	v_mul_f32_e32 v4, v4, v7
	v_cvt_pk_bf16_f32 v1, v1, v4
	v_mul_f32_e32 v4, 0xbfb8aa3b, v8
	v_exp_f32_e32 v4, v4
	s_nop 0
	v_add_f32_e32 v4, 1.0, v4
	v_rcp_f32_e32 v4, v4
	s_nop 0
	v_mul_f32_e32 v4, v8, v4
	v_mul_f32_e32 v2, v4, v2
	v_mul_f32_e32 v4, 0xbfb8aa3b, v9
	v_exp_f32_e32 v4, v4
	s_nop 0
	v_add_f32_e32 v4, 1.0, v4
	v_rcp_f32_e32 v4, v4
	s_nop 0
	v_mul_f32_e32 v4, v9, v4
	v_mul_f32_e32 v3, v4, v3
	v_cvt_pk_bf16_f32 v2, v2, v3
	v_mul_f32_e32 v3, 0xbfb8aa3b, v10
	v_mul_f32_e32 v4, 0xbfb8aa3b, v11
	v_exp_f32_e32 v3, v3
	v_exp_f32_e32 v4, v4
	v_add_f32_e32 v3, 1.0, v3
	v_add_f32_e32 v4, 1.0, v4
	v_rcp_f32_e32 v3, v3
	v_rcp_f32_e32 v4, v4
	v_mul_f32_e32 v3, v10, v3
	v_mul_f32_e32 v4, v11, v4
	v_mul_f32_e32 v3, v3, v16
	v_mul_f32_e32 v4, v4, v17
	v_cvt_pk_bf16_f32 v3, v3, v4
	v_add_u32_e32 v4, 0xb0, v151
	v_mad_i64_i32 v[4:5], s[44:45], v4, s29, v[114:115]
	v_lshl_add_u64 v[4:5], v[4:5], 0, v[116:117]
	s_mov_b64 s[44:45], -1
	global_store_dwordx4 v[4:5], v[0:3], off
	s_cbranch_vccnz .LBB0_575
	s_lshl_b32 s42, s8, 8
	s_ashr_i32 s43, s42, 31
	v_lshl_add_u64 v[0:1], s[42:43], 2, v[138:139]
	global_load_dword v158, v[0:1], off
	global_load_dword v156, v[0:1], off offset:64
	global_load_dword v154, v[0:1], off offset:128
	global_load_dword v152, v[0:1], off offset:192
	global_load_dword v150, v[0:1], off offset:512
	global_load_dword v148, v[0:1], off offset:576
	global_load_dword v146, v[0:1], off offset:640
	global_load_dword v144, v[0:1], off offset:704
	s_andn2_b64 vcc, exec, s[2:3]
	s_cmp_lg_u32 s2, 0
	s_cselect_b32 s100, 1, 0
	s_branch .LBB0_574
